# v100 base with 56 redundant post-barrier lgkmcnt(0) waits removed (setprio pairs kept)
# speedup vs baseline: 1.0060x; 1.0060x over previous
; #define PG8_STAGE(bufoff, gbase, voff) do { _Pragma("unroll") for (int _i = 0; _i < 2; ++_i) \
;         __builtin_amdgcn_global_load_lds((const unsigned*)((const char*)(gbase) + (voff)[_i]), (LAS unsigned*)(lds + (bufoff) + ldsw + _i * 8192), 16, 0, 0); } while (0)
; #define PG8_LDA(dst, b, h) do { _Pragma("unroll") for (int m = 0; m < 4; ++m) _Pragma("unroll") for (int k = 0; k < 2; ++k) dst[m][k] = *(const LAS bf16x8*)(lds + PG8_SA(b, h) + aoff + m * 2048 + k * 1024); } while (0)
; #define PG8_LDB(dst, b, h) do { _Pragma("unroll") for (int n = 0; n < 2; ++n) _Pragma("unroll") for (int k = 0; k < 2; ++k) dst[n][k] = *(const LAS bf16x8*)(lds + PG8_SB(b, h) + boff + n * 2048 + k * 1024); } while (0)
; #define PG8_MMA(ai, bj, At, Bt) do { __builtin_amdgcn_s_setprio(1); _Pragma("unroll") for (int m = 0; m < 4; ++m) _Pragma("unroll") for (int n = 0; n < 2; ++n) _Pragma("unroll") for (int k = 0; k < 2; ++k) \
;         acc[ai][bj][m][n] = __builtin_amdgcn_mfma_f32_16x16x32_bf16(Bt[n][k], At[m][k], acc[ai][bj][m][n], 0, 0, 0); __builtin_amdgcn_s_setprio(0); } while (0)
; #define PG8_WAIT_V(n) asm volatile("s_waitcnt vmcnt(" #n ")" ::: "memory")
; #define PG8_WAIT_L(n) asm volatile("s_waitcnt lgkmcnt(" #n ")" ::: "memory")
; #define PG8_BAR __builtin_amdgcn_s_barrier()
; #define PG8_SCHED __builtin_amdgcn_sched_barrier(0)
; template <class Epi>
; __device__ __forceinline__ void gemm_phase(LAS unsigned char* lds, const Gemm g, const StaticOrder& S, const Epi& E) {
;     ...
;             const bool last = (t == nt - 2);
;             const char* a1 = cA + (size_t)(t + 1) * kstep;
;             const char* a2 = last ? nA : cA + (size_t)(t + 2) * kstep; const char* b2 = last ? nB : cB + (size_t)(t + 2) * kstep;
;             const char* a3 = a2 + kstep; const char* b3 = b2 + kstep;
;             PG8_LDB(B0, 0, 0); PG8_LDB(B1, 0, 1); PG8_SCHED; PG8_LDA(At, 0, 0); PG8_STAGE(PG8_SA(1, 1), a1 + hstepA, voffA);
;             PG8_WAIT_V(8); PG8_WAIT_L(0); PG8_BAR; PG8_MMA(0, 0, At, B0); PG8_MMA(0, 1, At, B1); PG8_BAR; PG8_SCHED;
;             PG8_LDA(At, 0, 1); PG8_STAGE(PG8_SB(0, 0), b2, voffB); PG8_STAGE(PG8_SB(0, 1), b2 + hstepB, voffB); PG8_STAGE(PG8_SA(0, 0), a2, voffA);
.LBB0_163:
	s_add_u32 s22, s44, 0xfffc0080
	s_addc_u32 s23, s45, -1
	s_add_i32 s66, 0, 0x10000
	s_cmp_eq_u32 s65, 12
	s_cselect_b32 s47, s35, s23
	s_cselect_b32 s46, s61, s22
	v_add_u32_e32 v142, s66, v144
	s_cselect_b32 s23, s15, s64
	s_cselect_b32 s22, s62, s63
	s_add_i32 s68, 0, 0x14000
	ds_read_b128 v[148:151], v142
	ds_read_b128 v[152:155], v142 offset:1024
	ds_read_b128 v[156:159], v142 offset:2048
	ds_read_b128 v[160:163], v142 offset:3072
	v_add_u32_e32 v142, s68, v144
	ds_read_b128 v[164:167], v142
	ds_read_b128 v[168:171], v142 offset:1024
	ds_read_b128 v[172:175], v142 offset:2048
	ds_read_b128 v[176:179], v142 offset:3072
	v_lshl_add_u64 v[142:143], s[44:45], 0, v[138:139]
	s_add_i32 m0, s53, 0xc000
	ds_read_b128 v[180:183], v146
	ds_read_b128 v[184:187], v146 offset:1024
	ds_read_b128 v[188:191], v146 offset:2048
	ds_read_b128 v[192:195], v146 offset:3072
	ds_read_b128 v[210:213], v146 offset:4096
	ds_read_b128 v[214:217], v146 offset:5120
	ds_read_b128 v[218:221], v146 offset:6144
	ds_read_b128 v[222:225], v146 offset:7168
	global_load_lds_dwordx4 v[142:143], off
	v_lshl_add_u64 v[142:143], s[44:45], 0, v[140:141]
	s_add_i32 m0, s53, 0xe000
	s_nop 0
	global_load_lds_dwordx4 v[142:143], off
	s_waitcnt vmcnt(8)
	s_waitcnt lgkmcnt(0)
	s_barrier
	s_setprio 1
	v_mfma_f32_16x16x32_bf16 v[128:131], v[148:151], v[180:183], v[128:131]
	v_mfma_f32_16x16x32_bf16 v[120:123], v[156:159], v[180:183], v[120:123]
	v_mfma_f32_16x16x32_bf16 v[112:115], v[148:151], v[188:191], v[112:115]
	v_mfma_f32_16x16x32_bf16 v[100:103], v[156:159], v[188:191], v[100:103]
	v_mfma_f32_16x16x32_bf16 v[92:95], v[148:151], v[210:213], v[92:95]
	v_mfma_f32_16x16x32_bf16 v[84:87], v[156:159], v[210:213], v[84:87]
	v_mfma_f32_16x16x32_bf16 v[76:79], v[148:151], v[218:221], v[76:79]
	v_mfma_f32_16x16x32_bf16 v[68:71], v[156:159], v[218:221], v[68:71]
	v_mfma_f32_16x16x32_bf16 v[128:131], v[152:155], v[184:187], v[128:131]
	v_mfma_f32_16x16x32_bf16 v[120:123], v[160:163], v[184:187], v[120:123]
	v_mfma_f32_16x16x32_bf16 v[112:115], v[152:155], v[192:195], v[112:115]
	v_mfma_f32_16x16x32_bf16 v[100:103], v[160:163], v[192:195], v[100:103]
	v_mfma_f32_16x16x32_bf16 v[92:95], v[152:155], v[214:217], v[92:95]
	v_mfma_f32_16x16x32_bf16 v[84:87], v[160:163], v[214:217], v[84:87]
	v_mfma_f32_16x16x32_bf16 v[76:79], v[152:155], v[222:225], v[76:79]
	v_mfma_f32_16x16x32_bf16 v[68:71], v[160:163], v[222:225], v[68:71]
	s_setprio 0
	s_setprio 1
	v_mfma_f32_16x16x32_bf16 v[124:127], v[164:167], v[180:183], v[124:127]
	v_mfma_f32_16x16x32_bf16 v[116:119], v[172:175], v[180:183], v[116:119]
	v_mfma_f32_16x16x32_bf16 v[108:111], v[164:167], v[188:191], v[108:111]
	v_mfma_f32_16x16x32_bf16 v[104:107], v[172:175], v[188:191], v[104:107]
	v_mfma_f32_16x16x32_bf16 v[96:99], v[164:167], v[210:213], v[96:99]
	v_mfma_f32_16x16x32_bf16 v[88:91], v[172:175], v[210:213], v[88:91]
	v_mfma_f32_16x16x32_bf16 v[80:83], v[164:167], v[218:221], v[80:83]
	v_mfma_f32_16x16x32_bf16 v[72:75], v[172:175], v[218:221], v[72:75]
	v_mfma_f32_16x16x32_bf16 v[124:127], v[168:171], v[184:187], v[124:127]
	v_mfma_f32_16x16x32_bf16 v[116:119], v[176:179], v[184:187], v[116:119]
	v_mfma_f32_16x16x32_bf16 v[108:111], v[168:171], v[192:195], v[108:111]
	v_mfma_f32_16x16x32_bf16 v[104:107], v[176:179], v[192:195], v[104:107]
	v_mfma_f32_16x16x32_bf16 v[96:99], v[168:171], v[214:217], v[96:99]
	v_mfma_f32_16x16x32_bf16 v[88:91], v[176:179], v[214:217], v[88:91]
	v_mfma_f32_16x16x32_bf16 v[80:83], v[168:171], v[222:225], v[80:83]
	v_mfma_f32_16x16x32_bf16 v[72:75], v[176:179], v[222:225], v[72:75]
	s_setprio 0
	s_barrier
	s_add_i32 s66, s66, s52
	v_lshl_add_u64 v[142:143], s[22:23], 0, v[134:135]
	s_mov_b32 m0, s66
	ds_read_b128 v[180:183], v146 offset:16384
	ds_read_b128 v[184:187], v146 offset:17408
	ds_read_b128 v[188:191], v146 offset:18432
	ds_read_b128 v[192:195], v146 offset:19456
	ds_read_b128 v[210:213], v146 offset:20480
	ds_read_b128 v[214:217], v146 offset:21504
	ds_read_b128 v[218:221], v146 offset:22528
	ds_read_b128 v[222:225], v146 offset:23552
	global_load_lds_dwordx4 v[142:143], off
	s_add_i32 m0, s66, 0x2000
	s_add_u32 s66, s22, 0x10000
	v_lshl_add_u64 v[196:197], s[22:23], 0, v[0:1]
	s_addc_u32 s67, s23, 0
	s_add_i32 s68, s68, s52
	global_load_lds_dwordx4 v[196:197], off
	v_lshl_add_u64 v[198:199], s[66:67], 0, v[134:135]
	s_mov_b32 m0, s68
	v_lshl_add_u64 v[226:227], s[46:47], 0, v[132:133]
	global_load_lds_dwordx4 v[198:199], off
	v_lshl_add_u64 v[198:199], s[66:67], 0, v[0:1]
	s_add_i32 m0, s68, 0x2000
	s_nop 0
	global_load_lds_dwordx4 v[198:199], off
	v_lshl_add_u64 v[198:199], s[46:47], 0, v[136:137]
	s_mov_b32 m0, s53
	s_nop 0
	global_load_lds_dwordx4 v[198:199], off
	s_mov_b32 m0, s54
	s_nop 0
	global_load_lds_dwordx4 v[226:227], off
	s_waitcnt vmcnt(8)
	s_waitcnt lgkmcnt(0)
	s_barrier
; #define PG8_STAGE(bufoff, gbase, voff) do { _Pragma("unroll") for (int _i = 0; _i < 2; ++_i) \
;         __builtin_amdgcn_global_load_lds((const unsigned*)((const char*)(gbase) + (voff)[_i]), (LAS unsigned*)(lds + (bufoff) + ldsw + _i * 8192), 16, 0, 0); } while (0)
; #define PG8_LDA(dst, b, h) do { _Pragma("unroll") for (int m = 0; m < 4; ++m) _Pragma("unroll") for (int k = 0; k < 2; ++k) dst[m][k] = *(const LAS bf16x8*)(lds + PG8_SA(b, h) + aoff + m * 2048 + k * 1024); } while (0)
; #define PG8_LDB(dst, b, h) do { _Pragma("unroll") for (int n = 0; n < 2; ++n) _Pragma("unroll") for (int k = 0; k < 2; ++k) dst[n][k] = *(const LAS bf16x8*)(lds + PG8_SB(b, h) + boff + n * 2048 + k * 1024); } while (0)
; #define PG8_MMA(ai, bj, At, Bt) do { __builtin_amdgcn_s_setprio(1); _Pragma("unroll") for (int m = 0; m < 4; ++m) _Pragma("unroll") for (int n = 0; n < 2; ++n) _Pragma("unroll") for (int k = 0; k < 2; ++k) \
;         acc[ai][bj][m][n] = __builtin_amdgcn_mfma_f32_16x16x32_bf16(Bt[n][k], At[m][k], acc[ai][bj][m][n], 0, 0, 0); __builtin_amdgcn_s_setprio(0); } while (0)
; #define PG8_WAIT_V(n) asm volatile("s_waitcnt vmcnt(" #n ")" ::: "memory")
; #define PG8_WAIT_L(n) asm volatile("s_waitcnt lgkmcnt(" #n ")" ::: "memory")
; #define PG8_BAR __builtin_amdgcn_s_barrier()
; #define PG8_SCHED __builtin_amdgcn_sched_barrier(0)
; template <class Epi>
; __device__ __forceinline__ void gemm_phase(LAS unsigned char* lds, const Gemm g, const StaticOrder& S, const Epi& E) {
;     ...
;             PG8_WAIT_V(8); PG8_WAIT_L(0); PG8_BAR; PG8_MMA(1, 0, At, B0); PG8_MMA(1, 1, At, B1); PG8_BAR; PG8_SCHED;
;             PG8_LDB(B0, 1, 0); PG8_LDB(B1, 1, 1); PG8_SCHED; PG8_LDA(At, 1, 0); PG8_STAGE(PG8_SA(0, 1), a2 + hstepA, voffA);
;             PG8_WAIT_V(8); PG8_WAIT_L(0); PG8_BAR; PG8_MMA(0, 0, At, B0); PG8_MMA(0, 1, At, B1); PG8_BAR; PG8_SCHED;
	s_setprio 1
	v_mfma_f32_16x16x32_bf16 v[60:63], v[148:151], v[180:183], v[60:63]
	v_mfma_f32_16x16x32_bf16 v[52:55], v[156:159], v[180:183], v[52:55]
	v_mfma_f32_16x16x32_bf16 v[44:47], v[148:151], v[188:191], v[44:47]
	v_mfma_f32_16x16x32_bf16 v[36:39], v[156:159], v[188:191], v[36:39]
	v_mfma_f32_16x16x32_bf16 v[28:31], v[148:151], v[210:213], v[28:31]
	v_mfma_f32_16x16x32_bf16 v[20:23], v[156:159], v[210:213], v[20:23]
	v_mfma_f32_16x16x32_bf16 v[4:7], v[148:151], v[218:221], v[4:7]
	v_mfma_f32_16x16x32_bf16 v[12:15], v[156:159], v[218:221], v[12:15]
	v_mfma_f32_16x16x32_bf16 v[60:63], v[152:155], v[184:187], v[60:63]
	v_mfma_f32_16x16x32_bf16 v[52:55], v[160:163], v[184:187], v[52:55]
	v_mfma_f32_16x16x32_bf16 v[44:47], v[152:155], v[192:195], v[44:47]
	v_mfma_f32_16x16x32_bf16 v[36:39], v[160:163], v[192:195], v[36:39]
	v_mfma_f32_16x16x32_bf16 v[28:31], v[152:155], v[214:217], v[28:31]
	v_mfma_f32_16x16x32_bf16 v[20:23], v[160:163], v[214:217], v[20:23]
	v_mfma_f32_16x16x32_bf16 v[4:7], v[152:155], v[222:225], v[4:7]
	v_mfma_f32_16x16x32_bf16 v[12:15], v[160:163], v[222:225], v[12:15]
	s_setprio 0
	s_setprio 1
	v_mfma_f32_16x16x32_bf16 v[64:67], v[164:167], v[180:183], v[64:67]
	v_mfma_f32_16x16x32_bf16 v[56:59], v[172:175], v[180:183], v[56:59]
	v_mfma_f32_16x16x32_bf16 v[48:51], v[164:167], v[188:191], v[48:51]
	v_mfma_f32_16x16x32_bf16 v[40:43], v[172:175], v[188:191], v[40:43]
	v_mfma_f32_16x16x32_bf16 v[32:35], v[164:167], v[210:213], v[32:35]
	v_mfma_f32_16x16x32_bf16 v[24:27], v[172:175], v[210:213], v[24:27]
	v_mfma_f32_16x16x32_bf16 v[8:11], v[164:167], v[218:221], v[8:11]
	v_mfma_f32_16x16x32_bf16 v[16:19], v[172:175], v[218:221], v[16:19]
	v_mfma_f32_16x16x32_bf16 v[64:67], v[168:171], v[184:187], v[64:67]
	v_mfma_f32_16x16x32_bf16 v[56:59], v[176:179], v[184:187], v[56:59]
	v_mfma_f32_16x16x32_bf16 v[48:51], v[168:171], v[192:195], v[48:51]
	v_mfma_f32_16x16x32_bf16 v[40:43], v[176:179], v[192:195], v[40:43]
	v_mfma_f32_16x16x32_bf16 v[32:35], v[168:171], v[214:217], v[32:35]
	v_mfma_f32_16x16x32_bf16 v[24:27], v[176:179], v[214:217], v[24:27]
	v_mfma_f32_16x16x32_bf16 v[8:11], v[168:171], v[222:225], v[8:11]
	v_mfma_f32_16x16x32_bf16 v[16:19], v[176:179], v[222:225], v[16:19]
	s_setprio 0
	s_barrier
	s_add_i32 s66, 0, 0x18000
	v_add_u32_e32 v147, s66, v144
	s_add_i32 s67, 0, 0x1c000
	ds_read_b128 v[148:151], v147
	ds_read_b128 v[152:155], v147 offset:1024
	ds_read_b128 v[156:159], v147 offset:2048
	ds_read_b128 v[160:163], v147 offset:3072
	v_add_u32_e32 v147, s67, v144
	ds_read_b128 v[164:167], v147
	ds_read_b128 v[168:171], v147 offset:1024
	ds_read_b128 v[172:175], v147 offset:2048
	ds_read_b128 v[176:179], v147 offset:3072
	s_add_u32 s46, s46, 0x40000
	s_addc_u32 s47, s47, 0
	s_mov_b32 m0, s55
	v_lshl_add_u64 v[228:229], s[46:47], 0, v[136:137]
	ds_read_b128 v[180:183], v146 offset:32768
	ds_read_b128 v[184:187], v146 offset:33792
	ds_read_b128 v[188:191], v146 offset:34816
	ds_read_b128 v[192:195], v146 offset:35840
	ds_read_b128 v[210:213], v146 offset:36864
	ds_read_b128 v[214:217], v146 offset:37888
	ds_read_b128 v[218:221], v146 offset:38912
	ds_read_b128 v[222:225], v146 offset:39936
	global_load_lds_dwordx4 v[228:229], off
	v_lshl_add_u64 v[228:229], s[46:47], 0, v[132:133]
	s_mov_b32 m0, s56
	s_nop 0
	global_load_lds_dwordx4 v[228:229], off
	s_waitcnt vmcnt(8)
	s_waitcnt lgkmcnt(0)
	s_barrier
	s_setprio 1
	v_mfma_f32_16x16x32_bf16 v[128:131], v[148:151], v[180:183], v[128:131]
	v_mfma_f32_16x16x32_bf16 v[120:123], v[156:159], v[180:183], v[120:123]
	v_mfma_f32_16x16x32_bf16 v[112:115], v[148:151], v[188:191], v[112:115]
	v_mfma_f32_16x16x32_bf16 v[100:103], v[156:159], v[188:191], v[100:103]
	v_mfma_f32_16x16x32_bf16 v[92:95], v[148:151], v[210:213], v[92:95]
	v_mfma_f32_16x16x32_bf16 v[84:87], v[156:159], v[210:213], v[84:87]
	v_mfma_f32_16x16x32_bf16 v[76:79], v[148:151], v[218:221], v[76:79]
	v_mfma_f32_16x16x32_bf16 v[68:71], v[156:159], v[218:221], v[68:71]
	v_mfma_f32_16x16x32_bf16 v[128:131], v[152:155], v[184:187], v[128:131]
	v_mfma_f32_16x16x32_bf16 v[120:123], v[160:163], v[184:187], v[120:123]
	v_mfma_f32_16x16x32_bf16 v[112:115], v[152:155], v[192:195], v[112:115]
	v_mfma_f32_16x16x32_bf16 v[100:103], v[160:163], v[192:195], v[100:103]
	v_mfma_f32_16x16x32_bf16 v[92:95], v[152:155], v[214:217], v[92:95]
	v_mfma_f32_16x16x32_bf16 v[84:87], v[160:163], v[214:217], v[84:87]
	v_mfma_f32_16x16x32_bf16 v[76:79], v[152:155], v[222:225], v[76:79]
	v_mfma_f32_16x16x32_bf16 v[68:71], v[160:163], v[222:225], v[68:71]
	s_setprio 0
	s_setprio 1
	v_mfma_f32_16x16x32_bf16 v[124:127], v[164:167], v[180:183], v[124:127]
	v_mfma_f32_16x16x32_bf16 v[116:119], v[172:175], v[180:183], v[116:119]
	v_mfma_f32_16x16x32_bf16 v[108:111], v[164:167], v[188:191], v[108:111]
	v_mfma_f32_16x16x32_bf16 v[104:107], v[172:175], v[188:191], v[104:107]
	v_mfma_f32_16x16x32_bf16 v[96:99], v[164:167], v[210:213], v[96:99]
	v_mfma_f32_16x16x32_bf16 v[88:91], v[172:175], v[210:213], v[88:91]
	v_mfma_f32_16x16x32_bf16 v[80:83], v[164:167], v[218:221], v[80:83]
	v_mfma_f32_16x16x32_bf16 v[72:75], v[172:175], v[218:221], v[72:75]
	v_mfma_f32_16x16x32_bf16 v[124:127], v[168:171], v[184:187], v[124:127]
	v_mfma_f32_16x16x32_bf16 v[116:119], v[176:179], v[184:187], v[116:119]
	v_mfma_f32_16x16x32_bf16 v[108:111], v[168:171], v[192:195], v[108:111]
	v_mfma_f32_16x16x32_bf16 v[104:107], v[176:179], v[192:195], v[104:107]
	v_mfma_f32_16x16x32_bf16 v[96:99], v[168:171], v[214:217], v[96:99]
	v_mfma_f32_16x16x32_bf16 v[88:91], v[176:179], v[214:217], v[88:91]
	v_mfma_f32_16x16x32_bf16 v[80:83], v[168:171], v[222:225], v[80:83]
	v_mfma_f32_16x16x32_bf16 v[72:75], v[176:179], v[222:225], v[72:75]
	s_setprio 0
	s_barrier
; #define PG8_STAGE(bufoff, gbase, voff) do { _Pragma("unroll") for (int _i = 0; _i < 2; ++_i) \
;         __builtin_amdgcn_global_load_lds((const unsigned*)((const char*)(gbase) + (voff)[_i]), (LAS unsigned*)(lds + (bufoff) + ldsw + _i * 8192), 16, 0, 0); } while (0)
; #define PG8_LDA(dst, b, h) do { _Pragma("unroll") for (int m = 0; m < 4; ++m) _Pragma("unroll") for (int k = 0; k < 2; ++k) dst[m][k] = *(const LAS bf16x8*)(lds + PG8_SA(b, h) + aoff + m * 2048 + k * 1024); } while (0)
; #define PG8_MMA(ai, bj, At, Bt) do { __builtin_amdgcn_s_setprio(1); _Pragma("unroll") for (int m = 0; m < 4; ++m) _Pragma("unroll") for (int n = 0; n < 2; ++n) _Pragma("unroll") for (int k = 0; k < 2; ++k) \
;         acc[ai][bj][m][n] = __builtin_amdgcn_mfma_f32_16x16x32_bf16(Bt[n][k], At[m][k], acc[ai][bj][m][n], 0, 0, 0); __builtin_amdgcn_s_setprio(0); } while (0)
; #define PG8_WAIT_V(n) asm volatile("s_waitcnt vmcnt(" #n ")" ::: "memory")
; #define PG8_WAIT_L(n) asm volatile("s_waitcnt lgkmcnt(" #n ")" ::: "memory")
; #define PG8_BAR __builtin_amdgcn_s_barrier()
; #define PG8_SCHED __builtin_amdgcn_sched_barrier(0)
; template <class Epi>
; __device__ __forceinline__ void gemm_phase(LAS unsigned char* lds, const Gemm g, const StaticOrder& S, const Epi& E) {
;     ...
;             PG8_LDA(At, 1, 1); PG8_STAGE(PG8_SB(1, 0), b3, voffB); PG8_STAGE(PG8_SB(1, 1), b3 + hstepB, voffB); PG8_STAGE(PG8_SA(1, 0), a3, voffA);
;             PG8_WAIT_V(8); PG8_WAIT_L(0); PG8_BAR; PG8_MMA(1, 0, At, B0); PG8_MMA(1, 1, At, B1); PG8_BAR; PG8_SCHED;
;         }
;         if (wr == 0) PG8_BAR;
	s_add_i32 s46, s66, s52
	v_lshl_add_u64 v[142:143], v[142:143], 0, s[30:31]
	s_mov_b32 m0, s46
	ds_read_b128 v[180:183], v146 offset:49152
	ds_read_b128 v[184:187], v146 offset:50176
	ds_read_b128 v[188:191], v146 offset:51200
	ds_read_b128 v[192:195], v146 offset:52224
	ds_read_b128 v[210:213], v146 offset:53248
	ds_read_b128 v[214:217], v146 offset:54272
	ds_read_b128 v[218:221], v146 offset:55296
	ds_read_b128 v[222:225], v146 offset:56320
	global_load_lds_dwordx4 v[142:143], off
	s_add_i32 m0, s46, 0x2000
	s_add_u32 s22, s22, 0x10080
	v_lshl_add_u64 v[142:143], v[196:197], 0, s[30:31]
	s_addc_u32 s23, s23, 0
	s_add_i32 s46, s67, s52
	global_load_lds_dwordx4 v[142:143], off
	v_lshl_add_u64 v[142:143], s[22:23], 0, v[134:135]
	s_mov_b32 m0, s46
	s_nop 0
	global_load_lds_dwordx4 v[142:143], off
	v_lshl_add_u64 v[142:143], s[22:23], 0, v[0:1]
	s_add_i32 m0, s46, 0x2000
	s_nop 0
	global_load_lds_dwordx4 v[142:143], off
	v_lshl_add_u64 v[142:143], v[198:199], 0, s[30:31]
	s_mov_b32 m0, s28
	s_nop 0
	global_load_lds_dwordx4 v[142:143], off
	v_lshl_add_u64 v[142:143], v[226:227], 0, s[30:31]
	s_mov_b32 m0, s57
	s_nop 0
	global_load_lds_dwordx4 v[142:143], off
	s_waitcnt vmcnt(8)
	s_waitcnt lgkmcnt(0)
	s_barrier
	s_setprio 1
	v_mfma_f32_16x16x32_bf16 v[60:63], v[148:151], v[180:183], v[60:63]
	v_mfma_f32_16x16x32_bf16 v[52:55], v[156:159], v[180:183], v[52:55]
	v_mfma_f32_16x16x32_bf16 v[44:47], v[148:151], v[188:191], v[44:47]
	v_mfma_f32_16x16x32_bf16 v[36:39], v[156:159], v[188:191], v[36:39]
	v_mfma_f32_16x16x32_bf16 v[28:31], v[148:151], v[210:213], v[28:31]
	v_mfma_f32_16x16x32_bf16 v[20:23], v[156:159], v[210:213], v[20:23]
	v_mfma_f32_16x16x32_bf16 v[4:7], v[148:151], v[218:221], v[4:7]
	v_mfma_f32_16x16x32_bf16 v[12:15], v[156:159], v[218:221], v[12:15]
	v_mfma_f32_16x16x32_bf16 v[60:63], v[152:155], v[184:187], v[60:63]
	v_mfma_f32_16x16x32_bf16 v[52:55], v[160:163], v[184:187], v[52:55]
	v_mfma_f32_16x16x32_bf16 v[44:47], v[152:155], v[192:195], v[44:47]
	v_mfma_f32_16x16x32_bf16 v[36:39], v[160:163], v[192:195], v[36:39]
	v_mfma_f32_16x16x32_bf16 v[28:31], v[152:155], v[214:217], v[28:31]
	v_mfma_f32_16x16x32_bf16 v[20:23], v[160:163], v[214:217], v[20:23]
	v_mfma_f32_16x16x32_bf16 v[4:7], v[152:155], v[222:225], v[4:7]
	v_mfma_f32_16x16x32_bf16 v[12:15], v[160:163], v[222:225], v[12:15]
	s_setprio 0
	s_setprio 1
	v_mfma_f32_16x16x32_bf16 v[64:67], v[164:167], v[180:183], v[64:67]
	v_mfma_f32_16x16x32_bf16 v[56:59], v[172:175], v[180:183], v[56:59]
	v_mfma_f32_16x16x32_bf16 v[48:51], v[164:167], v[188:191], v[48:51]
	v_mfma_f32_16x16x32_bf16 v[40:43], v[172:175], v[188:191], v[40:43]
	v_mfma_f32_16x16x32_bf16 v[32:35], v[164:167], v[210:213], v[32:35]
	v_mfma_f32_16x16x32_bf16 v[24:27], v[172:175], v[210:213], v[24:27]
	v_mfma_f32_16x16x32_bf16 v[8:11], v[164:167], v[218:221], v[8:11]
	v_mfma_f32_16x16x32_bf16 v[16:19], v[172:175], v[218:221], v[16:19]
	v_mfma_f32_16x16x32_bf16 v[64:67], v[168:171], v[184:187], v[64:67]
	v_mfma_f32_16x16x32_bf16 v[56:59], v[176:179], v[184:187], v[56:59]
	v_mfma_f32_16x16x32_bf16 v[48:51], v[168:171], v[192:195], v[48:51]
	v_mfma_f32_16x16x32_bf16 v[40:43], v[176:179], v[192:195], v[40:43]
	v_mfma_f32_16x16x32_bf16 v[32:35], v[168:171], v[214:217], v[32:35]
	v_mfma_f32_16x16x32_bf16 v[24:27], v[176:179], v[214:217], v[24:27]
	v_mfma_f32_16x16x32_bf16 v[8:11], v[168:171], v[222:225], v[8:11]
	v_mfma_f32_16x16x32_bf16 v[16:19], v[176:179], v[222:225], v[16:19]
	s_setprio 0
	s_barrier
	s_add_i32 s65, s65, 2
	s_add_u32 s44, s44, 0x100
	s_addc_u32 s45, s45, 0
	s_add_u32 s63, s63, 0x100
	s_addc_u32 s64, s64, 0
	s_cmp_gt_u32 s65, 13
	s_cbranch_scc0 .LBB0_163
	s_and_b64 vcc, exec, s[12:13]
	s_cbranch_vccz .LBB0_166
	s_barrier

; #define PG8_STAGE(bufoff, gbase, voff) do { _Pragma("unroll") for (int _i = 0; _i < 2; ++_i) \
;         __builtin_amdgcn_global_load_lds((const unsigned*)((const char*)(gbase) + (voff)[_i]), (LAS unsigned*)(lds + (bufoff) + ldsw + _i * 8192), 16, 0, 0); } while (0)
; #define PG8_LDA(dst, b, h) do { _Pragma("unroll") for (int m = 0; m < 4; ++m) _Pragma("unroll") for (int k = 0; k < 2; ++k) dst[m][k] = *(const LAS bf16x8*)(lds + PG8_SA(b, h) + aoff + m * 2048 + k * 1024); } while (0)
; #define PG8_LDB(dst, b, h) do { _Pragma("unroll") for (int n = 0; n < 2; ++n) _Pragma("unroll") for (int k = 0; k < 2; ++k) dst[n][k] = *(const LAS bf16x8*)(lds + PG8_SB(b, h) + boff + n * 2048 + k * 1024); } while (0)
; #define PG8_MMA(ai, bj, At, Bt) do { __builtin_amdgcn_s_setprio(1); _Pragma("unroll") for (int m = 0; m < 4; ++m) _Pragma("unroll") for (int n = 0; n < 2; ++n) _Pragma("unroll") for (int k = 0; k < 2; ++k) \
;         acc[ai][bj][m][n] = __builtin_amdgcn_mfma_f32_16x16x32_bf16(Bt[n][k], At[m][k], acc[ai][bj][m][n], 0, 0, 0); __builtin_amdgcn_s_setprio(0); } while (0)
; #define PG8_WAIT_V(n) asm volatile("s_waitcnt vmcnt(" #n ")" ::: "memory")
; #define PG8_WAIT_L(n) asm volatile("s_waitcnt lgkmcnt(" #n ")" ::: "memory")
; #define PG8_BAR __builtin_amdgcn_s_barrier()
; #define PG8_SCHED __builtin_amdgcn_sched_barrier(0)
; template <class Epi>
; __device__ __forceinline__ void gemm_phase(LAS unsigned char* lds, const Gemm g, const StaticOrder& S, const Epi& E) {
;     ...
;         for (int t = 0; t < nt; t += 2) {
;             const bool last = (t == nt - 2);
;             const char* a1 = cA + (size_t)(t + 1) * kstep;
;             const char* a2 = last ? nA : cA + (size_t)(t + 2) * kstep; const char* b2 = last ? nB : cB + (size_t)(t + 2) * kstep;
;             const char* a3 = a2 + kstep; const char* b3 = b2 + kstep;
;             PG8_LDB(B0, 0, 0); PG8_LDB(B1, 0, 1); PG8_SCHED; PG8_LDA(At, 0, 0); PG8_STAGE(PG8_SA(1, 1), a1 + hstepA, voffA);
;             PG8_WAIT_V(8); PG8_WAIT_L(0); PG8_BAR; PG8_MMA(0, 0, At, B0); PG8_MMA(0, 1, At, B1); PG8_BAR; PG8_SCHED;
;             PG8_LDA(At, 0, 1); PG8_STAGE(PG8_SB(0, 0), b2, voffB); PG8_STAGE(PG8_SB(0, 1), b2 + hstepB, voffB); PG8_STAGE(PG8_SA(0, 0), a2, voffA);
.LBB0_240:
	s_add_u32 s48, s46, 0x100
	s_addc_u32 s49, s47, 0
	s_add_i32 s70, 0, 0x10000
	s_cmp_eq_u32 s69, 40
	s_cselect_b32 s51, s5, s49
	s_cselect_b32 s50, s4, s48
	s_cselect_b32 s23, s41, s68
	s_cselect_b32 s22, s40, s67
	s_add_i32 s71, 0, 0x14000
	v_add_u32_e32 v144, s70, v230
	v_add_u32_e32 v160, s71, v230
	ds_read_b128 v[132:135], v144
	ds_read_b128 v[136:139], v144 offset:1024
	ds_read_b128 v[140:143], v144 offset:2048
	ds_read_b128 v[144:147], v144 offset:3072
	ds_read_b128 v[148:151], v160
	ds_read_b128 v[152:155], v160 offset:1024
	ds_read_b128 v[156:159], v160 offset:2048
	ds_read_b128 v[160:163], v160 offset:3072
	v_lshl_add_u64 v[196:197], s[46:47], 0, v[194:195]
	s_add_i32 m0, s57, 0xc000
	ds_read_b128 v[164:167], v232
	ds_read_b128 v[168:171], v232 offset:1024
	ds_read_b128 v[172:175], v232 offset:2048
	ds_read_b128 v[176:179], v232 offset:3072
	ds_read_b128 v[180:183], v232 offset:4096
	ds_read_b128 v[184:187], v232 offset:5120
	ds_read_b128 v[212:215], v232 offset:6144
	ds_read_b128 v[216:219], v232 offset:7168
	global_load_lds_dwordx4 v[196:197], off
	v_lshl_add_u64 v[196:197], s[46:47], 0, v[210:211]
	s_add_i32 m0, s57, 0xe000
	s_nop 0
	global_load_lds_dwordx4 v[196:197], off
	s_waitcnt vmcnt(8)
	s_waitcnt lgkmcnt(0)
	s_barrier
	s_setprio 1
	v_mfma_f32_16x16x32_bf16 v[128:131], v[132:135], v[164:167], v[128:131]
	v_mfma_f32_16x16x32_bf16 v[124:127], v[140:143], v[164:167], v[124:127]
	v_mfma_f32_16x16x32_bf16 v[112:115], v[132:135], v[172:175], v[112:115]
	v_mfma_f32_16x16x32_bf16 v[108:111], v[140:143], v[172:175], v[108:111]
	v_mfma_f32_16x16x32_bf16 v[96:99], v[132:135], v[180:183], v[96:99]
	v_mfma_f32_16x16x32_bf16 v[92:95], v[140:143], v[180:183], v[92:95]
	v_mfma_f32_16x16x32_bf16 v[80:83], v[132:135], v[212:215], v[80:83]
	v_mfma_f32_16x16x32_bf16 v[76:79], v[140:143], v[212:215], v[76:79]
	v_mfma_f32_16x16x32_bf16 v[128:131], v[136:139], v[168:171], v[128:131]
	v_mfma_f32_16x16x32_bf16 v[124:127], v[144:147], v[168:171], v[124:127]
	v_mfma_f32_16x16x32_bf16 v[112:115], v[136:139], v[176:179], v[112:115]
	v_mfma_f32_16x16x32_bf16 v[108:111], v[144:147], v[176:179], v[108:111]
	v_mfma_f32_16x16x32_bf16 v[96:99], v[136:139], v[184:187], v[96:99]
	v_mfma_f32_16x16x32_bf16 v[92:95], v[144:147], v[184:187], v[92:95]
	v_mfma_f32_16x16x32_bf16 v[80:83], v[136:139], v[216:219], v[80:83]
	v_mfma_f32_16x16x32_bf16 v[76:79], v[144:147], v[216:219], v[76:79]
	s_setprio 0
	s_setprio 1
	v_mfma_f32_16x16x32_bf16 v[120:123], v[148:151], v[164:167], v[120:123]
	v_mfma_f32_16x16x32_bf16 v[116:119], v[156:159], v[164:167], v[116:119]
	v_mfma_f32_16x16x32_bf16 v[104:107], v[148:151], v[172:175], v[104:107]
	v_mfma_f32_16x16x32_bf16 v[100:103], v[156:159], v[172:175], v[100:103]
	v_mfma_f32_16x16x32_bf16 v[88:91], v[148:151], v[180:183], v[88:91]
	v_mfma_f32_16x16x32_bf16 v[84:87], v[156:159], v[180:183], v[84:87]
	v_mfma_f32_16x16x32_bf16 v[72:75], v[148:151], v[212:215], v[72:75]
	v_mfma_f32_16x16x32_bf16 v[68:71], v[156:159], v[212:215], v[68:71]
	v_mfma_f32_16x16x32_bf16 v[120:123], v[152:155], v[168:171], v[120:123]
	v_mfma_f32_16x16x32_bf16 v[116:119], v[160:163], v[168:171], v[116:119]
	v_mfma_f32_16x16x32_bf16 v[104:107], v[152:155], v[176:179], v[104:107]
	v_mfma_f32_16x16x32_bf16 v[100:103], v[160:163], v[176:179], v[100:103]
	v_mfma_f32_16x16x32_bf16 v[88:91], v[152:155], v[184:187], v[88:91]
	v_mfma_f32_16x16x32_bf16 v[84:87], v[160:163], v[184:187], v[84:87]
	v_mfma_f32_16x16x32_bf16 v[72:75], v[152:155], v[216:219], v[72:75]
	v_mfma_f32_16x16x32_bf16 v[68:71], v[160:163], v[216:219], v[68:71]
	s_setprio 0
	s_barrier
	s_add_i32 s46, s70, s54
	v_lshl_add_u64 v[196:197], s[22:23], 0, v[190:191]
	s_mov_b32 m0, s46
	ds_read_b128 v[164:167], v232 offset:16384
	ds_read_b128 v[168:171], v232 offset:17408
	ds_read_b128 v[172:175], v232 offset:18432
	ds_read_b128 v[176:179], v232 offset:19456
	ds_read_b128 v[180:183], v232 offset:20480
	ds_read_b128 v[184:187], v232 offset:21504
	ds_read_b128 v[212:215], v232 offset:22528
	ds_read_b128 v[216:219], v232 offset:23552
	global_load_lds_dwordx4 v[196:197], off
	s_add_i32 m0, s46, 0x2000
	s_add_u32 s46, s22, 0x2c000
	v_lshl_add_u64 v[198:199], s[22:23], 0, v[0:1]
	s_addc_u32 s47, s23, 0
	s_add_i32 s70, s71, s54
	global_load_lds_dwordx4 v[198:199], off
	v_lshl_add_u64 v[220:221], s[46:47], 0, v[190:191]
	s_mov_b32 m0, s70
	v_lshl_add_u64 v[222:223], s[50:51], 0, v[188:189]
	global_load_lds_dwordx4 v[220:221], off
	v_lshl_add_u64 v[220:221], s[46:47], 0, v[0:1]
	s_add_i32 m0, s70, 0x2000
	s_nop 0
	global_load_lds_dwordx4 v[220:221], off
	v_lshl_add_u64 v[220:221], s[50:51], 0, v[192:193]
	s_mov_b32 m0, s57
	s_nop 0
	global_load_lds_dwordx4 v[220:221], off
	s_mov_b32 m0, s58
	s_nop 0
	global_load_lds_dwordx4 v[222:223], off
	s_waitcnt vmcnt(8)
	s_waitcnt lgkmcnt(0)
	s_barrier
; #define PG8_STAGE(bufoff, gbase, voff) do { _Pragma("unroll") for (int _i = 0; _i < 2; ++_i) \
;         __builtin_amdgcn_global_load_lds((const unsigned*)((const char*)(gbase) + (voff)[_i]), (LAS unsigned*)(lds + (bufoff) + ldsw + _i * 8192), 16, 0, 0); } while (0)
; #define PG8_LDA(dst, b, h) do { _Pragma("unroll") for (int m = 0; m < 4; ++m) _Pragma("unroll") for (int k = 0; k < 2; ++k) dst[m][k] = *(const LAS bf16x8*)(lds + PG8_SA(b, h) + aoff + m * 2048 + k * 1024); } while (0)
; #define PG8_LDB(dst, b, h) do { _Pragma("unroll") for (int n = 0; n < 2; ++n) _Pragma("unroll") for (int k = 0; k < 2; ++k) dst[n][k] = *(const LAS bf16x8*)(lds + PG8_SB(b, h) + boff + n * 2048 + k * 1024); } while (0)
; #define PG8_MMA(ai, bj, At, Bt) do { __builtin_amdgcn_s_setprio(1); _Pragma("unroll") for (int m = 0; m < 4; ++m) _Pragma("unroll") for (int n = 0; n < 2; ++n) _Pragma("unroll") for (int k = 0; k < 2; ++k) \
;         acc[ai][bj][m][n] = __builtin_amdgcn_mfma_f32_16x16x32_bf16(Bt[n][k], At[m][k], acc[ai][bj][m][n], 0, 0, 0); __builtin_amdgcn_s_setprio(0); } while (0)
; #define PG8_WAIT_V(n) asm volatile("s_waitcnt vmcnt(" #n ")" ::: "memory")
; #define PG8_WAIT_L(n) asm volatile("s_waitcnt lgkmcnt(" #n ")" ::: "memory")
; #define PG8_BAR __builtin_amdgcn_s_barrier()
; #define PG8_SCHED __builtin_amdgcn_sched_barrier(0)
; template <class Epi>
; __device__ __forceinline__ void gemm_phase(LAS unsigned char* lds, const Gemm g, const StaticOrder& S, const Epi& E) {
;     ...
;             PG8_WAIT_V(8); PG8_WAIT_L(0); PG8_BAR; PG8_MMA(1, 0, At, B0); PG8_MMA(1, 1, At, B1); PG8_BAR; PG8_SCHED;
;             PG8_LDB(B0, 1, 0); PG8_LDB(B1, 1, 1); PG8_SCHED; PG8_LDA(At, 1, 0); PG8_STAGE(PG8_SA(0, 1), a2 + hstepA, voffA);
;             PG8_WAIT_V(8); PG8_WAIT_L(0); PG8_BAR; PG8_MMA(0, 0, At, B0); PG8_MMA(0, 1, At, B1); PG8_BAR; PG8_SCHED;
	s_setprio 1
	v_mfma_f32_16x16x32_bf16 v[64:67], v[132:135], v[164:167], v[64:67]
	v_mfma_f32_16x16x32_bf16 v[60:63], v[140:143], v[164:167], v[60:63]
	v_mfma_f32_16x16x32_bf16 v[48:51], v[132:135], v[172:175], v[48:51]
	v_mfma_f32_16x16x32_bf16 v[44:47], v[140:143], v[172:175], v[44:47]
	v_mfma_f32_16x16x32_bf16 v[32:35], v[132:135], v[180:183], v[32:35]
	v_mfma_f32_16x16x32_bf16 v[28:31], v[140:143], v[180:183], v[28:31]
	v_mfma_f32_16x16x32_bf16 v[16:19], v[132:135], v[212:215], v[16:19]
	v_mfma_f32_16x16x32_bf16 v[12:15], v[140:143], v[212:215], v[12:15]
	v_mfma_f32_16x16x32_bf16 v[64:67], v[136:139], v[168:171], v[64:67]
	v_mfma_f32_16x16x32_bf16 v[60:63], v[144:147], v[168:171], v[60:63]
	v_mfma_f32_16x16x32_bf16 v[48:51], v[136:139], v[176:179], v[48:51]
	v_mfma_f32_16x16x32_bf16 v[44:47], v[144:147], v[176:179], v[44:47]
	v_mfma_f32_16x16x32_bf16 v[32:35], v[136:139], v[184:187], v[32:35]
	v_mfma_f32_16x16x32_bf16 v[28:31], v[144:147], v[184:187], v[28:31]
	v_mfma_f32_16x16x32_bf16 v[16:19], v[136:139], v[216:219], v[16:19]
	v_mfma_f32_16x16x32_bf16 v[12:15], v[144:147], v[216:219], v[12:15]
	s_setprio 0
	s_setprio 1
	v_mfma_f32_16x16x32_bf16 v[56:59], v[148:151], v[164:167], v[56:59]
	v_mfma_f32_16x16x32_bf16 v[52:55], v[156:159], v[164:167], v[52:55]
	v_mfma_f32_16x16x32_bf16 v[40:43], v[148:151], v[172:175], v[40:43]
	v_mfma_f32_16x16x32_bf16 v[36:39], v[156:159], v[172:175], v[36:39]
	v_mfma_f32_16x16x32_bf16 v[24:27], v[148:151], v[180:183], v[24:27]
	v_mfma_f32_16x16x32_bf16 v[20:23], v[156:159], v[180:183], v[20:23]
	v_mfma_f32_16x16x32_bf16 v[8:11], v[148:151], v[212:215], v[8:11]
	v_mfma_f32_16x16x32_bf16 v[4:7], v[156:159], v[212:215], v[4:7]
	v_mfma_f32_16x16x32_bf16 v[56:59], v[152:155], v[168:171], v[56:59]
	v_mfma_f32_16x16x32_bf16 v[52:55], v[160:163], v[168:171], v[52:55]
	v_mfma_f32_16x16x32_bf16 v[40:43], v[152:155], v[176:179], v[40:43]
	v_mfma_f32_16x16x32_bf16 v[36:39], v[160:163], v[176:179], v[36:39]
	v_mfma_f32_16x16x32_bf16 v[24:27], v[152:155], v[184:187], v[24:27]
	v_mfma_f32_16x16x32_bf16 v[20:23], v[160:163], v[184:187], v[20:23]
	v_mfma_f32_16x16x32_bf16 v[8:11], v[152:155], v[216:219], v[8:11]
	v_mfma_f32_16x16x32_bf16 v[4:7], v[160:163], v[216:219], v[4:7]
	s_setprio 0
	s_barrier
	s_add_i32 s70, 0, 0x18000
	s_add_i32 s71, 0, 0x1c000
	v_add_u32_e32 v144, s70, v230
	v_add_u32_e32 v160, s71, v230
	ds_read_b128 v[132:135], v144
	ds_read_b128 v[136:139], v144 offset:1024
	ds_read_b128 v[140:143], v144 offset:2048
	ds_read_b128 v[144:147], v144 offset:3072
	ds_read_b128 v[148:151], v160
	ds_read_b128 v[152:155], v160 offset:1024
	ds_read_b128 v[156:159], v160 offset:2048
	ds_read_b128 v[160:163], v160 offset:3072
	s_add_u32 s46, s50, 0xb0000
	s_addc_u32 s47, s51, 0
	s_mov_b32 m0, s59
	v_lshl_add_u64 v[224:225], s[46:47], 0, v[192:193]
	ds_read_b128 v[164:167], v232 offset:32768
	ds_read_b128 v[168:171], v232 offset:33792
	ds_read_b128 v[172:175], v232 offset:34816
	ds_read_b128 v[176:179], v232 offset:35840
	ds_read_b128 v[180:183], v232 offset:36864
	ds_read_b128 v[184:187], v232 offset:37888
	ds_read_b128 v[212:215], v232 offset:38912
	ds_read_b128 v[216:219], v232 offset:39936
	global_load_lds_dwordx4 v[224:225], off
	v_lshl_add_u64 v[224:225], s[46:47], 0, v[188:189]
	s_mov_b32 m0, s60
	s_nop 0
	global_load_lds_dwordx4 v[224:225], off
	s_waitcnt vmcnt(8)
	s_waitcnt lgkmcnt(0)
	s_barrier
	s_setprio 1
	v_mfma_f32_16x16x32_bf16 v[128:131], v[132:135], v[164:167], v[128:131]
	v_mfma_f32_16x16x32_bf16 v[124:127], v[140:143], v[164:167], v[124:127]
	v_mfma_f32_16x16x32_bf16 v[112:115], v[132:135], v[172:175], v[112:115]
	v_mfma_f32_16x16x32_bf16 v[108:111], v[140:143], v[172:175], v[108:111]
	v_mfma_f32_16x16x32_bf16 v[96:99], v[132:135], v[180:183], v[96:99]
	v_mfma_f32_16x16x32_bf16 v[92:95], v[140:143], v[180:183], v[92:95]
	v_mfma_f32_16x16x32_bf16 v[80:83], v[132:135], v[212:215], v[80:83]
	v_mfma_f32_16x16x32_bf16 v[76:79], v[140:143], v[212:215], v[76:79]
	v_mfma_f32_16x16x32_bf16 v[128:131], v[136:139], v[168:171], v[128:131]
	v_mfma_f32_16x16x32_bf16 v[124:127], v[144:147], v[168:171], v[124:127]
	v_mfma_f32_16x16x32_bf16 v[112:115], v[136:139], v[176:179], v[112:115]
	v_mfma_f32_16x16x32_bf16 v[108:111], v[144:147], v[176:179], v[108:111]
	v_mfma_f32_16x16x32_bf16 v[96:99], v[136:139], v[184:187], v[96:99]
	v_mfma_f32_16x16x32_bf16 v[92:95], v[144:147], v[184:187], v[92:95]
	v_mfma_f32_16x16x32_bf16 v[80:83], v[136:139], v[216:219], v[80:83]
	v_mfma_f32_16x16x32_bf16 v[76:79], v[144:147], v[216:219], v[76:79]
	s_setprio 0
	s_setprio 1
	v_mfma_f32_16x16x32_bf16 v[120:123], v[148:151], v[164:167], v[120:123]
	v_mfma_f32_16x16x32_bf16 v[116:119], v[156:159], v[164:167], v[116:119]
	v_mfma_f32_16x16x32_bf16 v[104:107], v[148:151], v[172:175], v[104:107]
	v_mfma_f32_16x16x32_bf16 v[100:103], v[156:159], v[172:175], v[100:103]
	v_mfma_f32_16x16x32_bf16 v[88:91], v[148:151], v[180:183], v[88:91]
	v_mfma_f32_16x16x32_bf16 v[84:87], v[156:159], v[180:183], v[84:87]
	v_mfma_f32_16x16x32_bf16 v[72:75], v[148:151], v[212:215], v[72:75]
	v_mfma_f32_16x16x32_bf16 v[68:71], v[156:159], v[212:215], v[68:71]
	v_mfma_f32_16x16x32_bf16 v[120:123], v[152:155], v[168:171], v[120:123]
	v_mfma_f32_16x16x32_bf16 v[116:119], v[160:163], v[168:171], v[116:119]
	v_mfma_f32_16x16x32_bf16 v[104:107], v[152:155], v[176:179], v[104:107]
	v_mfma_f32_16x16x32_bf16 v[100:103], v[160:163], v[176:179], v[100:103]
	v_mfma_f32_16x16x32_bf16 v[88:91], v[152:155], v[184:187], v[88:91]
	v_mfma_f32_16x16x32_bf16 v[84:87], v[160:163], v[184:187], v[84:87]
	v_mfma_f32_16x16x32_bf16 v[72:75], v[152:155], v[216:219], v[72:75]
	v_mfma_f32_16x16x32_bf16 v[68:71], v[160:163], v[216:219], v[68:71]
	s_setprio 0
	s_barrier
; #define PG8_STAGE(bufoff, gbase, voff) do { _Pragma("unroll") for (int _i = 0; _i < 2; ++_i) \
;         __builtin_amdgcn_global_load_lds((const unsigned*)((const char*)(gbase) + (voff)[_i]), (LAS unsigned*)(lds + (bufoff) + ldsw + _i * 8192), 16, 0, 0); } while (0)
; #define PG8_LDA(dst, b, h) do { _Pragma("unroll") for (int m = 0; m < 4; ++m) _Pragma("unroll") for (int k = 0; k < 2; ++k) dst[m][k] = *(const LAS bf16x8*)(lds + PG8_SA(b, h) + aoff + m * 2048 + k * 1024); } while (0)
; #define PG8_MMA(ai, bj, At, Bt) do { __builtin_amdgcn_s_setprio(1); _Pragma("unroll") for (int m = 0; m < 4; ++m) _Pragma("unroll") for (int n = 0; n < 2; ++n) _Pragma("unroll") for (int k = 0; k < 2; ++k) \
;         acc[ai][bj][m][n] = __builtin_amdgcn_mfma_f32_16x16x32_bf16(Bt[n][k], At[m][k], acc[ai][bj][m][n], 0, 0, 0); __builtin_amdgcn_s_setprio(0); } while (0)
; #define PG8_WAIT_V(n) asm volatile("s_waitcnt vmcnt(" #n ")" ::: "memory")
; #define PG8_WAIT_L(n) asm volatile("s_waitcnt lgkmcnt(" #n ")" ::: "memory")
; #define PG8_BAR __builtin_amdgcn_s_barrier()
; #define PG8_SCHED __builtin_amdgcn_sched_barrier(0)
; template <class Epi>
; __device__ __forceinline__ void gemm_phase(LAS unsigned char* lds, const Gemm g, const StaticOrder& S, const Epi& E) {
;     ...
;             PG8_LDA(At, 1, 1); PG8_STAGE(PG8_SB(1, 0), b3, voffB); PG8_STAGE(PG8_SB(1, 1), b3 + hstepB, voffB); PG8_STAGE(PG8_SA(1, 0), a3, voffA);
;             PG8_WAIT_V(8); PG8_WAIT_L(0); PG8_BAR; PG8_MMA(1, 0, At, B0); PG8_MMA(1, 1, At, B1); PG8_BAR; PG8_SCHED;
;         }
;         if (wr == 0) PG8_BAR;
	s_add_i32 s46, s70, s54
	v_lshl_add_u64 v[196:197], v[196:197], 0, s[30:31]
	s_mov_b32 m0, s46
	ds_read_b128 v[164:167], v232 offset:49152
	ds_read_b128 v[168:171], v232 offset:50176
	ds_read_b128 v[172:175], v232 offset:51200
	ds_read_b128 v[176:179], v232 offset:52224
	ds_read_b128 v[180:183], v232 offset:53248
	ds_read_b128 v[184:187], v232 offset:54272
	ds_read_b128 v[212:215], v232 offset:55296
	ds_read_b128 v[216:219], v232 offset:56320
	global_load_lds_dwordx4 v[196:197], off
	s_add_i32 m0, s46, 0x2000
	s_add_u32 s22, s22, 0x2c080
	v_lshl_add_u64 v[196:197], v[198:199], 0, s[30:31]
	s_addc_u32 s23, s23, 0
	s_add_i32 s46, s71, s54
	global_load_lds_dwordx4 v[196:197], off
	v_lshl_add_u64 v[196:197], s[22:23], 0, v[190:191]
	s_mov_b32 m0, s46
	s_nop 0
	global_load_lds_dwordx4 v[196:197], off
	v_lshl_add_u64 v[196:197], s[22:23], 0, v[0:1]
	s_add_i32 m0, s46, 0x2000
	s_nop 0
	global_load_lds_dwordx4 v[196:197], off
	v_lshl_add_u64 v[196:197], v[220:221], 0, s[30:31]
	s_mov_b32 m0, s28
	s_nop 0
	global_load_lds_dwordx4 v[196:197], off
	v_lshl_add_u64 v[196:197], v[222:223], 0, s[30:31]
	s_mov_b32 m0, s61
	s_nop 0
	global_load_lds_dwordx4 v[196:197], off
	s_waitcnt vmcnt(8)
	s_waitcnt lgkmcnt(0)
	s_barrier
	s_setprio 1
	v_mfma_f32_16x16x32_bf16 v[64:67], v[132:135], v[164:167], v[64:67]
	v_mfma_f32_16x16x32_bf16 v[60:63], v[140:143], v[164:167], v[60:63]
	v_mfma_f32_16x16x32_bf16 v[48:51], v[132:135], v[172:175], v[48:51]
	v_mfma_f32_16x16x32_bf16 v[44:47], v[140:143], v[172:175], v[44:47]
	v_mfma_f32_16x16x32_bf16 v[32:35], v[132:135], v[180:183], v[32:35]
	v_mfma_f32_16x16x32_bf16 v[28:31], v[140:143], v[180:183], v[28:31]
	v_mfma_f32_16x16x32_bf16 v[16:19], v[132:135], v[212:215], v[16:19]
	v_mfma_f32_16x16x32_bf16 v[12:15], v[140:143], v[212:215], v[12:15]
	v_mfma_f32_16x16x32_bf16 v[64:67], v[136:139], v[168:171], v[64:67]
	v_mfma_f32_16x16x32_bf16 v[60:63], v[144:147], v[168:171], v[60:63]
	v_mfma_f32_16x16x32_bf16 v[48:51], v[136:139], v[176:179], v[48:51]
	v_mfma_f32_16x16x32_bf16 v[44:47], v[144:147], v[176:179], v[44:47]
	v_mfma_f32_16x16x32_bf16 v[32:35], v[136:139], v[184:187], v[32:35]
	v_mfma_f32_16x16x32_bf16 v[28:31], v[144:147], v[184:187], v[28:31]
	v_mfma_f32_16x16x32_bf16 v[16:19], v[136:139], v[216:219], v[16:19]
	v_mfma_f32_16x16x32_bf16 v[12:15], v[144:147], v[216:219], v[12:15]
	s_setprio 0
	s_setprio 1
	v_mfma_f32_16x16x32_bf16 v[56:59], v[148:151], v[164:167], v[56:59]
	v_mfma_f32_16x16x32_bf16 v[52:55], v[156:159], v[164:167], v[52:55]
	v_mfma_f32_16x16x32_bf16 v[40:43], v[148:151], v[172:175], v[40:43]
	v_mfma_f32_16x16x32_bf16 v[36:39], v[156:159], v[172:175], v[36:39]
	v_mfma_f32_16x16x32_bf16 v[24:27], v[148:151], v[180:183], v[24:27]
	v_mfma_f32_16x16x32_bf16 v[20:23], v[156:159], v[180:183], v[20:23]
	v_mfma_f32_16x16x32_bf16 v[8:11], v[148:151], v[212:215], v[8:11]
	v_mfma_f32_16x16x32_bf16 v[4:7], v[156:159], v[212:215], v[4:7]
	v_mfma_f32_16x16x32_bf16 v[56:59], v[152:155], v[168:171], v[56:59]
	v_mfma_f32_16x16x32_bf16 v[52:55], v[160:163], v[168:171], v[52:55]
	v_mfma_f32_16x16x32_bf16 v[40:43], v[152:155], v[176:179], v[40:43]
	v_mfma_f32_16x16x32_bf16 v[36:39], v[160:163], v[176:179], v[36:39]
	v_mfma_f32_16x16x32_bf16 v[24:27], v[152:155], v[184:187], v[24:27]
	v_mfma_f32_16x16x32_bf16 v[20:23], v[160:163], v[184:187], v[20:23]
	v_mfma_f32_16x16x32_bf16 v[8:11], v[152:155], v[216:219], v[8:11]
	v_mfma_f32_16x16x32_bf16 v[4:7], v[160:163], v[216:219], v[4:7]
	s_setprio 0
	s_barrier
	s_add_i32 s69, s69, 2
	s_add_u32 s67, s67, 0x100
	s_addc_u32 s68, s68, 0
	s_cmp_gt_u32 s69, 41
	s_mov_b64 s[46:47], s[48:49]
	s_cbranch_scc0 .LBB0_240
	v_mov_b64_e32 v[208:209], 0xaff
	s_and_b64 vcc, exec, s[38:39]
	s_cbranch_vccz .LBB0_243
	s_barrier

; #define PG8_STAGE(bufoff, gbase, voff) do { _Pragma("unroll") for (int _i = 0; _i < 2; ++_i) \
;         __builtin_amdgcn_global_load_lds((const unsigned*)((const char*)(gbase) + (voff)[_i]), (LAS unsigned*)(lds + (bufoff) + ldsw + _i * 8192), 16, 0, 0); } while (0)
; #define PG8_LDA(dst, b, h) do { _Pragma("unroll") for (int m = 0; m < 4; ++m) _Pragma("unroll") for (int k = 0; k < 2; ++k) dst[m][k] = *(const LAS bf16x8*)(lds + PG8_SA(b, h) + aoff + m * 2048 + k * 1024); } while (0)
; #define PG8_LDB(dst, b, h) do { _Pragma("unroll") for (int n = 0; n < 2; ++n) _Pragma("unroll") for (int k = 0; k < 2; ++k) dst[n][k] = *(const LAS bf16x8*)(lds + PG8_SB(b, h) + boff + n * 2048 + k * 1024); } while (0)
; #define PG8_MMA(ai, bj, At, Bt) do { __builtin_amdgcn_s_setprio(1); _Pragma("unroll") for (int m = 0; m < 4; ++m) _Pragma("unroll") for (int n = 0; n < 2; ++n) _Pragma("unroll") for (int k = 0; k < 2; ++k) \
;         acc[ai][bj][m][n] = __builtin_amdgcn_mfma_f32_16x16x32_bf16(Bt[n][k], At[m][k], acc[ai][bj][m][n], 0, 0, 0); __builtin_amdgcn_s_setprio(0); } while (0)
; #define PG8_WAIT_V(n) asm volatile("s_waitcnt vmcnt(" #n ")" ::: "memory")
; #define PG8_WAIT_L(n) asm volatile("s_waitcnt lgkmcnt(" #n ")" ::: "memory")
; #define PG8_BAR __builtin_amdgcn_s_barrier()
; #define PG8_SCHED __builtin_amdgcn_sched_barrier(0)
; template <class Epi>
; __device__ __forceinline__ void gemm_phase(LAS unsigned char* lds, const Gemm g, const StaticOrder& S, const Epi& E) {
;     ...
;         for (int t = 0; t < nt; t += 2) {
;             const bool last = (t == nt - 2);
;             const char* a1 = cA + (size_t)(t + 1) * kstep;
;             const char* a2 = last ? nA : cA + (size_t)(t + 2) * kstep; const char* b2 = last ? nB : cB + (size_t)(t + 2) * kstep;
;             const char* a3 = a2 + kstep; const char* b3 = b2 + kstep;
;             PG8_LDB(B0, 0, 0); PG8_LDB(B1, 0, 1); PG8_SCHED; PG8_LDA(At, 0, 0); PG8_STAGE(PG8_SA(1, 1), a1 + hstepA, voffA);
;             PG8_WAIT_V(8); PG8_WAIT_L(0); PG8_BAR; PG8_MMA(0, 0, At, B0); PG8_MMA(0, 1, At, B1); PG8_BAR; PG8_SCHED;
;             PG8_LDA(At, 0, 1); PG8_STAGE(PG8_SB(0, 0), b2, voffB); PG8_STAGE(PG8_SB(0, 1), b2 + hstepB, voffB); PG8_STAGE(PG8_SA(0, 0), a2, voffA);
.LBB0_323:
	s_add_u32 s22, s34, 0xfffc0080
	s_addc_u32 s23, s35, -1
	s_add_i32 s52, 0, 0x10000
	s_cmp_eq_u32 s51, 12
	s_cselect_b32 s39, s41, s23
	s_cselect_b32 s38, s46, s22
	s_cselect_b32 s23, s47, s50
	s_cselect_b32 s22, s48, s49
	s_add_i32 s54, 0, 0x14000
	v_add_u32_e32 v160, s52, v147
	v_add_u32_e32 v172, s54, v147
	ds_read_b128 v[132:135], v160
	ds_read_b128 v[136:139], v160 offset:1024
	ds_read_b128 v[156:159], v160 offset:2048
	ds_read_b128 v[160:163], v160 offset:3072
	ds_read_b128 v[164:167], v172
	ds_read_b128 v[168:171], v172 offset:1024
	ds_read_b128 v[176:179], v172 offset:2048
	ds_read_b128 v[180:183], v172 offset:3072
	v_lshl_add_u64 v[172:173], s[34:35], 0, v[152:153]
	s_add_i32 m0, s75, 0xc000
	ds_read_b128 v[184:187], v174
	ds_read_b128 v[188:191], v174 offset:1024
	ds_read_b128 v[192:195], v174 offset:2048
	ds_read_b128 v[210:213], v174 offset:3072
	ds_read_b128 v[214:217], v174 offset:4096
	ds_read_b128 v[218:221], v174 offset:5120
	ds_read_b128 v[222:225], v174 offset:6144
	ds_read_b128 v[226:229], v174 offset:7168
	global_load_lds_dwordx4 v[172:173], off
	v_lshl_add_u64 v[172:173], s[34:35], 0, v[154:155]
	s_add_i32 m0, s75, 0xe000
	s_nop 0
	global_load_lds_dwordx4 v[172:173], off
	s_waitcnt vmcnt(8)
	s_waitcnt lgkmcnt(0)
	s_barrier
	s_setprio 1
	v_mfma_f32_16x16x32_bf16 v[128:131], v[132:135], v[184:187], v[128:131]
	v_mfma_f32_16x16x32_bf16 v[124:127], v[156:159], v[184:187], v[124:127]
	v_mfma_f32_16x16x32_bf16 v[112:115], v[132:135], v[192:195], v[112:115]
	v_mfma_f32_16x16x32_bf16 v[108:111], v[156:159], v[192:195], v[108:111]
	v_mfma_f32_16x16x32_bf16 v[96:99], v[132:135], v[214:217], v[96:99]
	v_mfma_f32_16x16x32_bf16 v[92:95], v[156:159], v[214:217], v[92:95]
	v_mfma_f32_16x16x32_bf16 v[80:83], v[132:135], v[222:225], v[80:83]
	v_mfma_f32_16x16x32_bf16 v[76:79], v[156:159], v[222:225], v[76:79]
	v_mfma_f32_16x16x32_bf16 v[128:131], v[136:139], v[188:191], v[128:131]
	v_mfma_f32_16x16x32_bf16 v[124:127], v[160:163], v[188:191], v[124:127]
	v_mfma_f32_16x16x32_bf16 v[112:115], v[136:139], v[210:213], v[112:115]
	v_mfma_f32_16x16x32_bf16 v[108:111], v[160:163], v[210:213], v[108:111]
	v_mfma_f32_16x16x32_bf16 v[96:99], v[136:139], v[218:221], v[96:99]
	v_mfma_f32_16x16x32_bf16 v[92:95], v[160:163], v[218:221], v[92:95]
	v_mfma_f32_16x16x32_bf16 v[80:83], v[136:139], v[226:229], v[80:83]
	v_mfma_f32_16x16x32_bf16 v[76:79], v[160:163], v[226:229], v[76:79]
	s_setprio 0
	s_setprio 1
	v_mfma_f32_16x16x32_bf16 v[120:123], v[164:167], v[184:187], v[120:123]
	v_mfma_f32_16x16x32_bf16 v[116:119], v[176:179], v[184:187], v[116:119]
	v_mfma_f32_16x16x32_bf16 v[104:107], v[164:167], v[192:195], v[104:107]
	v_mfma_f32_16x16x32_bf16 v[100:103], v[176:179], v[192:195], v[100:103]
	v_mfma_f32_16x16x32_bf16 v[88:91], v[164:167], v[214:217], v[88:91]
	v_mfma_f32_16x16x32_bf16 v[84:87], v[176:179], v[214:217], v[84:87]
	v_mfma_f32_16x16x32_bf16 v[72:75], v[164:167], v[222:225], v[72:75]
	v_mfma_f32_16x16x32_bf16 v[68:71], v[176:179], v[222:225], v[68:71]
	v_mfma_f32_16x16x32_bf16 v[120:123], v[168:171], v[188:191], v[120:123]
	v_mfma_f32_16x16x32_bf16 v[116:119], v[180:183], v[188:191], v[116:119]
	v_mfma_f32_16x16x32_bf16 v[104:107], v[168:171], v[210:213], v[104:107]
	v_mfma_f32_16x16x32_bf16 v[100:103], v[180:183], v[210:213], v[100:103]
	v_mfma_f32_16x16x32_bf16 v[88:91], v[168:171], v[218:221], v[88:91]
	v_mfma_f32_16x16x32_bf16 v[84:87], v[180:183], v[218:221], v[84:87]
	v_mfma_f32_16x16x32_bf16 v[72:75], v[168:171], v[226:229], v[72:75]
	v_mfma_f32_16x16x32_bf16 v[68:71], v[180:183], v[226:229], v[68:71]
	s_setprio 0
	s_barrier
	s_add_i32 s52, s52, s74
	v_lshl_add_u64 v[172:173], s[22:23], 0, v[142:143]
	s_mov_b32 m0, s52
	ds_read_b128 v[184:187], v174 offset:16384
	ds_read_b128 v[188:191], v174 offset:17408
	ds_read_b128 v[192:195], v174 offset:18432
	ds_read_b128 v[210:213], v174 offset:19456
	ds_read_b128 v[214:217], v174 offset:20480
	ds_read_b128 v[218:221], v174 offset:21504
	ds_read_b128 v[222:225], v174 offset:22528
	ds_read_b128 v[226:229], v174 offset:23552
	global_load_lds_dwordx4 v[172:173], off
	s_add_i32 m0, s52, 0x2000
	s_add_u32 s52, s22, 0x10000
	v_lshl_add_u64 v[196:197], s[22:23], 0, v[0:1]
	s_addc_u32 s53, s23, 0
	s_add_i32 s54, s54, s74
	global_load_lds_dwordx4 v[196:197], off
	v_lshl_add_u64 v[198:199], s[52:53], 0, v[142:143]
	s_mov_b32 m0, s54
	v_lshl_add_u64 v[230:231], s[38:39], 0, v[140:141]
	global_load_lds_dwordx4 v[198:199], off
	v_lshl_add_u64 v[198:199], s[52:53], 0, v[0:1]
	s_add_i32 m0, s54, 0x2000
	s_nop 0
	global_load_lds_dwordx4 v[198:199], off
	v_lshl_add_u64 v[198:199], s[38:39], 0, v[144:145]
	s_mov_b32 m0, s75
	s_nop 0
	global_load_lds_dwordx4 v[198:199], off
	s_mov_b32 m0, s76
	s_nop 0
	global_load_lds_dwordx4 v[230:231], off
	s_waitcnt vmcnt(8)
	s_waitcnt lgkmcnt(0)
	s_barrier
; #define PG8_STAGE(bufoff, gbase, voff) do { _Pragma("unroll") for (int _i = 0; _i < 2; ++_i) \
;         __builtin_amdgcn_global_load_lds((const unsigned*)((const char*)(gbase) + (voff)[_i]), (LAS unsigned*)(lds + (bufoff) + ldsw + _i * 8192), 16, 0, 0); } while (0)
; #define PG8_LDA(dst, b, h) do { _Pragma("unroll") for (int m = 0; m < 4; ++m) _Pragma("unroll") for (int k = 0; k < 2; ++k) dst[m][k] = *(const LAS bf16x8*)(lds + PG8_SA(b, h) + aoff + m * 2048 + k * 1024); } while (0)
; #define PG8_LDB(dst, b, h) do { _Pragma("unroll") for (int n = 0; n < 2; ++n) _Pragma("unroll") for (int k = 0; k < 2; ++k) dst[n][k] = *(const LAS bf16x8*)(lds + PG8_SB(b, h) + boff + n * 2048 + k * 1024); } while (0)
; #define PG8_MMA(ai, bj, At, Bt) do { __builtin_amdgcn_s_setprio(1); _Pragma("unroll") for (int m = 0; m < 4; ++m) _Pragma("unroll") for (int n = 0; n < 2; ++n) _Pragma("unroll") for (int k = 0; k < 2; ++k) \
;         acc[ai][bj][m][n] = __builtin_amdgcn_mfma_f32_16x16x32_bf16(Bt[n][k], At[m][k], acc[ai][bj][m][n], 0, 0, 0); __builtin_amdgcn_s_setprio(0); } while (0)
; #define PG8_WAIT_V(n) asm volatile("s_waitcnt vmcnt(" #n ")" ::: "memory")
; #define PG8_WAIT_L(n) asm volatile("s_waitcnt lgkmcnt(" #n ")" ::: "memory")
; #define PG8_BAR __builtin_amdgcn_s_barrier()
; #define PG8_SCHED __builtin_amdgcn_sched_barrier(0)
; template <class Epi>
; __device__ __forceinline__ void gemm_phase(LAS unsigned char* lds, const Gemm g, const StaticOrder& S, const Epi& E) {
;     ...
;             PG8_WAIT_V(8); PG8_WAIT_L(0); PG8_BAR; PG8_MMA(1, 0, At, B0); PG8_MMA(1, 1, At, B1); PG8_BAR; PG8_SCHED;
;             PG8_LDB(B0, 1, 0); PG8_LDB(B1, 1, 1); PG8_SCHED; PG8_LDA(At, 1, 0); PG8_STAGE(PG8_SA(0, 1), a2 + hstepA, voffA);
;             PG8_WAIT_V(8); PG8_WAIT_L(0); PG8_BAR; PG8_MMA(0, 0, At, B0); PG8_MMA(0, 1, At, B1); PG8_BAR; PG8_SCHED;
	s_setprio 1
	v_mfma_f32_16x16x32_bf16 v[64:67], v[132:135], v[184:187], v[64:67]
	v_mfma_f32_16x16x32_bf16 v[60:63], v[156:159], v[184:187], v[60:63]
	v_mfma_f32_16x16x32_bf16 v[48:51], v[132:135], v[192:195], v[48:51]
	v_mfma_f32_16x16x32_bf16 v[44:47], v[156:159], v[192:195], v[44:47]
	v_mfma_f32_16x16x32_bf16 v[32:35], v[132:135], v[214:217], v[32:35]
	v_mfma_f32_16x16x32_bf16 v[28:31], v[156:159], v[214:217], v[28:31]
	v_mfma_f32_16x16x32_bf16 v[16:19], v[132:135], v[222:225], v[16:19]
	v_mfma_f32_16x16x32_bf16 v[12:15], v[156:159], v[222:225], v[12:15]
	v_mfma_f32_16x16x32_bf16 v[64:67], v[136:139], v[188:191], v[64:67]
	v_mfma_f32_16x16x32_bf16 v[60:63], v[160:163], v[188:191], v[60:63]
	v_mfma_f32_16x16x32_bf16 v[48:51], v[136:139], v[210:213], v[48:51]
	v_mfma_f32_16x16x32_bf16 v[44:47], v[160:163], v[210:213], v[44:47]
	v_mfma_f32_16x16x32_bf16 v[32:35], v[136:139], v[218:221], v[32:35]
	v_mfma_f32_16x16x32_bf16 v[28:31], v[160:163], v[218:221], v[28:31]
	v_mfma_f32_16x16x32_bf16 v[16:19], v[136:139], v[226:229], v[16:19]
	v_mfma_f32_16x16x32_bf16 v[12:15], v[160:163], v[226:229], v[12:15]
	s_setprio 0
	s_setprio 1
	v_mfma_f32_16x16x32_bf16 v[56:59], v[164:167], v[184:187], v[56:59]
	v_mfma_f32_16x16x32_bf16 v[52:55], v[176:179], v[184:187], v[52:55]
	v_mfma_f32_16x16x32_bf16 v[40:43], v[164:167], v[192:195], v[40:43]
	v_mfma_f32_16x16x32_bf16 v[36:39], v[176:179], v[192:195], v[36:39]
	v_mfma_f32_16x16x32_bf16 v[24:27], v[164:167], v[214:217], v[24:27]
	v_mfma_f32_16x16x32_bf16 v[20:23], v[176:179], v[214:217], v[20:23]
	v_mfma_f32_16x16x32_bf16 v[8:11], v[164:167], v[222:225], v[8:11]
	v_mfma_f32_16x16x32_bf16 v[4:7], v[176:179], v[222:225], v[4:7]
	v_mfma_f32_16x16x32_bf16 v[56:59], v[168:171], v[188:191], v[56:59]
	v_mfma_f32_16x16x32_bf16 v[52:55], v[180:183], v[188:191], v[52:55]
	v_mfma_f32_16x16x32_bf16 v[40:43], v[168:171], v[210:213], v[40:43]
	v_mfma_f32_16x16x32_bf16 v[36:39], v[180:183], v[210:213], v[36:39]
	v_mfma_f32_16x16x32_bf16 v[24:27], v[168:171], v[218:221], v[24:27]
	v_mfma_f32_16x16x32_bf16 v[20:23], v[180:183], v[218:221], v[20:23]
	v_mfma_f32_16x16x32_bf16 v[8:11], v[168:171], v[226:229], v[8:11]
	v_mfma_f32_16x16x32_bf16 v[4:7], v[180:183], v[226:229], v[4:7]
	s_setprio 0
	s_barrier
	s_add_i32 s52, 0, 0x18000
	s_add_i32 s53, 0, 0x1c000
	v_add_u32_e32 v160, s52, v147
	v_add_u32_e32 v175, s53, v147
	ds_read_b128 v[132:135], v160
	ds_read_b128 v[136:139], v160 offset:1024
	ds_read_b128 v[156:159], v160 offset:2048
	ds_read_b128 v[160:163], v160 offset:3072
	ds_read_b128 v[164:167], v175
	ds_read_b128 v[168:171], v175 offset:1024
	ds_read_b128 v[176:179], v175 offset:2048
	ds_read_b128 v[180:183], v175 offset:3072
	s_add_u32 s38, s38, 0x40000
	s_addc_u32 s39, s39, 0
	s_mov_b32 m0, s77
	v_lshl_add_u64 v[232:233], s[38:39], 0, v[144:145]
	ds_read_b128 v[184:187], v174 offset:32768
	ds_read_b128 v[188:191], v174 offset:33792
	ds_read_b128 v[192:195], v174 offset:34816
	ds_read_b128 v[210:213], v174 offset:35840
	ds_read_b128 v[214:217], v174 offset:36864
	ds_read_b128 v[218:221], v174 offset:37888
	ds_read_b128 v[222:225], v174 offset:38912
	ds_read_b128 v[226:229], v174 offset:39936
	global_load_lds_dwordx4 v[232:233], off
	v_lshl_add_u64 v[232:233], s[38:39], 0, v[140:141]
	s_mov_b32 m0, s78
	s_nop 0
	global_load_lds_dwordx4 v[232:233], off
	s_waitcnt vmcnt(8)
	s_waitcnt lgkmcnt(0)
	s_barrier
	s_setprio 1
	v_mfma_f32_16x16x32_bf16 v[128:131], v[132:135], v[184:187], v[128:131]
	v_mfma_f32_16x16x32_bf16 v[124:127], v[156:159], v[184:187], v[124:127]
	v_mfma_f32_16x16x32_bf16 v[112:115], v[132:135], v[192:195], v[112:115]
	v_mfma_f32_16x16x32_bf16 v[108:111], v[156:159], v[192:195], v[108:111]
	v_mfma_f32_16x16x32_bf16 v[96:99], v[132:135], v[214:217], v[96:99]
	v_mfma_f32_16x16x32_bf16 v[92:95], v[156:159], v[214:217], v[92:95]
	v_mfma_f32_16x16x32_bf16 v[80:83], v[132:135], v[222:225], v[80:83]
	v_mfma_f32_16x16x32_bf16 v[76:79], v[156:159], v[222:225], v[76:79]
	v_mfma_f32_16x16x32_bf16 v[128:131], v[136:139], v[188:191], v[128:131]
	v_mfma_f32_16x16x32_bf16 v[124:127], v[160:163], v[188:191], v[124:127]
	v_mfma_f32_16x16x32_bf16 v[112:115], v[136:139], v[210:213], v[112:115]
	v_mfma_f32_16x16x32_bf16 v[108:111], v[160:163], v[210:213], v[108:111]
	v_mfma_f32_16x16x32_bf16 v[96:99], v[136:139], v[218:221], v[96:99]
	v_mfma_f32_16x16x32_bf16 v[92:95], v[160:163], v[218:221], v[92:95]
	v_mfma_f32_16x16x32_bf16 v[80:83], v[136:139], v[226:229], v[80:83]
	v_mfma_f32_16x16x32_bf16 v[76:79], v[160:163], v[226:229], v[76:79]
	s_setprio 0
	s_setprio 1
	v_mfma_f32_16x16x32_bf16 v[120:123], v[164:167], v[184:187], v[120:123]
	v_mfma_f32_16x16x32_bf16 v[116:119], v[176:179], v[184:187], v[116:119]
	v_mfma_f32_16x16x32_bf16 v[104:107], v[164:167], v[192:195], v[104:107]
	v_mfma_f32_16x16x32_bf16 v[100:103], v[176:179], v[192:195], v[100:103]
	v_mfma_f32_16x16x32_bf16 v[88:91], v[164:167], v[214:217], v[88:91]
	v_mfma_f32_16x16x32_bf16 v[84:87], v[176:179], v[214:217], v[84:87]
	v_mfma_f32_16x16x32_bf16 v[72:75], v[164:167], v[222:225], v[72:75]
	v_mfma_f32_16x16x32_bf16 v[68:71], v[176:179], v[222:225], v[68:71]
	v_mfma_f32_16x16x32_bf16 v[120:123], v[168:171], v[188:191], v[120:123]
	v_mfma_f32_16x16x32_bf16 v[116:119], v[180:183], v[188:191], v[116:119]
	v_mfma_f32_16x16x32_bf16 v[104:107], v[168:171], v[210:213], v[104:107]
	v_mfma_f32_16x16x32_bf16 v[100:103], v[180:183], v[210:213], v[100:103]
	v_mfma_f32_16x16x32_bf16 v[88:91], v[168:171], v[218:221], v[88:91]
	v_mfma_f32_16x16x32_bf16 v[84:87], v[180:183], v[218:221], v[84:87]
	v_mfma_f32_16x16x32_bf16 v[72:75], v[168:171], v[226:229], v[72:75]
	v_mfma_f32_16x16x32_bf16 v[68:71], v[180:183], v[226:229], v[68:71]
	s_setprio 0
	s_barrier
; #define PG8_STAGE(bufoff, gbase, voff) do { _Pragma("unroll") for (int _i = 0; _i < 2; ++_i) \
;         __builtin_amdgcn_global_load_lds((const unsigned*)((const char*)(gbase) + (voff)[_i]), (LAS unsigned*)(lds + (bufoff) + ldsw + _i * 8192), 16, 0, 0); } while (0)
; #define PG8_LDA(dst, b, h) do { _Pragma("unroll") for (int m = 0; m < 4; ++m) _Pragma("unroll") for (int k = 0; k < 2; ++k) dst[m][k] = *(const LAS bf16x8*)(lds + PG8_SA(b, h) + aoff + m * 2048 + k * 1024); } while (0)
; #define PG8_MMA(ai, bj, At, Bt) do { __builtin_amdgcn_s_setprio(1); _Pragma("unroll") for (int m = 0; m < 4; ++m) _Pragma("unroll") for (int n = 0; n < 2; ++n) _Pragma("unroll") for (int k = 0; k < 2; ++k) \
;         acc[ai][bj][m][n] = __builtin_amdgcn_mfma_f32_16x16x32_bf16(Bt[n][k], At[m][k], acc[ai][bj][m][n], 0, 0, 0); __builtin_amdgcn_s_setprio(0); } while (0)
; #define PG8_WAIT_V(n) asm volatile("s_waitcnt vmcnt(" #n ")" ::: "memory")
; #define PG8_WAIT_L(n) asm volatile("s_waitcnt lgkmcnt(" #n ")" ::: "memory")
; #define PG8_BAR __builtin_amdgcn_s_barrier()
; #define PG8_SCHED __builtin_amdgcn_sched_barrier(0)
; template <class Epi>
; __device__ __forceinline__ void gemm_phase(LAS unsigned char* lds, const Gemm g, const StaticOrder& S, const Epi& E) {
;     ...
;             PG8_LDA(At, 1, 1); PG8_STAGE(PG8_SB(1, 0), b3, voffB); PG8_STAGE(PG8_SB(1, 1), b3 + hstepB, voffB); PG8_STAGE(PG8_SA(1, 0), a3, voffA);
;             PG8_WAIT_V(8); PG8_WAIT_L(0); PG8_BAR; PG8_MMA(1, 0, At, B0); PG8_MMA(1, 1, At, B1); PG8_BAR; PG8_SCHED;
;         }
;         if (wr == 0) PG8_BAR;
	s_add_i32 s38, s52, s74
	v_lshl_add_u64 v[172:173], v[172:173], 0, s[30:31]
	s_mov_b32 m0, s38
	ds_read_b128 v[184:187], v174 offset:49152
	ds_read_b128 v[188:191], v174 offset:50176
	ds_read_b128 v[192:195], v174 offset:51200
	ds_read_b128 v[210:213], v174 offset:52224
	ds_read_b128 v[214:217], v174 offset:53248
	ds_read_b128 v[218:221], v174 offset:54272
	ds_read_b128 v[222:225], v174 offset:55296
	ds_read_b128 v[226:229], v174 offset:56320
	global_load_lds_dwordx4 v[172:173], off
	s_add_i32 m0, s38, 0x2000
	s_add_u32 s22, s22, 0x10080
	v_lshl_add_u64 v[172:173], v[196:197], 0, s[30:31]
	s_addc_u32 s23, s23, 0
	s_add_i32 s38, s53, s74
	global_load_lds_dwordx4 v[172:173], off
	v_lshl_add_u64 v[172:173], s[22:23], 0, v[142:143]
	s_mov_b32 m0, s38
	s_nop 0
	global_load_lds_dwordx4 v[172:173], off
	v_lshl_add_u64 v[172:173], s[22:23], 0, v[0:1]
	s_add_i32 m0, s38, 0x2000
	s_nop 0
	global_load_lds_dwordx4 v[172:173], off
	v_lshl_add_u64 v[172:173], v[198:199], 0, s[30:31]
	s_mov_b32 m0, s85
	s_nop 0
	global_load_lds_dwordx4 v[172:173], off
	v_lshl_add_u64 v[172:173], v[230:231], 0, s[30:31]
	s_mov_b32 m0, s86
	s_nop 0
	global_load_lds_dwordx4 v[172:173], off
	s_waitcnt vmcnt(8)
	s_waitcnt lgkmcnt(0)
	s_barrier
	s_setprio 1
	v_mfma_f32_16x16x32_bf16 v[64:67], v[132:135], v[184:187], v[64:67]
	v_mfma_f32_16x16x32_bf16 v[60:63], v[156:159], v[184:187], v[60:63]
	v_mfma_f32_16x16x32_bf16 v[48:51], v[132:135], v[192:195], v[48:51]
	v_mfma_f32_16x16x32_bf16 v[44:47], v[156:159], v[192:195], v[44:47]
	v_mfma_f32_16x16x32_bf16 v[32:35], v[132:135], v[214:217], v[32:35]
	v_mfma_f32_16x16x32_bf16 v[28:31], v[156:159], v[214:217], v[28:31]
	v_mfma_f32_16x16x32_bf16 v[16:19], v[132:135], v[222:225], v[16:19]
	v_mfma_f32_16x16x32_bf16 v[12:15], v[156:159], v[222:225], v[12:15]
	v_mfma_f32_16x16x32_bf16 v[64:67], v[136:139], v[188:191], v[64:67]
	v_mfma_f32_16x16x32_bf16 v[60:63], v[160:163], v[188:191], v[60:63]
	v_mfma_f32_16x16x32_bf16 v[48:51], v[136:139], v[210:213], v[48:51]
	v_mfma_f32_16x16x32_bf16 v[44:47], v[160:163], v[210:213], v[44:47]
	v_mfma_f32_16x16x32_bf16 v[32:35], v[136:139], v[218:221], v[32:35]
	v_mfma_f32_16x16x32_bf16 v[28:31], v[160:163], v[218:221], v[28:31]
	v_mfma_f32_16x16x32_bf16 v[16:19], v[136:139], v[226:229], v[16:19]
	v_mfma_f32_16x16x32_bf16 v[12:15], v[160:163], v[226:229], v[12:15]
	s_setprio 0
	s_setprio 1
	v_mfma_f32_16x16x32_bf16 v[56:59], v[164:167], v[184:187], v[56:59]
	v_mfma_f32_16x16x32_bf16 v[52:55], v[176:179], v[184:187], v[52:55]
	v_mfma_f32_16x16x32_bf16 v[40:43], v[164:167], v[192:195], v[40:43]
	v_mfma_f32_16x16x32_bf16 v[36:39], v[176:179], v[192:195], v[36:39]
	v_mfma_f32_16x16x32_bf16 v[24:27], v[164:167], v[214:217], v[24:27]
	v_mfma_f32_16x16x32_bf16 v[20:23], v[176:179], v[214:217], v[20:23]
	v_mfma_f32_16x16x32_bf16 v[8:11], v[164:167], v[222:225], v[8:11]
	v_mfma_f32_16x16x32_bf16 v[4:7], v[176:179], v[222:225], v[4:7]
	v_mfma_f32_16x16x32_bf16 v[56:59], v[168:171], v[188:191], v[56:59]
	v_mfma_f32_16x16x32_bf16 v[52:55], v[180:183], v[188:191], v[52:55]
	v_mfma_f32_16x16x32_bf16 v[40:43], v[168:171], v[210:213], v[40:43]
	v_mfma_f32_16x16x32_bf16 v[36:39], v[180:183], v[210:213], v[36:39]
	v_mfma_f32_16x16x32_bf16 v[24:27], v[168:171], v[218:221], v[24:27]
	v_mfma_f32_16x16x32_bf16 v[20:23], v[180:183], v[218:221], v[20:23]
	v_mfma_f32_16x16x32_bf16 v[8:11], v[168:171], v[226:229], v[8:11]
	v_mfma_f32_16x16x32_bf16 v[4:7], v[180:183], v[226:229], v[4:7]
	s_setprio 0
	s_barrier
	s_add_i32 s51, s51, 2
	s_add_u32 s34, s34, 0x100
	s_addc_u32 s35, s35, 0
	s_add_u32 s49, s49, 0x100
	s_addc_u32 s50, s50, 0
	s_cmp_gt_u32 s51, 13
	s_cbranch_scc0 .LBB0_323
	s_and_b64 vcc, exec, s[14:15]
	s_cbranch_vccz .LBB0_326
	s_barrier

; #define PG8_STAGE(bufoff, gbase, voff) do { _Pragma("unroll") for (int _i = 0; _i < 2; ++_i) \
;         __builtin_amdgcn_global_load_lds((const unsigned*)((const char*)(gbase) + (voff)[_i]), (LAS unsigned*)(lds + (bufoff) + ldsw + _i * 8192), 16, 0, 0); } while (0)
; #define PG8_LDA(dst, b, h) do { _Pragma("unroll") for (int m = 0; m < 4; ++m) _Pragma("unroll") for (int k = 0; k < 2; ++k) dst[m][k] = *(const LAS bf16x8*)(lds + PG8_SA(b, h) + aoff + m * 2048 + k * 1024); } while (0)
; #define PG8_LDB(dst, b, h) do { _Pragma("unroll") for (int n = 0; n < 2; ++n) _Pragma("unroll") for (int k = 0; k < 2; ++k) dst[n][k] = *(const LAS bf16x8*)(lds + PG8_SB(b, h) + boff + n * 2048 + k * 1024); } while (0)
; #define PG8_MMA(ai, bj, At, Bt) do { __builtin_amdgcn_s_setprio(1); _Pragma("unroll") for (int m = 0; m < 4; ++m) _Pragma("unroll") for (int n = 0; n < 2; ++n) _Pragma("unroll") for (int k = 0; k < 2; ++k) \
;         acc[ai][bj][m][n] = __builtin_amdgcn_mfma_f32_16x16x32_bf16(Bt[n][k], At[m][k], acc[ai][bj][m][n], 0, 0, 0); __builtin_amdgcn_s_setprio(0); } while (0)
; #define PG8_WAIT_V(n) asm volatile("s_waitcnt vmcnt(" #n ")" ::: "memory")
; #define PG8_WAIT_L(n) asm volatile("s_waitcnt lgkmcnt(" #n ")" ::: "memory")
; #define PG8_BAR __builtin_amdgcn_s_barrier()
; #define PG8_SCHED __builtin_amdgcn_sched_barrier(0)
; template <class Epi>
; __device__ __forceinline__ void gemm_phase(LAS unsigned char* lds, const Gemm g, const StaticOrder& S, const Epi& E) {
;     ...
;         for (int t = 0; t < nt; t += 2) {
;             const bool last = (t == nt - 2);
;             const char* a1 = cA + (size_t)(t + 1) * kstep;
;             const char* a2 = last ? nA : cA + (size_t)(t + 2) * kstep; const char* b2 = last ? nB : cB + (size_t)(t + 2) * kstep;
;             const char* a3 = a2 + kstep; const char* b3 = b2 + kstep;
;             PG8_LDB(B0, 0, 0); PG8_LDB(B1, 0, 1); PG8_SCHED; PG8_LDA(At, 0, 0); PG8_STAGE(PG8_SA(1, 1), a1 + hstepA, voffA);
;             PG8_WAIT_V(8); PG8_WAIT_L(0); PG8_BAR; PG8_MMA(0, 0, At, B0); PG8_MMA(0, 1, At, B1); PG8_BAR; PG8_SCHED;
;             PG8_LDA(At, 0, 1); PG8_STAGE(PG8_SB(0, 0), b2, voffB); PG8_STAGE(PG8_SB(0, 1), b2 + hstepB, voffB); PG8_STAGE(PG8_SA(0, 0), a2, voffA);
.LBB0_551:
	s_add_u32 s22, s44, 0xfffc0080
	s_addc_u32 s23, s45, -1
	s_add_i32 s66, 0, 0x10000
	s_cmp_eq_u32 s65, 12
	s_cselect_b32 s47, s35, s23
	s_cselect_b32 s46, s61, s22
	v_add_u32_e32 v150, s66, v152
	s_cselect_b32 s23, s15, s64
	s_cselect_b32 s22, s62, s63
	s_add_i32 s68, 0, 0x14000
	ds_read_b128 v[142:145], v150
	ds_read_b128 v[146:149], v150 offset:1024
	ds_read_b128 v[156:159], v150 offset:2048
	ds_read_b128 v[160:163], v150 offset:3072
	v_add_u32_e32 v150, s68, v152
	ds_read_b128 v[164:167], v150
	ds_read_b128 v[168:171], v150 offset:1024
	ds_read_b128 v[172:175], v150 offset:2048
	ds_read_b128 v[176:179], v150 offset:3072
	v_lshl_add_u64 v[150:151], s[44:45], 0, v[138:139]
	s_add_i32 m0, s52, 0xc000
	ds_read_b128 v[180:183], v154
	ds_read_b128 v[184:187], v154 offset:1024
	ds_read_b128 v[188:191], v154 offset:2048
	ds_read_b128 v[192:195], v154 offset:3072
	ds_read_b128 v[210:213], v154 offset:4096
	ds_read_b128 v[214:217], v154 offset:5120
	ds_read_b128 v[218:221], v154 offset:6144
	ds_read_b128 v[222:225], v154 offset:7168
	global_load_lds_dwordx4 v[150:151], off
	v_lshl_add_u64 v[150:151], s[44:45], 0, v[140:141]
	s_add_i32 m0, s52, 0xe000
	s_nop 0
	global_load_lds_dwordx4 v[150:151], off
	s_waitcnt vmcnt(8)
	s_waitcnt lgkmcnt(0)
	s_barrier
	s_setprio 1
	v_mfma_f32_16x16x32_bf16 v[128:131], v[142:145], v[180:183], v[128:131]
	v_mfma_f32_16x16x32_bf16 v[124:127], v[156:159], v[180:183], v[124:127]
	v_mfma_f32_16x16x32_bf16 v[120:123], v[142:145], v[188:191], v[120:123]
	v_mfma_f32_16x16x32_bf16 v[116:119], v[156:159], v[188:191], v[116:119]
	v_mfma_f32_16x16x32_bf16 v[112:115], v[142:145], v[210:213], v[112:115]
	v_mfma_f32_16x16x32_bf16 v[108:111], v[156:159], v[210:213], v[108:111]
	v_mfma_f32_16x16x32_bf16 v[104:107], v[142:145], v[218:221], v[104:107]
	v_mfma_f32_16x16x32_bf16 v[100:103], v[156:159], v[218:221], v[100:103]
	v_mfma_f32_16x16x32_bf16 v[128:131], v[146:149], v[184:187], v[128:131]
	v_mfma_f32_16x16x32_bf16 v[124:127], v[160:163], v[184:187], v[124:127]
	v_mfma_f32_16x16x32_bf16 v[120:123], v[146:149], v[192:195], v[120:123]
	v_mfma_f32_16x16x32_bf16 v[116:119], v[160:163], v[192:195], v[116:119]
	v_mfma_f32_16x16x32_bf16 v[112:115], v[146:149], v[214:217], v[112:115]
	v_mfma_f32_16x16x32_bf16 v[108:111], v[160:163], v[214:217], v[108:111]
	v_mfma_f32_16x16x32_bf16 v[104:107], v[146:149], v[222:225], v[104:107]
	v_mfma_f32_16x16x32_bf16 v[100:103], v[160:163], v[222:225], v[100:103]
	s_setprio 0
	s_setprio 1
	v_mfma_f32_16x16x32_bf16 v[64:67], v[164:167], v[180:183], v[64:67]
	v_mfma_f32_16x16x32_bf16 v[60:63], v[172:175], v[180:183], v[60:63]
	v_mfma_f32_16x16x32_bf16 v[56:59], v[164:167], v[188:191], v[56:59]
	v_mfma_f32_16x16x32_bf16 v[52:55], v[172:175], v[188:191], v[52:55]
	v_mfma_f32_16x16x32_bf16 v[48:51], v[164:167], v[210:213], v[48:51]
	v_mfma_f32_16x16x32_bf16 v[44:47], v[172:175], v[210:213], v[44:47]
	v_mfma_f32_16x16x32_bf16 v[40:43], v[164:167], v[218:221], v[40:43]
	v_mfma_f32_16x16x32_bf16 v[36:39], v[172:175], v[218:221], v[36:39]
	v_mfma_f32_16x16x32_bf16 v[64:67], v[168:171], v[184:187], v[64:67]
	v_mfma_f32_16x16x32_bf16 v[60:63], v[176:179], v[184:187], v[60:63]
	v_mfma_f32_16x16x32_bf16 v[56:59], v[168:171], v[192:195], v[56:59]
	v_mfma_f32_16x16x32_bf16 v[52:55], v[176:179], v[192:195], v[52:55]
	v_mfma_f32_16x16x32_bf16 v[48:51], v[168:171], v[214:217], v[48:51]
	v_mfma_f32_16x16x32_bf16 v[44:47], v[176:179], v[214:217], v[44:47]
	v_mfma_f32_16x16x32_bf16 v[40:43], v[168:171], v[222:225], v[40:43]
	v_mfma_f32_16x16x32_bf16 v[36:39], v[176:179], v[222:225], v[36:39]
	s_setprio 0
	s_barrier
	s_add_i32 s66, s66, s51
	v_lshl_add_u64 v[150:151], s[22:23], 0, v[134:135]
	s_mov_b32 m0, s66
	ds_read_b128 v[180:183], v154 offset:16384
	ds_read_b128 v[184:187], v154 offset:17408
	ds_read_b128 v[188:191], v154 offset:18432
	ds_read_b128 v[192:195], v154 offset:19456
	ds_read_b128 v[210:213], v154 offset:20480
	ds_read_b128 v[214:217], v154 offset:21504
	ds_read_b128 v[218:221], v154 offset:22528
	ds_read_b128 v[222:225], v154 offset:23552
	global_load_lds_dwordx4 v[150:151], off
	s_add_i32 m0, s66, 0x2000
	s_add_u32 s66, s22, 0x10000
	v_lshl_add_u64 v[196:197], s[22:23], 0, v[0:1]
	s_addc_u32 s67, s23, 0
	s_add_i32 s68, s68, s51
	global_load_lds_dwordx4 v[196:197], off
	v_lshl_add_u64 v[198:199], s[66:67], 0, v[134:135]
	s_mov_b32 m0, s68
	v_lshl_add_u64 v[226:227], s[46:47], 0, v[132:133]
	global_load_lds_dwordx4 v[198:199], off
	v_lshl_add_u64 v[198:199], s[66:67], 0, v[0:1]
	s_add_i32 m0, s68, 0x2000
	s_nop 0
	global_load_lds_dwordx4 v[198:199], off
	v_lshl_add_u64 v[198:199], s[46:47], 0, v[136:137]
	s_mov_b32 m0, s52
	s_nop 0
	global_load_lds_dwordx4 v[198:199], off
	s_mov_b32 m0, s53
	s_nop 0
	global_load_lds_dwordx4 v[226:227], off
	s_waitcnt vmcnt(8)
	s_waitcnt lgkmcnt(0)
	s_barrier
; #define PG8_STAGE(bufoff, gbase, voff) do { _Pragma("unroll") for (int _i = 0; _i < 2; ++_i) \
;         __builtin_amdgcn_global_load_lds((const unsigned*)((const char*)(gbase) + (voff)[_i]), (LAS unsigned*)(lds + (bufoff) + ldsw + _i * 8192), 16, 0, 0); } while (0)
; #define PG8_LDA(dst, b, h) do { _Pragma("unroll") for (int m = 0; m < 4; ++m) _Pragma("unroll") for (int k = 0; k < 2; ++k) dst[m][k] = *(const LAS bf16x8*)(lds + PG8_SA(b, h) + aoff + m * 2048 + k * 1024); } while (0)
; #define PG8_LDB(dst, b, h) do { _Pragma("unroll") for (int n = 0; n < 2; ++n) _Pragma("unroll") for (int k = 0; k < 2; ++k) dst[n][k] = *(const LAS bf16x8*)(lds + PG8_SB(b, h) + boff + n * 2048 + k * 1024); } while (0)
; #define PG8_MMA(ai, bj, At, Bt) do { __builtin_amdgcn_s_setprio(1); _Pragma("unroll") for (int m = 0; m < 4; ++m) _Pragma("unroll") for (int n = 0; n < 2; ++n) _Pragma("unroll") for (int k = 0; k < 2; ++k) \
;         acc[ai][bj][m][n] = __builtin_amdgcn_mfma_f32_16x16x32_bf16(Bt[n][k], At[m][k], acc[ai][bj][m][n], 0, 0, 0); __builtin_amdgcn_s_setprio(0); } while (0)
; #define PG8_WAIT_V(n) asm volatile("s_waitcnt vmcnt(" #n ")" ::: "memory")
; #define PG8_WAIT_L(n) asm volatile("s_waitcnt lgkmcnt(" #n ")" ::: "memory")
; #define PG8_BAR __builtin_amdgcn_s_barrier()
; #define PG8_SCHED __builtin_amdgcn_sched_barrier(0)
; template <class Epi>
; __device__ __forceinline__ void gemm_phase(LAS unsigned char* lds, const Gemm g, const StaticOrder& S, const Epi& E) {
;     ...
;             PG8_WAIT_V(8); PG8_WAIT_L(0); PG8_BAR; PG8_MMA(1, 0, At, B0); PG8_MMA(1, 1, At, B1); PG8_BAR; PG8_SCHED;
;             PG8_LDB(B0, 1, 0); PG8_LDB(B1, 1, 1); PG8_SCHED; PG8_LDA(At, 1, 0); PG8_STAGE(PG8_SA(0, 1), a2 + hstepA, voffA);
;             PG8_WAIT_V(8); PG8_WAIT_L(0); PG8_BAR; PG8_MMA(0, 0, At, B0); PG8_MMA(0, 1, At, B1); PG8_BAR; PG8_SCHED;
	s_setprio 1
	v_mfma_f32_16x16x32_bf16 v[96:99], v[142:145], v[180:183], v[96:99]
	v_mfma_f32_16x16x32_bf16 v[92:95], v[156:159], v[180:183], v[92:95]
	v_mfma_f32_16x16x32_bf16 v[88:91], v[142:145], v[188:191], v[88:91]
	v_mfma_f32_16x16x32_bf16 v[84:87], v[156:159], v[188:191], v[84:87]
	v_mfma_f32_16x16x32_bf16 v[80:83], v[142:145], v[210:213], v[80:83]
	v_mfma_f32_16x16x32_bf16 v[76:79], v[156:159], v[210:213], v[76:79]
	v_mfma_f32_16x16x32_bf16 v[72:75], v[142:145], v[218:221], v[72:75]
	v_mfma_f32_16x16x32_bf16 v[68:71], v[156:159], v[218:221], v[68:71]
	v_mfma_f32_16x16x32_bf16 v[96:99], v[146:149], v[184:187], v[96:99]
	v_mfma_f32_16x16x32_bf16 v[92:95], v[160:163], v[184:187], v[92:95]
	v_mfma_f32_16x16x32_bf16 v[88:91], v[146:149], v[192:195], v[88:91]
	v_mfma_f32_16x16x32_bf16 v[84:87], v[160:163], v[192:195], v[84:87]
	v_mfma_f32_16x16x32_bf16 v[80:83], v[146:149], v[214:217], v[80:83]
	v_mfma_f32_16x16x32_bf16 v[76:79], v[160:163], v[214:217], v[76:79]
	v_mfma_f32_16x16x32_bf16 v[72:75], v[146:149], v[222:225], v[72:75]
	v_mfma_f32_16x16x32_bf16 v[68:71], v[160:163], v[222:225], v[68:71]
	s_setprio 0
	s_setprio 1
	v_mfma_f32_16x16x32_bf16 v[32:35], v[164:167], v[180:183], v[32:35]
	v_mfma_f32_16x16x32_bf16 v[28:31], v[172:175], v[180:183], v[28:31]
	v_mfma_f32_16x16x32_bf16 v[24:27], v[164:167], v[188:191], v[24:27]
	v_mfma_f32_16x16x32_bf16 v[20:23], v[172:175], v[188:191], v[20:23]
	v_mfma_f32_16x16x32_bf16 v[16:19], v[164:167], v[210:213], v[16:19]
	v_mfma_f32_16x16x32_bf16 v[12:15], v[172:175], v[210:213], v[12:15]
	v_mfma_f32_16x16x32_bf16 v[8:11], v[164:167], v[218:221], v[8:11]
	v_mfma_f32_16x16x32_bf16 v[4:7], v[172:175], v[218:221], v[4:7]
	v_mfma_f32_16x16x32_bf16 v[32:35], v[168:171], v[184:187], v[32:35]
	v_mfma_f32_16x16x32_bf16 v[28:31], v[176:179], v[184:187], v[28:31]
	v_mfma_f32_16x16x32_bf16 v[24:27], v[168:171], v[192:195], v[24:27]
	v_mfma_f32_16x16x32_bf16 v[20:23], v[176:179], v[192:195], v[20:23]
	v_mfma_f32_16x16x32_bf16 v[16:19], v[168:171], v[214:217], v[16:19]
	v_mfma_f32_16x16x32_bf16 v[12:15], v[176:179], v[214:217], v[12:15]
	v_mfma_f32_16x16x32_bf16 v[8:11], v[168:171], v[222:225], v[8:11]
	v_mfma_f32_16x16x32_bf16 v[4:7], v[176:179], v[222:225], v[4:7]
	s_setprio 0
	s_barrier
	s_add_i32 s66, 0, 0x18000
	v_add_u32_e32 v155, s66, v152
	s_add_i32 s67, 0, 0x1c000
	ds_read_b128 v[142:145], v155
	ds_read_b128 v[146:149], v155 offset:1024
	ds_read_b128 v[156:159], v155 offset:2048
	ds_read_b128 v[160:163], v155 offset:3072
	v_add_u32_e32 v155, s67, v152
	ds_read_b128 v[164:167], v155
	ds_read_b128 v[168:171], v155 offset:1024
	ds_read_b128 v[172:175], v155 offset:2048
	ds_read_b128 v[176:179], v155 offset:3072
	s_add_u32 s46, s46, 0x40000
	s_addc_u32 s47, s47, 0
	s_mov_b32 m0, s54
	v_lshl_add_u64 v[228:229], s[46:47], 0, v[136:137]
	ds_read_b128 v[180:183], v154 offset:32768
	ds_read_b128 v[184:187], v154 offset:33792
	ds_read_b128 v[188:191], v154 offset:34816
	ds_read_b128 v[192:195], v154 offset:35840
	ds_read_b128 v[210:213], v154 offset:36864
	ds_read_b128 v[214:217], v154 offset:37888
	ds_read_b128 v[218:221], v154 offset:38912
	ds_read_b128 v[222:225], v154 offset:39936
	global_load_lds_dwordx4 v[228:229], off
	v_lshl_add_u64 v[228:229], s[46:47], 0, v[132:133]
	s_mov_b32 m0, s55
	s_nop 0
	global_load_lds_dwordx4 v[228:229], off
	s_waitcnt vmcnt(8)
	s_waitcnt lgkmcnt(0)
	s_barrier
	s_setprio 1
	v_mfma_f32_16x16x32_bf16 v[128:131], v[142:145], v[180:183], v[128:131]
	v_mfma_f32_16x16x32_bf16 v[124:127], v[156:159], v[180:183], v[124:127]
	v_mfma_f32_16x16x32_bf16 v[120:123], v[142:145], v[188:191], v[120:123]
	v_mfma_f32_16x16x32_bf16 v[116:119], v[156:159], v[188:191], v[116:119]
	v_mfma_f32_16x16x32_bf16 v[112:115], v[142:145], v[210:213], v[112:115]
	v_mfma_f32_16x16x32_bf16 v[108:111], v[156:159], v[210:213], v[108:111]
	v_mfma_f32_16x16x32_bf16 v[104:107], v[142:145], v[218:221], v[104:107]
	v_mfma_f32_16x16x32_bf16 v[100:103], v[156:159], v[218:221], v[100:103]
	v_mfma_f32_16x16x32_bf16 v[128:131], v[146:149], v[184:187], v[128:131]
	v_mfma_f32_16x16x32_bf16 v[124:127], v[160:163], v[184:187], v[124:127]
	v_mfma_f32_16x16x32_bf16 v[120:123], v[146:149], v[192:195], v[120:123]
	v_mfma_f32_16x16x32_bf16 v[116:119], v[160:163], v[192:195], v[116:119]
	v_mfma_f32_16x16x32_bf16 v[112:115], v[146:149], v[214:217], v[112:115]
	v_mfma_f32_16x16x32_bf16 v[108:111], v[160:163], v[214:217], v[108:111]
	v_mfma_f32_16x16x32_bf16 v[104:107], v[146:149], v[222:225], v[104:107]
	v_mfma_f32_16x16x32_bf16 v[100:103], v[160:163], v[222:225], v[100:103]
	s_setprio 0
	s_setprio 1
	v_mfma_f32_16x16x32_bf16 v[64:67], v[164:167], v[180:183], v[64:67]
	v_mfma_f32_16x16x32_bf16 v[60:63], v[172:175], v[180:183], v[60:63]
	v_mfma_f32_16x16x32_bf16 v[56:59], v[164:167], v[188:191], v[56:59]
	v_mfma_f32_16x16x32_bf16 v[52:55], v[172:175], v[188:191], v[52:55]
	v_mfma_f32_16x16x32_bf16 v[48:51], v[164:167], v[210:213], v[48:51]
	v_mfma_f32_16x16x32_bf16 v[44:47], v[172:175], v[210:213], v[44:47]
	v_mfma_f32_16x16x32_bf16 v[40:43], v[164:167], v[218:221], v[40:43]
	v_mfma_f32_16x16x32_bf16 v[36:39], v[172:175], v[218:221], v[36:39]
	v_mfma_f32_16x16x32_bf16 v[64:67], v[168:171], v[184:187], v[64:67]
	v_mfma_f32_16x16x32_bf16 v[60:63], v[176:179], v[184:187], v[60:63]
	v_mfma_f32_16x16x32_bf16 v[56:59], v[168:171], v[192:195], v[56:59]
	v_mfma_f32_16x16x32_bf16 v[52:55], v[176:179], v[192:195], v[52:55]
	v_mfma_f32_16x16x32_bf16 v[48:51], v[168:171], v[214:217], v[48:51]
	v_mfma_f32_16x16x32_bf16 v[44:47], v[176:179], v[214:217], v[44:47]
	v_mfma_f32_16x16x32_bf16 v[40:43], v[168:171], v[222:225], v[40:43]
	v_mfma_f32_16x16x32_bf16 v[36:39], v[176:179], v[222:225], v[36:39]
	s_setprio 0
	s_barrier
; #define PG8_STAGE(bufoff, gbase, voff) do { _Pragma("unroll") for (int _i = 0; _i < 2; ++_i) \
;         __builtin_amdgcn_global_load_lds((const unsigned*)((const char*)(gbase) + (voff)[_i]), (LAS unsigned*)(lds + (bufoff) + ldsw + _i * 8192), 16, 0, 0); } while (0)
; #define PG8_LDA(dst, b, h) do { _Pragma("unroll") for (int m = 0; m < 4; ++m) _Pragma("unroll") for (int k = 0; k < 2; ++k) dst[m][k] = *(const LAS bf16x8*)(lds + PG8_SA(b, h) + aoff + m * 2048 + k * 1024); } while (0)
; #define PG8_MMA(ai, bj, At, Bt) do { __builtin_amdgcn_s_setprio(1); _Pragma("unroll") for (int m = 0; m < 4; ++m) _Pragma("unroll") for (int n = 0; n < 2; ++n) _Pragma("unroll") for (int k = 0; k < 2; ++k) \
;         acc[ai][bj][m][n] = __builtin_amdgcn_mfma_f32_16x16x32_bf16(Bt[n][k], At[m][k], acc[ai][bj][m][n], 0, 0, 0); __builtin_amdgcn_s_setprio(0); } while (0)
; #define PG8_WAIT_V(n) asm volatile("s_waitcnt vmcnt(" #n ")" ::: "memory")
; #define PG8_WAIT_L(n) asm volatile("s_waitcnt lgkmcnt(" #n ")" ::: "memory")
; #define PG8_BAR __builtin_amdgcn_s_barrier()
; #define PG8_SCHED __builtin_amdgcn_sched_barrier(0)
; template <class Epi>
; __device__ __forceinline__ void gemm_phase(LAS unsigned char* lds, const Gemm g, const StaticOrder& S, const Epi& E) {
;     ...
;             PG8_LDA(At, 1, 1); PG8_STAGE(PG8_SB(1, 0), b3, voffB); PG8_STAGE(PG8_SB(1, 1), b3 + hstepB, voffB); PG8_STAGE(PG8_SA(1, 0), a3, voffA);
;             PG8_WAIT_V(8); PG8_WAIT_L(0); PG8_BAR; PG8_MMA(1, 0, At, B0); PG8_MMA(1, 1, At, B1); PG8_BAR; PG8_SCHED;
;         }
;         if (wr == 0) PG8_BAR;
	s_add_i32 s46, s66, s51
	v_lshl_add_u64 v[150:151], v[150:151], 0, s[30:31]
	s_mov_b32 m0, s46
	ds_read_b128 v[180:183], v154 offset:49152
	ds_read_b128 v[184:187], v154 offset:50176
	ds_read_b128 v[188:191], v154 offset:51200
	ds_read_b128 v[192:195], v154 offset:52224
	ds_read_b128 v[210:213], v154 offset:53248
	ds_read_b128 v[214:217], v154 offset:54272
	ds_read_b128 v[218:221], v154 offset:55296
	ds_read_b128 v[222:225], v154 offset:56320
	global_load_lds_dwordx4 v[150:151], off
	s_add_i32 m0, s46, 0x2000
	s_add_u32 s22, s22, 0x10080
	v_lshl_add_u64 v[150:151], v[196:197], 0, s[30:31]
	s_addc_u32 s23, s23, 0
	s_add_i32 s46, s67, s51
	global_load_lds_dwordx4 v[150:151], off
	v_lshl_add_u64 v[150:151], s[22:23], 0, v[134:135]
	s_mov_b32 m0, s46
	s_nop 0
	global_load_lds_dwordx4 v[150:151], off
	v_lshl_add_u64 v[150:151], s[22:23], 0, v[0:1]
	s_add_i32 m0, s46, 0x2000
	s_nop 0
	global_load_lds_dwordx4 v[150:151], off
	v_lshl_add_u64 v[150:151], v[198:199], 0, s[30:31]
	s_mov_b32 m0, s56
	s_nop 0
	global_load_lds_dwordx4 v[150:151], off
	v_lshl_add_u64 v[150:151], v[226:227], 0, s[30:31]
	s_mov_b32 m0, s57
	s_nop 0
	global_load_lds_dwordx4 v[150:151], off
	s_waitcnt vmcnt(8)
	s_waitcnt lgkmcnt(0)
	s_barrier
	s_setprio 1
	v_mfma_f32_16x16x32_bf16 v[96:99], v[142:145], v[180:183], v[96:99]
	v_mfma_f32_16x16x32_bf16 v[92:95], v[156:159], v[180:183], v[92:95]
	v_mfma_f32_16x16x32_bf16 v[88:91], v[142:145], v[188:191], v[88:91]
	v_mfma_f32_16x16x32_bf16 v[84:87], v[156:159], v[188:191], v[84:87]
	v_mfma_f32_16x16x32_bf16 v[80:83], v[142:145], v[210:213], v[80:83]
	v_mfma_f32_16x16x32_bf16 v[76:79], v[156:159], v[210:213], v[76:79]
	v_mfma_f32_16x16x32_bf16 v[72:75], v[142:145], v[218:221], v[72:75]
	v_mfma_f32_16x16x32_bf16 v[68:71], v[156:159], v[218:221], v[68:71]
	v_mfma_f32_16x16x32_bf16 v[96:99], v[146:149], v[184:187], v[96:99]
	v_mfma_f32_16x16x32_bf16 v[92:95], v[160:163], v[184:187], v[92:95]
	v_mfma_f32_16x16x32_bf16 v[88:91], v[146:149], v[192:195], v[88:91]
	v_mfma_f32_16x16x32_bf16 v[84:87], v[160:163], v[192:195], v[84:87]
	v_mfma_f32_16x16x32_bf16 v[80:83], v[146:149], v[214:217], v[80:83]
	v_mfma_f32_16x16x32_bf16 v[76:79], v[160:163], v[214:217], v[76:79]
	v_mfma_f32_16x16x32_bf16 v[72:75], v[146:149], v[222:225], v[72:75]
	v_mfma_f32_16x16x32_bf16 v[68:71], v[160:163], v[222:225], v[68:71]
	s_setprio 0
	s_setprio 1
	v_mfma_f32_16x16x32_bf16 v[32:35], v[164:167], v[180:183], v[32:35]
	v_mfma_f32_16x16x32_bf16 v[28:31], v[172:175], v[180:183], v[28:31]
	v_mfma_f32_16x16x32_bf16 v[24:27], v[164:167], v[188:191], v[24:27]
	v_mfma_f32_16x16x32_bf16 v[20:23], v[172:175], v[188:191], v[20:23]
	v_mfma_f32_16x16x32_bf16 v[16:19], v[164:167], v[210:213], v[16:19]
	v_mfma_f32_16x16x32_bf16 v[12:15], v[172:175], v[210:213], v[12:15]
	v_mfma_f32_16x16x32_bf16 v[8:11], v[164:167], v[218:221], v[8:11]
	v_mfma_f32_16x16x32_bf16 v[4:7], v[172:175], v[218:221], v[4:7]
	v_mfma_f32_16x16x32_bf16 v[32:35], v[168:171], v[184:187], v[32:35]
	v_mfma_f32_16x16x32_bf16 v[28:31], v[176:179], v[184:187], v[28:31]
	v_mfma_f32_16x16x32_bf16 v[24:27], v[168:171], v[192:195], v[24:27]
	v_mfma_f32_16x16x32_bf16 v[20:23], v[176:179], v[192:195], v[20:23]
	v_mfma_f32_16x16x32_bf16 v[16:19], v[168:171], v[214:217], v[16:19]
	v_mfma_f32_16x16x32_bf16 v[12:15], v[176:179], v[214:217], v[12:15]
	v_mfma_f32_16x16x32_bf16 v[8:11], v[168:171], v[222:225], v[8:11]
	v_mfma_f32_16x16x32_bf16 v[4:7], v[176:179], v[222:225], v[4:7]
	s_setprio 0
	s_barrier
	s_add_i32 s65, s65, 2
	s_add_u32 s44, s44, 0x100
	s_addc_u32 s45, s45, 0
	s_add_u32 s63, s63, 0x100
	s_addc_u32 s64, s64, 0
	s_cmp_gt_u32 s65, 13
	s_cbranch_scc0 .LBB0_551
	v_readlane_b32 s64, v252, 28
	s_and_b64 vcc, exec, s[12:13]
	v_readlane_b32 s65, v252, 29
	s_cbranch_vccz .LBB0_554
	s_barrier

; #define PG8_STAGE(bufoff, gbase, voff) do { _Pragma("unroll") for (int _i = 0; _i < 2; ++_i) \
;         __builtin_amdgcn_global_load_lds((const unsigned*)((const char*)(gbase) + (voff)[_i]), (LAS unsigned*)(lds + (bufoff) + ldsw + _i * 8192), 16, 0, 0); } while (0)
; #define PG8_LDA(dst, b, h) do { _Pragma("unroll") for (int m = 0; m < 4; ++m) _Pragma("unroll") for (int k = 0; k < 2; ++k) dst[m][k] = *(const LAS bf16x8*)(lds + PG8_SA(b, h) + aoff + m * 2048 + k * 1024); } while (0)
; #define PG8_LDB(dst, b, h) do { _Pragma("unroll") for (int n = 0; n < 2; ++n) _Pragma("unroll") for (int k = 0; k < 2; ++k) dst[n][k] = *(const LAS bf16x8*)(lds + PG8_SB(b, h) + boff + n * 2048 + k * 1024); } while (0)
; #define PG8_MMA(ai, bj, At, Bt) do { __builtin_amdgcn_s_setprio(1); _Pragma("unroll") for (int m = 0; m < 4; ++m) _Pragma("unroll") for (int n = 0; n < 2; ++n) _Pragma("unroll") for (int k = 0; k < 2; ++k) \
;         acc[ai][bj][m][n] = __builtin_amdgcn_mfma_f32_16x16x32_bf16(Bt[n][k], At[m][k], acc[ai][bj][m][n], 0, 0, 0); __builtin_amdgcn_s_setprio(0); } while (0)
; #define PG8_WAIT_V(n) asm volatile("s_waitcnt vmcnt(" #n ")" ::: "memory")
; #define PG8_WAIT_L(n) asm volatile("s_waitcnt lgkmcnt(" #n ")" ::: "memory")
; #define PG8_BAR __builtin_amdgcn_s_barrier()
; #define PG8_SCHED __builtin_amdgcn_sched_barrier(0)
; template <class Epi>
; __device__ __forceinline__ void gemm_phase(LAS unsigned char* lds, const Gemm g, const StaticOrder& S, const Epi& E) {
;     ...
;         for (int t = 0; t < nt; t += 2) {
;             const bool last = (t == nt - 2);
;             const char* a1 = cA + (size_t)(t + 1) * kstep;
;             const char* a2 = last ? nA : cA + (size_t)(t + 2) * kstep; const char* b2 = last ? nB : cB + (size_t)(t + 2) * kstep;
;             const char* a3 = a2 + kstep; const char* b3 = b2 + kstep;
;             PG8_LDB(B0, 0, 0); PG8_LDB(B1, 0, 1); PG8_SCHED; PG8_LDA(At, 0, 0); PG8_STAGE(PG8_SA(1, 1), a1 + hstepA, voffA);
;             PG8_WAIT_V(8); PG8_WAIT_L(0); PG8_BAR; PG8_MMA(0, 0, At, B0); PG8_MMA(0, 1, At, B1); PG8_BAR; PG8_SCHED;
;             PG8_LDA(At, 0, 1); PG8_STAGE(PG8_SB(0, 0), b2, voffB); PG8_STAGE(PG8_SB(0, 1), b2 + hstepB, voffB); PG8_STAGE(PG8_SA(0, 0), a2, voffA);
.LBB0_660:
	s_add_u32 s38, s34, 0x100
	s_addc_u32 s39, s35, 0
	s_add_i32 s63, 0, 0x10000
	s_cmp_eq_u32 s62, 2
	s_cselect_b32 s41, s5, s39
	s_cselect_b32 s40, s4, s38
	s_cselect_b32 s23, s15, s61
	s_cselect_b32 s22, s14, s60
	s_add_i32 s64, 0, 0x14000
	v_add_u32_e32 v158, s63, v170
	v_add_u32_e32 v173, s64, v170
	ds_read_b128 v[146:149], v158
	ds_read_b128 v[150:153], v158 offset:1024
	ds_read_b128 v[154:157], v158 offset:2048
	ds_read_b128 v[158:161], v158 offset:3072
	ds_read_b128 v[162:165], v173
	ds_read_b128 v[166:169], v173 offset:1024
	ds_read_b128 v[174:177], v173 offset:2048
	ds_read_b128 v[178:181], v173 offset:3072
	v_lshl_add_u64 v[194:195], s[34:35], 0, v[142:143]
	s_add_i32 m0, s51, 0xc000
	ds_read_b128 v[182:185], v172
	ds_read_b128 v[186:189], v172 offset:1024
	ds_read_b128 v[190:193], v172 offset:2048
	ds_read_b128 v[210:213], v172 offset:3072
	ds_read_b128 v[214:217], v172 offset:4096
	ds_read_b128 v[218:221], v172 offset:5120
	ds_read_b128 v[222:225], v172 offset:6144
	ds_read_b128 v[226:229], v172 offset:7168
	global_load_lds_dwordx4 v[194:195], off
	v_lshl_add_u64 v[194:195], s[34:35], 0, v[144:145]
	s_add_i32 m0, s51, 0xe000
	s_nop 0
	global_load_lds_dwordx4 v[194:195], off
	s_waitcnt vmcnt(8)
	s_waitcnt lgkmcnt(0)
	s_barrier
	s_setprio 1
	v_mfma_f32_16x16x32_bf16 v[128:131], v[146:149], v[182:185], v[128:131]
	v_mfma_f32_16x16x32_bf16 v[124:127], v[154:157], v[182:185], v[124:127]
	v_mfma_f32_16x16x32_bf16 v[112:115], v[146:149], v[190:193], v[112:115]
	v_mfma_f32_16x16x32_bf16 v[108:111], v[154:157], v[190:193], v[108:111]
	v_mfma_f32_16x16x32_bf16 v[96:99], v[146:149], v[214:217], v[96:99]
	v_mfma_f32_16x16x32_bf16 v[92:95], v[154:157], v[214:217], v[92:95]
	v_mfma_f32_16x16x32_bf16 v[80:83], v[146:149], v[222:225], v[80:83]
	v_mfma_f32_16x16x32_bf16 v[76:79], v[154:157], v[222:225], v[76:79]
	v_mfma_f32_16x16x32_bf16 v[128:131], v[150:153], v[186:189], v[128:131]
	v_mfma_f32_16x16x32_bf16 v[124:127], v[158:161], v[186:189], v[124:127]
	v_mfma_f32_16x16x32_bf16 v[112:115], v[150:153], v[210:213], v[112:115]
	v_mfma_f32_16x16x32_bf16 v[108:111], v[158:161], v[210:213], v[108:111]
	v_mfma_f32_16x16x32_bf16 v[96:99], v[150:153], v[218:221], v[96:99]
	v_mfma_f32_16x16x32_bf16 v[92:95], v[158:161], v[218:221], v[92:95]
	v_mfma_f32_16x16x32_bf16 v[80:83], v[150:153], v[226:229], v[80:83]
	v_mfma_f32_16x16x32_bf16 v[76:79], v[158:161], v[226:229], v[76:79]
	s_setprio 0
	s_setprio 1
	v_mfma_f32_16x16x32_bf16 v[120:123], v[162:165], v[182:185], v[120:123]
	v_mfma_f32_16x16x32_bf16 v[116:119], v[174:177], v[182:185], v[116:119]
	v_mfma_f32_16x16x32_bf16 v[104:107], v[162:165], v[190:193], v[104:107]
	v_mfma_f32_16x16x32_bf16 v[100:103], v[174:177], v[190:193], v[100:103]
	v_mfma_f32_16x16x32_bf16 v[88:91], v[162:165], v[214:217], v[88:91]
	v_mfma_f32_16x16x32_bf16 v[84:87], v[174:177], v[214:217], v[84:87]
	v_mfma_f32_16x16x32_bf16 v[72:75], v[162:165], v[222:225], v[72:75]
	v_mfma_f32_16x16x32_bf16 v[68:71], v[174:177], v[222:225], v[68:71]
	v_mfma_f32_16x16x32_bf16 v[120:123], v[166:169], v[186:189], v[120:123]
	v_mfma_f32_16x16x32_bf16 v[116:119], v[178:181], v[186:189], v[116:119]
	v_mfma_f32_16x16x32_bf16 v[104:107], v[166:169], v[210:213], v[104:107]
	v_mfma_f32_16x16x32_bf16 v[100:103], v[178:181], v[210:213], v[100:103]
	v_mfma_f32_16x16x32_bf16 v[88:91], v[166:169], v[218:221], v[88:91]
	v_mfma_f32_16x16x32_bf16 v[84:87], v[178:181], v[218:221], v[84:87]
	v_mfma_f32_16x16x32_bf16 v[72:75], v[166:169], v[226:229], v[72:75]
	v_mfma_f32_16x16x32_bf16 v[68:71], v[178:181], v[226:229], v[68:71]
	s_setprio 0
	s_barrier
	s_add_i32 s34, s63, s50
	v_lshl_add_u64 v[194:195], s[22:23], 0, v[134:135]
	s_mov_b32 m0, s34
	ds_read_b128 v[182:185], v172 offset:16384
	ds_read_b128 v[186:189], v172 offset:17408
	ds_read_b128 v[190:193], v172 offset:18432
	ds_read_b128 v[210:213], v172 offset:19456
	ds_read_b128 v[214:217], v172 offset:20480
	ds_read_b128 v[218:221], v172 offset:21504
	ds_read_b128 v[222:225], v172 offset:22528
	ds_read_b128 v[226:229], v172 offset:23552
	global_load_lds_dwordx4 v[194:195], off
	s_add_i32 m0, s34, 0x2000
	s_add_u32 s34, s22, 0x6000
	v_lshl_add_u64 v[196:197], s[22:23], 0, v[0:1]
	s_addc_u32 s35, s23, 0
	s_add_i32 s63, s64, s50
	global_load_lds_dwordx4 v[196:197], off
	v_lshl_add_u64 v[198:199], s[34:35], 0, v[134:135]
	s_mov_b32 m0, s63
	v_lshl_add_u64 v[230:231], s[40:41], 0, v[132:133]
	global_load_lds_dwordx4 v[198:199], off
	v_lshl_add_u64 v[198:199], s[34:35], 0, v[0:1]
	s_add_i32 m0, s63, 0x2000
	s_nop 0
	global_load_lds_dwordx4 v[198:199], off
	v_lshl_add_u64 v[198:199], s[40:41], 0, v[136:137]
	s_mov_b32 m0, s51
	s_nop 0
	global_load_lds_dwordx4 v[198:199], off
	s_mov_b32 m0, s52
	s_nop 0
	global_load_lds_dwordx4 v[230:231], off
	s_waitcnt vmcnt(8)
	s_waitcnt lgkmcnt(0)
	s_barrier
; #define PG8_STAGE(bufoff, gbase, voff) do { _Pragma("unroll") for (int _i = 0; _i < 2; ++_i) \
;         __builtin_amdgcn_global_load_lds((const unsigned*)((const char*)(gbase) + (voff)[_i]), (LAS unsigned*)(lds + (bufoff) + ldsw + _i * 8192), 16, 0, 0); } while (0)
; #define PG8_LDA(dst, b, h) do { _Pragma("unroll") for (int m = 0; m < 4; ++m) _Pragma("unroll") for (int k = 0; k < 2; ++k) dst[m][k] = *(const LAS bf16x8*)(lds + PG8_SA(b, h) + aoff + m * 2048 + k * 1024); } while (0)
; #define PG8_LDB(dst, b, h) do { _Pragma("unroll") for (int n = 0; n < 2; ++n) _Pragma("unroll") for (int k = 0; k < 2; ++k) dst[n][k] = *(const LAS bf16x8*)(lds + PG8_SB(b, h) + boff + n * 2048 + k * 1024); } while (0)
; #define PG8_MMA(ai, bj, At, Bt) do { __builtin_amdgcn_s_setprio(1); _Pragma("unroll") for (int m = 0; m < 4; ++m) _Pragma("unroll") for (int n = 0; n < 2; ++n) _Pragma("unroll") for (int k = 0; k < 2; ++k) \
;         acc[ai][bj][m][n] = __builtin_amdgcn_mfma_f32_16x16x32_bf16(Bt[n][k], At[m][k], acc[ai][bj][m][n], 0, 0, 0); __builtin_amdgcn_s_setprio(0); } while (0)
; #define PG8_WAIT_V(n) asm volatile("s_waitcnt vmcnt(" #n ")" ::: "memory")
; #define PG8_WAIT_L(n) asm volatile("s_waitcnt lgkmcnt(" #n ")" ::: "memory")
; #define PG8_BAR __builtin_amdgcn_s_barrier()
; #define PG8_SCHED __builtin_amdgcn_sched_barrier(0)
; template <class Epi>
; __device__ __forceinline__ void gemm_phase(LAS unsigned char* lds, const Gemm g, const StaticOrder& S, const Epi& E) {
;     ...
;             PG8_WAIT_V(8); PG8_WAIT_L(0); PG8_BAR; PG8_MMA(1, 0, At, B0); PG8_MMA(1, 1, At, B1); PG8_BAR; PG8_SCHED;
;             PG8_LDB(B0, 1, 0); PG8_LDB(B1, 1, 1); PG8_SCHED; PG8_LDA(At, 1, 0); PG8_STAGE(PG8_SA(0, 1), a2 + hstepA, voffA);
;             PG8_WAIT_V(8); PG8_WAIT_L(0); PG8_BAR; PG8_MMA(0, 0, At, B0); PG8_MMA(0, 1, At, B1); PG8_BAR; PG8_SCHED;
	s_setprio 1
	v_mfma_f32_16x16x32_bf16 v[64:67], v[146:149], v[182:185], v[64:67]
	v_mfma_f32_16x16x32_bf16 v[60:63], v[154:157], v[182:185], v[60:63]
	v_mfma_f32_16x16x32_bf16 v[48:51], v[146:149], v[190:193], v[48:51]
	v_mfma_f32_16x16x32_bf16 v[44:47], v[154:157], v[190:193], v[44:47]
	v_mfma_f32_16x16x32_bf16 v[32:35], v[146:149], v[214:217], v[32:35]
	v_mfma_f32_16x16x32_bf16 v[28:31], v[154:157], v[214:217], v[28:31]
	v_mfma_f32_16x16x32_bf16 v[16:19], v[146:149], v[222:225], v[16:19]
	v_mfma_f32_16x16x32_bf16 v[12:15], v[154:157], v[222:225], v[12:15]
	v_mfma_f32_16x16x32_bf16 v[64:67], v[150:153], v[186:189], v[64:67]
	v_mfma_f32_16x16x32_bf16 v[60:63], v[158:161], v[186:189], v[60:63]
	v_mfma_f32_16x16x32_bf16 v[48:51], v[150:153], v[210:213], v[48:51]
	v_mfma_f32_16x16x32_bf16 v[44:47], v[158:161], v[210:213], v[44:47]
	v_mfma_f32_16x16x32_bf16 v[32:35], v[150:153], v[218:221], v[32:35]
	v_mfma_f32_16x16x32_bf16 v[28:31], v[158:161], v[218:221], v[28:31]
	v_mfma_f32_16x16x32_bf16 v[16:19], v[150:153], v[226:229], v[16:19]
	v_mfma_f32_16x16x32_bf16 v[12:15], v[158:161], v[226:229], v[12:15]
	s_setprio 0
	s_setprio 1
	v_mfma_f32_16x16x32_bf16 v[56:59], v[162:165], v[182:185], v[56:59]
	v_mfma_f32_16x16x32_bf16 v[52:55], v[174:177], v[182:185], v[52:55]
	v_mfma_f32_16x16x32_bf16 v[40:43], v[162:165], v[190:193], v[40:43]
	v_mfma_f32_16x16x32_bf16 v[36:39], v[174:177], v[190:193], v[36:39]
	v_mfma_f32_16x16x32_bf16 v[24:27], v[162:165], v[214:217], v[24:27]
	v_mfma_f32_16x16x32_bf16 v[20:23], v[174:177], v[214:217], v[20:23]
	v_mfma_f32_16x16x32_bf16 v[8:11], v[162:165], v[222:225], v[8:11]
	v_mfma_f32_16x16x32_bf16 v[4:7], v[174:177], v[222:225], v[4:7]
	v_mfma_f32_16x16x32_bf16 v[56:59], v[166:169], v[186:189], v[56:59]
	v_mfma_f32_16x16x32_bf16 v[52:55], v[178:181], v[186:189], v[52:55]
	v_mfma_f32_16x16x32_bf16 v[40:43], v[166:169], v[210:213], v[40:43]
	v_mfma_f32_16x16x32_bf16 v[36:39], v[178:181], v[210:213], v[36:39]
	v_mfma_f32_16x16x32_bf16 v[24:27], v[166:169], v[218:221], v[24:27]
	v_mfma_f32_16x16x32_bf16 v[20:23], v[178:181], v[218:221], v[20:23]
	v_mfma_f32_16x16x32_bf16 v[8:11], v[166:169], v[226:229], v[8:11]
	v_mfma_f32_16x16x32_bf16 v[4:7], v[178:181], v[226:229], v[4:7]
	s_setprio 0
	s_barrier
	s_add_i32 s63, 0, 0x18000
	s_add_i32 s64, 0, 0x1c000
	v_add_u32_e32 v158, s63, v170
	v_add_u32_e32 v173, s64, v170
	ds_read_b128 v[146:149], v158
	ds_read_b128 v[150:153], v158 offset:1024
	ds_read_b128 v[154:157], v158 offset:2048
	ds_read_b128 v[158:161], v158 offset:3072
	ds_read_b128 v[162:165], v173
	ds_read_b128 v[166:169], v173 offset:1024
	ds_read_b128 v[174:177], v173 offset:2048
	ds_read_b128 v[178:181], v173 offset:3072
	s_add_u32 s34, s40, 0xea000
	s_addc_u32 s35, s41, 0
	s_mov_b32 m0, s53
	v_lshl_add_u64 v[232:233], s[34:35], 0, v[136:137]
	ds_read_b128 v[182:185], v172 offset:32768
	ds_read_b128 v[186:189], v172 offset:33792
	ds_read_b128 v[190:193], v172 offset:34816
	ds_read_b128 v[210:213], v172 offset:35840
	ds_read_b128 v[214:217], v172 offset:36864
	ds_read_b128 v[218:221], v172 offset:37888
	ds_read_b128 v[222:225], v172 offset:38912
	ds_read_b128 v[226:229], v172 offset:39936
	global_load_lds_dwordx4 v[232:233], off
	v_lshl_add_u64 v[232:233], s[34:35], 0, v[132:133]
	s_mov_b32 m0, s54
	s_nop 0
	global_load_lds_dwordx4 v[232:233], off
	s_waitcnt vmcnt(8)
	s_waitcnt lgkmcnt(0)
	s_barrier
	s_setprio 1
	v_mfma_f32_16x16x32_bf16 v[128:131], v[146:149], v[182:185], v[128:131]
	v_mfma_f32_16x16x32_bf16 v[124:127], v[154:157], v[182:185], v[124:127]
	v_mfma_f32_16x16x32_bf16 v[112:115], v[146:149], v[190:193], v[112:115]
	v_mfma_f32_16x16x32_bf16 v[108:111], v[154:157], v[190:193], v[108:111]
	v_mfma_f32_16x16x32_bf16 v[96:99], v[146:149], v[214:217], v[96:99]
	v_mfma_f32_16x16x32_bf16 v[92:95], v[154:157], v[214:217], v[92:95]
	v_mfma_f32_16x16x32_bf16 v[80:83], v[146:149], v[222:225], v[80:83]
	v_mfma_f32_16x16x32_bf16 v[76:79], v[154:157], v[222:225], v[76:79]
	v_mfma_f32_16x16x32_bf16 v[128:131], v[150:153], v[186:189], v[128:131]
	v_mfma_f32_16x16x32_bf16 v[124:127], v[158:161], v[186:189], v[124:127]
	v_mfma_f32_16x16x32_bf16 v[112:115], v[150:153], v[210:213], v[112:115]
	v_mfma_f32_16x16x32_bf16 v[108:111], v[158:161], v[210:213], v[108:111]
	v_mfma_f32_16x16x32_bf16 v[96:99], v[150:153], v[218:221], v[96:99]
	v_mfma_f32_16x16x32_bf16 v[92:95], v[158:161], v[218:221], v[92:95]
	v_mfma_f32_16x16x32_bf16 v[80:83], v[150:153], v[226:229], v[80:83]
	v_mfma_f32_16x16x32_bf16 v[76:79], v[158:161], v[226:229], v[76:79]
	s_setprio 0
	s_setprio 1
	v_mfma_f32_16x16x32_bf16 v[120:123], v[162:165], v[182:185], v[120:123]
	v_mfma_f32_16x16x32_bf16 v[116:119], v[174:177], v[182:185], v[116:119]
	v_mfma_f32_16x16x32_bf16 v[104:107], v[162:165], v[190:193], v[104:107]
	v_mfma_f32_16x16x32_bf16 v[100:103], v[174:177], v[190:193], v[100:103]
	v_mfma_f32_16x16x32_bf16 v[88:91], v[162:165], v[214:217], v[88:91]
	v_mfma_f32_16x16x32_bf16 v[84:87], v[174:177], v[214:217], v[84:87]
	v_mfma_f32_16x16x32_bf16 v[72:75], v[162:165], v[222:225], v[72:75]
	v_mfma_f32_16x16x32_bf16 v[68:71], v[174:177], v[222:225], v[68:71]
	v_mfma_f32_16x16x32_bf16 v[120:123], v[166:169], v[186:189], v[120:123]
	v_mfma_f32_16x16x32_bf16 v[116:119], v[178:181], v[186:189], v[116:119]
	v_mfma_f32_16x16x32_bf16 v[104:107], v[166:169], v[210:213], v[104:107]
	v_mfma_f32_16x16x32_bf16 v[100:103], v[178:181], v[210:213], v[100:103]
	v_mfma_f32_16x16x32_bf16 v[88:91], v[166:169], v[218:221], v[88:91]
	v_mfma_f32_16x16x32_bf16 v[84:87], v[178:181], v[218:221], v[84:87]
	v_mfma_f32_16x16x32_bf16 v[72:75], v[166:169], v[226:229], v[72:75]
	v_mfma_f32_16x16x32_bf16 v[68:71], v[178:181], v[226:229], v[68:71]
	s_setprio 0
	s_barrier
; #define PG8_STAGE(bufoff, gbase, voff) do { _Pragma("unroll") for (int _i = 0; _i < 2; ++_i) \
;         __builtin_amdgcn_global_load_lds((const unsigned*)((const char*)(gbase) + (voff)[_i]), (LAS unsigned*)(lds + (bufoff) + ldsw + _i * 8192), 16, 0, 0); } while (0)
; #define PG8_LDA(dst, b, h) do { _Pragma("unroll") for (int m = 0; m < 4; ++m) _Pragma("unroll") for (int k = 0; k < 2; ++k) dst[m][k] = *(const LAS bf16x8*)(lds + PG8_SA(b, h) + aoff + m * 2048 + k * 1024); } while (0)
; #define PG8_MMA(ai, bj, At, Bt) do { __builtin_amdgcn_s_setprio(1); _Pragma("unroll") for (int m = 0; m < 4; ++m) _Pragma("unroll") for (int n = 0; n < 2; ++n) _Pragma("unroll") for (int k = 0; k < 2; ++k) \
;         acc[ai][bj][m][n] = __builtin_amdgcn_mfma_f32_16x16x32_bf16(Bt[n][k], At[m][k], acc[ai][bj][m][n], 0, 0, 0); __builtin_amdgcn_s_setprio(0); } while (0)
; #define PG8_WAIT_V(n) asm volatile("s_waitcnt vmcnt(" #n ")" ::: "memory")
; #define PG8_WAIT_L(n) asm volatile("s_waitcnt lgkmcnt(" #n ")" ::: "memory")
; #define PG8_BAR __builtin_amdgcn_s_barrier()
; #define PG8_SCHED __builtin_amdgcn_sched_barrier(0)
; template <class Epi>
; __device__ __forceinline__ void gemm_phase(LAS unsigned char* lds, const Gemm g, const StaticOrder& S, const Epi& E) {
;     ...
;             PG8_LDA(At, 1, 1); PG8_STAGE(PG8_SB(1, 0), b3, voffB); PG8_STAGE(PG8_SB(1, 1), b3 + hstepB, voffB); PG8_STAGE(PG8_SA(1, 0), a3, voffA);
;             PG8_WAIT_V(8); PG8_WAIT_L(0); PG8_BAR; PG8_MMA(1, 0, At, B0); PG8_MMA(1, 1, At, B1); PG8_BAR; PG8_SCHED;
;         }
;         if (wr == 0) PG8_BAR;
	s_add_i32 s34, s63, s50
	v_lshl_add_u64 v[194:195], v[194:195], 0, s[30:31]
	s_mov_b32 m0, s34
	ds_read_b128 v[182:185], v172 offset:49152
	ds_read_b128 v[186:189], v172 offset:50176
	ds_read_b128 v[190:193], v172 offset:51200
	ds_read_b128 v[210:213], v172 offset:52224
	ds_read_b128 v[214:217], v172 offset:53248
	ds_read_b128 v[218:221], v172 offset:54272
	ds_read_b128 v[222:225], v172 offset:55296
	ds_read_b128 v[226:229], v172 offset:56320
	global_load_lds_dwordx4 v[194:195], off
	s_add_i32 m0, s34, 0x2000
	s_add_u32 s22, s22, 0x6080
	v_lshl_add_u64 v[194:195], v[196:197], 0, s[30:31]
	s_addc_u32 s23, s23, 0
	s_add_i32 s34, s64, s50
	global_load_lds_dwordx4 v[194:195], off
	v_lshl_add_u64 v[194:195], s[22:23], 0, v[134:135]
	s_mov_b32 m0, s34
	s_nop 0
	global_load_lds_dwordx4 v[194:195], off
	v_lshl_add_u64 v[194:195], s[22:23], 0, v[0:1]
	s_add_i32 m0, s34, 0x2000
	s_nop 0
	global_load_lds_dwordx4 v[194:195], off
	v_lshl_add_u64 v[194:195], v[198:199], 0, s[30:31]
	s_mov_b32 m0, s55
	s_nop 0
	global_load_lds_dwordx4 v[194:195], off
	v_lshl_add_u64 v[194:195], v[230:231], 0, s[30:31]
	s_mov_b32 m0, s56
	s_nop 0
	global_load_lds_dwordx4 v[194:195], off
	s_waitcnt vmcnt(8)
	s_waitcnt lgkmcnt(0)
	s_barrier
	s_setprio 1
	v_mfma_f32_16x16x32_bf16 v[64:67], v[146:149], v[182:185], v[64:67]
	v_mfma_f32_16x16x32_bf16 v[60:63], v[154:157], v[182:185], v[60:63]
	v_mfma_f32_16x16x32_bf16 v[48:51], v[146:149], v[190:193], v[48:51]
	v_mfma_f32_16x16x32_bf16 v[44:47], v[154:157], v[190:193], v[44:47]
	v_mfma_f32_16x16x32_bf16 v[32:35], v[146:149], v[214:217], v[32:35]
	v_mfma_f32_16x16x32_bf16 v[28:31], v[154:157], v[214:217], v[28:31]
	v_mfma_f32_16x16x32_bf16 v[16:19], v[146:149], v[222:225], v[16:19]
	v_mfma_f32_16x16x32_bf16 v[12:15], v[154:157], v[222:225], v[12:15]
	v_mfma_f32_16x16x32_bf16 v[64:67], v[150:153], v[186:189], v[64:67]
	v_mfma_f32_16x16x32_bf16 v[60:63], v[158:161], v[186:189], v[60:63]
	v_mfma_f32_16x16x32_bf16 v[48:51], v[150:153], v[210:213], v[48:51]
	v_mfma_f32_16x16x32_bf16 v[44:47], v[158:161], v[210:213], v[44:47]
	v_mfma_f32_16x16x32_bf16 v[32:35], v[150:153], v[218:221], v[32:35]
	v_mfma_f32_16x16x32_bf16 v[28:31], v[158:161], v[218:221], v[28:31]
	v_mfma_f32_16x16x32_bf16 v[16:19], v[150:153], v[226:229], v[16:19]
	v_mfma_f32_16x16x32_bf16 v[12:15], v[158:161], v[226:229], v[12:15]
	s_setprio 0
	s_setprio 1
	v_mfma_f32_16x16x32_bf16 v[56:59], v[162:165], v[182:185], v[56:59]
	v_mfma_f32_16x16x32_bf16 v[52:55], v[174:177], v[182:185], v[52:55]
	v_mfma_f32_16x16x32_bf16 v[40:43], v[162:165], v[190:193], v[40:43]
	v_mfma_f32_16x16x32_bf16 v[36:39], v[174:177], v[190:193], v[36:39]
	v_mfma_f32_16x16x32_bf16 v[24:27], v[162:165], v[214:217], v[24:27]
	v_mfma_f32_16x16x32_bf16 v[20:23], v[174:177], v[214:217], v[20:23]
	v_mfma_f32_16x16x32_bf16 v[8:11], v[162:165], v[222:225], v[8:11]
	v_mfma_f32_16x16x32_bf16 v[4:7], v[174:177], v[222:225], v[4:7]
	v_mfma_f32_16x16x32_bf16 v[56:59], v[166:169], v[186:189], v[56:59]
	v_mfma_f32_16x16x32_bf16 v[52:55], v[178:181], v[186:189], v[52:55]
	v_mfma_f32_16x16x32_bf16 v[40:43], v[166:169], v[210:213], v[40:43]
	v_mfma_f32_16x16x32_bf16 v[36:39], v[178:181], v[210:213], v[36:39]
	v_mfma_f32_16x16x32_bf16 v[24:27], v[166:169], v[218:221], v[24:27]
	v_mfma_f32_16x16x32_bf16 v[20:23], v[178:181], v[218:221], v[20:23]
	v_mfma_f32_16x16x32_bf16 v[8:11], v[166:169], v[226:229], v[8:11]
	v_mfma_f32_16x16x32_bf16 v[4:7], v[178:181], v[226:229], v[4:7]
	s_setprio 0
	s_barrier
	s_add_i32 s62, s62, 2
	s_add_u32 s60, s60, 0x100
	s_addc_u32 s61, s61, 0
	s_cmp_gt_u32 s62, 3
	s_mov_b64 s[34:35], s[38:39]
	s_cbranch_scc0 .LBB0_660
	s_and_b64 vcc, exec, s[12:13]
	s_cbranch_vccz .LBB0_663
	s_barrier

; #define PG8_STAGE(bufoff, gbase, voff) do { _Pragma("unroll") for (int _i = 0; _i < 2; ++_i) \
;         __builtin_amdgcn_global_load_lds((const unsigned*)((const char*)(gbase) + (voff)[_i]), (LAS unsigned*)(lds + (bufoff) + ldsw + _i * 8192), 16, 0, 0); } while (0)
; #define PG8_LDA(dst, b, h) do { _Pragma("unroll") for (int m = 0; m < 4; ++m) _Pragma("unroll") for (int k = 0; k < 2; ++k) dst[m][k] = *(const LAS bf16x8*)(lds + PG8_SA(b, h) + aoff + m * 2048 + k * 1024); } while (0)
; #define PG8_LDB(dst, b, h) do { _Pragma("unroll") for (int n = 0; n < 2; ++n) _Pragma("unroll") for (int k = 0; k < 2; ++k) dst[n][k] = *(const LAS bf16x8*)(lds + PG8_SB(b, h) + boff + n * 2048 + k * 1024); } while (0)
; #define PG8_MMA(ai, bj, At, Bt) do { __builtin_amdgcn_s_setprio(1); _Pragma("unroll") for (int m = 0; m < 4; ++m) _Pragma("unroll") for (int n = 0; n < 2; ++n) _Pragma("unroll") for (int k = 0; k < 2; ++k) \
;         acc[ai][bj][m][n] = __builtin_amdgcn_mfma_f32_16x16x32_bf16(Bt[n][k], At[m][k], acc[ai][bj][m][n], 0, 0, 0); __builtin_amdgcn_s_setprio(0); } while (0)
; #define PG8_WAIT_V(n) asm volatile("s_waitcnt vmcnt(" #n ")" ::: "memory")
; #define PG8_WAIT_L(n) asm volatile("s_waitcnt lgkmcnt(" #n ")" ::: "memory")
; template <class Epi>
; __device__ __forceinline__ void gemm_phase(LAS unsigned char* lds, const Gemm g, const StaticOrder& S, const Epi& E) {
;     ...
;         const bool has_next = S.next(ui + 1, nxt);
;         const char* nA = has_next ? (const char*)g.A + (size_t)nxt.pm * tstepA : cA; const char* nB = has_next ? (const char*)g.Bt + (size_t)nxt.pn * tstepB : cB;
; #pragma unroll 1
;         for (int t = 0; t < nt; t += 2) {
;             const bool last = (t == nt - 2);
;             const char* a1 = cA + (size_t)(t + 1) * kstep;
;             const char* a2 = last ? nA : cA + (size_t)(t + 2) * kstep; const char* b2 = last ? nB : cB + (size_t)(t + 2) * kstep;
;             const char* a3 = a2 + kstep; const char* b3 = b2 + kstep;
;             PG8_LDB(B0, 0, 0); PG8_LDB(B1, 0, 1); PG8_SCHED; PG8_LDA(At, 0, 0); PG8_STAGE(PG8_SA(1, 1), a1 + hstepA, voffA);
;             PG8_WAIT_V(8); PG8_WAIT_L(0); PG8_BAR; PG8_MMA(0, 0, At, B0); PG8_MMA(0, 1, At, B1); PG8_BAR; PG8_SCHED;
;             PG8_LDA(At, 0, 1); PG8_STAGE(PG8_SB(0, 0), b2, voffB); PG8_STAGE(PG8_SB(0, 1), b2 + hstepB, voffB); PG8_STAGE(PG8_SA(0, 0), a2, voffA);
.LBB0_710:
	s_add_u32 s52, s42, s22
	s_addc_u32 s53, s43, 0
	s_add_u32 s23, s52, 0x100
	s_addc_u32 s50, s53, 0
	s_and_b64 s[48:49], s[46:47], exec
	s_cselect_b32 s49, s35, s50
	s_cselect_b32 s48, s34, s23
	s_add_u32 s22, s40, s22
	s_addc_u32 s23, s41, 0
	s_add_u32 s50, s22, 0x100
	s_addc_u32 s51, s23, 0
	s_add_i32 s80, 0, 0x10000
	s_and_b64 s[22:23], s[46:47], exec
	s_cselect_b32 s51, s15, s51
	s_cselect_b32 s50, s71, s50
	s_add_i32 s47, 0, 0x14000
	s_add_u32 s54, s52, 0xea080
	s_addc_u32 s55, s53, 0
	s_add_i32 s79, s80, s60
	s_add_i32 m0, s61, 0xc000
	s_add_i32 s82, s61, 0xe000
	s_add_i32 s76, s79, 0x2000
	v_add_u32_e32 v146, s80, v148
	s_add_u32 s52, s50, 0x4000
	ds_read_b128 v[138:141], v146
	ds_read_b128 v[142:145], v146 offset:1024
	ds_read_b128 v[152:155], v146 offset:2048
	ds_read_b128 v[156:159], v146 offset:3072
	v_add_u32_e32 v146, s47, v148
	s_addc_u32 s53, s51, 0
	s_add_i32 s78, s47, s60
	ds_read_b128 v[160:163], v146
	ds_read_b128 v[164:167], v146 offset:1024
	ds_read_b128 v[168:171], v146 offset:2048
	ds_read_b128 v[172:175], v146 offset:3072
	s_add_i32 s77, s78, 0x2000
	s_add_i32 s75, 0, 0x18000
	s_add_i32 s74, 0, 0x1c000
	s_add_u32 s22, s48, 0xea000
	s_addc_u32 s23, s49, 0
	s_add_i32 s73, s75, s60
	s_add_i32 s72, s73, 0x2000
	s_add_u32 s46, s50, 0x4080
	s_addc_u32 s47, s51, 0
	s_add_i32 s81, s74, s60
	s_add_i32 s80, s81, 0x2000
	v_lshl_add_u64 v[146:147], s[54:55], 0, v[136:137]
	ds_read_b128 v[176:179], v150
	ds_read_b128 v[180:183], v150 offset:1024
	ds_read_b128 v[184:187], v150 offset:2048
	ds_read_b128 v[188:191], v150 offset:3072
	ds_read_b128 v[192:195], v150 offset:4096
	ds_read_b128 v[210:213], v150 offset:5120
	ds_read_b128 v[214:217], v150 offset:6144
	ds_read_b128 v[218:221], v150 offset:7168
	global_load_lds_dwordx4 v[146:147], off
	v_lshl_add_u64 v[146:147], s[54:55], 0, v[132:133]
	s_mov_b32 m0, s82
	s_nop 0
	global_load_lds_dwordx4 v[146:147], off
	s_waitcnt vmcnt(8)
	s_waitcnt lgkmcnt(0)
	s_barrier
	s_setprio 1
	v_mfma_f32_16x16x32_bf16 v[128:131], v[138:141], v[176:179], v[128:131]
	v_mfma_f32_16x16x32_bf16 v[124:127], v[152:155], v[176:179], v[124:127]
	v_mfma_f32_16x16x32_bf16 v[112:115], v[138:141], v[184:187], v[112:115]
	v_mfma_f32_16x16x32_bf16 v[108:111], v[152:155], v[184:187], v[108:111]
	v_mfma_f32_16x16x32_bf16 v[96:99], v[138:141], v[192:195], v[96:99]
	v_mfma_f32_16x16x32_bf16 v[92:95], v[152:155], v[192:195], v[92:95]
	v_mfma_f32_16x16x32_bf16 v[80:83], v[138:141], v[214:217], v[80:83]
	v_mfma_f32_16x16x32_bf16 v[76:79], v[152:155], v[214:217], v[76:79]
	v_mfma_f32_16x16x32_bf16 v[128:131], v[142:145], v[180:183], v[128:131]
	v_mfma_f32_16x16x32_bf16 v[124:127], v[156:159], v[180:183], v[124:127]
	v_mfma_f32_16x16x32_bf16 v[112:115], v[142:145], v[188:191], v[112:115]
	v_mfma_f32_16x16x32_bf16 v[108:111], v[156:159], v[188:191], v[108:111]
	v_mfma_f32_16x16x32_bf16 v[96:99], v[142:145], v[210:213], v[96:99]
	v_mfma_f32_16x16x32_bf16 v[92:95], v[156:159], v[210:213], v[92:95]
	v_mfma_f32_16x16x32_bf16 v[80:83], v[142:145], v[218:221], v[80:83]
	v_mfma_f32_16x16x32_bf16 v[76:79], v[156:159], v[218:221], v[76:79]
	s_setprio 0
	s_setprio 1
	v_mfma_f32_16x16x32_bf16 v[120:123], v[160:163], v[176:179], v[120:123]
	v_mfma_f32_16x16x32_bf16 v[116:119], v[168:171], v[176:179], v[116:119]
	v_mfma_f32_16x16x32_bf16 v[104:107], v[160:163], v[184:187], v[104:107]
	v_mfma_f32_16x16x32_bf16 v[100:103], v[168:171], v[184:187], v[100:103]
	v_mfma_f32_16x16x32_bf16 v[88:91], v[160:163], v[192:195], v[88:91]
	v_mfma_f32_16x16x32_bf16 v[84:87], v[168:171], v[192:195], v[84:87]
	v_mfma_f32_16x16x32_bf16 v[72:75], v[160:163], v[214:217], v[72:75]
	v_mfma_f32_16x16x32_bf16 v[68:71], v[168:171], v[214:217], v[68:71]
	v_mfma_f32_16x16x32_bf16 v[120:123], v[164:167], v[180:183], v[120:123]
	v_mfma_f32_16x16x32_bf16 v[116:119], v[172:175], v[180:183], v[116:119]
	v_mfma_f32_16x16x32_bf16 v[104:107], v[164:167], v[188:191], v[104:107]
	v_mfma_f32_16x16x32_bf16 v[100:103], v[172:175], v[188:191], v[100:103]
	v_mfma_f32_16x16x32_bf16 v[88:91], v[164:167], v[210:213], v[88:91]
	v_mfma_f32_16x16x32_bf16 v[84:87], v[172:175], v[210:213], v[84:87]
	v_mfma_f32_16x16x32_bf16 v[72:75], v[164:167], v[218:221], v[72:75]
	v_mfma_f32_16x16x32_bf16 v[68:71], v[172:175], v[218:221], v[68:71]
	s_setprio 0
	s_barrier
	s_mov_b32 m0, s79
	v_lshl_add_u64 v[146:147], s[50:51], 0, v[134:135]
	ds_read_b128 v[176:179], v150 offset:16384
	ds_read_b128 v[180:183], v150 offset:17408
	ds_read_b128 v[184:187], v150 offset:18432
	ds_read_b128 v[188:191], v150 offset:19456
	ds_read_b128 v[192:195], v150 offset:20480
	ds_read_b128 v[210:213], v150 offset:21504
	ds_read_b128 v[214:217], v150 offset:22528
	ds_read_b128 v[218:221], v150 offset:23552
	global_load_lds_dwordx4 v[146:147], off
	v_lshl_add_u64 v[196:197], s[50:51], 0, v[0:1]
	s_mov_b32 m0, s76
	v_lshl_add_u64 v[198:199], s[52:53], 0, v[134:135]
	global_load_lds_dwordx4 v[196:197], off
	s_mov_b32 m0, s78
	v_lshl_add_u64 v[222:223], s[48:49], 0, v[132:133]
	global_load_lds_dwordx4 v[198:199], off
	v_lshl_add_u64 v[198:199], s[52:53], 0, v[0:1]
	s_mov_b32 m0, s77
	s_nop 0
	global_load_lds_dwordx4 v[198:199], off
	v_lshl_add_u64 v[198:199], s[48:49], 0, v[136:137]
	s_mov_b32 m0, s61
	s_nop 0
	global_load_lds_dwordx4 v[198:199], off
	s_mov_b32 m0, s62
	s_nop 0
	global_load_lds_dwordx4 v[222:223], off
	s_waitcnt vmcnt(8)
	s_waitcnt lgkmcnt(0)
	s_barrier
; #define PG8_STAGE(bufoff, gbase, voff) do { _Pragma("unroll") for (int _i = 0; _i < 2; ++_i) \
;         __builtin_amdgcn_global_load_lds((const unsigned*)((const char*)(gbase) + (voff)[_i]), (LAS unsigned*)(lds + (bufoff) + ldsw + _i * 8192), 16, 0, 0); } while (0)
; #define PG8_LDA(dst, b, h) do { _Pragma("unroll") for (int m = 0; m < 4; ++m) _Pragma("unroll") for (int k = 0; k < 2; ++k) dst[m][k] = *(const LAS bf16x8*)(lds + PG8_SA(b, h) + aoff + m * 2048 + k * 1024); } while (0)
; #define PG8_LDB(dst, b, h) do { _Pragma("unroll") for (int n = 0; n < 2; ++n) _Pragma("unroll") for (int k = 0; k < 2; ++k) dst[n][k] = *(const LAS bf16x8*)(lds + PG8_SB(b, h) + boff + n * 2048 + k * 1024); } while (0)
; #define PG8_MMA(ai, bj, At, Bt) do { __builtin_amdgcn_s_setprio(1); _Pragma("unroll") for (int m = 0; m < 4; ++m) _Pragma("unroll") for (int n = 0; n < 2; ++n) _Pragma("unroll") for (int k = 0; k < 2; ++k) \
;         acc[ai][bj][m][n] = __builtin_amdgcn_mfma_f32_16x16x32_bf16(Bt[n][k], At[m][k], acc[ai][bj][m][n], 0, 0, 0); __builtin_amdgcn_s_setprio(0); } while (0)
; #define PG8_WAIT_V(n) asm volatile("s_waitcnt vmcnt(" #n ")" ::: "memory")
; #define PG8_WAIT_L(n) asm volatile("s_waitcnt lgkmcnt(" #n ")" ::: "memory")
; #define PG8_BAR __builtin_amdgcn_s_barrier()
; #define PG8_SCHED __builtin_amdgcn_sched_barrier(0)
; template <class Epi>
; __device__ __forceinline__ void gemm_phase(LAS unsigned char* lds, const Gemm g, const StaticOrder& S, const Epi& E) {
;     ...
;             PG8_WAIT_V(8); PG8_WAIT_L(0); PG8_BAR; PG8_MMA(1, 0, At, B0); PG8_MMA(1, 1, At, B1); PG8_BAR; PG8_SCHED;
;             PG8_LDB(B0, 1, 0); PG8_LDB(B1, 1, 1); PG8_SCHED; PG8_LDA(At, 1, 0); PG8_STAGE(PG8_SA(0, 1), a2 + hstepA, voffA);
;             PG8_WAIT_V(8); PG8_WAIT_L(0); PG8_BAR; PG8_MMA(0, 0, At, B0); PG8_MMA(0, 1, At, B1); PG8_BAR; PG8_SCHED;
	s_setprio 1
	v_mfma_f32_16x16x32_bf16 v[64:67], v[138:141], v[176:179], v[64:67]
	v_mfma_f32_16x16x32_bf16 v[60:63], v[152:155], v[176:179], v[60:63]
	v_mfma_f32_16x16x32_bf16 v[48:51], v[138:141], v[184:187], v[48:51]
	v_mfma_f32_16x16x32_bf16 v[44:47], v[152:155], v[184:187], v[44:47]
	v_mfma_f32_16x16x32_bf16 v[32:35], v[138:141], v[192:195], v[32:35]
	v_mfma_f32_16x16x32_bf16 v[28:31], v[152:155], v[192:195], v[28:31]
	v_mfma_f32_16x16x32_bf16 v[16:19], v[138:141], v[214:217], v[16:19]
	v_mfma_f32_16x16x32_bf16 v[12:15], v[152:155], v[214:217], v[12:15]
	v_mfma_f32_16x16x32_bf16 v[64:67], v[142:145], v[180:183], v[64:67]
	v_mfma_f32_16x16x32_bf16 v[60:63], v[156:159], v[180:183], v[60:63]
	v_mfma_f32_16x16x32_bf16 v[48:51], v[142:145], v[188:191], v[48:51]
	v_mfma_f32_16x16x32_bf16 v[44:47], v[156:159], v[188:191], v[44:47]
	v_mfma_f32_16x16x32_bf16 v[32:35], v[142:145], v[210:213], v[32:35]
	v_mfma_f32_16x16x32_bf16 v[28:31], v[156:159], v[210:213], v[28:31]
	v_mfma_f32_16x16x32_bf16 v[16:19], v[142:145], v[218:221], v[16:19]
	v_mfma_f32_16x16x32_bf16 v[12:15], v[156:159], v[218:221], v[12:15]
	s_setprio 0
	s_setprio 1
	v_mfma_f32_16x16x32_bf16 v[56:59], v[160:163], v[176:179], v[56:59]
	v_mfma_f32_16x16x32_bf16 v[52:55], v[168:171], v[176:179], v[52:55]
	v_mfma_f32_16x16x32_bf16 v[40:43], v[160:163], v[184:187], v[40:43]
	v_mfma_f32_16x16x32_bf16 v[36:39], v[168:171], v[184:187], v[36:39]
	v_mfma_f32_16x16x32_bf16 v[24:27], v[160:163], v[192:195], v[24:27]
	v_mfma_f32_16x16x32_bf16 v[20:23], v[168:171], v[192:195], v[20:23]
	v_mfma_f32_16x16x32_bf16 v[8:11], v[160:163], v[214:217], v[8:11]
	v_mfma_f32_16x16x32_bf16 v[4:7], v[168:171], v[214:217], v[4:7]
	v_mfma_f32_16x16x32_bf16 v[56:59], v[164:167], v[180:183], v[56:59]
	v_mfma_f32_16x16x32_bf16 v[52:55], v[172:175], v[180:183], v[52:55]
	v_mfma_f32_16x16x32_bf16 v[40:43], v[164:167], v[188:191], v[40:43]
	v_mfma_f32_16x16x32_bf16 v[36:39], v[172:175], v[188:191], v[36:39]
	v_mfma_f32_16x16x32_bf16 v[24:27], v[164:167], v[210:213], v[24:27]
	v_mfma_f32_16x16x32_bf16 v[20:23], v[172:175], v[210:213], v[20:23]
	v_mfma_f32_16x16x32_bf16 v[8:11], v[164:167], v[218:221], v[8:11]
	v_mfma_f32_16x16x32_bf16 v[4:7], v[172:175], v[218:221], v[4:7]
	s_setprio 0
	s_barrier
	v_add_u32_e32 v151, s75, v148
	ds_read_b128 v[138:141], v151
	ds_read_b128 v[142:145], v151 offset:1024
	ds_read_b128 v[152:155], v151 offset:2048
	ds_read_b128 v[156:159], v151 offset:3072
	v_add_u32_e32 v151, s74, v148
	ds_read_b128 v[160:163], v151
	ds_read_b128 v[164:167], v151 offset:1024
	ds_read_b128 v[168:171], v151 offset:2048
	ds_read_b128 v[172:175], v151 offset:3072
	s_mov_b32 m0, s63
	v_lshl_add_u64 v[224:225], s[22:23], 0, v[136:137]
	ds_read_b128 v[176:179], v150 offset:32768
	ds_read_b128 v[180:183], v150 offset:33792
	ds_read_b128 v[184:187], v150 offset:34816
	ds_read_b128 v[188:191], v150 offset:35840
	ds_read_b128 v[192:195], v150 offset:36864
	ds_read_b128 v[210:213], v150 offset:37888
	ds_read_b128 v[214:217], v150 offset:38912
	ds_read_b128 v[218:221], v150 offset:39936
	global_load_lds_dwordx4 v[224:225], off
	v_lshl_add_u64 v[224:225], s[22:23], 0, v[132:133]
	s_mov_b32 m0, s64
	s_nop 0
	global_load_lds_dwordx4 v[224:225], off
	s_waitcnt vmcnt(8)
	s_waitcnt lgkmcnt(0)
	s_barrier
	s_setprio 1
	v_mfma_f32_16x16x32_bf16 v[128:131], v[138:141], v[176:179], v[128:131]
	v_mfma_f32_16x16x32_bf16 v[124:127], v[152:155], v[176:179], v[124:127]
	v_mfma_f32_16x16x32_bf16 v[112:115], v[138:141], v[184:187], v[112:115]
	v_mfma_f32_16x16x32_bf16 v[108:111], v[152:155], v[184:187], v[108:111]
	v_mfma_f32_16x16x32_bf16 v[96:99], v[138:141], v[192:195], v[96:99]
	v_mfma_f32_16x16x32_bf16 v[92:95], v[152:155], v[192:195], v[92:95]
	v_mfma_f32_16x16x32_bf16 v[80:83], v[138:141], v[214:217], v[80:83]
	v_mfma_f32_16x16x32_bf16 v[76:79], v[152:155], v[214:217], v[76:79]
	v_mfma_f32_16x16x32_bf16 v[128:131], v[142:145], v[180:183], v[128:131]
	v_mfma_f32_16x16x32_bf16 v[124:127], v[156:159], v[180:183], v[124:127]
	v_mfma_f32_16x16x32_bf16 v[112:115], v[142:145], v[188:191], v[112:115]
	v_mfma_f32_16x16x32_bf16 v[108:111], v[156:159], v[188:191], v[108:111]
	v_mfma_f32_16x16x32_bf16 v[96:99], v[142:145], v[210:213], v[96:99]
	v_mfma_f32_16x16x32_bf16 v[92:95], v[156:159], v[210:213], v[92:95]
	v_mfma_f32_16x16x32_bf16 v[80:83], v[142:145], v[218:221], v[80:83]
	v_mfma_f32_16x16x32_bf16 v[76:79], v[156:159], v[218:221], v[76:79]
	s_setprio 0
	s_setprio 1
	v_mfma_f32_16x16x32_bf16 v[120:123], v[160:163], v[176:179], v[120:123]
	v_mfma_f32_16x16x32_bf16 v[116:119], v[168:171], v[176:179], v[116:119]
	v_mfma_f32_16x16x32_bf16 v[104:107], v[160:163], v[184:187], v[104:107]
	v_mfma_f32_16x16x32_bf16 v[100:103], v[168:171], v[184:187], v[100:103]
	v_mfma_f32_16x16x32_bf16 v[88:91], v[160:163], v[192:195], v[88:91]
	v_mfma_f32_16x16x32_bf16 v[84:87], v[168:171], v[192:195], v[84:87]
	v_mfma_f32_16x16x32_bf16 v[72:75], v[160:163], v[214:217], v[72:75]
	v_mfma_f32_16x16x32_bf16 v[68:71], v[168:171], v[214:217], v[68:71]
	v_mfma_f32_16x16x32_bf16 v[120:123], v[164:167], v[180:183], v[120:123]
	v_mfma_f32_16x16x32_bf16 v[116:119], v[172:175], v[180:183], v[116:119]
	v_mfma_f32_16x16x32_bf16 v[104:107], v[164:167], v[188:191], v[104:107]
	v_mfma_f32_16x16x32_bf16 v[100:103], v[172:175], v[188:191], v[100:103]
	v_mfma_f32_16x16x32_bf16 v[88:91], v[164:167], v[210:213], v[88:91]
	v_mfma_f32_16x16x32_bf16 v[84:87], v[172:175], v[210:213], v[84:87]
	v_mfma_f32_16x16x32_bf16 v[72:75], v[164:167], v[218:221], v[72:75]
	v_mfma_f32_16x16x32_bf16 v[68:71], v[172:175], v[218:221], v[68:71]
	s_setprio 0
	s_barrier
; #define PG8_STAGE(bufoff, gbase, voff) do { _Pragma("unroll") for (int _i = 0; _i < 2; ++_i) \
;         __builtin_amdgcn_global_load_lds((const unsigned*)((const char*)(gbase) + (voff)[_i]), (LAS unsigned*)(lds + (bufoff) + ldsw + _i * 8192), 16, 0, 0); } while (0)
; #define PG8_LDA(dst, b, h) do { _Pragma("unroll") for (int m = 0; m < 4; ++m) _Pragma("unroll") for (int k = 0; k < 2; ++k) dst[m][k] = *(const LAS bf16x8*)(lds + PG8_SA(b, h) + aoff + m * 2048 + k * 1024); } while (0)
; #define PG8_MMA(ai, bj, At, Bt) do { __builtin_amdgcn_s_setprio(1); _Pragma("unroll") for (int m = 0; m < 4; ++m) _Pragma("unroll") for (int n = 0; n < 2; ++n) _Pragma("unroll") for (int k = 0; k < 2; ++k) \
;         acc[ai][bj][m][n] = __builtin_amdgcn_mfma_f32_16x16x32_bf16(Bt[n][k], At[m][k], acc[ai][bj][m][n], 0, 0, 0); __builtin_amdgcn_s_setprio(0); } while (0)
; #define PG8_WAIT_V(n) asm volatile("s_waitcnt vmcnt(" #n ")" ::: "memory")
; #define PG8_WAIT_L(n) asm volatile("s_waitcnt lgkmcnt(" #n ")" ::: "memory")
; #define PG8_BAR __builtin_amdgcn_s_barrier()
; #define PG8_SCHED __builtin_amdgcn_sched_barrier(0)
; template <class Epi>
; __device__ __forceinline__ void gemm_phase(LAS unsigned char* lds, const Gemm g, const StaticOrder& S, const Epi& E) {
;     ...
;             PG8_LDA(At, 1, 1); PG8_STAGE(PG8_SB(1, 0), b3, voffB); PG8_STAGE(PG8_SB(1, 1), b3 + hstepB, voffB); PG8_STAGE(PG8_SA(1, 0), a3, voffA);
;             PG8_WAIT_V(8); PG8_WAIT_L(0); PG8_BAR; PG8_MMA(1, 0, At, B0); PG8_MMA(1, 1, At, B1); PG8_BAR; PG8_SCHED;
;         }
;         if (wr == 0) PG8_BAR;
	s_mov_b32 m0, s73
	v_lshl_add_u64 v[146:147], v[146:147], 0, s[30:31]
	ds_read_b128 v[176:179], v150 offset:49152
	ds_read_b128 v[180:183], v150 offset:50176
	ds_read_b128 v[184:187], v150 offset:51200
	ds_read_b128 v[188:191], v150 offset:52224
	ds_read_b128 v[192:195], v150 offset:53248
	ds_read_b128 v[210:213], v150 offset:54272
	ds_read_b128 v[214:217], v150 offset:55296
	ds_read_b128 v[218:221], v150 offset:56320
	global_load_lds_dwordx4 v[146:147], off
	v_lshl_add_u64 v[146:147], v[196:197], 0, s[30:31]
	s_mov_b32 m0, s72
	s_nop 0
	global_load_lds_dwordx4 v[146:147], off
	v_lshl_add_u64 v[146:147], s[46:47], 0, v[134:135]
	s_mov_b32 m0, s81
	s_nop 0
	global_load_lds_dwordx4 v[146:147], off
	v_lshl_add_u64 v[146:147], s[46:47], 0, v[0:1]
	s_mov_b32 m0, s80
	s_nop 0
	global_load_lds_dwordx4 v[146:147], off
	v_lshl_add_u64 v[146:147], v[198:199], 0, s[30:31]
	s_mov_b32 m0, s65
	s_nop 0
	global_load_lds_dwordx4 v[146:147], off
	v_lshl_add_u64 v[146:147], v[222:223], 0, s[30:31]
	s_mov_b32 m0, s66
	s_nop 0
	global_load_lds_dwordx4 v[146:147], off
	s_waitcnt vmcnt(8)
	s_waitcnt lgkmcnt(0)
	s_barrier
	s_setprio 1
	v_mfma_f32_16x16x32_bf16 v[64:67], v[138:141], v[176:179], v[64:67]
	v_mfma_f32_16x16x32_bf16 v[60:63], v[152:155], v[176:179], v[60:63]
	v_mfma_f32_16x16x32_bf16 v[48:51], v[138:141], v[184:187], v[48:51]
	v_mfma_f32_16x16x32_bf16 v[44:47], v[152:155], v[184:187], v[44:47]
	v_mfma_f32_16x16x32_bf16 v[32:35], v[138:141], v[192:195], v[32:35]
	v_mfma_f32_16x16x32_bf16 v[28:31], v[152:155], v[192:195], v[28:31]
	v_mfma_f32_16x16x32_bf16 v[16:19], v[138:141], v[214:217], v[16:19]
	v_mfma_f32_16x16x32_bf16 v[12:15], v[152:155], v[214:217], v[12:15]
	v_mfma_f32_16x16x32_bf16 v[64:67], v[142:145], v[180:183], v[64:67]
	v_mfma_f32_16x16x32_bf16 v[60:63], v[156:159], v[180:183], v[60:63]
	v_mfma_f32_16x16x32_bf16 v[48:51], v[142:145], v[188:191], v[48:51]
	v_mfma_f32_16x16x32_bf16 v[44:47], v[156:159], v[188:191], v[44:47]
	v_mfma_f32_16x16x32_bf16 v[32:35], v[142:145], v[210:213], v[32:35]
	v_mfma_f32_16x16x32_bf16 v[28:31], v[156:159], v[210:213], v[28:31]
	v_mfma_f32_16x16x32_bf16 v[16:19], v[142:145], v[218:221], v[16:19]
	v_mfma_f32_16x16x32_bf16 v[12:15], v[156:159], v[218:221], v[12:15]
	s_setprio 0
	s_setprio 1
	v_mfma_f32_16x16x32_bf16 v[56:59], v[160:163], v[176:179], v[56:59]
	v_mfma_f32_16x16x32_bf16 v[52:55], v[168:171], v[176:179], v[52:55]
	v_mfma_f32_16x16x32_bf16 v[40:43], v[160:163], v[184:187], v[40:43]
	v_mfma_f32_16x16x32_bf16 v[36:39], v[168:171], v[184:187], v[36:39]
	v_mfma_f32_16x16x32_bf16 v[24:27], v[160:163], v[192:195], v[24:27]
	v_mfma_f32_16x16x32_bf16 v[20:23], v[168:171], v[192:195], v[20:23]
	v_mfma_f32_16x16x32_bf16 v[8:11], v[160:163], v[214:217], v[8:11]
	v_mfma_f32_16x16x32_bf16 v[4:7], v[168:171], v[214:217], v[4:7]
	v_mfma_f32_16x16x32_bf16 v[56:59], v[164:167], v[180:183], v[56:59]
	v_mfma_f32_16x16x32_bf16 v[52:55], v[172:175], v[180:183], v[52:55]
	v_mfma_f32_16x16x32_bf16 v[40:43], v[164:167], v[188:191], v[40:43]
	v_mfma_f32_16x16x32_bf16 v[36:39], v[172:175], v[188:191], v[36:39]
	v_mfma_f32_16x16x32_bf16 v[24:27], v[164:167], v[210:213], v[24:27]
	v_mfma_f32_16x16x32_bf16 v[20:23], v[172:175], v[210:213], v[20:23]
	v_mfma_f32_16x16x32_bf16 v[8:11], v[164:167], v[218:221], v[8:11]
	v_mfma_f32_16x16x32_bf16 v[4:7], v[172:175], v[218:221], v[4:7]
	s_setprio 0
	s_barrier
	s_movk_i32 s22, 0x100
	s_andn2_b64 vcc, exec, s[4:5]
	s_mov_b64 s[46:47], -1
	s_mov_b64 s[4:5], 0
	s_cbranch_vccz .LBB0_710
	s_and_b64 vcc, exec, s[12:13]
	s_cbranch_vccz .LBB0_713
	s_barrier

; #define PG8_STAGE(bufoff, gbase, voff) do { _Pragma("unroll") for (int _i = 0; _i < 2; ++_i) \
;         __builtin_amdgcn_global_load_lds((const unsigned*)((const char*)(gbase) + (voff)[_i]), (LAS unsigned*)(lds + (bufoff) + ldsw + _i * 8192), 16, 0, 0); } while (0)
; #define PG8_LDA(dst, b, h) do { _Pragma("unroll") for (int m = 0; m < 4; ++m) _Pragma("unroll") for (int k = 0; k < 2; ++k) dst[m][k] = *(const LAS bf16x8*)(lds + PG8_SA(b, h) + aoff + m * 2048 + k * 1024); } while (0)
; #define PG8_LDB(dst, b, h) do { _Pragma("unroll") for (int n = 0; n < 2; ++n) _Pragma("unroll") for (int k = 0; k < 2; ++k) dst[n][k] = *(const LAS bf16x8*)(lds + PG8_SB(b, h) + boff + n * 2048 + k * 1024); } while (0)
; #define PG8_MMA(ai, bj, At, Bt) do { __builtin_amdgcn_s_setprio(1); _Pragma("unroll") for (int m = 0; m < 4; ++m) _Pragma("unroll") for (int n = 0; n < 2; ++n) _Pragma("unroll") for (int k = 0; k < 2; ++k) \
;         acc[ai][bj][m][n] = __builtin_amdgcn_mfma_f32_16x16x32_bf16(Bt[n][k], At[m][k], acc[ai][bj][m][n], 0, 0, 0); __builtin_amdgcn_s_setprio(0); } while (0)
; #define PG8_WAIT_V(n) asm volatile("s_waitcnt vmcnt(" #n ")" ::: "memory")
; #define PG8_WAIT_L(n) asm volatile("s_waitcnt lgkmcnt(" #n ")" ::: "memory")
; #define PG8_BAR __builtin_amdgcn_s_barrier()
; #define PG8_SCHED __builtin_amdgcn_sched_barrier(0)
; template <class Epi>
; __device__ __forceinline__ void gemm_phase(LAS unsigned char* lds, const Gemm g, const StaticOrder& S, const Epi& E) {
;     ...
;         for (int t = 0; t < nt; t += 2) {
;             const bool last = (t == nt - 2);
;             const char* a1 = cA + (size_t)(t + 1) * kstep;
;             const char* a2 = last ? nA : cA + (size_t)(t + 2) * kstep; const char* b2 = last ? nB : cB + (size_t)(t + 2) * kstep;
;             const char* a3 = a2 + kstep; const char* b3 = b2 + kstep;
;             PG8_LDB(B0, 0, 0); PG8_LDB(B1, 0, 1); PG8_SCHED; PG8_LDA(At, 0, 0); PG8_STAGE(PG8_SA(1, 1), a1 + hstepA, voffA);
;             PG8_WAIT_V(8); PG8_WAIT_L(0); PG8_BAR; PG8_MMA(0, 0, At, B0); PG8_MMA(0, 1, At, B1); PG8_BAR; PG8_SCHED;
;             PG8_LDA(At, 0, 1); PG8_STAGE(PG8_SB(0, 0), b2, voffB); PG8_STAGE(PG8_SB(0, 1), b2 + hstepB, voffB); PG8_STAGE(PG8_SA(0, 0), a2, voffA);
.LBB0_732:
	s_add_u32 s52, s42, s22
	s_addc_u32 s53, s43, 0
	s_add_u32 s23, s52, 0x100
	s_addc_u32 s50, s53, 0
	s_and_b64 s[48:49], s[46:47], exec
	s_cselect_b32 s49, s15, s50
	s_cselect_b32 s48, s70, s23
	s_add_u32 s22, s40, s22
	s_addc_u32 s23, s41, 0
	s_add_u32 s50, s22, 0x100
	s_addc_u32 s51, s23, 0
	s_add_i32 s79, 0, 0x10000
	s_and_b64 s[22:23], s[46:47], exec
	s_cselect_b32 s51, s35, s51
	s_cselect_b32 s50, s34, s50
	s_add_i32 s47, 0, 0x14000
	s_add_u32 s54, s52, 0x10080
	s_addc_u32 s55, s53, 0
	s_add_i32 s78, s79, s60
	s_add_i32 m0, s61, 0xc000
	s_add_i32 s81, s61, 0xe000
	s_add_i32 s75, s78, 0x2000
	v_add_u32_e32 v146, s79, v148
	s_add_u32 s52, s50, 0x3a800
	ds_read_b128 v[138:141], v146
	ds_read_b128 v[142:145], v146 offset:1024
	ds_read_b128 v[152:155], v146 offset:2048
	ds_read_b128 v[156:159], v146 offset:3072
	v_add_u32_e32 v146, s47, v148
	s_addc_u32 s53, s51, 0
	s_add_i32 s77, s47, s60
	ds_read_b128 v[160:163], v146
	ds_read_b128 v[164:167], v146 offset:1024
	ds_read_b128 v[168:171], v146 offset:2048
	ds_read_b128 v[172:175], v146 offset:3072
	s_add_i32 s76, s77, 0x2000
	s_add_i32 s74, 0, 0x18000
	s_add_i32 s73, 0, 0x1c000
	s_add_u32 s22, s48, 0x10000
	s_addc_u32 s23, s49, 0
	s_add_i32 s72, s74, s60
	s_add_i32 s71, s72, 0x2000
	s_add_u32 s46, s50, 0x3a880
	s_addc_u32 s47, s51, 0
	s_add_i32 s80, s73, s60
	s_add_i32 s79, s80, 0x2000
	v_lshl_add_u64 v[146:147], s[54:55], 0, v[136:137]
	ds_read_b128 v[176:179], v150
	ds_read_b128 v[180:183], v150 offset:1024
	ds_read_b128 v[184:187], v150 offset:2048
	ds_read_b128 v[188:191], v150 offset:3072
	ds_read_b128 v[192:195], v150 offset:4096
	ds_read_b128 v[210:213], v150 offset:5120
	ds_read_b128 v[214:217], v150 offset:6144
	ds_read_b128 v[218:221], v150 offset:7168
	global_load_lds_dwordx4 v[146:147], off
	v_lshl_add_u64 v[146:147], s[54:55], 0, v[132:133]
	s_mov_b32 m0, s81
	s_nop 0
	global_load_lds_dwordx4 v[146:147], off
	s_waitcnt vmcnt(8)
	s_waitcnt lgkmcnt(0)
	s_barrier
	s_setprio 1
	v_mfma_f32_16x16x32_bf16 v[128:131], v[138:141], v[176:179], v[128:131]
	v_mfma_f32_16x16x32_bf16 v[124:127], v[152:155], v[176:179], v[124:127]
	v_mfma_f32_16x16x32_bf16 v[120:123], v[138:141], v[184:187], v[120:123]
	v_mfma_f32_16x16x32_bf16 v[116:119], v[152:155], v[184:187], v[116:119]
	v_mfma_f32_16x16x32_bf16 v[112:115], v[138:141], v[192:195], v[112:115]
	v_mfma_f32_16x16x32_bf16 v[108:111], v[152:155], v[192:195], v[108:111]
	v_mfma_f32_16x16x32_bf16 v[104:107], v[138:141], v[214:217], v[104:107]
	v_mfma_f32_16x16x32_bf16 v[100:103], v[152:155], v[214:217], v[100:103]
	v_mfma_f32_16x16x32_bf16 v[128:131], v[142:145], v[180:183], v[128:131]
	v_mfma_f32_16x16x32_bf16 v[124:127], v[156:159], v[180:183], v[124:127]
	v_mfma_f32_16x16x32_bf16 v[120:123], v[142:145], v[188:191], v[120:123]
	v_mfma_f32_16x16x32_bf16 v[116:119], v[156:159], v[188:191], v[116:119]
	v_mfma_f32_16x16x32_bf16 v[112:115], v[142:145], v[210:213], v[112:115]
	v_mfma_f32_16x16x32_bf16 v[108:111], v[156:159], v[210:213], v[108:111]
	v_mfma_f32_16x16x32_bf16 v[104:107], v[142:145], v[218:221], v[104:107]
	v_mfma_f32_16x16x32_bf16 v[100:103], v[156:159], v[218:221], v[100:103]
	s_setprio 0
	s_setprio 1
	v_mfma_f32_16x16x32_bf16 v[64:67], v[160:163], v[176:179], v[64:67]
	v_mfma_f32_16x16x32_bf16 v[60:63], v[168:171], v[176:179], v[60:63]
	v_mfma_f32_16x16x32_bf16 v[56:59], v[160:163], v[184:187], v[56:59]
	v_mfma_f32_16x16x32_bf16 v[52:55], v[168:171], v[184:187], v[52:55]
	v_mfma_f32_16x16x32_bf16 v[48:51], v[160:163], v[192:195], v[48:51]
	v_mfma_f32_16x16x32_bf16 v[44:47], v[168:171], v[192:195], v[44:47]
	v_mfma_f32_16x16x32_bf16 v[40:43], v[160:163], v[214:217], v[40:43]
	v_mfma_f32_16x16x32_bf16 v[36:39], v[168:171], v[214:217], v[36:39]
	v_mfma_f32_16x16x32_bf16 v[64:67], v[164:167], v[180:183], v[64:67]
	v_mfma_f32_16x16x32_bf16 v[60:63], v[172:175], v[180:183], v[60:63]
	v_mfma_f32_16x16x32_bf16 v[56:59], v[164:167], v[188:191], v[56:59]
	v_mfma_f32_16x16x32_bf16 v[52:55], v[172:175], v[188:191], v[52:55]
	v_mfma_f32_16x16x32_bf16 v[48:51], v[164:167], v[210:213], v[48:51]
	v_mfma_f32_16x16x32_bf16 v[44:47], v[172:175], v[210:213], v[44:47]
	v_mfma_f32_16x16x32_bf16 v[40:43], v[164:167], v[218:221], v[40:43]
	v_mfma_f32_16x16x32_bf16 v[36:39], v[172:175], v[218:221], v[36:39]
	s_setprio 0
	s_barrier
	s_mov_b32 m0, s78
	v_lshl_add_u64 v[146:147], s[50:51], 0, v[134:135]
	ds_read_b128 v[176:179], v150 offset:16384
	ds_read_b128 v[180:183], v150 offset:17408
	ds_read_b128 v[184:187], v150 offset:18432
	ds_read_b128 v[188:191], v150 offset:19456
	ds_read_b128 v[192:195], v150 offset:20480
	ds_read_b128 v[210:213], v150 offset:21504
	ds_read_b128 v[214:217], v150 offset:22528
	ds_read_b128 v[218:221], v150 offset:23552
	global_load_lds_dwordx4 v[146:147], off
	v_lshl_add_u64 v[196:197], s[50:51], 0, v[0:1]
	s_mov_b32 m0, s75
	v_lshl_add_u64 v[198:199], s[52:53], 0, v[134:135]
	global_load_lds_dwordx4 v[196:197], off
	s_mov_b32 m0, s77
	v_lshl_add_u64 v[222:223], s[48:49], 0, v[132:133]
	global_load_lds_dwordx4 v[198:199], off
	v_lshl_add_u64 v[198:199], s[52:53], 0, v[0:1]
	s_mov_b32 m0, s76
	s_nop 0
	global_load_lds_dwordx4 v[198:199], off
	v_lshl_add_u64 v[198:199], s[48:49], 0, v[136:137]
	s_mov_b32 m0, s61
	s_nop 0
	global_load_lds_dwordx4 v[198:199], off
	s_mov_b32 m0, s62
	s_nop 0
	global_load_lds_dwordx4 v[222:223], off
	s_waitcnt vmcnt(8)
	s_waitcnt lgkmcnt(0)
	s_barrier
; #define PG8_STAGE(bufoff, gbase, voff) do { _Pragma("unroll") for (int _i = 0; _i < 2; ++_i) \
;         __builtin_amdgcn_global_load_lds((const unsigned*)((const char*)(gbase) + (voff)[_i]), (LAS unsigned*)(lds + (bufoff) + ldsw + _i * 8192), 16, 0, 0); } while (0)
; #define PG8_LDA(dst, b, h) do { _Pragma("unroll") for (int m = 0; m < 4; ++m) _Pragma("unroll") for (int k = 0; k < 2; ++k) dst[m][k] = *(const LAS bf16x8*)(lds + PG8_SA(b, h) + aoff + m * 2048 + k * 1024); } while (0)
; #define PG8_LDB(dst, b, h) do { _Pragma("unroll") for (int n = 0; n < 2; ++n) _Pragma("unroll") for (int k = 0; k < 2; ++k) dst[n][k] = *(const LAS bf16x8*)(lds + PG8_SB(b, h) + boff + n * 2048 + k * 1024); } while (0)
; #define PG8_MMA(ai, bj, At, Bt) do { __builtin_amdgcn_s_setprio(1); _Pragma("unroll") for (int m = 0; m < 4; ++m) _Pragma("unroll") for (int n = 0; n < 2; ++n) _Pragma("unroll") for (int k = 0; k < 2; ++k) \
;         acc[ai][bj][m][n] = __builtin_amdgcn_mfma_f32_16x16x32_bf16(Bt[n][k], At[m][k], acc[ai][bj][m][n], 0, 0, 0); __builtin_amdgcn_s_setprio(0); } while (0)
; #define PG8_WAIT_V(n) asm volatile("s_waitcnt vmcnt(" #n ")" ::: "memory")
; #define PG8_WAIT_L(n) asm volatile("s_waitcnt lgkmcnt(" #n ")" ::: "memory")
; #define PG8_BAR __builtin_amdgcn_s_barrier()
; #define PG8_SCHED __builtin_amdgcn_sched_barrier(0)
; template <class Epi>
; __device__ __forceinline__ void gemm_phase(LAS unsigned char* lds, const Gemm g, const StaticOrder& S, const Epi& E) {
;     ...
;             PG8_WAIT_V(8); PG8_WAIT_L(0); PG8_BAR; PG8_MMA(1, 0, At, B0); PG8_MMA(1, 1, At, B1); PG8_BAR; PG8_SCHED;
;             PG8_LDB(B0, 1, 0); PG8_LDB(B1, 1, 1); PG8_SCHED; PG8_LDA(At, 1, 0); PG8_STAGE(PG8_SA(0, 1), a2 + hstepA, voffA);
;             PG8_WAIT_V(8); PG8_WAIT_L(0); PG8_BAR; PG8_MMA(0, 0, At, B0); PG8_MMA(0, 1, At, B1); PG8_BAR; PG8_SCHED;
	s_setprio 1
	v_mfma_f32_16x16x32_bf16 v[96:99], v[138:141], v[176:179], v[96:99]
	v_mfma_f32_16x16x32_bf16 v[92:95], v[152:155], v[176:179], v[92:95]
	v_mfma_f32_16x16x32_bf16 v[88:91], v[138:141], v[184:187], v[88:91]
	v_mfma_f32_16x16x32_bf16 v[84:87], v[152:155], v[184:187], v[84:87]
	v_mfma_f32_16x16x32_bf16 v[80:83], v[138:141], v[192:195], v[80:83]
	v_mfma_f32_16x16x32_bf16 v[76:79], v[152:155], v[192:195], v[76:79]
	v_mfma_f32_16x16x32_bf16 v[72:75], v[138:141], v[214:217], v[72:75]
	v_mfma_f32_16x16x32_bf16 v[68:71], v[152:155], v[214:217], v[68:71]
	v_mfma_f32_16x16x32_bf16 v[96:99], v[142:145], v[180:183], v[96:99]
	v_mfma_f32_16x16x32_bf16 v[92:95], v[156:159], v[180:183], v[92:95]
	v_mfma_f32_16x16x32_bf16 v[88:91], v[142:145], v[188:191], v[88:91]
	v_mfma_f32_16x16x32_bf16 v[84:87], v[156:159], v[188:191], v[84:87]
	v_mfma_f32_16x16x32_bf16 v[80:83], v[142:145], v[210:213], v[80:83]
	v_mfma_f32_16x16x32_bf16 v[76:79], v[156:159], v[210:213], v[76:79]
	v_mfma_f32_16x16x32_bf16 v[72:75], v[142:145], v[218:221], v[72:75]
	v_mfma_f32_16x16x32_bf16 v[68:71], v[156:159], v[218:221], v[68:71]
	s_setprio 0
	s_setprio 1
	v_mfma_f32_16x16x32_bf16 v[32:35], v[160:163], v[176:179], v[32:35]
	v_mfma_f32_16x16x32_bf16 v[28:31], v[168:171], v[176:179], v[28:31]
	v_mfma_f32_16x16x32_bf16 v[24:27], v[160:163], v[184:187], v[24:27]
	v_mfma_f32_16x16x32_bf16 v[20:23], v[168:171], v[184:187], v[20:23]
	v_mfma_f32_16x16x32_bf16 v[16:19], v[160:163], v[192:195], v[16:19]
	v_mfma_f32_16x16x32_bf16 v[12:15], v[168:171], v[192:195], v[12:15]
	v_mfma_f32_16x16x32_bf16 v[8:11], v[160:163], v[214:217], v[8:11]
	v_mfma_f32_16x16x32_bf16 v[4:7], v[168:171], v[214:217], v[4:7]
	v_mfma_f32_16x16x32_bf16 v[32:35], v[164:167], v[180:183], v[32:35]
	v_mfma_f32_16x16x32_bf16 v[28:31], v[172:175], v[180:183], v[28:31]
	v_mfma_f32_16x16x32_bf16 v[24:27], v[164:167], v[188:191], v[24:27]
	v_mfma_f32_16x16x32_bf16 v[20:23], v[172:175], v[188:191], v[20:23]
	v_mfma_f32_16x16x32_bf16 v[16:19], v[164:167], v[210:213], v[16:19]
	v_mfma_f32_16x16x32_bf16 v[12:15], v[172:175], v[210:213], v[12:15]
	v_mfma_f32_16x16x32_bf16 v[8:11], v[164:167], v[218:221], v[8:11]
	v_mfma_f32_16x16x32_bf16 v[4:7], v[172:175], v[218:221], v[4:7]
	s_setprio 0
	s_barrier
	v_add_u32_e32 v151, s74, v148
	ds_read_b128 v[138:141], v151
	ds_read_b128 v[142:145], v151 offset:1024
	ds_read_b128 v[152:155], v151 offset:2048
	ds_read_b128 v[156:159], v151 offset:3072
	v_add_u32_e32 v151, s73, v148
	ds_read_b128 v[160:163], v151
	ds_read_b128 v[164:167], v151 offset:1024
	ds_read_b128 v[168:171], v151 offset:2048
	ds_read_b128 v[172:175], v151 offset:3072
	s_mov_b32 m0, s63
	v_lshl_add_u64 v[224:225], s[22:23], 0, v[136:137]
	ds_read_b128 v[176:179], v150 offset:32768
	ds_read_b128 v[180:183], v150 offset:33792
	ds_read_b128 v[184:187], v150 offset:34816
	ds_read_b128 v[188:191], v150 offset:35840
	ds_read_b128 v[192:195], v150 offset:36864
	ds_read_b128 v[210:213], v150 offset:37888
	ds_read_b128 v[214:217], v150 offset:38912
	ds_read_b128 v[218:221], v150 offset:39936
	global_load_lds_dwordx4 v[224:225], off
	v_lshl_add_u64 v[224:225], s[22:23], 0, v[132:133]
	s_mov_b32 m0, s64
	s_nop 0
	global_load_lds_dwordx4 v[224:225], off
	s_waitcnt vmcnt(8)
	s_waitcnt lgkmcnt(0)
	s_barrier
	s_setprio 1
	v_mfma_f32_16x16x32_bf16 v[128:131], v[138:141], v[176:179], v[128:131]
	v_mfma_f32_16x16x32_bf16 v[124:127], v[152:155], v[176:179], v[124:127]
	v_mfma_f32_16x16x32_bf16 v[120:123], v[138:141], v[184:187], v[120:123]
	v_mfma_f32_16x16x32_bf16 v[116:119], v[152:155], v[184:187], v[116:119]
	v_mfma_f32_16x16x32_bf16 v[112:115], v[138:141], v[192:195], v[112:115]
	v_mfma_f32_16x16x32_bf16 v[108:111], v[152:155], v[192:195], v[108:111]
	v_mfma_f32_16x16x32_bf16 v[104:107], v[138:141], v[214:217], v[104:107]
	v_mfma_f32_16x16x32_bf16 v[100:103], v[152:155], v[214:217], v[100:103]
	v_mfma_f32_16x16x32_bf16 v[128:131], v[142:145], v[180:183], v[128:131]
	v_mfma_f32_16x16x32_bf16 v[124:127], v[156:159], v[180:183], v[124:127]
	v_mfma_f32_16x16x32_bf16 v[120:123], v[142:145], v[188:191], v[120:123]
	v_mfma_f32_16x16x32_bf16 v[116:119], v[156:159], v[188:191], v[116:119]
	v_mfma_f32_16x16x32_bf16 v[112:115], v[142:145], v[210:213], v[112:115]
	v_mfma_f32_16x16x32_bf16 v[108:111], v[156:159], v[210:213], v[108:111]
	v_mfma_f32_16x16x32_bf16 v[104:107], v[142:145], v[218:221], v[104:107]
	v_mfma_f32_16x16x32_bf16 v[100:103], v[156:159], v[218:221], v[100:103]
	s_setprio 0
	s_setprio 1
	v_mfma_f32_16x16x32_bf16 v[64:67], v[160:163], v[176:179], v[64:67]
	v_mfma_f32_16x16x32_bf16 v[60:63], v[168:171], v[176:179], v[60:63]
	v_mfma_f32_16x16x32_bf16 v[56:59], v[160:163], v[184:187], v[56:59]
	v_mfma_f32_16x16x32_bf16 v[52:55], v[168:171], v[184:187], v[52:55]
	v_mfma_f32_16x16x32_bf16 v[48:51], v[160:163], v[192:195], v[48:51]
	v_mfma_f32_16x16x32_bf16 v[44:47], v[168:171], v[192:195], v[44:47]
	v_mfma_f32_16x16x32_bf16 v[40:43], v[160:163], v[214:217], v[40:43]
	v_mfma_f32_16x16x32_bf16 v[36:39], v[168:171], v[214:217], v[36:39]
	v_mfma_f32_16x16x32_bf16 v[64:67], v[164:167], v[180:183], v[64:67]
	v_mfma_f32_16x16x32_bf16 v[60:63], v[172:175], v[180:183], v[60:63]
	v_mfma_f32_16x16x32_bf16 v[56:59], v[164:167], v[188:191], v[56:59]
	v_mfma_f32_16x16x32_bf16 v[52:55], v[172:175], v[188:191], v[52:55]
	v_mfma_f32_16x16x32_bf16 v[48:51], v[164:167], v[210:213], v[48:51]
	v_mfma_f32_16x16x32_bf16 v[44:47], v[172:175], v[210:213], v[44:47]
	v_mfma_f32_16x16x32_bf16 v[40:43], v[164:167], v[218:221], v[40:43]
	v_mfma_f32_16x16x32_bf16 v[36:39], v[172:175], v[218:221], v[36:39]
	s_setprio 0
	s_barrier
; #define PG8_STAGE(bufoff, gbase, voff) do { _Pragma("unroll") for (int _i = 0; _i < 2; ++_i) \
;         __builtin_amdgcn_global_load_lds((const unsigned*)((const char*)(gbase) + (voff)[_i]), (LAS unsigned*)(lds + (bufoff) + ldsw + _i * 8192), 16, 0, 0); } while (0)
; #define PG8_LDA(dst, b, h) do { _Pragma("unroll") for (int m = 0; m < 4; ++m) _Pragma("unroll") for (int k = 0; k < 2; ++k) dst[m][k] = *(const LAS bf16x8*)(lds + PG8_SA(b, h) + aoff + m * 2048 + k * 1024); } while (0)
; #define PG8_MMA(ai, bj, At, Bt) do { __builtin_amdgcn_s_setprio(1); _Pragma("unroll") for (int m = 0; m < 4; ++m) _Pragma("unroll") for (int n = 0; n < 2; ++n) _Pragma("unroll") for (int k = 0; k < 2; ++k) \
;         acc[ai][bj][m][n] = __builtin_amdgcn_mfma_f32_16x16x32_bf16(Bt[n][k], At[m][k], acc[ai][bj][m][n], 0, 0, 0); __builtin_amdgcn_s_setprio(0); } while (0)
; #define PG8_WAIT_V(n) asm volatile("s_waitcnt vmcnt(" #n ")" ::: "memory")
; #define PG8_WAIT_L(n) asm volatile("s_waitcnt lgkmcnt(" #n ")" ::: "memory")
; #define PG8_BAR __builtin_amdgcn_s_barrier()
; #define PG8_SCHED __builtin_amdgcn_sched_barrier(0)
; template <class Epi>
; __device__ __forceinline__ void gemm_phase(LAS unsigned char* lds, const Gemm g, const StaticOrder& S, const Epi& E) {
;     ...
;             PG8_LDA(At, 1, 1); PG8_STAGE(PG8_SB(1, 0), b3, voffB); PG8_STAGE(PG8_SB(1, 1), b3 + hstepB, voffB); PG8_STAGE(PG8_SA(1, 0), a3, voffA);
;             PG8_WAIT_V(8); PG8_WAIT_L(0); PG8_BAR; PG8_MMA(1, 0, At, B0); PG8_MMA(1, 1, At, B1); PG8_BAR; PG8_SCHED;
;         }
;         if (wr == 0) PG8_BAR;
	s_mov_b32 m0, s72
	v_lshl_add_u64 v[146:147], v[146:147], 0, s[30:31]
	ds_read_b128 v[176:179], v150 offset:49152
	ds_read_b128 v[180:183], v150 offset:50176
	ds_read_b128 v[184:187], v150 offset:51200
	ds_read_b128 v[188:191], v150 offset:52224
	ds_read_b128 v[192:195], v150 offset:53248
	ds_read_b128 v[210:213], v150 offset:54272
	ds_read_b128 v[214:217], v150 offset:55296
	ds_read_b128 v[218:221], v150 offset:56320
	global_load_lds_dwordx4 v[146:147], off
	v_lshl_add_u64 v[146:147], v[196:197], 0, s[30:31]
	s_mov_b32 m0, s71
	s_nop 0
	global_load_lds_dwordx4 v[146:147], off
	v_lshl_add_u64 v[146:147], s[46:47], 0, v[134:135]
	s_mov_b32 m0, s80
	s_nop 0
	global_load_lds_dwordx4 v[146:147], off
	v_lshl_add_u64 v[146:147], s[46:47], 0, v[0:1]
	s_mov_b32 m0, s79
	s_nop 0
	global_load_lds_dwordx4 v[146:147], off
	v_lshl_add_u64 v[146:147], v[198:199], 0, s[30:31]
	s_mov_b32 m0, s28
	s_nop 0
	global_load_lds_dwordx4 v[146:147], off
	v_lshl_add_u64 v[146:147], v[222:223], 0, s[30:31]
	s_mov_b32 m0, s65
	s_nop 0
	global_load_lds_dwordx4 v[146:147], off
	s_waitcnt vmcnt(8)
	s_waitcnt lgkmcnt(0)
	s_barrier
	s_setprio 1
	v_mfma_f32_16x16x32_bf16 v[96:99], v[138:141], v[176:179], v[96:99]
	v_mfma_f32_16x16x32_bf16 v[92:95], v[152:155], v[176:179], v[92:95]
	v_mfma_f32_16x16x32_bf16 v[88:91], v[138:141], v[184:187], v[88:91]
	v_mfma_f32_16x16x32_bf16 v[84:87], v[152:155], v[184:187], v[84:87]
	v_mfma_f32_16x16x32_bf16 v[80:83], v[138:141], v[192:195], v[80:83]
	v_mfma_f32_16x16x32_bf16 v[76:79], v[152:155], v[192:195], v[76:79]
	v_mfma_f32_16x16x32_bf16 v[72:75], v[138:141], v[214:217], v[72:75]
	v_mfma_f32_16x16x32_bf16 v[68:71], v[152:155], v[214:217], v[68:71]
	v_mfma_f32_16x16x32_bf16 v[96:99], v[142:145], v[180:183], v[96:99]
	v_mfma_f32_16x16x32_bf16 v[92:95], v[156:159], v[180:183], v[92:95]
	v_mfma_f32_16x16x32_bf16 v[88:91], v[142:145], v[188:191], v[88:91]
	v_mfma_f32_16x16x32_bf16 v[84:87], v[156:159], v[188:191], v[84:87]
	v_mfma_f32_16x16x32_bf16 v[80:83], v[142:145], v[210:213], v[80:83]
	v_mfma_f32_16x16x32_bf16 v[76:79], v[156:159], v[210:213], v[76:79]
	v_mfma_f32_16x16x32_bf16 v[72:75], v[142:145], v[218:221], v[72:75]
	v_mfma_f32_16x16x32_bf16 v[68:71], v[156:159], v[218:221], v[68:71]
	s_setprio 0
	s_setprio 1
	v_mfma_f32_16x16x32_bf16 v[32:35], v[160:163], v[176:179], v[32:35]
	v_mfma_f32_16x16x32_bf16 v[28:31], v[168:171], v[176:179], v[28:31]
	v_mfma_f32_16x16x32_bf16 v[24:27], v[160:163], v[184:187], v[24:27]
	v_mfma_f32_16x16x32_bf16 v[20:23], v[168:171], v[184:187], v[20:23]
	v_mfma_f32_16x16x32_bf16 v[16:19], v[160:163], v[192:195], v[16:19]
	v_mfma_f32_16x16x32_bf16 v[12:15], v[168:171], v[192:195], v[12:15]
	v_mfma_f32_16x16x32_bf16 v[8:11], v[160:163], v[214:217], v[8:11]
	v_mfma_f32_16x16x32_bf16 v[4:7], v[168:171], v[214:217], v[4:7]
	v_mfma_f32_16x16x32_bf16 v[32:35], v[164:167], v[180:183], v[32:35]
	v_mfma_f32_16x16x32_bf16 v[28:31], v[172:175], v[180:183], v[28:31]
	v_mfma_f32_16x16x32_bf16 v[24:27], v[164:167], v[188:191], v[24:27]
	v_mfma_f32_16x16x32_bf16 v[20:23], v[172:175], v[188:191], v[20:23]
	v_mfma_f32_16x16x32_bf16 v[16:19], v[164:167], v[210:213], v[16:19]
	v_mfma_f32_16x16x32_bf16 v[12:15], v[172:175], v[210:213], v[12:15]
	v_mfma_f32_16x16x32_bf16 v[8:11], v[164:167], v[218:221], v[8:11]
	v_mfma_f32_16x16x32_bf16 v[4:7], v[172:175], v[218:221], v[4:7]
	s_setprio 0
	s_barrier
	s_movk_i32 s22, 0x100
	s_andn2_b64 vcc, exec, s[4:5]
	s_mov_b64 s[46:47], -1
	s_mov_b64 s[4:5], 0
	s_cbranch_vccz .LBB0_732
	s_and_b64 vcc, exec, s[12:13]
	s_cbranch_vccz .LBB0_735
	s_barrier

; #define PG8_STAGE(bufoff, gbase, voff) do { _Pragma("unroll") for (int _i = 0; _i < 2; ++_i) \
;         __builtin_amdgcn_global_load_lds((const unsigned*)((const char*)(gbase) + (voff)[_i]), (LAS unsigned*)(lds + (bufoff) + ldsw + _i * 8192), 16, 0, 0); } while (0)
; #define PG8_LDA(dst, b, h) do { _Pragma("unroll") for (int m = 0; m < 4; ++m) _Pragma("unroll") for (int k = 0; k < 2; ++k) dst[m][k] = *(const LAS bf16x8*)(lds + PG8_SA(b, h) + aoff + m * 2048 + k * 1024); } while (0)
; #define PG8_LDB(dst, b, h) do { _Pragma("unroll") for (int n = 0; n < 2; ++n) _Pragma("unroll") for (int k = 0; k < 2; ++k) dst[n][k] = *(const LAS bf16x8*)(lds + PG8_SB(b, h) + boff + n * 2048 + k * 1024); } while (0)
; #define PG8_MMA(ai, bj, At, Bt) do { __builtin_amdgcn_s_setprio(1); _Pragma("unroll") for (int m = 0; m < 4; ++m) _Pragma("unroll") for (int n = 0; n < 2; ++n) _Pragma("unroll") for (int k = 0; k < 2; ++k) \
;         acc[ai][bj][m][n] = __builtin_amdgcn_mfma_f32_16x16x32_bf16(Bt[n][k], At[m][k], acc[ai][bj][m][n], 0, 0, 0); __builtin_amdgcn_s_setprio(0); } while (0)
; #define PG8_WAIT_V(n) asm volatile("s_waitcnt vmcnt(" #n ")" ::: "memory")
; #define PG8_WAIT_L(n) asm volatile("s_waitcnt lgkmcnt(" #n ")" ::: "memory")
; #define PG8_BAR __builtin_amdgcn_s_barrier()
; #define PG8_SCHED __builtin_amdgcn_sched_barrier(0)
; template <class Epi>
; __device__ __forceinline__ void gemm_phase(LAS unsigned char* lds, const Gemm g, const StaticOrder& S, const Epi& E) {
;     ...
;         for (int t = 0; t < nt; t += 2) {
;             const bool last = (t == nt - 2);
;             const char* a1 = cA + (size_t)(t + 1) * kstep;
;             const char* a2 = last ? nA : cA + (size_t)(t + 2) * kstep; const char* b2 = last ? nB : cB + (size_t)(t + 2) * kstep;
;             const char* a3 = a2 + kstep; const char* b3 = b2 + kstep;
;             PG8_LDB(B0, 0, 0); PG8_LDB(B1, 0, 1); PG8_SCHED; PG8_LDA(At, 0, 0); PG8_STAGE(PG8_SA(1, 1), a1 + hstepA, voffA);
;             PG8_WAIT_V(8); PG8_WAIT_L(0); PG8_BAR; PG8_MMA(0, 0, At, B0); PG8_MMA(0, 1, At, B1); PG8_BAR; PG8_SCHED;
;             PG8_LDA(At, 0, 1); PG8_STAGE(PG8_SB(0, 0), b2, voffB); PG8_STAGE(PG8_SB(0, 1), b2 + hstepB, voffB); PG8_STAGE(PG8_SA(0, 0), a2, voffA);
.LBB0_880:
	s_add_u32 s22, s48, 0xfffc0080
	s_addc_u32 s23, s49, -1
	s_add_i32 s72, 0, 0x10000
	s_cmp_eq_u32 s71, 12
	s_cselect_b32 s51, s39, s23
	s_cselect_b32 s50, s67, s22
	v_add_u32_e32 v150, s72, v152
	s_cselect_b32 s23, s35, s70
	s_cselect_b32 s22, s68, s69
	s_add_i32 s74, 0, 0x14000
	ds_read_b128 v[142:145], v150
	ds_read_b128 v[146:149], v150 offset:1024
	ds_read_b128 v[156:159], v150 offset:2048
	ds_read_b128 v[160:163], v150 offset:3072
	v_add_u32_e32 v150, s74, v152
	ds_read_b128 v[164:167], v150
	ds_read_b128 v[168:171], v150 offset:1024
	ds_read_b128 v[172:175], v150 offset:2048
	ds_read_b128 v[176:179], v150 offset:3072
	v_lshl_add_u64 v[150:151], s[48:49], 0, v[138:139]
	s_add_i32 m0, s58, 0xc000
	ds_read_b128 v[180:183], v154
	ds_read_b128 v[184:187], v154 offset:1024
	ds_read_b128 v[188:191], v154 offset:2048
	ds_read_b128 v[192:195], v154 offset:3072
	ds_read_b128 v[210:213], v154 offset:4096
	ds_read_b128 v[214:217], v154 offset:5120
	ds_read_b128 v[218:221], v154 offset:6144
	ds_read_b128 v[222:225], v154 offset:7168
	global_load_lds_dwordx4 v[150:151], off
	v_lshl_add_u64 v[150:151], s[48:49], 0, v[140:141]
	s_add_i32 m0, s58, 0xe000
	s_nop 0
	global_load_lds_dwordx4 v[150:151], off
	s_waitcnt vmcnt(8)
	s_waitcnt lgkmcnt(0)
	s_barrier
	s_setprio 1
	v_mfma_f32_16x16x32_bf16 v[128:131], v[142:145], v[180:183], v[128:131]
	v_mfma_f32_16x16x32_bf16 v[124:127], v[156:159], v[180:183], v[124:127]
	v_mfma_f32_16x16x32_bf16 v[112:115], v[142:145], v[188:191], v[112:115]
	v_mfma_f32_16x16x32_bf16 v[108:111], v[156:159], v[188:191], v[108:111]
	v_mfma_f32_16x16x32_bf16 v[96:99], v[142:145], v[210:213], v[96:99]
	v_mfma_f32_16x16x32_bf16 v[92:95], v[156:159], v[210:213], v[92:95]
	v_mfma_f32_16x16x32_bf16 v[80:83], v[142:145], v[218:221], v[80:83]
	v_mfma_f32_16x16x32_bf16 v[76:79], v[156:159], v[218:221], v[76:79]
	v_mfma_f32_16x16x32_bf16 v[128:131], v[146:149], v[184:187], v[128:131]
	v_mfma_f32_16x16x32_bf16 v[124:127], v[160:163], v[184:187], v[124:127]
	v_mfma_f32_16x16x32_bf16 v[112:115], v[146:149], v[192:195], v[112:115]
	v_mfma_f32_16x16x32_bf16 v[108:111], v[160:163], v[192:195], v[108:111]
	v_mfma_f32_16x16x32_bf16 v[96:99], v[146:149], v[214:217], v[96:99]
	v_mfma_f32_16x16x32_bf16 v[92:95], v[160:163], v[214:217], v[92:95]
	v_mfma_f32_16x16x32_bf16 v[80:83], v[146:149], v[222:225], v[80:83]
	v_mfma_f32_16x16x32_bf16 v[76:79], v[160:163], v[222:225], v[76:79]
	s_setprio 0
	s_setprio 1
	v_mfma_f32_16x16x32_bf16 v[120:123], v[164:167], v[180:183], v[120:123]
	v_mfma_f32_16x16x32_bf16 v[116:119], v[172:175], v[180:183], v[116:119]
	v_mfma_f32_16x16x32_bf16 v[104:107], v[164:167], v[188:191], v[104:107]
	v_mfma_f32_16x16x32_bf16 v[100:103], v[172:175], v[188:191], v[100:103]
	v_mfma_f32_16x16x32_bf16 v[88:91], v[164:167], v[210:213], v[88:91]
	v_mfma_f32_16x16x32_bf16 v[84:87], v[172:175], v[210:213], v[84:87]
	v_mfma_f32_16x16x32_bf16 v[72:75], v[164:167], v[218:221], v[72:75]
	v_mfma_f32_16x16x32_bf16 v[68:71], v[172:175], v[218:221], v[68:71]
	v_mfma_f32_16x16x32_bf16 v[120:123], v[168:171], v[184:187], v[120:123]
	v_mfma_f32_16x16x32_bf16 v[116:119], v[176:179], v[184:187], v[116:119]
	v_mfma_f32_16x16x32_bf16 v[104:107], v[168:171], v[192:195], v[104:107]
	v_mfma_f32_16x16x32_bf16 v[100:103], v[176:179], v[192:195], v[100:103]
	v_mfma_f32_16x16x32_bf16 v[88:91], v[168:171], v[214:217], v[88:91]
	v_mfma_f32_16x16x32_bf16 v[84:87], v[176:179], v[214:217], v[84:87]
	v_mfma_f32_16x16x32_bf16 v[72:75], v[168:171], v[222:225], v[72:75]
	v_mfma_f32_16x16x32_bf16 v[68:71], v[176:179], v[222:225], v[68:71]
	s_setprio 0
	s_barrier
	s_add_i32 s72, s72, s57
	v_lshl_add_u64 v[150:151], s[22:23], 0, v[134:135]
	s_mov_b32 m0, s72
	ds_read_b128 v[180:183], v154 offset:16384
	ds_read_b128 v[184:187], v154 offset:17408
	ds_read_b128 v[188:191], v154 offset:18432
	ds_read_b128 v[192:195], v154 offset:19456
	ds_read_b128 v[210:213], v154 offset:20480
	ds_read_b128 v[214:217], v154 offset:21504
	ds_read_b128 v[218:221], v154 offset:22528
	ds_read_b128 v[222:225], v154 offset:23552
	global_load_lds_dwordx4 v[150:151], off
	s_add_i32 m0, s72, 0x2000
	s_add_u32 s72, s22, 0x10000
	v_lshl_add_u64 v[196:197], s[22:23], 0, v[0:1]
	s_addc_u32 s73, s23, 0
	s_add_i32 s74, s74, s57
	global_load_lds_dwordx4 v[196:197], off
	v_lshl_add_u64 v[198:199], s[72:73], 0, v[134:135]
	s_mov_b32 m0, s74
	v_lshl_add_u64 v[226:227], s[50:51], 0, v[132:133]
	global_load_lds_dwordx4 v[198:199], off
	v_lshl_add_u64 v[198:199], s[72:73], 0, v[0:1]
	s_add_i32 m0, s74, 0x2000
	s_nop 0
	global_load_lds_dwordx4 v[198:199], off
	v_lshl_add_u64 v[198:199], s[50:51], 0, v[136:137]
	s_mov_b32 m0, s58
	s_nop 0
	global_load_lds_dwordx4 v[198:199], off
	s_mov_b32 m0, s59
	s_nop 0
	global_load_lds_dwordx4 v[226:227], off
	s_waitcnt vmcnt(8)
	s_waitcnt lgkmcnt(0)
	s_barrier
; #define PG8_STAGE(bufoff, gbase, voff) do { _Pragma("unroll") for (int _i = 0; _i < 2; ++_i) \
;         __builtin_amdgcn_global_load_lds((const unsigned*)((const char*)(gbase) + (voff)[_i]), (LAS unsigned*)(lds + (bufoff) + ldsw + _i * 8192), 16, 0, 0); } while (0)
; #define PG8_LDA(dst, b, h) do { _Pragma("unroll") for (int m = 0; m < 4; ++m) _Pragma("unroll") for (int k = 0; k < 2; ++k) dst[m][k] = *(const LAS bf16x8*)(lds + PG8_SA(b, h) + aoff + m * 2048 + k * 1024); } while (0)
; #define PG8_LDB(dst, b, h) do { _Pragma("unroll") for (int n = 0; n < 2; ++n) _Pragma("unroll") for (int k = 0; k < 2; ++k) dst[n][k] = *(const LAS bf16x8*)(lds + PG8_SB(b, h) + boff + n * 2048 + k * 1024); } while (0)
; #define PG8_MMA(ai, bj, At, Bt) do { __builtin_amdgcn_s_setprio(1); _Pragma("unroll") for (int m = 0; m < 4; ++m) _Pragma("unroll") for (int n = 0; n < 2; ++n) _Pragma("unroll") for (int k = 0; k < 2; ++k) \
;         acc[ai][bj][m][n] = __builtin_amdgcn_mfma_f32_16x16x32_bf16(Bt[n][k], At[m][k], acc[ai][bj][m][n], 0, 0, 0); __builtin_amdgcn_s_setprio(0); } while (0)
; #define PG8_WAIT_V(n) asm volatile("s_waitcnt vmcnt(" #n ")" ::: "memory")
; #define PG8_WAIT_L(n) asm volatile("s_waitcnt lgkmcnt(" #n ")" ::: "memory")
; #define PG8_BAR __builtin_amdgcn_s_barrier()
; #define PG8_SCHED __builtin_amdgcn_sched_barrier(0)
; template <class Epi>
; __device__ __forceinline__ void gemm_phase(LAS unsigned char* lds, const Gemm g, const StaticOrder& S, const Epi& E) {
;     ...
;             PG8_WAIT_V(8); PG8_WAIT_L(0); PG8_BAR; PG8_MMA(1, 0, At, B0); PG8_MMA(1, 1, At, B1); PG8_BAR; PG8_SCHED;
;             PG8_LDB(B0, 1, 0); PG8_LDB(B1, 1, 1); PG8_SCHED; PG8_LDA(At, 1, 0); PG8_STAGE(PG8_SA(0, 1), a2 + hstepA, voffA);
;             PG8_WAIT_V(8); PG8_WAIT_L(0); PG8_BAR; PG8_MMA(0, 0, At, B0); PG8_MMA(0, 1, At, B1); PG8_BAR; PG8_SCHED;
	s_setprio 1
	v_mfma_f32_16x16x32_bf16 v[64:67], v[142:145], v[180:183], v[64:67]
	v_mfma_f32_16x16x32_bf16 v[60:63], v[156:159], v[180:183], v[60:63]
	v_mfma_f32_16x16x32_bf16 v[48:51], v[142:145], v[188:191], v[48:51]
	v_mfma_f32_16x16x32_bf16 v[44:47], v[156:159], v[188:191], v[44:47]
	v_mfma_f32_16x16x32_bf16 v[32:35], v[142:145], v[210:213], v[32:35]
	v_mfma_f32_16x16x32_bf16 v[28:31], v[156:159], v[210:213], v[28:31]
	v_mfma_f32_16x16x32_bf16 v[16:19], v[142:145], v[218:221], v[16:19]
	v_mfma_f32_16x16x32_bf16 v[12:15], v[156:159], v[218:221], v[12:15]
	v_mfma_f32_16x16x32_bf16 v[64:67], v[146:149], v[184:187], v[64:67]
	v_mfma_f32_16x16x32_bf16 v[60:63], v[160:163], v[184:187], v[60:63]
	v_mfma_f32_16x16x32_bf16 v[48:51], v[146:149], v[192:195], v[48:51]
	v_mfma_f32_16x16x32_bf16 v[44:47], v[160:163], v[192:195], v[44:47]
	v_mfma_f32_16x16x32_bf16 v[32:35], v[146:149], v[214:217], v[32:35]
	v_mfma_f32_16x16x32_bf16 v[28:31], v[160:163], v[214:217], v[28:31]
	v_mfma_f32_16x16x32_bf16 v[16:19], v[146:149], v[222:225], v[16:19]
	v_mfma_f32_16x16x32_bf16 v[12:15], v[160:163], v[222:225], v[12:15]
	s_setprio 0
	s_setprio 1
	v_mfma_f32_16x16x32_bf16 v[56:59], v[164:167], v[180:183], v[56:59]
	v_mfma_f32_16x16x32_bf16 v[52:55], v[172:175], v[180:183], v[52:55]
	v_mfma_f32_16x16x32_bf16 v[40:43], v[164:167], v[188:191], v[40:43]
	v_mfma_f32_16x16x32_bf16 v[36:39], v[172:175], v[188:191], v[36:39]
	v_mfma_f32_16x16x32_bf16 v[24:27], v[164:167], v[210:213], v[24:27]
	v_mfma_f32_16x16x32_bf16 v[20:23], v[172:175], v[210:213], v[20:23]
	v_mfma_f32_16x16x32_bf16 v[8:11], v[164:167], v[218:221], v[8:11]
	v_mfma_f32_16x16x32_bf16 v[4:7], v[172:175], v[218:221], v[4:7]
	v_mfma_f32_16x16x32_bf16 v[56:59], v[168:171], v[184:187], v[56:59]
	v_mfma_f32_16x16x32_bf16 v[52:55], v[176:179], v[184:187], v[52:55]
	v_mfma_f32_16x16x32_bf16 v[40:43], v[168:171], v[192:195], v[40:43]
	v_mfma_f32_16x16x32_bf16 v[36:39], v[176:179], v[192:195], v[36:39]
	v_mfma_f32_16x16x32_bf16 v[24:27], v[168:171], v[214:217], v[24:27]
	v_mfma_f32_16x16x32_bf16 v[20:23], v[176:179], v[214:217], v[20:23]
	v_mfma_f32_16x16x32_bf16 v[8:11], v[168:171], v[222:225], v[8:11]
	v_mfma_f32_16x16x32_bf16 v[4:7], v[176:179], v[222:225], v[4:7]
	s_setprio 0
	s_barrier
	s_add_i32 s72, 0, 0x18000
	v_add_u32_e32 v155, s72, v152
	s_add_i32 s73, 0, 0x1c000
	ds_read_b128 v[142:145], v155
	ds_read_b128 v[146:149], v155 offset:1024
	ds_read_b128 v[156:159], v155 offset:2048
	ds_read_b128 v[160:163], v155 offset:3072
	v_add_u32_e32 v155, s73, v152
	ds_read_b128 v[164:167], v155
	ds_read_b128 v[168:171], v155 offset:1024
	ds_read_b128 v[172:175], v155 offset:2048
	ds_read_b128 v[176:179], v155 offset:3072
	s_add_u32 s50, s50, 0x40000
	s_addc_u32 s51, s51, 0
	s_mov_b32 m0, s60
	v_lshl_add_u64 v[228:229], s[50:51], 0, v[136:137]
	ds_read_b128 v[180:183], v154 offset:32768
	ds_read_b128 v[184:187], v154 offset:33792
	ds_read_b128 v[188:191], v154 offset:34816
	ds_read_b128 v[192:195], v154 offset:35840
	ds_read_b128 v[210:213], v154 offset:36864
	ds_read_b128 v[214:217], v154 offset:37888
	ds_read_b128 v[218:221], v154 offset:38912
	ds_read_b128 v[222:225], v154 offset:39936
	global_load_lds_dwordx4 v[228:229], off
	v_lshl_add_u64 v[228:229], s[50:51], 0, v[132:133]
	s_mov_b32 m0, s61
	s_nop 0
	global_load_lds_dwordx4 v[228:229], off
	s_waitcnt vmcnt(8)
	s_waitcnt lgkmcnt(0)
	s_barrier
	s_setprio 1
	v_mfma_f32_16x16x32_bf16 v[128:131], v[142:145], v[180:183], v[128:131]
	v_mfma_f32_16x16x32_bf16 v[124:127], v[156:159], v[180:183], v[124:127]
	v_mfma_f32_16x16x32_bf16 v[112:115], v[142:145], v[188:191], v[112:115]
	v_mfma_f32_16x16x32_bf16 v[108:111], v[156:159], v[188:191], v[108:111]
	v_mfma_f32_16x16x32_bf16 v[96:99], v[142:145], v[210:213], v[96:99]
	v_mfma_f32_16x16x32_bf16 v[92:95], v[156:159], v[210:213], v[92:95]
	v_mfma_f32_16x16x32_bf16 v[80:83], v[142:145], v[218:221], v[80:83]
	v_mfma_f32_16x16x32_bf16 v[76:79], v[156:159], v[218:221], v[76:79]
	v_mfma_f32_16x16x32_bf16 v[128:131], v[146:149], v[184:187], v[128:131]
	v_mfma_f32_16x16x32_bf16 v[124:127], v[160:163], v[184:187], v[124:127]
	v_mfma_f32_16x16x32_bf16 v[112:115], v[146:149], v[192:195], v[112:115]
	v_mfma_f32_16x16x32_bf16 v[108:111], v[160:163], v[192:195], v[108:111]
	v_mfma_f32_16x16x32_bf16 v[96:99], v[146:149], v[214:217], v[96:99]
	v_mfma_f32_16x16x32_bf16 v[92:95], v[160:163], v[214:217], v[92:95]
	v_mfma_f32_16x16x32_bf16 v[80:83], v[146:149], v[222:225], v[80:83]
	v_mfma_f32_16x16x32_bf16 v[76:79], v[160:163], v[222:225], v[76:79]
	s_setprio 0
	s_setprio 1
	v_mfma_f32_16x16x32_bf16 v[120:123], v[164:167], v[180:183], v[120:123]
	v_mfma_f32_16x16x32_bf16 v[116:119], v[172:175], v[180:183], v[116:119]
	v_mfma_f32_16x16x32_bf16 v[104:107], v[164:167], v[188:191], v[104:107]
	v_mfma_f32_16x16x32_bf16 v[100:103], v[172:175], v[188:191], v[100:103]
	v_mfma_f32_16x16x32_bf16 v[88:91], v[164:167], v[210:213], v[88:91]
	v_mfma_f32_16x16x32_bf16 v[84:87], v[172:175], v[210:213], v[84:87]
	v_mfma_f32_16x16x32_bf16 v[72:75], v[164:167], v[218:221], v[72:75]
	v_mfma_f32_16x16x32_bf16 v[68:71], v[172:175], v[218:221], v[68:71]
	v_mfma_f32_16x16x32_bf16 v[120:123], v[168:171], v[184:187], v[120:123]
	v_mfma_f32_16x16x32_bf16 v[116:119], v[176:179], v[184:187], v[116:119]
	v_mfma_f32_16x16x32_bf16 v[104:107], v[168:171], v[192:195], v[104:107]
	v_mfma_f32_16x16x32_bf16 v[100:103], v[176:179], v[192:195], v[100:103]
	v_mfma_f32_16x16x32_bf16 v[88:91], v[168:171], v[214:217], v[88:91]
	v_mfma_f32_16x16x32_bf16 v[84:87], v[176:179], v[214:217], v[84:87]
	v_mfma_f32_16x16x32_bf16 v[72:75], v[168:171], v[222:225], v[72:75]
	v_mfma_f32_16x16x32_bf16 v[68:71], v[176:179], v[222:225], v[68:71]
	s_setprio 0
	s_barrier
; #define PG8_STAGE(bufoff, gbase, voff) do { _Pragma("unroll") for (int _i = 0; _i < 2; ++_i) \
;         __builtin_amdgcn_global_load_lds((const unsigned*)((const char*)(gbase) + (voff)[_i]), (LAS unsigned*)(lds + (bufoff) + ldsw + _i * 8192), 16, 0, 0); } while (0)
; #define PG8_LDA(dst, b, h) do { _Pragma("unroll") for (int m = 0; m < 4; ++m) _Pragma("unroll") for (int k = 0; k < 2; ++k) dst[m][k] = *(const LAS bf16x8*)(lds + PG8_SA(b, h) + aoff + m * 2048 + k * 1024); } while (0)
; #define PG8_MMA(ai, bj, At, Bt) do { __builtin_amdgcn_s_setprio(1); _Pragma("unroll") for (int m = 0; m < 4; ++m) _Pragma("unroll") for (int n = 0; n < 2; ++n) _Pragma("unroll") for (int k = 0; k < 2; ++k) \
;         acc[ai][bj][m][n] = __builtin_amdgcn_mfma_f32_16x16x32_bf16(Bt[n][k], At[m][k], acc[ai][bj][m][n], 0, 0, 0); __builtin_amdgcn_s_setprio(0); } while (0)
; #define PG8_WAIT_V(n) asm volatile("s_waitcnt vmcnt(" #n ")" ::: "memory")
; #define PG8_WAIT_L(n) asm volatile("s_waitcnt lgkmcnt(" #n ")" ::: "memory")
; #define PG8_BAR __builtin_amdgcn_s_barrier()
; #define PG8_SCHED __builtin_amdgcn_sched_barrier(0)
; template <class Epi>
; __device__ __forceinline__ void gemm_phase(LAS unsigned char* lds, const Gemm g, const StaticOrder& S, const Epi& E) {
;     ...
;             PG8_LDA(At, 1, 1); PG8_STAGE(PG8_SB(1, 0), b3, voffB); PG8_STAGE(PG8_SB(1, 1), b3 + hstepB, voffB); PG8_STAGE(PG8_SA(1, 0), a3, voffA);
;             PG8_WAIT_V(8); PG8_WAIT_L(0); PG8_BAR; PG8_MMA(1, 0, At, B0); PG8_MMA(1, 1, At, B1); PG8_BAR; PG8_SCHED;
;         }
;         if (wr == 0) PG8_BAR;
	s_add_i32 s50, s72, s57
	v_lshl_add_u64 v[150:151], v[150:151], 0, s[30:31]
	s_mov_b32 m0, s50
	ds_read_b128 v[180:183], v154 offset:49152
	ds_read_b128 v[184:187], v154 offset:50176
	ds_read_b128 v[188:191], v154 offset:51200
	ds_read_b128 v[192:195], v154 offset:52224
	ds_read_b128 v[210:213], v154 offset:53248
	ds_read_b128 v[214:217], v154 offset:54272
	ds_read_b128 v[218:221], v154 offset:55296
	ds_read_b128 v[222:225], v154 offset:56320
	global_load_lds_dwordx4 v[150:151], off
	s_add_i32 m0, s50, 0x2000
	s_add_u32 s22, s22, 0x10080
	v_lshl_add_u64 v[150:151], v[196:197], 0, s[30:31]
	s_addc_u32 s23, s23, 0
	s_add_i32 s50, s73, s57
	global_load_lds_dwordx4 v[150:151], off
	v_lshl_add_u64 v[150:151], s[22:23], 0, v[134:135]
	s_mov_b32 m0, s50
	s_nop 0
	global_load_lds_dwordx4 v[150:151], off
	v_lshl_add_u64 v[150:151], s[22:23], 0, v[0:1]
	s_add_i32 m0, s50, 0x2000
	s_nop 0
	global_load_lds_dwordx4 v[150:151], off
	v_lshl_add_u64 v[150:151], v[198:199], 0, s[30:31]
	s_mov_b32 m0, s62
	s_nop 0
	global_load_lds_dwordx4 v[150:151], off
	v_lshl_add_u64 v[150:151], v[226:227], 0, s[30:31]
	s_mov_b32 m0, s63
	s_nop 0
	global_load_lds_dwordx4 v[150:151], off
	s_waitcnt vmcnt(8)
	s_waitcnt lgkmcnt(0)
	s_barrier
	s_setprio 1
	v_mfma_f32_16x16x32_bf16 v[64:67], v[142:145], v[180:183], v[64:67]
	v_mfma_f32_16x16x32_bf16 v[60:63], v[156:159], v[180:183], v[60:63]
	v_mfma_f32_16x16x32_bf16 v[48:51], v[142:145], v[188:191], v[48:51]
	v_mfma_f32_16x16x32_bf16 v[44:47], v[156:159], v[188:191], v[44:47]
	v_mfma_f32_16x16x32_bf16 v[32:35], v[142:145], v[210:213], v[32:35]
	v_mfma_f32_16x16x32_bf16 v[28:31], v[156:159], v[210:213], v[28:31]
	v_mfma_f32_16x16x32_bf16 v[16:19], v[142:145], v[218:221], v[16:19]
	v_mfma_f32_16x16x32_bf16 v[12:15], v[156:159], v[218:221], v[12:15]
	v_mfma_f32_16x16x32_bf16 v[64:67], v[146:149], v[184:187], v[64:67]
	v_mfma_f32_16x16x32_bf16 v[60:63], v[160:163], v[184:187], v[60:63]
	v_mfma_f32_16x16x32_bf16 v[48:51], v[146:149], v[192:195], v[48:51]
	v_mfma_f32_16x16x32_bf16 v[44:47], v[160:163], v[192:195], v[44:47]
	v_mfma_f32_16x16x32_bf16 v[32:35], v[146:149], v[214:217], v[32:35]
	v_mfma_f32_16x16x32_bf16 v[28:31], v[160:163], v[214:217], v[28:31]
	v_mfma_f32_16x16x32_bf16 v[16:19], v[146:149], v[222:225], v[16:19]
	v_mfma_f32_16x16x32_bf16 v[12:15], v[160:163], v[222:225], v[12:15]
	s_setprio 0
	s_setprio 1
	v_mfma_f32_16x16x32_bf16 v[56:59], v[164:167], v[180:183], v[56:59]
	v_mfma_f32_16x16x32_bf16 v[52:55], v[172:175], v[180:183], v[52:55]
	v_mfma_f32_16x16x32_bf16 v[40:43], v[164:167], v[188:191], v[40:43]
	v_mfma_f32_16x16x32_bf16 v[36:39], v[172:175], v[188:191], v[36:39]
	v_mfma_f32_16x16x32_bf16 v[24:27], v[164:167], v[210:213], v[24:27]
	v_mfma_f32_16x16x32_bf16 v[20:23], v[172:175], v[210:213], v[20:23]
	v_mfma_f32_16x16x32_bf16 v[8:11], v[164:167], v[218:221], v[8:11]
	v_mfma_f32_16x16x32_bf16 v[4:7], v[172:175], v[218:221], v[4:7]
	v_mfma_f32_16x16x32_bf16 v[56:59], v[168:171], v[184:187], v[56:59]
	v_mfma_f32_16x16x32_bf16 v[52:55], v[176:179], v[184:187], v[52:55]
	v_mfma_f32_16x16x32_bf16 v[40:43], v[168:171], v[192:195], v[40:43]
	v_mfma_f32_16x16x32_bf16 v[36:39], v[176:179], v[192:195], v[36:39]
	v_mfma_f32_16x16x32_bf16 v[24:27], v[168:171], v[214:217], v[24:27]
	v_mfma_f32_16x16x32_bf16 v[20:23], v[176:179], v[214:217], v[20:23]
	v_mfma_f32_16x16x32_bf16 v[8:11], v[168:171], v[222:225], v[8:11]
	v_mfma_f32_16x16x32_bf16 v[4:7], v[176:179], v[222:225], v[4:7]
	s_setprio 0
	s_barrier
	s_add_i32 s71, s71, 2
	s_add_u32 s48, s48, 0x100
	s_addc_u32 s49, s49, 0
	s_add_u32 s69, s69, 0x100
	s_addc_u32 s70, s70, 0
	s_cmp_gt_u32 s71, 13
	s_cbranch_scc0 .LBB0_880
	s_and_b64 vcc, exec, s[14:15]
	s_cbranch_vccz .LBB0_883
	s_barrier

; #define PG8_STAGE(bufoff, gbase, voff) do { _Pragma("unroll") for (int _i = 0; _i < 2; ++_i) \
;         __builtin_amdgcn_global_load_lds((const unsigned*)((const char*)(gbase) + (voff)[_i]), (LAS unsigned*)(lds + (bufoff) + ldsw + _i * 8192), 16, 0, 0); } while (0)
; #define PG8_LDA(dst, b, h) do { _Pragma("unroll") for (int m = 0; m < 4; ++m) _Pragma("unroll") for (int k = 0; k < 2; ++k) dst[m][k] = *(const LAS bf16x8*)(lds + PG8_SA(b, h) + aoff + m * 2048 + k * 1024); } while (0)
; #define PG8_LDB(dst, b, h) do { _Pragma("unroll") for (int n = 0; n < 2; ++n) _Pragma("unroll") for (int k = 0; k < 2; ++k) dst[n][k] = *(const LAS bf16x8*)(lds + PG8_SB(b, h) + boff + n * 2048 + k * 1024); } while (0)
; #define PG8_MMA(ai, bj, At, Bt) do { __builtin_amdgcn_s_setprio(1); _Pragma("unroll") for (int m = 0; m < 4; ++m) _Pragma("unroll") for (int n = 0; n < 2; ++n) _Pragma("unroll") for (int k = 0; k < 2; ++k) \
;         acc[ai][bj][m][n] = __builtin_amdgcn_mfma_f32_16x16x32_bf16(Bt[n][k], At[m][k], acc[ai][bj][m][n], 0, 0, 0); __builtin_amdgcn_s_setprio(0); } while (0)
; #define PG8_WAIT_V(n) asm volatile("s_waitcnt vmcnt(" #n ")" ::: "memory")
; #define PG8_WAIT_L(n) asm volatile("s_waitcnt lgkmcnt(" #n ")" ::: "memory")
; #define PG8_BAR __builtin_amdgcn_s_barrier()
; #define PG8_SCHED __builtin_amdgcn_sched_barrier(0)
; template <class Epi>
; __device__ __forceinline__ void gemm_phase(LAS unsigned char* lds, const Gemm g, const StaticOrder& S, const Epi& E) {
;     ...
;         for (int t = 0; t < nt; t += 2) {
;             const bool last = (t == nt - 2);
;             const char* a1 = cA + (size_t)(t + 1) * kstep;
;             const char* a2 = last ? nA : cA + (size_t)(t + 2) * kstep; const char* b2 = last ? nB : cB + (size_t)(t + 2) * kstep;
;             const char* a3 = a2 + kstep; const char* b3 = b2 + kstep;
;             PG8_LDB(B0, 0, 0); PG8_LDB(B1, 0, 1); PG8_SCHED; PG8_LDA(At, 0, 0); PG8_STAGE(PG8_SA(1, 1), a1 + hstepA, voffA);
;             PG8_WAIT_V(8); PG8_WAIT_L(0); PG8_BAR; PG8_MMA(0, 0, At, B0); PG8_MMA(0, 1, At, B1); PG8_BAR; PG8_SCHED;
;             PG8_LDA(At, 0, 1); PG8_STAGE(PG8_SB(0, 0), b2, voffB); PG8_STAGE(PG8_SB(0, 1), b2 + hstepB, voffB); PG8_STAGE(PG8_SA(0, 0), a2, voffA);
.LBB0_902:
	s_add_u32 s22, s50, s4
	s_addc_u32 s23, s51, s5
	s_add_u32 s22, s22, 0x100
	s_addc_u32 s23, s23, 0
	s_add_u32 s73, s70, s4
	s_addc_u32 s74, s71, s5
	s_add_i32 s75, 0, 0x10000
	s_cmpk_eq_i32 s4, 0x300
	s_cselect_b32 s53, s47, s23
	s_cselect_b32 s52, s46, s22
	s_cselect_b32 s23, s41, s74
	s_cselect_b32 s22, s45, s73
	s_add_i32 s73, 0, 0x14000
	v_add_u32_e32 v148, s75, v242
	v_add_u32_e32 v164, s73, v242
	ds_read_b128 v[136:139], v148
	ds_read_b128 v[140:143], v148 offset:1024
	ds_read_b128 v[144:147], v148 offset:2048
	ds_read_b128 v[148:151], v148 offset:3072
	ds_read_b128 v[152:155], v164
	ds_read_b128 v[156:159], v164 offset:1024
	ds_read_b128 v[160:163], v164 offset:2048
	ds_read_b128 v[164:167], v164 offset:3072
	v_lshl_add_u64 v[196:197], v[134:135], 0, s[4:5]
	s_add_i32 m0, s61, 0xc000
	ds_read_b128 v[168:171], v244
	ds_read_b128 v[172:175], v244 offset:1024
	ds_read_b128 v[176:179], v244 offset:2048
	ds_read_b128 v[180:183], v244 offset:3072
	ds_read_b128 v[184:187], v244 offset:4096
	ds_read_b128 v[188:191], v244 offset:5120
	ds_read_b128 v[192:195], v244 offset:6144
	ds_read_b128 v[220:223], v244 offset:7168
	global_load_lds_dwordx4 v[196:197], off
	v_lshl_add_u64 v[196:197], v[132:133], 0, s[4:5]
	s_add_i32 m0, s61, 0xe000
	s_nop 0
	global_load_lds_dwordx4 v[196:197], off
	s_waitcnt vmcnt(8)
	s_waitcnt lgkmcnt(0)
	s_barrier
	s_setprio 1
	v_mfma_f32_16x16x32_bf16 v[128:131], v[136:139], v[168:171], v[128:131]
	v_mfma_f32_16x16x32_bf16 v[124:127], v[144:147], v[168:171], v[124:127]
	v_mfma_f32_16x16x32_bf16 v[112:115], v[136:139], v[176:179], v[112:115]
	v_mfma_f32_16x16x32_bf16 v[108:111], v[144:147], v[176:179], v[108:111]
	v_mfma_f32_16x16x32_bf16 v[96:99], v[136:139], v[184:187], v[96:99]
	v_mfma_f32_16x16x32_bf16 v[92:95], v[144:147], v[184:187], v[92:95]
	v_mfma_f32_16x16x32_bf16 v[80:83], v[136:139], v[192:195], v[80:83]
	v_mfma_f32_16x16x32_bf16 v[76:79], v[144:147], v[192:195], v[76:79]
	v_mfma_f32_16x16x32_bf16 v[128:131], v[140:143], v[172:175], v[128:131]
	v_mfma_f32_16x16x32_bf16 v[124:127], v[148:151], v[172:175], v[124:127]
	v_mfma_f32_16x16x32_bf16 v[112:115], v[140:143], v[180:183], v[112:115]
	v_mfma_f32_16x16x32_bf16 v[108:111], v[148:151], v[180:183], v[108:111]
	v_mfma_f32_16x16x32_bf16 v[96:99], v[140:143], v[188:191], v[96:99]
	v_mfma_f32_16x16x32_bf16 v[92:95], v[148:151], v[188:191], v[92:95]
	v_mfma_f32_16x16x32_bf16 v[80:83], v[140:143], v[220:223], v[80:83]
	v_mfma_f32_16x16x32_bf16 v[76:79], v[148:151], v[220:223], v[76:79]
	s_setprio 0
	s_setprio 1
	v_mfma_f32_16x16x32_bf16 v[120:123], v[152:155], v[168:171], v[120:123]
	v_mfma_f32_16x16x32_bf16 v[116:119], v[160:163], v[168:171], v[116:119]
	v_mfma_f32_16x16x32_bf16 v[104:107], v[152:155], v[176:179], v[104:107]
	v_mfma_f32_16x16x32_bf16 v[100:103], v[160:163], v[176:179], v[100:103]
	v_mfma_f32_16x16x32_bf16 v[88:91], v[152:155], v[184:187], v[88:91]
	v_mfma_f32_16x16x32_bf16 v[84:87], v[160:163], v[184:187], v[84:87]
	v_mfma_f32_16x16x32_bf16 v[72:75], v[152:155], v[192:195], v[72:75]
	v_mfma_f32_16x16x32_bf16 v[68:71], v[160:163], v[192:195], v[68:71]
	v_mfma_f32_16x16x32_bf16 v[120:123], v[156:159], v[172:175], v[120:123]
	v_mfma_f32_16x16x32_bf16 v[116:119], v[164:167], v[172:175], v[116:119]
	v_mfma_f32_16x16x32_bf16 v[104:107], v[156:159], v[180:183], v[104:107]
	v_mfma_f32_16x16x32_bf16 v[100:103], v[164:167], v[180:183], v[100:103]
	v_mfma_f32_16x16x32_bf16 v[88:91], v[156:159], v[188:191], v[88:91]
	v_mfma_f32_16x16x32_bf16 v[84:87], v[164:167], v[188:191], v[84:87]
	v_mfma_f32_16x16x32_bf16 v[72:75], v[156:159], v[220:223], v[72:75]
	v_mfma_f32_16x16x32_bf16 v[68:71], v[164:167], v[220:223], v[68:71]
	s_setprio 0
	s_barrier
	s_add_i32 s74, s75, s60
	v_lshl_add_u64 v[196:197], s[22:23], 0, v[212:213]
	s_mov_b32 m0, s74
	ds_read_b128 v[168:171], v244 offset:16384
	ds_read_b128 v[172:175], v244 offset:17408
	ds_read_b128 v[176:179], v244 offset:18432
	ds_read_b128 v[180:183], v244 offset:19456
	ds_read_b128 v[184:187], v244 offset:20480
	ds_read_b128 v[188:191], v244 offset:21504
	ds_read_b128 v[192:195], v244 offset:22528
	ds_read_b128 v[220:223], v244 offset:23552
	global_load_lds_dwordx4 v[196:197], off
	s_add_i32 m0, s74, 0x2000
	s_add_u32 s74, s22, 0x8000
	v_lshl_add_u64 v[198:199], s[22:23], 0, v[0:1]
	s_addc_u32 s75, s23, 0
	s_add_i32 s73, s73, s60
	global_load_lds_dwordx4 v[198:199], off
	v_lshl_add_u64 v[224:225], s[74:75], 0, v[212:213]
	s_mov_b32 m0, s73
	v_lshl_add_u64 v[226:227], s[52:53], 0, v[210:211]
	global_load_lds_dwordx4 v[224:225], off
	v_lshl_add_u64 v[224:225], s[74:75], 0, v[0:1]
	s_add_i32 m0, s73, 0x2000
	s_nop 0
	global_load_lds_dwordx4 v[224:225], off
	v_lshl_add_u64 v[224:225], s[52:53], 0, v[214:215]
	s_mov_b32 m0, s61
	s_nop 0
	global_load_lds_dwordx4 v[224:225], off
	s_mov_b32 m0, s62
	s_nop 0
	global_load_lds_dwordx4 v[226:227], off
	s_waitcnt vmcnt(8)
	s_waitcnt lgkmcnt(0)
	s_barrier
; #define PG8_STAGE(bufoff, gbase, voff) do { _Pragma("unroll") for (int _i = 0; _i < 2; ++_i) \
;         __builtin_amdgcn_global_load_lds((const unsigned*)((const char*)(gbase) + (voff)[_i]), (LAS unsigned*)(lds + (bufoff) + ldsw + _i * 8192), 16, 0, 0); } while (0)
; #define PG8_LDA(dst, b, h) do { _Pragma("unroll") for (int m = 0; m < 4; ++m) _Pragma("unroll") for (int k = 0; k < 2; ++k) dst[m][k] = *(const LAS bf16x8*)(lds + PG8_SA(b, h) + aoff + m * 2048 + k * 1024); } while (0)
; #define PG8_LDB(dst, b, h) do { _Pragma("unroll") for (int n = 0; n < 2; ++n) _Pragma("unroll") for (int k = 0; k < 2; ++k) dst[n][k] = *(const LAS bf16x8*)(lds + PG8_SB(b, h) + boff + n * 2048 + k * 1024); } while (0)
; #define PG8_MMA(ai, bj, At, Bt) do { __builtin_amdgcn_s_setprio(1); _Pragma("unroll") for (int m = 0; m < 4; ++m) _Pragma("unroll") for (int n = 0; n < 2; ++n) _Pragma("unroll") for (int k = 0; k < 2; ++k) \
;         acc[ai][bj][m][n] = __builtin_amdgcn_mfma_f32_16x16x32_bf16(Bt[n][k], At[m][k], acc[ai][bj][m][n], 0, 0, 0); __builtin_amdgcn_s_setprio(0); } while (0)
; #define PG8_WAIT_V(n) asm volatile("s_waitcnt vmcnt(" #n ")" ::: "memory")
; #define PG8_WAIT_L(n) asm volatile("s_waitcnt lgkmcnt(" #n ")" ::: "memory")
; #define PG8_BAR __builtin_amdgcn_s_barrier()
; #define PG8_SCHED __builtin_amdgcn_sched_barrier(0)
; template <class Epi>
; __device__ __forceinline__ void gemm_phase(LAS unsigned char* lds, const Gemm g, const StaticOrder& S, const Epi& E) {
;     ...
;             PG8_WAIT_V(8); PG8_WAIT_L(0); PG8_BAR; PG8_MMA(1, 0, At, B0); PG8_MMA(1, 1, At, B1); PG8_BAR; PG8_SCHED;
;             PG8_LDB(B0, 1, 0); PG8_LDB(B1, 1, 1); PG8_SCHED; PG8_LDA(At, 1, 0); PG8_STAGE(PG8_SA(0, 1), a2 + hstepA, voffA);
;             PG8_WAIT_V(8); PG8_WAIT_L(0); PG8_BAR; PG8_MMA(0, 0, At, B0); PG8_MMA(0, 1, At, B1); PG8_BAR; PG8_SCHED;
	s_setprio 1
	v_mfma_f32_16x16x32_bf16 v[64:67], v[136:139], v[168:171], v[64:67]
	v_mfma_f32_16x16x32_bf16 v[60:63], v[144:147], v[168:171], v[60:63]
	v_mfma_f32_16x16x32_bf16 v[48:51], v[136:139], v[176:179], v[48:51]
	v_mfma_f32_16x16x32_bf16 v[44:47], v[144:147], v[176:179], v[44:47]
	v_mfma_f32_16x16x32_bf16 v[32:35], v[136:139], v[184:187], v[32:35]
	v_mfma_f32_16x16x32_bf16 v[28:31], v[144:147], v[184:187], v[28:31]
	v_mfma_f32_16x16x32_bf16 v[16:19], v[136:139], v[192:195], v[16:19]
	v_mfma_f32_16x16x32_bf16 v[12:15], v[144:147], v[192:195], v[12:15]
	v_mfma_f32_16x16x32_bf16 v[64:67], v[140:143], v[172:175], v[64:67]
	v_mfma_f32_16x16x32_bf16 v[60:63], v[148:151], v[172:175], v[60:63]
	v_mfma_f32_16x16x32_bf16 v[48:51], v[140:143], v[180:183], v[48:51]
	v_mfma_f32_16x16x32_bf16 v[44:47], v[148:151], v[180:183], v[44:47]
	v_mfma_f32_16x16x32_bf16 v[32:35], v[140:143], v[188:191], v[32:35]
	v_mfma_f32_16x16x32_bf16 v[28:31], v[148:151], v[188:191], v[28:31]
	v_mfma_f32_16x16x32_bf16 v[16:19], v[140:143], v[220:223], v[16:19]
	v_mfma_f32_16x16x32_bf16 v[12:15], v[148:151], v[220:223], v[12:15]
	s_setprio 0
	s_setprio 1
	v_mfma_f32_16x16x32_bf16 v[56:59], v[152:155], v[168:171], v[56:59]
	v_mfma_f32_16x16x32_bf16 v[52:55], v[160:163], v[168:171], v[52:55]
	v_mfma_f32_16x16x32_bf16 v[40:43], v[152:155], v[176:179], v[40:43]
	v_mfma_f32_16x16x32_bf16 v[36:39], v[160:163], v[176:179], v[36:39]
	v_mfma_f32_16x16x32_bf16 v[24:27], v[152:155], v[184:187], v[24:27]
	v_mfma_f32_16x16x32_bf16 v[20:23], v[160:163], v[184:187], v[20:23]
	v_mfma_f32_16x16x32_bf16 v[8:11], v[152:155], v[192:195], v[8:11]
	v_mfma_f32_16x16x32_bf16 v[4:7], v[160:163], v[192:195], v[4:7]
	v_mfma_f32_16x16x32_bf16 v[56:59], v[156:159], v[172:175], v[56:59]
	v_mfma_f32_16x16x32_bf16 v[52:55], v[164:167], v[172:175], v[52:55]
	v_mfma_f32_16x16x32_bf16 v[40:43], v[156:159], v[180:183], v[40:43]
	v_mfma_f32_16x16x32_bf16 v[36:39], v[164:167], v[180:183], v[36:39]
	v_mfma_f32_16x16x32_bf16 v[24:27], v[156:159], v[188:191], v[24:27]
	v_mfma_f32_16x16x32_bf16 v[20:23], v[164:167], v[188:191], v[20:23]
	v_mfma_f32_16x16x32_bf16 v[8:11], v[156:159], v[220:223], v[8:11]
	v_mfma_f32_16x16x32_bf16 v[4:7], v[164:167], v[220:223], v[4:7]
	s_setprio 0
	s_barrier
	s_add_i32 s73, 0, 0x18000
	s_add_i32 s74, 0, 0x1c000
	v_add_u32_e32 v148, s73, v242
	v_add_u32_e32 v164, s74, v242
	ds_read_b128 v[136:139], v148
	ds_read_b128 v[140:143], v148 offset:1024
	ds_read_b128 v[144:147], v148 offset:2048
	ds_read_b128 v[148:151], v148 offset:3072
	ds_read_b128 v[152:155], v164
	ds_read_b128 v[156:159], v164 offset:1024
	ds_read_b128 v[160:163], v164 offset:2048
	ds_read_b128 v[164:167], v164 offset:3072
	s_add_u32 s52, s52, s28
	s_addc_u32 s53, s53, 0
	s_mov_b32 m0, s63
	v_lshl_add_u64 v[228:229], s[52:53], 0, v[214:215]
	ds_read_b128 v[168:171], v244 offset:32768
	ds_read_b128 v[172:175], v244 offset:33792
	ds_read_b128 v[176:179], v244 offset:34816
	ds_read_b128 v[180:183], v244 offset:35840
	ds_read_b128 v[184:187], v244 offset:36864
	ds_read_b128 v[188:191], v244 offset:37888
	ds_read_b128 v[192:195], v244 offset:38912
	ds_read_b128 v[220:223], v244 offset:39936
	global_load_lds_dwordx4 v[228:229], off
	v_lshl_add_u64 v[228:229], s[52:53], 0, v[210:211]
	s_mov_b32 m0, s64
	s_nop 0
	global_load_lds_dwordx4 v[228:229], off
	s_waitcnt vmcnt(8)
	s_waitcnt lgkmcnt(0)
	s_barrier
	s_setprio 1
	v_mfma_f32_16x16x32_bf16 v[128:131], v[136:139], v[168:171], v[128:131]
	v_mfma_f32_16x16x32_bf16 v[124:127], v[144:147], v[168:171], v[124:127]
	v_mfma_f32_16x16x32_bf16 v[112:115], v[136:139], v[176:179], v[112:115]
	v_mfma_f32_16x16x32_bf16 v[108:111], v[144:147], v[176:179], v[108:111]
	v_mfma_f32_16x16x32_bf16 v[96:99], v[136:139], v[184:187], v[96:99]
	v_mfma_f32_16x16x32_bf16 v[92:95], v[144:147], v[184:187], v[92:95]
	v_mfma_f32_16x16x32_bf16 v[80:83], v[136:139], v[192:195], v[80:83]
	v_mfma_f32_16x16x32_bf16 v[76:79], v[144:147], v[192:195], v[76:79]
	v_mfma_f32_16x16x32_bf16 v[128:131], v[140:143], v[172:175], v[128:131]
	v_mfma_f32_16x16x32_bf16 v[124:127], v[148:151], v[172:175], v[124:127]
	v_mfma_f32_16x16x32_bf16 v[112:115], v[140:143], v[180:183], v[112:115]
	v_mfma_f32_16x16x32_bf16 v[108:111], v[148:151], v[180:183], v[108:111]
	v_mfma_f32_16x16x32_bf16 v[96:99], v[140:143], v[188:191], v[96:99]
	v_mfma_f32_16x16x32_bf16 v[92:95], v[148:151], v[188:191], v[92:95]
	v_mfma_f32_16x16x32_bf16 v[80:83], v[140:143], v[220:223], v[80:83]
	v_mfma_f32_16x16x32_bf16 v[76:79], v[148:151], v[220:223], v[76:79]
	s_setprio 0
	s_setprio 1
	v_mfma_f32_16x16x32_bf16 v[120:123], v[152:155], v[168:171], v[120:123]
	v_mfma_f32_16x16x32_bf16 v[116:119], v[160:163], v[168:171], v[116:119]
	v_mfma_f32_16x16x32_bf16 v[104:107], v[152:155], v[176:179], v[104:107]
	v_mfma_f32_16x16x32_bf16 v[100:103], v[160:163], v[176:179], v[100:103]
	v_mfma_f32_16x16x32_bf16 v[88:91], v[152:155], v[184:187], v[88:91]
	v_mfma_f32_16x16x32_bf16 v[84:87], v[160:163], v[184:187], v[84:87]
	v_mfma_f32_16x16x32_bf16 v[72:75], v[152:155], v[192:195], v[72:75]
	v_mfma_f32_16x16x32_bf16 v[68:71], v[160:163], v[192:195], v[68:71]
	v_mfma_f32_16x16x32_bf16 v[120:123], v[156:159], v[172:175], v[120:123]
	v_mfma_f32_16x16x32_bf16 v[116:119], v[164:167], v[172:175], v[116:119]
	v_mfma_f32_16x16x32_bf16 v[104:107], v[156:159], v[180:183], v[104:107]
	v_mfma_f32_16x16x32_bf16 v[100:103], v[164:167], v[180:183], v[100:103]
	v_mfma_f32_16x16x32_bf16 v[88:91], v[156:159], v[188:191], v[88:91]
	v_mfma_f32_16x16x32_bf16 v[84:87], v[164:167], v[188:191], v[84:87]
	v_mfma_f32_16x16x32_bf16 v[72:75], v[156:159], v[220:223], v[72:75]
	v_mfma_f32_16x16x32_bf16 v[68:71], v[164:167], v[220:223], v[68:71]
	s_setprio 0
	s_barrier
; #define PG8_STAGE(bufoff, gbase, voff) do { _Pragma("unroll") for (int _i = 0; _i < 2; ++_i) \
;         __builtin_amdgcn_global_load_lds((const unsigned*)((const char*)(gbase) + (voff)[_i]), (LAS unsigned*)(lds + (bufoff) + ldsw + _i * 8192), 16, 0, 0); } while (0)
; #define PG8_LDA(dst, b, h) do { _Pragma("unroll") for (int m = 0; m < 4; ++m) _Pragma("unroll") for (int k = 0; k < 2; ++k) dst[m][k] = *(const LAS bf16x8*)(lds + PG8_SA(b, h) + aoff + m * 2048 + k * 1024); } while (0)
; #define PG8_MMA(ai, bj, At, Bt) do { __builtin_amdgcn_s_setprio(1); _Pragma("unroll") for (int m = 0; m < 4; ++m) _Pragma("unroll") for (int n = 0; n < 2; ++n) _Pragma("unroll") for (int k = 0; k < 2; ++k) \
;         acc[ai][bj][m][n] = __builtin_amdgcn_mfma_f32_16x16x32_bf16(Bt[n][k], At[m][k], acc[ai][bj][m][n], 0, 0, 0); __builtin_amdgcn_s_setprio(0); } while (0)
; #define PG8_WAIT_V(n) asm volatile("s_waitcnt vmcnt(" #n ")" ::: "memory")
; #define PG8_WAIT_L(n) asm volatile("s_waitcnt lgkmcnt(" #n ")" ::: "memory")
; #define PG8_BAR __builtin_amdgcn_s_barrier()
; #define PG8_SCHED __builtin_amdgcn_sched_barrier(0)
; template <class Epi>
; __device__ __forceinline__ void gemm_phase(LAS unsigned char* lds, const Gemm g, const StaticOrder& S, const Epi& E) {
;     ...
;             PG8_LDA(At, 1, 1); PG8_STAGE(PG8_SB(1, 0), b3, voffB); PG8_STAGE(PG8_SB(1, 1), b3 + hstepB, voffB); PG8_STAGE(PG8_SA(1, 0), a3, voffA);
;             PG8_WAIT_V(8); PG8_WAIT_L(0); PG8_BAR; PG8_MMA(1, 0, At, B0); PG8_MMA(1, 1, At, B1); PG8_BAR; PG8_SCHED;
;         }
;         if (wr == 0) PG8_BAR;
	s_add_i32 s52, s73, s60
	v_lshl_add_u64 v[196:197], v[196:197], 0, s[30:31]
	s_mov_b32 m0, s52
	ds_read_b128 v[168:171], v244 offset:49152
	ds_read_b128 v[172:175], v244 offset:50176
	ds_read_b128 v[176:179], v244 offset:51200
	ds_read_b128 v[180:183], v244 offset:52224
	ds_read_b128 v[184:187], v244 offset:53248
	ds_read_b128 v[188:191], v244 offset:54272
	ds_read_b128 v[192:195], v244 offset:55296
	ds_read_b128 v[220:223], v244 offset:56320
	global_load_lds_dwordx4 v[196:197], off
	s_add_i32 m0, s52, 0x2000
	s_add_u32 s22, s22, 0x8080
	v_lshl_add_u64 v[196:197], v[198:199], 0, s[30:31]
	s_addc_u32 s23, s23, 0
	s_add_i32 s52, s74, s60
	global_load_lds_dwordx4 v[196:197], off
	v_lshl_add_u64 v[196:197], s[22:23], 0, v[212:213]
	s_mov_b32 m0, s52
	s_nop 0
	global_load_lds_dwordx4 v[196:197], off
	v_lshl_add_u64 v[196:197], s[22:23], 0, v[0:1]
	s_add_i32 m0, s52, 0x2000
	s_nop 0
	global_load_lds_dwordx4 v[196:197], off
	v_lshl_add_u64 v[196:197], v[224:225], 0, s[30:31]
	s_mov_b32 m0, s65
	s_nop 0
	global_load_lds_dwordx4 v[196:197], off
	v_lshl_add_u64 v[196:197], v[226:227], 0, s[30:31]
	s_mov_b32 m0, s66
	s_nop 0
	global_load_lds_dwordx4 v[196:197], off
	s_waitcnt vmcnt(8)
	s_waitcnt lgkmcnt(0)
	s_barrier
	s_setprio 1
	v_mfma_f32_16x16x32_bf16 v[64:67], v[136:139], v[168:171], v[64:67]
	v_mfma_f32_16x16x32_bf16 v[60:63], v[144:147], v[168:171], v[60:63]
	v_mfma_f32_16x16x32_bf16 v[48:51], v[136:139], v[176:179], v[48:51]
	v_mfma_f32_16x16x32_bf16 v[44:47], v[144:147], v[176:179], v[44:47]
	v_mfma_f32_16x16x32_bf16 v[32:35], v[136:139], v[184:187], v[32:35]
	v_mfma_f32_16x16x32_bf16 v[28:31], v[144:147], v[184:187], v[28:31]
	v_mfma_f32_16x16x32_bf16 v[16:19], v[136:139], v[192:195], v[16:19]
	v_mfma_f32_16x16x32_bf16 v[12:15], v[144:147], v[192:195], v[12:15]
	v_mfma_f32_16x16x32_bf16 v[64:67], v[140:143], v[172:175], v[64:67]
	v_mfma_f32_16x16x32_bf16 v[60:63], v[148:151], v[172:175], v[60:63]
	v_mfma_f32_16x16x32_bf16 v[48:51], v[140:143], v[180:183], v[48:51]
	v_mfma_f32_16x16x32_bf16 v[44:47], v[148:151], v[180:183], v[44:47]
	v_mfma_f32_16x16x32_bf16 v[32:35], v[140:143], v[188:191], v[32:35]
	v_mfma_f32_16x16x32_bf16 v[28:31], v[148:151], v[188:191], v[28:31]
	v_mfma_f32_16x16x32_bf16 v[16:19], v[140:143], v[220:223], v[16:19]
	v_mfma_f32_16x16x32_bf16 v[12:15], v[148:151], v[220:223], v[12:15]
	s_setprio 0
	s_setprio 1
	v_mfma_f32_16x16x32_bf16 v[56:59], v[152:155], v[168:171], v[56:59]
	v_mfma_f32_16x16x32_bf16 v[52:55], v[160:163], v[168:171], v[52:55]
	v_mfma_f32_16x16x32_bf16 v[40:43], v[152:155], v[176:179], v[40:43]
	v_mfma_f32_16x16x32_bf16 v[36:39], v[160:163], v[176:179], v[36:39]
	v_mfma_f32_16x16x32_bf16 v[24:27], v[152:155], v[184:187], v[24:27]
	v_mfma_f32_16x16x32_bf16 v[20:23], v[160:163], v[184:187], v[20:23]
	v_mfma_f32_16x16x32_bf16 v[8:11], v[152:155], v[192:195], v[8:11]
	v_mfma_f32_16x16x32_bf16 v[4:7], v[160:163], v[192:195], v[4:7]
	v_mfma_f32_16x16x32_bf16 v[56:59], v[156:159], v[172:175], v[56:59]
	v_mfma_f32_16x16x32_bf16 v[52:55], v[164:167], v[172:175], v[52:55]
	v_mfma_f32_16x16x32_bf16 v[40:43], v[156:159], v[180:183], v[40:43]
	v_mfma_f32_16x16x32_bf16 v[36:39], v[164:167], v[180:183], v[36:39]
	v_mfma_f32_16x16x32_bf16 v[24:27], v[156:159], v[188:191], v[24:27]
	v_mfma_f32_16x16x32_bf16 v[20:23], v[164:167], v[188:191], v[20:23]
	v_mfma_f32_16x16x32_bf16 v[8:11], v[156:159], v[220:223], v[8:11]
	v_mfma_f32_16x16x32_bf16 v[4:7], v[164:167], v[220:223], v[4:7]
	s_setprio 0
	s_barrier
	s_add_i32 s72, s72, 2
	s_add_u32 s4, s4, 0x100
	s_addc_u32 s5, s5, 0
	s_cmp_gt_u32 s72, 5
	s_cbranch_scc0 .LBB0_902
	s_and_b64 vcc, exec, s[38:39]
	s_cbranch_vccz .LBB0_905
	s_barrier

; #define PG8_STAGE(bufoff, gbase, voff) do { _Pragma("unroll") for (int _i = 0; _i < 2; ++_i) \
;         __builtin_amdgcn_global_load_lds((const unsigned*)((const char*)(gbase) + (voff)[_i]), (LAS unsigned*)(lds + (bufoff) + ldsw + _i * 8192), 16, 0, 0); } while (0)
; #define PG8_LDA(dst, b, h) do { _Pragma("unroll") for (int m = 0; m < 4; ++m) _Pragma("unroll") for (int k = 0; k < 2; ++k) dst[m][k] = *(const LAS bf16x8*)(lds + PG8_SA(b, h) + aoff + m * 2048 + k * 1024); } while (0)
; #define PG8_LDB(dst, b, h) do { _Pragma("unroll") for (int n = 0; n < 2; ++n) _Pragma("unroll") for (int k = 0; k < 2; ++k) dst[n][k] = *(const LAS bf16x8*)(lds + PG8_SB(b, h) + boff + n * 2048 + k * 1024); } while (0)
; #define PG8_MMA(ai, bj, At, Bt) do { __builtin_amdgcn_s_setprio(1); _Pragma("unroll") for (int m = 0; m < 4; ++m) _Pragma("unroll") for (int n = 0; n < 2; ++n) _Pragma("unroll") for (int k = 0; k < 2; ++k) \
;         acc[ai][bj][m][n] = __builtin_amdgcn_mfma_f32_16x16x32_bf16(Bt[n][k], At[m][k], acc[ai][bj][m][n], 0, 0, 0); __builtin_amdgcn_s_setprio(0); } while (0)
; #define PG8_WAIT_V(n) asm volatile("s_waitcnt vmcnt(" #n ")" ::: "memory")
; #define PG8_WAIT_L(n) asm volatile("s_waitcnt lgkmcnt(" #n ")" ::: "memory")
; #define PG8_BAR __builtin_amdgcn_s_barrier()
; #define PG8_SCHED __builtin_amdgcn_sched_barrier(0)
; template <class Epi>
; __device__ __forceinline__ void gemm_phase(LAS unsigned char* lds, const Gemm g, const StaticOrder& S, const Epi& E) {
;     ...
;         for (int t = 0; t < nt; t += 2) {
;             const bool last = (t == nt - 2);
;             const char* a1 = cA + (size_t)(t + 1) * kstep;
;             const char* a2 = last ? nA : cA + (size_t)(t + 2) * kstep; const char* b2 = last ? nB : cB + (size_t)(t + 2) * kstep;
;             const char* a3 = a2 + kstep; const char* b3 = b2 + kstep;
;             PG8_LDB(B0, 0, 0); PG8_LDB(B1, 0, 1); PG8_SCHED; PG8_LDA(At, 0, 0); PG8_STAGE(PG8_SA(1, 1), a1 + hstepA, voffA);
;             PG8_WAIT_V(8); PG8_WAIT_L(0); PG8_BAR; PG8_MMA(0, 0, At, B0); PG8_MMA(0, 1, At, B1); PG8_BAR; PG8_SCHED;
;             PG8_LDA(At, 0, 1); PG8_STAGE(PG8_SB(0, 0), b2, voffB); PG8_STAGE(PG8_SB(0, 1), b2 + hstepB, voffB); PG8_STAGE(PG8_SA(0, 0), a2, voffA);
.LBB0_1005:
	s_add_u32 s22, s50, 0xfffc0080
	s_addc_u32 s23, s51, -1
	s_add_i32 s72, 0, 0x10000
	s_cmp_eq_u32 s71, 12
	s_cselect_b32 s53, s39, s23
	s_cselect_b32 s52, s67, s22
	s_cselect_b32 s23, s35, s70
	s_cselect_b32 s22, s68, s69
	s_add_i32 s74, 0, 0x14000
	v_add_u32_e32 v144, s72, v232
	v_add_u32_e32 v160, s74, v232
	ds_read_b128 v[132:135], v144
	ds_read_b128 v[136:139], v144 offset:1024
	ds_read_b128 v[140:143], v144 offset:2048
	ds_read_b128 v[144:147], v144 offset:3072
	ds_read_b128 v[148:151], v160
	ds_read_b128 v[152:155], v160 offset:1024
	ds_read_b128 v[156:159], v160 offset:2048
	ds_read_b128 v[160:163], v160 offset:3072
	v_lshl_add_u64 v[196:197], s[50:51], 0, v[194:195]
	s_add_i32 m0, s59, 0xc000
	ds_read_b128 v[164:167], v242
	ds_read_b128 v[168:171], v242 offset:1024
	ds_read_b128 v[172:175], v242 offset:2048
	ds_read_b128 v[176:179], v242 offset:3072
	ds_read_b128 v[180:183], v242 offset:4096
	ds_read_b128 v[184:187], v242 offset:5120
	ds_read_b128 v[212:215], v242 offset:6144
	ds_read_b128 v[216:219], v242 offset:7168
	global_load_lds_dwordx4 v[196:197], off
	v_lshl_add_u64 v[196:197], s[50:51], 0, v[210:211]
	s_add_i32 m0, s59, 0xe000
	s_nop 0
	global_load_lds_dwordx4 v[196:197], off
	s_waitcnt vmcnt(8)
	s_waitcnt lgkmcnt(0)
	s_barrier
	s_setprio 1
	v_mfma_f32_16x16x32_bf16 v[128:131], v[132:135], v[164:167], v[128:131]
	v_mfma_f32_16x16x32_bf16 v[124:127], v[140:143], v[164:167], v[124:127]
	v_mfma_f32_16x16x32_bf16 v[112:115], v[132:135], v[172:175], v[112:115]
	v_mfma_f32_16x16x32_bf16 v[108:111], v[140:143], v[172:175], v[108:111]
	v_mfma_f32_16x16x32_bf16 v[96:99], v[132:135], v[180:183], v[96:99]
	v_mfma_f32_16x16x32_bf16 v[92:95], v[140:143], v[180:183], v[92:95]
	v_mfma_f32_16x16x32_bf16 v[80:83], v[132:135], v[212:215], v[80:83]
	v_mfma_f32_16x16x32_bf16 v[76:79], v[140:143], v[212:215], v[76:79]
	v_mfma_f32_16x16x32_bf16 v[128:131], v[136:139], v[168:171], v[128:131]
	v_mfma_f32_16x16x32_bf16 v[124:127], v[144:147], v[168:171], v[124:127]
	v_mfma_f32_16x16x32_bf16 v[112:115], v[136:139], v[176:179], v[112:115]
	v_mfma_f32_16x16x32_bf16 v[108:111], v[144:147], v[176:179], v[108:111]
	v_mfma_f32_16x16x32_bf16 v[96:99], v[136:139], v[184:187], v[96:99]
	v_mfma_f32_16x16x32_bf16 v[92:95], v[144:147], v[184:187], v[92:95]
	v_mfma_f32_16x16x32_bf16 v[80:83], v[136:139], v[216:219], v[80:83]
	v_mfma_f32_16x16x32_bf16 v[76:79], v[144:147], v[216:219], v[76:79]
	s_setprio 0
	s_setprio 1
	v_mfma_f32_16x16x32_bf16 v[120:123], v[148:151], v[164:167], v[120:123]
	v_mfma_f32_16x16x32_bf16 v[116:119], v[156:159], v[164:167], v[116:119]
	v_mfma_f32_16x16x32_bf16 v[104:107], v[148:151], v[172:175], v[104:107]
	v_mfma_f32_16x16x32_bf16 v[100:103], v[156:159], v[172:175], v[100:103]
	v_mfma_f32_16x16x32_bf16 v[88:91], v[148:151], v[180:183], v[88:91]
	v_mfma_f32_16x16x32_bf16 v[84:87], v[156:159], v[180:183], v[84:87]
	v_mfma_f32_16x16x32_bf16 v[72:75], v[148:151], v[212:215], v[72:75]
	v_mfma_f32_16x16x32_bf16 v[68:71], v[156:159], v[212:215], v[68:71]
	v_mfma_f32_16x16x32_bf16 v[120:123], v[152:155], v[168:171], v[120:123]
	v_mfma_f32_16x16x32_bf16 v[116:119], v[160:163], v[168:171], v[116:119]
	v_mfma_f32_16x16x32_bf16 v[104:107], v[152:155], v[176:179], v[104:107]
	v_mfma_f32_16x16x32_bf16 v[100:103], v[160:163], v[176:179], v[100:103]
	v_mfma_f32_16x16x32_bf16 v[88:91], v[152:155], v[184:187], v[88:91]
	v_mfma_f32_16x16x32_bf16 v[84:87], v[160:163], v[184:187], v[84:87]
	v_mfma_f32_16x16x32_bf16 v[72:75], v[152:155], v[216:219], v[72:75]
	v_mfma_f32_16x16x32_bf16 v[68:71], v[160:163], v[216:219], v[68:71]
	s_setprio 0
	s_barrier
	s_add_i32 s72, s72, s58
	v_lshl_add_u64 v[196:197], s[22:23], 0, v[190:191]
	s_mov_b32 m0, s72
	ds_read_b128 v[164:167], v242 offset:16384
	ds_read_b128 v[168:171], v242 offset:17408
	ds_read_b128 v[172:175], v242 offset:18432
	ds_read_b128 v[176:179], v242 offset:19456
	ds_read_b128 v[180:183], v242 offset:20480
	ds_read_b128 v[184:187], v242 offset:21504
	ds_read_b128 v[212:215], v242 offset:22528
	ds_read_b128 v[216:219], v242 offset:23552
	global_load_lds_dwordx4 v[196:197], off
	s_add_i32 m0, s72, 0x2000
	s_add_u32 s72, s22, 0x10000
	v_lshl_add_u64 v[198:199], s[22:23], 0, v[0:1]
	s_addc_u32 s73, s23, 0
	s_add_i32 s74, s74, s58
	global_load_lds_dwordx4 v[198:199], off
	v_lshl_add_u64 v[220:221], s[72:73], 0, v[190:191]
	s_mov_b32 m0, s74
	v_lshl_add_u64 v[222:223], s[52:53], 0, v[188:189]
	global_load_lds_dwordx4 v[220:221], off
	v_lshl_add_u64 v[220:221], s[72:73], 0, v[0:1]
	s_add_i32 m0, s74, 0x2000
	s_nop 0
	global_load_lds_dwordx4 v[220:221], off
	v_lshl_add_u64 v[220:221], s[52:53], 0, v[192:193]
	s_mov_b32 m0, s59
	s_nop 0
	global_load_lds_dwordx4 v[220:221], off
	s_mov_b32 m0, s60
	s_nop 0
	global_load_lds_dwordx4 v[222:223], off
	s_waitcnt vmcnt(8)
	s_waitcnt lgkmcnt(0)
	s_barrier
; #define PG8_STAGE(bufoff, gbase, voff) do { _Pragma("unroll") for (int _i = 0; _i < 2; ++_i) \
;         __builtin_amdgcn_global_load_lds((const unsigned*)((const char*)(gbase) + (voff)[_i]), (LAS unsigned*)(lds + (bufoff) + ldsw + _i * 8192), 16, 0, 0); } while (0)
; #define PG8_LDA(dst, b, h) do { _Pragma("unroll") for (int m = 0; m < 4; ++m) _Pragma("unroll") for (int k = 0; k < 2; ++k) dst[m][k] = *(const LAS bf16x8*)(lds + PG8_SA(b, h) + aoff + m * 2048 + k * 1024); } while (0)
; #define PG8_LDB(dst, b, h) do { _Pragma("unroll") for (int n = 0; n < 2; ++n) _Pragma("unroll") for (int k = 0; k < 2; ++k) dst[n][k] = *(const LAS bf16x8*)(lds + PG8_SB(b, h) + boff + n * 2048 + k * 1024); } while (0)
; #define PG8_MMA(ai, bj, At, Bt) do { __builtin_amdgcn_s_setprio(1); _Pragma("unroll") for (int m = 0; m < 4; ++m) _Pragma("unroll") for (int n = 0; n < 2; ++n) _Pragma("unroll") for (int k = 0; k < 2; ++k) \
;         acc[ai][bj][m][n] = __builtin_amdgcn_mfma_f32_16x16x32_bf16(Bt[n][k], At[m][k], acc[ai][bj][m][n], 0, 0, 0); __builtin_amdgcn_s_setprio(0); } while (0)
; #define PG8_WAIT_V(n) asm volatile("s_waitcnt vmcnt(" #n ")" ::: "memory")
; #define PG8_WAIT_L(n) asm volatile("s_waitcnt lgkmcnt(" #n ")" ::: "memory")
; #define PG8_BAR __builtin_amdgcn_s_barrier()
; #define PG8_SCHED __builtin_amdgcn_sched_barrier(0)
; template <class Epi>
; __device__ __forceinline__ void gemm_phase(LAS unsigned char* lds, const Gemm g, const StaticOrder& S, const Epi& E) {
;     ...
;             PG8_WAIT_V(8); PG8_WAIT_L(0); PG8_BAR; PG8_MMA(1, 0, At, B0); PG8_MMA(1, 1, At, B1); PG8_BAR; PG8_SCHED;
;             PG8_LDB(B0, 1, 0); PG8_LDB(B1, 1, 1); PG8_SCHED; PG8_LDA(At, 1, 0); PG8_STAGE(PG8_SA(0, 1), a2 + hstepA, voffA);
;             PG8_WAIT_V(8); PG8_WAIT_L(0); PG8_BAR; PG8_MMA(0, 0, At, B0); PG8_MMA(0, 1, At, B1); PG8_BAR; PG8_SCHED;
	s_setprio 1
	v_mfma_f32_16x16x32_bf16 v[64:67], v[132:135], v[164:167], v[64:67]
	v_mfma_f32_16x16x32_bf16 v[60:63], v[140:143], v[164:167], v[60:63]
	v_mfma_f32_16x16x32_bf16 v[48:51], v[132:135], v[172:175], v[48:51]
	v_mfma_f32_16x16x32_bf16 v[44:47], v[140:143], v[172:175], v[44:47]
	v_mfma_f32_16x16x32_bf16 v[32:35], v[132:135], v[180:183], v[32:35]
	v_mfma_f32_16x16x32_bf16 v[28:31], v[140:143], v[180:183], v[28:31]
	v_mfma_f32_16x16x32_bf16 v[16:19], v[132:135], v[212:215], v[16:19]
	v_mfma_f32_16x16x32_bf16 v[12:15], v[140:143], v[212:215], v[12:15]
	v_mfma_f32_16x16x32_bf16 v[64:67], v[136:139], v[168:171], v[64:67]
	v_mfma_f32_16x16x32_bf16 v[60:63], v[144:147], v[168:171], v[60:63]
	v_mfma_f32_16x16x32_bf16 v[48:51], v[136:139], v[176:179], v[48:51]
	v_mfma_f32_16x16x32_bf16 v[44:47], v[144:147], v[176:179], v[44:47]
	v_mfma_f32_16x16x32_bf16 v[32:35], v[136:139], v[184:187], v[32:35]
	v_mfma_f32_16x16x32_bf16 v[28:31], v[144:147], v[184:187], v[28:31]
	v_mfma_f32_16x16x32_bf16 v[16:19], v[136:139], v[216:219], v[16:19]
	v_mfma_f32_16x16x32_bf16 v[12:15], v[144:147], v[216:219], v[12:15]
	s_setprio 0
	s_setprio 1
	v_mfma_f32_16x16x32_bf16 v[56:59], v[148:151], v[164:167], v[56:59]
	v_mfma_f32_16x16x32_bf16 v[52:55], v[156:159], v[164:167], v[52:55]
	v_mfma_f32_16x16x32_bf16 v[40:43], v[148:151], v[172:175], v[40:43]
	v_mfma_f32_16x16x32_bf16 v[36:39], v[156:159], v[172:175], v[36:39]
	v_mfma_f32_16x16x32_bf16 v[24:27], v[148:151], v[180:183], v[24:27]
	v_mfma_f32_16x16x32_bf16 v[20:23], v[156:159], v[180:183], v[20:23]
	v_mfma_f32_16x16x32_bf16 v[8:11], v[148:151], v[212:215], v[8:11]
	v_mfma_f32_16x16x32_bf16 v[4:7], v[156:159], v[212:215], v[4:7]
	v_mfma_f32_16x16x32_bf16 v[56:59], v[152:155], v[168:171], v[56:59]
	v_mfma_f32_16x16x32_bf16 v[52:55], v[160:163], v[168:171], v[52:55]
	v_mfma_f32_16x16x32_bf16 v[40:43], v[152:155], v[176:179], v[40:43]
	v_mfma_f32_16x16x32_bf16 v[36:39], v[160:163], v[176:179], v[36:39]
	v_mfma_f32_16x16x32_bf16 v[24:27], v[152:155], v[184:187], v[24:27]
	v_mfma_f32_16x16x32_bf16 v[20:23], v[160:163], v[184:187], v[20:23]
	v_mfma_f32_16x16x32_bf16 v[8:11], v[152:155], v[216:219], v[8:11]
	v_mfma_f32_16x16x32_bf16 v[4:7], v[160:163], v[216:219], v[4:7]
	s_setprio 0
	s_barrier
	s_add_i32 s72, 0, 0x18000
	s_add_i32 s73, 0, 0x1c000
	v_add_u32_e32 v144, s72, v232
	v_add_u32_e32 v160, s73, v232
	ds_read_b128 v[132:135], v144
	ds_read_b128 v[136:139], v144 offset:1024
	ds_read_b128 v[140:143], v144 offset:2048
	ds_read_b128 v[144:147], v144 offset:3072
	ds_read_b128 v[148:151], v160
	ds_read_b128 v[152:155], v160 offset:1024
	ds_read_b128 v[156:159], v160 offset:2048
	ds_read_b128 v[160:163], v160 offset:3072
	s_add_u32 s52, s52, 0x40000
	s_addc_u32 s53, s53, 0
	s_mov_b32 m0, s61
	v_lshl_add_u64 v[224:225], s[52:53], 0, v[192:193]
	ds_read_b128 v[164:167], v242 offset:32768
	ds_read_b128 v[168:171], v242 offset:33792
	ds_read_b128 v[172:175], v242 offset:34816
	ds_read_b128 v[176:179], v242 offset:35840
	ds_read_b128 v[180:183], v242 offset:36864
	ds_read_b128 v[184:187], v242 offset:37888
	ds_read_b128 v[212:215], v242 offset:38912
	ds_read_b128 v[216:219], v242 offset:39936
	global_load_lds_dwordx4 v[224:225], off
	v_lshl_add_u64 v[224:225], s[52:53], 0, v[188:189]
	s_mov_b32 m0, s62
	s_nop 0
	global_load_lds_dwordx4 v[224:225], off
	s_waitcnt vmcnt(8)
	s_waitcnt lgkmcnt(0)
	s_barrier
	s_setprio 1
	v_mfma_f32_16x16x32_bf16 v[128:131], v[132:135], v[164:167], v[128:131]
	v_mfma_f32_16x16x32_bf16 v[124:127], v[140:143], v[164:167], v[124:127]
	v_mfma_f32_16x16x32_bf16 v[112:115], v[132:135], v[172:175], v[112:115]
	v_mfma_f32_16x16x32_bf16 v[108:111], v[140:143], v[172:175], v[108:111]
	v_mfma_f32_16x16x32_bf16 v[96:99], v[132:135], v[180:183], v[96:99]
	v_mfma_f32_16x16x32_bf16 v[92:95], v[140:143], v[180:183], v[92:95]
	v_mfma_f32_16x16x32_bf16 v[80:83], v[132:135], v[212:215], v[80:83]
	v_mfma_f32_16x16x32_bf16 v[76:79], v[140:143], v[212:215], v[76:79]
	v_mfma_f32_16x16x32_bf16 v[128:131], v[136:139], v[168:171], v[128:131]
	v_mfma_f32_16x16x32_bf16 v[124:127], v[144:147], v[168:171], v[124:127]
	v_mfma_f32_16x16x32_bf16 v[112:115], v[136:139], v[176:179], v[112:115]
	v_mfma_f32_16x16x32_bf16 v[108:111], v[144:147], v[176:179], v[108:111]
	v_mfma_f32_16x16x32_bf16 v[96:99], v[136:139], v[184:187], v[96:99]
	v_mfma_f32_16x16x32_bf16 v[92:95], v[144:147], v[184:187], v[92:95]
	v_mfma_f32_16x16x32_bf16 v[80:83], v[136:139], v[216:219], v[80:83]
	v_mfma_f32_16x16x32_bf16 v[76:79], v[144:147], v[216:219], v[76:79]
	s_setprio 0
	s_setprio 1
	v_mfma_f32_16x16x32_bf16 v[120:123], v[148:151], v[164:167], v[120:123]
	v_mfma_f32_16x16x32_bf16 v[116:119], v[156:159], v[164:167], v[116:119]
	v_mfma_f32_16x16x32_bf16 v[104:107], v[148:151], v[172:175], v[104:107]
	v_mfma_f32_16x16x32_bf16 v[100:103], v[156:159], v[172:175], v[100:103]
	v_mfma_f32_16x16x32_bf16 v[88:91], v[148:151], v[180:183], v[88:91]
	v_mfma_f32_16x16x32_bf16 v[84:87], v[156:159], v[180:183], v[84:87]
	v_mfma_f32_16x16x32_bf16 v[72:75], v[148:151], v[212:215], v[72:75]
	v_mfma_f32_16x16x32_bf16 v[68:71], v[156:159], v[212:215], v[68:71]
	v_mfma_f32_16x16x32_bf16 v[120:123], v[152:155], v[168:171], v[120:123]
	v_mfma_f32_16x16x32_bf16 v[116:119], v[160:163], v[168:171], v[116:119]
	v_mfma_f32_16x16x32_bf16 v[104:107], v[152:155], v[176:179], v[104:107]
	v_mfma_f32_16x16x32_bf16 v[100:103], v[160:163], v[176:179], v[100:103]
	v_mfma_f32_16x16x32_bf16 v[88:91], v[152:155], v[184:187], v[88:91]
	v_mfma_f32_16x16x32_bf16 v[84:87], v[160:163], v[184:187], v[84:87]
	v_mfma_f32_16x16x32_bf16 v[72:75], v[152:155], v[216:219], v[72:75]
	v_mfma_f32_16x16x32_bf16 v[68:71], v[160:163], v[216:219], v[68:71]
	s_setprio 0
	s_barrier
; #define PG8_STAGE(bufoff, gbase, voff) do { _Pragma("unroll") for (int _i = 0; _i < 2; ++_i) \
;         __builtin_amdgcn_global_load_lds((const unsigned*)((const char*)(gbase) + (voff)[_i]), (LAS unsigned*)(lds + (bufoff) + ldsw + _i * 8192), 16, 0, 0); } while (0)
; #define PG8_LDA(dst, b, h) do { _Pragma("unroll") for (int m = 0; m < 4; ++m) _Pragma("unroll") for (int k = 0; k < 2; ++k) dst[m][k] = *(const LAS bf16x8*)(lds + PG8_SA(b, h) + aoff + m * 2048 + k * 1024); } while (0)
; #define PG8_MMA(ai, bj, At, Bt) do { __builtin_amdgcn_s_setprio(1); _Pragma("unroll") for (int m = 0; m < 4; ++m) _Pragma("unroll") for (int n = 0; n < 2; ++n) _Pragma("unroll") for (int k = 0; k < 2; ++k) \
;         acc[ai][bj][m][n] = __builtin_amdgcn_mfma_f32_16x16x32_bf16(Bt[n][k], At[m][k], acc[ai][bj][m][n], 0, 0, 0); __builtin_amdgcn_s_setprio(0); } while (0)
; #define PG8_WAIT_V(n) asm volatile("s_waitcnt vmcnt(" #n ")" ::: "memory")
; #define PG8_WAIT_L(n) asm volatile("s_waitcnt lgkmcnt(" #n ")" ::: "memory")
; #define PG8_BAR __builtin_amdgcn_s_barrier()
; #define PG8_SCHED __builtin_amdgcn_sched_barrier(0)
; template <class Epi>
; __device__ __forceinline__ void gemm_phase(LAS unsigned char* lds, const Gemm g, const StaticOrder& S, const Epi& E) {
;     ...
;             PG8_LDA(At, 1, 1); PG8_STAGE(PG8_SB(1, 0), b3, voffB); PG8_STAGE(PG8_SB(1, 1), b3 + hstepB, voffB); PG8_STAGE(PG8_SA(1, 0), a3, voffA);
;             PG8_WAIT_V(8); PG8_WAIT_L(0); PG8_BAR; PG8_MMA(1, 0, At, B0); PG8_MMA(1, 1, At, B1); PG8_BAR; PG8_SCHED;
;         }
;         if (wr == 0) PG8_BAR;
	s_add_i32 s52, s72, s58
	v_lshl_add_u64 v[196:197], v[196:197], 0, s[30:31]
	s_mov_b32 m0, s52
	ds_read_b128 v[164:167], v242 offset:49152
	ds_read_b128 v[168:171], v242 offset:50176
	ds_read_b128 v[172:175], v242 offset:51200
	ds_read_b128 v[176:179], v242 offset:52224
	ds_read_b128 v[180:183], v242 offset:53248
	ds_read_b128 v[184:187], v242 offset:54272
	ds_read_b128 v[212:215], v242 offset:55296
	ds_read_b128 v[216:219], v242 offset:56320
	global_load_lds_dwordx4 v[196:197], off
	s_add_i32 m0, s52, 0x2000
	s_add_u32 s22, s22, 0x10080
	v_lshl_add_u64 v[196:197], v[198:199], 0, s[30:31]
	s_addc_u32 s23, s23, 0
	s_add_i32 s52, s73, s58
	global_load_lds_dwordx4 v[196:197], off
	v_lshl_add_u64 v[196:197], s[22:23], 0, v[190:191]
	s_mov_b32 m0, s52
	s_nop 0
	global_load_lds_dwordx4 v[196:197], off
	v_lshl_add_u64 v[196:197], s[22:23], 0, v[0:1]
	s_add_i32 m0, s52, 0x2000
	s_nop 0
	global_load_lds_dwordx4 v[196:197], off
	v_lshl_add_u64 v[196:197], v[220:221], 0, s[30:31]
	s_mov_b32 m0, s28
	s_nop 0
	global_load_lds_dwordx4 v[196:197], off
	v_lshl_add_u64 v[196:197], v[222:223], 0, s[30:31]
	s_mov_b32 m0, s63
	s_nop 0
	global_load_lds_dwordx4 v[196:197], off
	s_waitcnt vmcnt(8)
	s_waitcnt lgkmcnt(0)
	s_barrier
	s_setprio 1
	v_mfma_f32_16x16x32_bf16 v[64:67], v[132:135], v[164:167], v[64:67]
	v_mfma_f32_16x16x32_bf16 v[60:63], v[140:143], v[164:167], v[60:63]
	v_mfma_f32_16x16x32_bf16 v[48:51], v[132:135], v[172:175], v[48:51]
	v_mfma_f32_16x16x32_bf16 v[44:47], v[140:143], v[172:175], v[44:47]
	v_mfma_f32_16x16x32_bf16 v[32:35], v[132:135], v[180:183], v[32:35]
	v_mfma_f32_16x16x32_bf16 v[28:31], v[140:143], v[180:183], v[28:31]
	v_mfma_f32_16x16x32_bf16 v[16:19], v[132:135], v[212:215], v[16:19]
	v_mfma_f32_16x16x32_bf16 v[12:15], v[140:143], v[212:215], v[12:15]
	v_mfma_f32_16x16x32_bf16 v[64:67], v[136:139], v[168:171], v[64:67]
	v_mfma_f32_16x16x32_bf16 v[60:63], v[144:147], v[168:171], v[60:63]
	v_mfma_f32_16x16x32_bf16 v[48:51], v[136:139], v[176:179], v[48:51]
	v_mfma_f32_16x16x32_bf16 v[44:47], v[144:147], v[176:179], v[44:47]
	v_mfma_f32_16x16x32_bf16 v[32:35], v[136:139], v[184:187], v[32:35]
	v_mfma_f32_16x16x32_bf16 v[28:31], v[144:147], v[184:187], v[28:31]
	v_mfma_f32_16x16x32_bf16 v[16:19], v[136:139], v[216:219], v[16:19]
	v_mfma_f32_16x16x32_bf16 v[12:15], v[144:147], v[216:219], v[12:15]
	s_setprio 0
	s_setprio 1
	v_mfma_f32_16x16x32_bf16 v[56:59], v[148:151], v[164:167], v[56:59]
	v_mfma_f32_16x16x32_bf16 v[52:55], v[156:159], v[164:167], v[52:55]
	v_mfma_f32_16x16x32_bf16 v[40:43], v[148:151], v[172:175], v[40:43]
	v_mfma_f32_16x16x32_bf16 v[36:39], v[156:159], v[172:175], v[36:39]
	v_mfma_f32_16x16x32_bf16 v[24:27], v[148:151], v[180:183], v[24:27]
	v_mfma_f32_16x16x32_bf16 v[20:23], v[156:159], v[180:183], v[20:23]
	v_mfma_f32_16x16x32_bf16 v[8:11], v[148:151], v[212:215], v[8:11]
	v_mfma_f32_16x16x32_bf16 v[4:7], v[156:159], v[212:215], v[4:7]
	v_mfma_f32_16x16x32_bf16 v[56:59], v[152:155], v[168:171], v[56:59]
	v_mfma_f32_16x16x32_bf16 v[52:55], v[160:163], v[168:171], v[52:55]
	v_mfma_f32_16x16x32_bf16 v[40:43], v[152:155], v[176:179], v[40:43]
	v_mfma_f32_16x16x32_bf16 v[36:39], v[160:163], v[176:179], v[36:39]
	v_mfma_f32_16x16x32_bf16 v[24:27], v[152:155], v[184:187], v[24:27]
	v_mfma_f32_16x16x32_bf16 v[20:23], v[160:163], v[184:187], v[20:23]
	v_mfma_f32_16x16x32_bf16 v[8:11], v[152:155], v[216:219], v[8:11]
	v_mfma_f32_16x16x32_bf16 v[4:7], v[160:163], v[216:219], v[4:7]
	s_setprio 0
	s_barrier
	s_add_i32 s71, s71, 2
	s_add_u32 s50, s50, 0x100
	s_addc_u32 s51, s51, 0
	s_add_u32 s69, s69, 0x100
	s_addc_u32 s70, s70, 0
	s_cmp_gt_u32 s71, 13
	s_cbranch_scc0 .LBB0_1005
	s_and_b64 vcc, exec, s[14:15]
	s_cbranch_vccz .LBB0_1008
	s_barrier

; #define PG8_STAGE(bufoff, gbase, voff) do { _Pragma("unroll") for (int _i = 0; _i < 2; ++_i) \
;         __builtin_amdgcn_global_load_lds((const unsigned*)((const char*)(gbase) + (voff)[_i]), (LAS unsigned*)(lds + (bufoff) + ldsw + _i * 8192), 16, 0, 0); } while (0)
; #define PG8_LDA(dst, b, h) do { _Pragma("unroll") for (int m = 0; m < 4; ++m) _Pragma("unroll") for (int k = 0; k < 2; ++k) dst[m][k] = *(const LAS bf16x8*)(lds + PG8_SA(b, h) + aoff + m * 2048 + k * 1024); } while (0)
; #define PG8_LDB(dst, b, h) do { _Pragma("unroll") for (int n = 0; n < 2; ++n) _Pragma("unroll") for (int k = 0; k < 2; ++k) dst[n][k] = *(const LAS bf16x8*)(lds + PG8_SB(b, h) + boff + n * 2048 + k * 1024); } while (0)
; #define PG8_MMA(ai, bj, At, Bt) do { __builtin_amdgcn_s_setprio(1); _Pragma("unroll") for (int m = 0; m < 4; ++m) _Pragma("unroll") for (int n = 0; n < 2; ++n) _Pragma("unroll") for (int k = 0; k < 2; ++k) \
;         acc[ai][bj][m][n] = __builtin_amdgcn_mfma_f32_16x16x32_bf16(Bt[n][k], At[m][k], acc[ai][bj][m][n], 0, 0, 0); __builtin_amdgcn_s_setprio(0); } while (0)
; #define PG8_WAIT_V(n) asm volatile("s_waitcnt vmcnt(" #n ")" ::: "memory")
; #define PG8_WAIT_L(n) asm volatile("s_waitcnt lgkmcnt(" #n ")" ::: "memory")
; #define PG8_BAR __builtin_amdgcn_s_barrier()
; #define PG8_SCHED __builtin_amdgcn_sched_barrier(0)
; template <class Epi>
; __device__ __forceinline__ void gemm_phase(LAS unsigned char* lds, const Gemm g, const StaticOrder& S, const Epi& E) {
;     ...
;         for (int t = 0; t < nt; t += 2) {
;             const bool last = (t == nt - 2);
;             const char* a1 = cA + (size_t)(t + 1) * kstep;
;             const char* a2 = last ? nA : cA + (size_t)(t + 2) * kstep; const char* b2 = last ? nB : cB + (size_t)(t + 2) * kstep;
;             const char* a3 = a2 + kstep; const char* b3 = b2 + kstep;
;             PG8_LDB(B0, 0, 0); PG8_LDB(B1, 0, 1); PG8_SCHED; PG8_LDA(At, 0, 0); PG8_STAGE(PG8_SA(1, 1), a1 + hstepA, voffA);
;             PG8_WAIT_V(8); PG8_WAIT_L(0); PG8_BAR; PG8_MMA(0, 0, At, B0); PG8_MMA(0, 1, At, B1); PG8_BAR; PG8_SCHED;
;             PG8_LDA(At, 0, 1); PG8_STAGE(PG8_SB(0, 0), b2, voffB); PG8_STAGE(PG8_SB(0, 1), b2 + hstepB, voffB); PG8_STAGE(PG8_SA(0, 0), a2, voffA);
.LBB0_1088:
	s_add_u32 s22, s46, 0xfffc0080
	s_addc_u32 s23, s47, -1
	s_add_i32 s68, 0, 0x10000
	s_cmp_eq_u32 s67, 12
	s_cselect_b32 s49, s35, s23
	s_cselect_b32 s48, s63, s22
	s_cselect_b32 s23, s15, s66
	s_cselect_b32 s22, s64, s65
	s_add_i32 s70, 0, 0x14000
	v_add_u32_e32 v154, s68, v158
	v_add_u32_e32 v161, s70, v158
	ds_read_b128 v[142:145], v154
	ds_read_b128 v[146:149], v154 offset:1024
	ds_read_b128 v[150:153], v154 offset:2048
	ds_read_b128 v[154:157], v154 offset:3072
	ds_read_b128 v[162:165], v161
	ds_read_b128 v[166:169], v161 offset:1024
	ds_read_b128 v[170:173], v161 offset:2048
	ds_read_b128 v[174:177], v161 offset:3072
	v_lshl_add_u64 v[198:199], s[46:47], 0, v[138:139]
	s_add_i32 m0, s55, 0xc000
	ds_read_b128 v[178:181], v160
	ds_read_b128 v[182:185], v160 offset:1024
	ds_read_b128 v[186:189], v160 offset:2048
	ds_read_b128 v[190:193], v160 offset:3072
	ds_read_b128 v[194:197], v160 offset:4096
	ds_read_b128 v[210:213], v160 offset:5120
	ds_read_b128 v[214:217], v160 offset:6144
	ds_read_b128 v[218:221], v160 offset:7168
	global_load_lds_dwordx4 v[198:199], off
	v_lshl_add_u64 v[198:199], s[46:47], 0, v[140:141]
	s_add_i32 m0, s55, 0xe000
	s_nop 0
	global_load_lds_dwordx4 v[198:199], off
	s_waitcnt vmcnt(8)
	s_waitcnt lgkmcnt(0)
	s_barrier
	s_setprio 1
	v_mfma_f32_16x16x32_bf16 v[128:131], v[142:145], v[178:181], v[128:131]
	v_mfma_f32_16x16x32_bf16 v[120:123], v[150:153], v[178:181], v[120:123]
	v_mfma_f32_16x16x32_bf16 v[108:111], v[142:145], v[186:189], v[108:111]
	v_mfma_f32_16x16x32_bf16 v[100:103], v[150:153], v[186:189], v[100:103]
	v_mfma_f32_16x16x32_bf16 v[92:95], v[142:145], v[194:197], v[92:95]
	v_mfma_f32_16x16x32_bf16 v[84:87], v[150:153], v[194:197], v[84:87]
	v_mfma_f32_16x16x32_bf16 v[76:79], v[142:145], v[214:217], v[76:79]
	v_mfma_f32_16x16x32_bf16 v[68:71], v[150:153], v[214:217], v[68:71]
	v_mfma_f32_16x16x32_bf16 v[128:131], v[146:149], v[182:185], v[128:131]
	v_mfma_f32_16x16x32_bf16 v[120:123], v[154:157], v[182:185], v[120:123]
	v_mfma_f32_16x16x32_bf16 v[108:111], v[146:149], v[190:193], v[108:111]
	v_mfma_f32_16x16x32_bf16 v[100:103], v[154:157], v[190:193], v[100:103]
	v_mfma_f32_16x16x32_bf16 v[92:95], v[146:149], v[210:213], v[92:95]
	v_mfma_f32_16x16x32_bf16 v[84:87], v[154:157], v[210:213], v[84:87]
	v_mfma_f32_16x16x32_bf16 v[76:79], v[146:149], v[218:221], v[76:79]
	v_mfma_f32_16x16x32_bf16 v[68:71], v[154:157], v[218:221], v[68:71]
	s_setprio 0
	s_setprio 1
	v_mfma_f32_16x16x32_bf16 v[124:127], v[162:165], v[178:181], v[124:127]
	v_mfma_f32_16x16x32_bf16 v[116:119], v[170:173], v[178:181], v[116:119]
	v_mfma_f32_16x16x32_bf16 v[112:115], v[162:165], v[186:189], v[112:115]
	v_mfma_f32_16x16x32_bf16 v[104:107], v[170:173], v[186:189], v[104:107]
	v_mfma_f32_16x16x32_bf16 v[96:99], v[162:165], v[194:197], v[96:99]
	v_mfma_f32_16x16x32_bf16 v[88:91], v[170:173], v[194:197], v[88:91]
	v_mfma_f32_16x16x32_bf16 v[80:83], v[162:165], v[214:217], v[80:83]
	v_mfma_f32_16x16x32_bf16 v[72:75], v[170:173], v[214:217], v[72:75]
	v_mfma_f32_16x16x32_bf16 v[124:127], v[166:169], v[182:185], v[124:127]
	v_mfma_f32_16x16x32_bf16 v[116:119], v[174:177], v[182:185], v[116:119]
	v_mfma_f32_16x16x32_bf16 v[112:115], v[166:169], v[190:193], v[112:115]
	v_mfma_f32_16x16x32_bf16 v[104:107], v[174:177], v[190:193], v[104:107]
	v_mfma_f32_16x16x32_bf16 v[96:99], v[166:169], v[210:213], v[96:99]
	v_mfma_f32_16x16x32_bf16 v[88:91], v[174:177], v[210:213], v[88:91]
	v_mfma_f32_16x16x32_bf16 v[80:83], v[166:169], v[218:221], v[80:83]
	v_mfma_f32_16x16x32_bf16 v[72:75], v[174:177], v[218:221], v[72:75]
	s_setprio 0
	s_barrier
	s_add_i32 s68, s68, s54
	v_lshl_add_u64 v[198:199], s[22:23], 0, v[134:135]
	s_mov_b32 m0, s68
	ds_read_b128 v[178:181], v160 offset:16384
	ds_read_b128 v[182:185], v160 offset:17408
	ds_read_b128 v[186:189], v160 offset:18432
	ds_read_b128 v[190:193], v160 offset:19456
	ds_read_b128 v[194:197], v160 offset:20480
	ds_read_b128 v[210:213], v160 offset:21504
	ds_read_b128 v[214:217], v160 offset:22528
	ds_read_b128 v[218:221], v160 offset:23552
	global_load_lds_dwordx4 v[198:199], off
	s_add_i32 m0, s68, 0x2000
	s_add_u32 s68, s22, 0x10000
	v_lshl_add_u64 v[222:223], s[22:23], 0, v[0:1]
	s_addc_u32 s69, s23, 0
	s_add_i32 s70, s70, s54
	global_load_lds_dwordx4 v[222:223], off
	v_lshl_add_u64 v[224:225], s[68:69], 0, v[134:135]
	s_mov_b32 m0, s70
	v_lshl_add_u64 v[226:227], s[48:49], 0, v[132:133]
	global_load_lds_dwordx4 v[224:225], off
	v_lshl_add_u64 v[224:225], s[68:69], 0, v[0:1]
	s_add_i32 m0, s70, 0x2000
	s_nop 0
	global_load_lds_dwordx4 v[224:225], off
	v_lshl_add_u64 v[224:225], s[48:49], 0, v[136:137]
	s_mov_b32 m0, s55
	s_nop 0
	global_load_lds_dwordx4 v[224:225], off
	s_mov_b32 m0, s56
	s_nop 0
	global_load_lds_dwordx4 v[226:227], off
	s_waitcnt vmcnt(8)
	s_waitcnt lgkmcnt(0)
	s_barrier
; #define PG8_STAGE(bufoff, gbase, voff) do { _Pragma("unroll") for (int _i = 0; _i < 2; ++_i) \
;         __builtin_amdgcn_global_load_lds((const unsigned*)((const char*)(gbase) + (voff)[_i]), (LAS unsigned*)(lds + (bufoff) + ldsw + _i * 8192), 16, 0, 0); } while (0)
; #define PG8_LDA(dst, b, h) do { _Pragma("unroll") for (int m = 0; m < 4; ++m) _Pragma("unroll") for (int k = 0; k < 2; ++k) dst[m][k] = *(const LAS bf16x8*)(lds + PG8_SA(b, h) + aoff + m * 2048 + k * 1024); } while (0)
; #define PG8_LDB(dst, b, h) do { _Pragma("unroll") for (int n = 0; n < 2; ++n) _Pragma("unroll") for (int k = 0; k < 2; ++k) dst[n][k] = *(const LAS bf16x8*)(lds + PG8_SB(b, h) + boff + n * 2048 + k * 1024); } while (0)
; #define PG8_MMA(ai, bj, At, Bt) do { __builtin_amdgcn_s_setprio(1); _Pragma("unroll") for (int m = 0; m < 4; ++m) _Pragma("unroll") for (int n = 0; n < 2; ++n) _Pragma("unroll") for (int k = 0; k < 2; ++k) \
;         acc[ai][bj][m][n] = __builtin_amdgcn_mfma_f32_16x16x32_bf16(Bt[n][k], At[m][k], acc[ai][bj][m][n], 0, 0, 0); __builtin_amdgcn_s_setprio(0); } while (0)
; #define PG8_WAIT_V(n) asm volatile("s_waitcnt vmcnt(" #n ")" ::: "memory")
; #define PG8_WAIT_L(n) asm volatile("s_waitcnt lgkmcnt(" #n ")" ::: "memory")
; #define PG8_BAR __builtin_amdgcn_s_barrier()
; #define PG8_SCHED __builtin_amdgcn_sched_barrier(0)
; template <class Epi>
; __device__ __forceinline__ void gemm_phase(LAS unsigned char* lds, const Gemm g, const StaticOrder& S, const Epi& E) {
;     ...
;             PG8_WAIT_V(8); PG8_WAIT_L(0); PG8_BAR; PG8_MMA(1, 0, At, B0); PG8_MMA(1, 1, At, B1); PG8_BAR; PG8_SCHED;
;             PG8_LDB(B0, 1, 0); PG8_LDB(B1, 1, 1); PG8_SCHED; PG8_LDA(At, 1, 0); PG8_STAGE(PG8_SA(0, 1), a2 + hstepA, voffA);
;             PG8_WAIT_V(8); PG8_WAIT_L(0); PG8_BAR; PG8_MMA(0, 0, At, B0); PG8_MMA(0, 1, At, B1); PG8_BAR; PG8_SCHED;
	s_setprio 1
	v_mfma_f32_16x16x32_bf16 v[60:63], v[142:145], v[178:181], v[60:63]
	v_mfma_f32_16x16x32_bf16 v[52:55], v[150:153], v[178:181], v[52:55]
	v_mfma_f32_16x16x32_bf16 v[44:47], v[142:145], v[186:189], v[44:47]
	v_mfma_f32_16x16x32_bf16 v[36:39], v[150:153], v[186:189], v[36:39]
	v_mfma_f32_16x16x32_bf16 v[28:31], v[142:145], v[194:197], v[28:31]
	v_mfma_f32_16x16x32_bf16 v[20:23], v[150:153], v[194:197], v[20:23]
	v_mfma_f32_16x16x32_bf16 v[4:7], v[142:145], v[214:217], v[4:7]
	v_mfma_f32_16x16x32_bf16 v[12:15], v[150:153], v[214:217], v[12:15]
	v_mfma_f32_16x16x32_bf16 v[60:63], v[146:149], v[182:185], v[60:63]
	v_mfma_f32_16x16x32_bf16 v[52:55], v[154:157], v[182:185], v[52:55]
	v_mfma_f32_16x16x32_bf16 v[44:47], v[146:149], v[190:193], v[44:47]
	v_mfma_f32_16x16x32_bf16 v[36:39], v[154:157], v[190:193], v[36:39]
	v_mfma_f32_16x16x32_bf16 v[28:31], v[146:149], v[210:213], v[28:31]
	v_mfma_f32_16x16x32_bf16 v[20:23], v[154:157], v[210:213], v[20:23]
	v_mfma_f32_16x16x32_bf16 v[4:7], v[146:149], v[218:221], v[4:7]
	v_mfma_f32_16x16x32_bf16 v[12:15], v[154:157], v[218:221], v[12:15]
	s_setprio 0
	s_setprio 1
	v_mfma_f32_16x16x32_bf16 v[64:67], v[162:165], v[178:181], v[64:67]
	v_mfma_f32_16x16x32_bf16 v[56:59], v[170:173], v[178:181], v[56:59]
	v_mfma_f32_16x16x32_bf16 v[48:51], v[162:165], v[186:189], v[48:51]
	v_mfma_f32_16x16x32_bf16 v[40:43], v[170:173], v[186:189], v[40:43]
	v_mfma_f32_16x16x32_bf16 v[32:35], v[162:165], v[194:197], v[32:35]
	v_mfma_f32_16x16x32_bf16 v[24:27], v[170:173], v[194:197], v[24:27]
	v_mfma_f32_16x16x32_bf16 v[8:11], v[162:165], v[214:217], v[8:11]
	v_mfma_f32_16x16x32_bf16 v[16:19], v[170:173], v[214:217], v[16:19]
	v_mfma_f32_16x16x32_bf16 v[64:67], v[166:169], v[182:185], v[64:67]
	v_mfma_f32_16x16x32_bf16 v[56:59], v[174:177], v[182:185], v[56:59]
	v_mfma_f32_16x16x32_bf16 v[48:51], v[166:169], v[190:193], v[48:51]
	v_mfma_f32_16x16x32_bf16 v[40:43], v[174:177], v[190:193], v[40:43]
	v_mfma_f32_16x16x32_bf16 v[32:35], v[166:169], v[210:213], v[32:35]
	v_mfma_f32_16x16x32_bf16 v[24:27], v[174:177], v[210:213], v[24:27]
	v_mfma_f32_16x16x32_bf16 v[8:11], v[166:169], v[218:221], v[8:11]
	v_mfma_f32_16x16x32_bf16 v[16:19], v[174:177], v[218:221], v[16:19]
	s_setprio 0
	s_barrier
	s_add_i32 s68, 0, 0x18000
	s_add_i32 s69, 0, 0x1c000
	v_add_u32_e32 v154, s68, v158
	v_add_u32_e32 v161, s69, v158
	ds_read_b128 v[142:145], v154
	ds_read_b128 v[146:149], v154 offset:1024
	ds_read_b128 v[150:153], v154 offset:2048
	ds_read_b128 v[154:157], v154 offset:3072
	ds_read_b128 v[162:165], v161
	ds_read_b128 v[166:169], v161 offset:1024
	ds_read_b128 v[170:173], v161 offset:2048
	ds_read_b128 v[174:177], v161 offset:3072
	s_add_u32 s48, s48, 0x40000
	s_addc_u32 s49, s49, 0
	s_mov_b32 m0, s57
	v_lshl_add_u64 v[228:229], s[48:49], 0, v[136:137]
	ds_read_b128 v[178:181], v160 offset:32768
	ds_read_b128 v[182:185], v160 offset:33792
	ds_read_b128 v[186:189], v160 offset:34816
	ds_read_b128 v[190:193], v160 offset:35840
	ds_read_b128 v[194:197], v160 offset:36864
	ds_read_b128 v[210:213], v160 offset:37888
	ds_read_b128 v[214:217], v160 offset:38912
	ds_read_b128 v[218:221], v160 offset:39936
	global_load_lds_dwordx4 v[228:229], off
	v_lshl_add_u64 v[228:229], s[48:49], 0, v[132:133]
	s_mov_b32 m0, s58
	s_nop 0
	global_load_lds_dwordx4 v[228:229], off
	s_waitcnt vmcnt(8)
	s_waitcnt lgkmcnt(0)
	s_barrier
	s_setprio 1
	v_mfma_f32_16x16x32_bf16 v[128:131], v[142:145], v[178:181], v[128:131]
	v_mfma_f32_16x16x32_bf16 v[120:123], v[150:153], v[178:181], v[120:123]
	v_mfma_f32_16x16x32_bf16 v[108:111], v[142:145], v[186:189], v[108:111]
	v_mfma_f32_16x16x32_bf16 v[100:103], v[150:153], v[186:189], v[100:103]
	v_mfma_f32_16x16x32_bf16 v[92:95], v[142:145], v[194:197], v[92:95]
	v_mfma_f32_16x16x32_bf16 v[84:87], v[150:153], v[194:197], v[84:87]
	v_mfma_f32_16x16x32_bf16 v[76:79], v[142:145], v[214:217], v[76:79]
	v_mfma_f32_16x16x32_bf16 v[68:71], v[150:153], v[214:217], v[68:71]
	v_mfma_f32_16x16x32_bf16 v[128:131], v[146:149], v[182:185], v[128:131]
	v_mfma_f32_16x16x32_bf16 v[120:123], v[154:157], v[182:185], v[120:123]
	v_mfma_f32_16x16x32_bf16 v[108:111], v[146:149], v[190:193], v[108:111]
	v_mfma_f32_16x16x32_bf16 v[100:103], v[154:157], v[190:193], v[100:103]
	v_mfma_f32_16x16x32_bf16 v[92:95], v[146:149], v[210:213], v[92:95]
	v_mfma_f32_16x16x32_bf16 v[84:87], v[154:157], v[210:213], v[84:87]
	v_mfma_f32_16x16x32_bf16 v[76:79], v[146:149], v[218:221], v[76:79]
	v_mfma_f32_16x16x32_bf16 v[68:71], v[154:157], v[218:221], v[68:71]
	s_setprio 0
	s_setprio 1
	v_mfma_f32_16x16x32_bf16 v[124:127], v[162:165], v[178:181], v[124:127]
	v_mfma_f32_16x16x32_bf16 v[116:119], v[170:173], v[178:181], v[116:119]
	v_mfma_f32_16x16x32_bf16 v[112:115], v[162:165], v[186:189], v[112:115]
	v_mfma_f32_16x16x32_bf16 v[104:107], v[170:173], v[186:189], v[104:107]
	v_mfma_f32_16x16x32_bf16 v[96:99], v[162:165], v[194:197], v[96:99]
	v_mfma_f32_16x16x32_bf16 v[88:91], v[170:173], v[194:197], v[88:91]
	v_mfma_f32_16x16x32_bf16 v[80:83], v[162:165], v[214:217], v[80:83]
	v_mfma_f32_16x16x32_bf16 v[72:75], v[170:173], v[214:217], v[72:75]
	v_mfma_f32_16x16x32_bf16 v[124:127], v[166:169], v[182:185], v[124:127]
	v_mfma_f32_16x16x32_bf16 v[116:119], v[174:177], v[182:185], v[116:119]
	v_mfma_f32_16x16x32_bf16 v[112:115], v[166:169], v[190:193], v[112:115]
	v_mfma_f32_16x16x32_bf16 v[104:107], v[174:177], v[190:193], v[104:107]
	v_mfma_f32_16x16x32_bf16 v[96:99], v[166:169], v[210:213], v[96:99]
	v_mfma_f32_16x16x32_bf16 v[88:91], v[174:177], v[210:213], v[88:91]
	v_mfma_f32_16x16x32_bf16 v[80:83], v[166:169], v[218:221], v[80:83]
	v_mfma_f32_16x16x32_bf16 v[72:75], v[174:177], v[218:221], v[72:75]
	s_setprio 0
	s_barrier
; #define PG8_STAGE(bufoff, gbase, voff) do { _Pragma("unroll") for (int _i = 0; _i < 2; ++_i) \
;         __builtin_amdgcn_global_load_lds((const unsigned*)((const char*)(gbase) + (voff)[_i]), (LAS unsigned*)(lds + (bufoff) + ldsw + _i * 8192), 16, 0, 0); } while (0)
; #define PG8_LDA(dst, b, h) do { _Pragma("unroll") for (int m = 0; m < 4; ++m) _Pragma("unroll") for (int k = 0; k < 2; ++k) dst[m][k] = *(const LAS bf16x8*)(lds + PG8_SA(b, h) + aoff + m * 2048 + k * 1024); } while (0)
; #define PG8_MMA(ai, bj, At, Bt) do { __builtin_amdgcn_s_setprio(1); _Pragma("unroll") for (int m = 0; m < 4; ++m) _Pragma("unroll") for (int n = 0; n < 2; ++n) _Pragma("unroll") for (int k = 0; k < 2; ++k) \
;         acc[ai][bj][m][n] = __builtin_amdgcn_mfma_f32_16x16x32_bf16(Bt[n][k], At[m][k], acc[ai][bj][m][n], 0, 0, 0); __builtin_amdgcn_s_setprio(0); } while (0)
; #define PG8_WAIT_V(n) asm volatile("s_waitcnt vmcnt(" #n ")" ::: "memory")
; #define PG8_WAIT_L(n) asm volatile("s_waitcnt lgkmcnt(" #n ")" ::: "memory")
; #define PG8_BAR __builtin_amdgcn_s_barrier()
; #define PG8_SCHED __builtin_amdgcn_sched_barrier(0)
; template <class Epi>
; __device__ __forceinline__ void gemm_phase(LAS unsigned char* lds, const Gemm g, const StaticOrder& S, const Epi& E) {
;     ...
;             PG8_LDA(At, 1, 1); PG8_STAGE(PG8_SB(1, 0), b3, voffB); PG8_STAGE(PG8_SB(1, 1), b3 + hstepB, voffB); PG8_STAGE(PG8_SA(1, 0), a3, voffA);
;             PG8_WAIT_V(8); PG8_WAIT_L(0); PG8_BAR; PG8_MMA(1, 0, At, B0); PG8_MMA(1, 1, At, B1); PG8_BAR; PG8_SCHED;
;         }
;         if (wr == 0) PG8_BAR;
	s_add_i32 s48, s68, s54
	v_lshl_add_u64 v[198:199], v[198:199], 0, s[30:31]
	s_mov_b32 m0, s48
	ds_read_b128 v[178:181], v160 offset:49152
	ds_read_b128 v[182:185], v160 offset:50176
	ds_read_b128 v[186:189], v160 offset:51200
	ds_read_b128 v[190:193], v160 offset:52224
	ds_read_b128 v[194:197], v160 offset:53248
	ds_read_b128 v[210:213], v160 offset:54272
	ds_read_b128 v[214:217], v160 offset:55296
	ds_read_b128 v[218:221], v160 offset:56320
	global_load_lds_dwordx4 v[198:199], off
	s_add_i32 m0, s48, 0x2000
	s_add_u32 s22, s22, 0x10080
	v_lshl_add_u64 v[198:199], v[222:223], 0, s[30:31]
	s_addc_u32 s23, s23, 0
	s_add_i32 s48, s69, s54
	global_load_lds_dwordx4 v[198:199], off
	v_lshl_add_u64 v[198:199], s[22:23], 0, v[134:135]
	s_mov_b32 m0, s48
	s_nop 0
	global_load_lds_dwordx4 v[198:199], off
	v_lshl_add_u64 v[198:199], s[22:23], 0, v[0:1]
	s_add_i32 m0, s48, 0x2000
	s_nop 0
	global_load_lds_dwordx4 v[198:199], off
	v_lshl_add_u64 v[198:199], v[224:225], 0, s[30:31]
	s_mov_b32 m0, s28
	s_nop 0
	global_load_lds_dwordx4 v[198:199], off
	v_lshl_add_u64 v[198:199], v[226:227], 0, s[30:31]
	s_mov_b32 m0, s59
	s_nop 0
	global_load_lds_dwordx4 v[198:199], off
	s_waitcnt vmcnt(8)
	s_waitcnt lgkmcnt(0)
	s_barrier
	s_setprio 1
	v_mfma_f32_16x16x32_bf16 v[60:63], v[142:145], v[178:181], v[60:63]
	v_mfma_f32_16x16x32_bf16 v[52:55], v[150:153], v[178:181], v[52:55]
	v_mfma_f32_16x16x32_bf16 v[44:47], v[142:145], v[186:189], v[44:47]
	v_mfma_f32_16x16x32_bf16 v[36:39], v[150:153], v[186:189], v[36:39]
	v_mfma_f32_16x16x32_bf16 v[28:31], v[142:145], v[194:197], v[28:31]
	v_mfma_f32_16x16x32_bf16 v[20:23], v[150:153], v[194:197], v[20:23]
	v_mfma_f32_16x16x32_bf16 v[4:7], v[142:145], v[214:217], v[4:7]
	v_mfma_f32_16x16x32_bf16 v[12:15], v[150:153], v[214:217], v[12:15]
	v_mfma_f32_16x16x32_bf16 v[60:63], v[146:149], v[182:185], v[60:63]
	v_mfma_f32_16x16x32_bf16 v[52:55], v[154:157], v[182:185], v[52:55]
	v_mfma_f32_16x16x32_bf16 v[44:47], v[146:149], v[190:193], v[44:47]
	v_mfma_f32_16x16x32_bf16 v[36:39], v[154:157], v[190:193], v[36:39]
	v_mfma_f32_16x16x32_bf16 v[28:31], v[146:149], v[210:213], v[28:31]
	v_mfma_f32_16x16x32_bf16 v[20:23], v[154:157], v[210:213], v[20:23]
	v_mfma_f32_16x16x32_bf16 v[4:7], v[146:149], v[218:221], v[4:7]
	v_mfma_f32_16x16x32_bf16 v[12:15], v[154:157], v[218:221], v[12:15]
	s_setprio 0
	s_setprio 1
	v_mfma_f32_16x16x32_bf16 v[64:67], v[162:165], v[178:181], v[64:67]
	v_mfma_f32_16x16x32_bf16 v[56:59], v[170:173], v[178:181], v[56:59]
	v_mfma_f32_16x16x32_bf16 v[48:51], v[162:165], v[186:189], v[48:51]
	v_mfma_f32_16x16x32_bf16 v[40:43], v[170:173], v[186:189], v[40:43]
	v_mfma_f32_16x16x32_bf16 v[32:35], v[162:165], v[194:197], v[32:35]
	v_mfma_f32_16x16x32_bf16 v[24:27], v[170:173], v[194:197], v[24:27]
	v_mfma_f32_16x16x32_bf16 v[8:11], v[162:165], v[214:217], v[8:11]
	v_mfma_f32_16x16x32_bf16 v[16:19], v[170:173], v[214:217], v[16:19]
	v_mfma_f32_16x16x32_bf16 v[64:67], v[166:169], v[182:185], v[64:67]
	v_mfma_f32_16x16x32_bf16 v[56:59], v[174:177], v[182:185], v[56:59]
	v_mfma_f32_16x16x32_bf16 v[48:51], v[166:169], v[190:193], v[48:51]
	v_mfma_f32_16x16x32_bf16 v[40:43], v[174:177], v[190:193], v[40:43]
	v_mfma_f32_16x16x32_bf16 v[32:35], v[166:169], v[210:213], v[32:35]
	v_mfma_f32_16x16x32_bf16 v[24:27], v[174:177], v[210:213], v[24:27]
	v_mfma_f32_16x16x32_bf16 v[8:11], v[166:169], v[218:221], v[8:11]
	v_mfma_f32_16x16x32_bf16 v[16:19], v[174:177], v[218:221], v[16:19]
	s_setprio 0
	s_barrier
	s_add_i32 s67, s67, 2
	s_add_u32 s46, s46, 0x100
	s_addc_u32 s47, s47, 0
	s_add_u32 s65, s65, 0x100
	s_addc_u32 s66, s66, 0
	s_cmp_gt_u32 s67, 13
	s_cbranch_scc0 .LBB0_1088
	s_and_b64 vcc, exec, s[12:13]
	s_cbranch_vccz .LBB0_1091
	s_barrier

; #define PG8_STAGE(bufoff, gbase, voff) do { _Pragma("unroll") for (int _i = 0; _i < 2; ++_i) \
;         __builtin_amdgcn_global_load_lds((const unsigned*)((const char*)(gbase) + (voff)[_i]), (LAS unsigned*)(lds + (bufoff) + ldsw + _i * 8192), 16, 0, 0); } while (0)
; #define PG8_LDA(dst, b, h) do { _Pragma("unroll") for (int m = 0; m < 4; ++m) _Pragma("unroll") for (int k = 0; k < 2; ++k) dst[m][k] = *(const LAS bf16x8*)(lds + PG8_SA(b, h) + aoff + m * 2048 + k * 1024); } while (0)
; #define PG8_LDB(dst, b, h) do { _Pragma("unroll") for (int n = 0; n < 2; ++n) _Pragma("unroll") for (int k = 0; k < 2; ++k) dst[n][k] = *(const LAS bf16x8*)(lds + PG8_SB(b, h) + boff + n * 2048 + k * 1024); } while (0)
; #define PG8_MMA(ai, bj, At, Bt) do { __builtin_amdgcn_s_setprio(1); _Pragma("unroll") for (int m = 0; m < 4; ++m) _Pragma("unroll") for (int n = 0; n < 2; ++n) _Pragma("unroll") for (int k = 0; k < 2; ++k) \
;         acc[ai][bj][m][n] = __builtin_amdgcn_mfma_f32_16x16x32_bf16(Bt[n][k], At[m][k], acc[ai][bj][m][n], 0, 0, 0); __builtin_amdgcn_s_setprio(0); } while (0)
; #define PG8_WAIT_V(n) asm volatile("s_waitcnt vmcnt(" #n ")" ::: "memory")
; #define PG8_WAIT_L(n) asm volatile("s_waitcnt lgkmcnt(" #n ")" ::: "memory")
; #define PG8_BAR __builtin_amdgcn_s_barrier()
; #define PG8_SCHED __builtin_amdgcn_sched_barrier(0)
; template <class Epi>
; __device__ __forceinline__ void gemm_phase(LAS unsigned char* lds, const Gemm g, const StaticOrder& S, const Epi& E) {
;     ...
;         for (int t = 0; t < nt; t += 2) {
;             const bool last = (t == nt - 2);
;             const char* a1 = cA + (size_t)(t + 1) * kstep;
;             const char* a2 = last ? nA : cA + (size_t)(t + 2) * kstep; const char* b2 = last ? nB : cB + (size_t)(t + 2) * kstep;
;             const char* a3 = a2 + kstep; const char* b3 = b2 + kstep;
;             PG8_LDB(B0, 0, 0); PG8_LDB(B1, 0, 1); PG8_SCHED; PG8_LDA(At, 0, 0); PG8_STAGE(PG8_SA(1, 1), a1 + hstepA, voffA);
;             PG8_WAIT_V(8); PG8_WAIT_L(0); PG8_BAR; PG8_MMA(0, 0, At, B0); PG8_MMA(0, 1, At, B1); PG8_BAR; PG8_SCHED;
;             PG8_LDA(At, 0, 1); PG8_STAGE(PG8_SB(0, 0), b2, voffB); PG8_STAGE(PG8_SB(0, 1), b2 + hstepB, voffB); PG8_STAGE(PG8_SA(0, 0), a2, voffA);
.LBB0_1163:
	s_add_u32 s48, s46, 0x100
	s_addc_u32 s49, s47, 0
	s_add_i32 s70, 0, 0x10000
	s_cmp_eq_u32 s69, 40
	s_cselect_b32 s51, s5, s49
	s_cselect_b32 s50, s4, s48
	s_cselect_b32 s23, s39, s68
	s_cselect_b32 s22, s38, s67
	s_add_i32 s71, 0, 0x14000
	v_add_u32_e32 v144, s70, v232
	v_add_u32_e32 v160, s71, v232
	ds_read_b128 v[132:135], v144
	ds_read_b128 v[136:139], v144 offset:1024
	ds_read_b128 v[140:143], v144 offset:2048
	ds_read_b128 v[144:147], v144 offset:3072
	ds_read_b128 v[148:151], v160
	ds_read_b128 v[152:155], v160 offset:1024
	ds_read_b128 v[156:159], v160 offset:2048
	ds_read_b128 v[160:163], v160 offset:3072
	v_lshl_add_u64 v[216:217], s[46:47], 0, v[194:195]
	s_add_i32 m0, s57, 0xc000
	ds_read_b128 v[164:167], v242
	ds_read_b128 v[168:171], v242 offset:1024
	ds_read_b128 v[172:175], v242 offset:2048
	ds_read_b128 v[176:179], v242 offset:3072
	ds_read_b128 v[180:183], v242 offset:4096
	ds_read_b128 v[184:187], v242 offset:5120
	ds_read_b128 v[196:199], v242 offset:6144
	ds_read_b128 v[212:215], v242 offset:7168
	global_load_lds_dwordx4 v[216:217], off
	v_lshl_add_u64 v[216:217], s[46:47], 0, v[210:211]
	s_add_i32 m0, s57, 0xe000
	s_nop 0
	global_load_lds_dwordx4 v[216:217], off
	s_waitcnt vmcnt(8)
	s_waitcnt lgkmcnt(0)
	s_barrier
	s_setprio 1
	v_mfma_f32_16x16x32_bf16 v[128:131], v[132:135], v[164:167], v[128:131]
	v_mfma_f32_16x16x32_bf16 v[124:127], v[140:143], v[164:167], v[124:127]
	v_mfma_f32_16x16x32_bf16 v[112:115], v[132:135], v[172:175], v[112:115]
	v_mfma_f32_16x16x32_bf16 v[108:111], v[140:143], v[172:175], v[108:111]
	v_mfma_f32_16x16x32_bf16 v[96:99], v[132:135], v[180:183], v[96:99]
	v_mfma_f32_16x16x32_bf16 v[92:95], v[140:143], v[180:183], v[92:95]
	v_mfma_f32_16x16x32_bf16 v[80:83], v[132:135], v[196:199], v[80:83]
	v_mfma_f32_16x16x32_bf16 v[76:79], v[140:143], v[196:199], v[76:79]
	v_mfma_f32_16x16x32_bf16 v[128:131], v[136:139], v[168:171], v[128:131]
	v_mfma_f32_16x16x32_bf16 v[124:127], v[144:147], v[168:171], v[124:127]
	v_mfma_f32_16x16x32_bf16 v[112:115], v[136:139], v[176:179], v[112:115]
	v_mfma_f32_16x16x32_bf16 v[108:111], v[144:147], v[176:179], v[108:111]
	v_mfma_f32_16x16x32_bf16 v[96:99], v[136:139], v[184:187], v[96:99]
	v_mfma_f32_16x16x32_bf16 v[92:95], v[144:147], v[184:187], v[92:95]
	v_mfma_f32_16x16x32_bf16 v[80:83], v[136:139], v[212:215], v[80:83]
	v_mfma_f32_16x16x32_bf16 v[76:79], v[144:147], v[212:215], v[76:79]
	s_setprio 0
	s_setprio 1
	v_mfma_f32_16x16x32_bf16 v[120:123], v[148:151], v[164:167], v[120:123]
	v_mfma_f32_16x16x32_bf16 v[116:119], v[156:159], v[164:167], v[116:119]
	v_mfma_f32_16x16x32_bf16 v[104:107], v[148:151], v[172:175], v[104:107]
	v_mfma_f32_16x16x32_bf16 v[100:103], v[156:159], v[172:175], v[100:103]
	v_mfma_f32_16x16x32_bf16 v[88:91], v[148:151], v[180:183], v[88:91]
	v_mfma_f32_16x16x32_bf16 v[84:87], v[156:159], v[180:183], v[84:87]
	v_mfma_f32_16x16x32_bf16 v[72:75], v[148:151], v[196:199], v[72:75]
	v_mfma_f32_16x16x32_bf16 v[68:71], v[156:159], v[196:199], v[68:71]
	v_mfma_f32_16x16x32_bf16 v[120:123], v[152:155], v[168:171], v[120:123]
	v_mfma_f32_16x16x32_bf16 v[116:119], v[160:163], v[168:171], v[116:119]
	v_mfma_f32_16x16x32_bf16 v[104:107], v[152:155], v[176:179], v[104:107]
	v_mfma_f32_16x16x32_bf16 v[100:103], v[160:163], v[176:179], v[100:103]
	v_mfma_f32_16x16x32_bf16 v[88:91], v[152:155], v[184:187], v[88:91]
	v_mfma_f32_16x16x32_bf16 v[84:87], v[160:163], v[184:187], v[84:87]
	v_mfma_f32_16x16x32_bf16 v[72:75], v[152:155], v[212:215], v[72:75]
	v_mfma_f32_16x16x32_bf16 v[68:71], v[160:163], v[212:215], v[68:71]
	s_setprio 0
	s_barrier
	s_add_i32 s46, s70, s56
	v_lshl_add_u64 v[216:217], s[22:23], 0, v[190:191]
	s_mov_b32 m0, s46
	ds_read_b128 v[164:167], v242 offset:16384
	ds_read_b128 v[168:171], v242 offset:17408
	ds_read_b128 v[172:175], v242 offset:18432
	ds_read_b128 v[176:179], v242 offset:19456
	ds_read_b128 v[180:183], v242 offset:20480
	ds_read_b128 v[184:187], v242 offset:21504
	ds_read_b128 v[196:199], v242 offset:22528
	ds_read_b128 v[212:215], v242 offset:23552
	global_load_lds_dwordx4 v[216:217], off
	s_add_i32 m0, s46, 0x2000
	s_add_u32 s46, s22, 0x2c000
	v_lshl_add_u64 v[218:219], s[22:23], 0, v[0:1]
	s_addc_u32 s47, s23, 0
	s_add_i32 s70, s71, s56
	global_load_lds_dwordx4 v[218:219], off
	v_lshl_add_u64 v[220:221], s[46:47], 0, v[190:191]
	s_mov_b32 m0, s70
	v_lshl_add_u64 v[222:223], s[50:51], 0, v[188:189]
	global_load_lds_dwordx4 v[220:221], off
	v_lshl_add_u64 v[220:221], s[46:47], 0, v[0:1]
	s_add_i32 m0, s70, 0x2000
	s_nop 0
	global_load_lds_dwordx4 v[220:221], off
	v_lshl_add_u64 v[220:221], s[50:51], 0, v[192:193]
	s_mov_b32 m0, s57
	s_nop 0
	global_load_lds_dwordx4 v[220:221], off
	s_mov_b32 m0, s58
	s_nop 0
	global_load_lds_dwordx4 v[222:223], off
	s_waitcnt vmcnt(8)
	s_waitcnt lgkmcnt(0)
	s_barrier
; #define PG8_STAGE(bufoff, gbase, voff) do { _Pragma("unroll") for (int _i = 0; _i < 2; ++_i) \
;         __builtin_amdgcn_global_load_lds((const unsigned*)((const char*)(gbase) + (voff)[_i]), (LAS unsigned*)(lds + (bufoff) + ldsw + _i * 8192), 16, 0, 0); } while (0)
; #define PG8_LDA(dst, b, h) do { _Pragma("unroll") for (int m = 0; m < 4; ++m) _Pragma("unroll") for (int k = 0; k < 2; ++k) dst[m][k] = *(const LAS bf16x8*)(lds + PG8_SA(b, h) + aoff + m * 2048 + k * 1024); } while (0)
; #define PG8_LDB(dst, b, h) do { _Pragma("unroll") for (int n = 0; n < 2; ++n) _Pragma("unroll") for (int k = 0; k < 2; ++k) dst[n][k] = *(const LAS bf16x8*)(lds + PG8_SB(b, h) + boff + n * 2048 + k * 1024); } while (0)
; #define PG8_MMA(ai, bj, At, Bt) do { __builtin_amdgcn_s_setprio(1); _Pragma("unroll") for (int m = 0; m < 4; ++m) _Pragma("unroll") for (int n = 0; n < 2; ++n) _Pragma("unroll") for (int k = 0; k < 2; ++k) \
;         acc[ai][bj][m][n] = __builtin_amdgcn_mfma_f32_16x16x32_bf16(Bt[n][k], At[m][k], acc[ai][bj][m][n], 0, 0, 0); __builtin_amdgcn_s_setprio(0); } while (0)
; #define PG8_WAIT_V(n) asm volatile("s_waitcnt vmcnt(" #n ")" ::: "memory")
; #define PG8_WAIT_L(n) asm volatile("s_waitcnt lgkmcnt(" #n ")" ::: "memory")
; #define PG8_BAR __builtin_amdgcn_s_barrier()
; #define PG8_SCHED __builtin_amdgcn_sched_barrier(0)
; template <class Epi>
; __device__ __forceinline__ void gemm_phase(LAS unsigned char* lds, const Gemm g, const StaticOrder& S, const Epi& E) {
;     ...
;             PG8_WAIT_V(8); PG8_WAIT_L(0); PG8_BAR; PG8_MMA(1, 0, At, B0); PG8_MMA(1, 1, At, B1); PG8_BAR; PG8_SCHED;
;             PG8_LDB(B0, 1, 0); PG8_LDB(B1, 1, 1); PG8_SCHED; PG8_LDA(At, 1, 0); PG8_STAGE(PG8_SA(0, 1), a2 + hstepA, voffA);
;             PG8_WAIT_V(8); PG8_WAIT_L(0); PG8_BAR; PG8_MMA(0, 0, At, B0); PG8_MMA(0, 1, At, B1); PG8_BAR; PG8_SCHED;
	s_setprio 1
	v_mfma_f32_16x16x32_bf16 v[64:67], v[132:135], v[164:167], v[64:67]
	v_mfma_f32_16x16x32_bf16 v[60:63], v[140:143], v[164:167], v[60:63]
	v_mfma_f32_16x16x32_bf16 v[48:51], v[132:135], v[172:175], v[48:51]
	v_mfma_f32_16x16x32_bf16 v[44:47], v[140:143], v[172:175], v[44:47]
	v_mfma_f32_16x16x32_bf16 v[32:35], v[132:135], v[180:183], v[32:35]
	v_mfma_f32_16x16x32_bf16 v[28:31], v[140:143], v[180:183], v[28:31]
	v_mfma_f32_16x16x32_bf16 v[16:19], v[132:135], v[196:199], v[16:19]
	v_mfma_f32_16x16x32_bf16 v[12:15], v[140:143], v[196:199], v[12:15]
	v_mfma_f32_16x16x32_bf16 v[64:67], v[136:139], v[168:171], v[64:67]
	v_mfma_f32_16x16x32_bf16 v[60:63], v[144:147], v[168:171], v[60:63]
	v_mfma_f32_16x16x32_bf16 v[48:51], v[136:139], v[176:179], v[48:51]
	v_mfma_f32_16x16x32_bf16 v[44:47], v[144:147], v[176:179], v[44:47]
	v_mfma_f32_16x16x32_bf16 v[32:35], v[136:139], v[184:187], v[32:35]
	v_mfma_f32_16x16x32_bf16 v[28:31], v[144:147], v[184:187], v[28:31]
	v_mfma_f32_16x16x32_bf16 v[16:19], v[136:139], v[212:215], v[16:19]
	v_mfma_f32_16x16x32_bf16 v[12:15], v[144:147], v[212:215], v[12:15]
	s_setprio 0
	s_setprio 1
	v_mfma_f32_16x16x32_bf16 v[56:59], v[148:151], v[164:167], v[56:59]
	v_mfma_f32_16x16x32_bf16 v[52:55], v[156:159], v[164:167], v[52:55]
	v_mfma_f32_16x16x32_bf16 v[40:43], v[148:151], v[172:175], v[40:43]
	v_mfma_f32_16x16x32_bf16 v[36:39], v[156:159], v[172:175], v[36:39]
	v_mfma_f32_16x16x32_bf16 v[24:27], v[148:151], v[180:183], v[24:27]
	v_mfma_f32_16x16x32_bf16 v[20:23], v[156:159], v[180:183], v[20:23]
	v_mfma_f32_16x16x32_bf16 v[8:11], v[148:151], v[196:199], v[8:11]
	v_mfma_f32_16x16x32_bf16 v[4:7], v[156:159], v[196:199], v[4:7]
	v_mfma_f32_16x16x32_bf16 v[56:59], v[152:155], v[168:171], v[56:59]
	v_mfma_f32_16x16x32_bf16 v[52:55], v[160:163], v[168:171], v[52:55]
	v_mfma_f32_16x16x32_bf16 v[40:43], v[152:155], v[176:179], v[40:43]
	v_mfma_f32_16x16x32_bf16 v[36:39], v[160:163], v[176:179], v[36:39]
	v_mfma_f32_16x16x32_bf16 v[24:27], v[152:155], v[184:187], v[24:27]
	v_mfma_f32_16x16x32_bf16 v[20:23], v[160:163], v[184:187], v[20:23]
	v_mfma_f32_16x16x32_bf16 v[8:11], v[152:155], v[212:215], v[8:11]
	v_mfma_f32_16x16x32_bf16 v[4:7], v[160:163], v[212:215], v[4:7]
	s_setprio 0
	s_barrier
	s_add_i32 s70, 0, 0x18000
	s_add_i32 s71, 0, 0x1c000
	v_add_u32_e32 v144, s70, v232
	v_add_u32_e32 v160, s71, v232
	ds_read_b128 v[132:135], v144
	ds_read_b128 v[136:139], v144 offset:1024
	ds_read_b128 v[140:143], v144 offset:2048
	ds_read_b128 v[144:147], v144 offset:3072
	ds_read_b128 v[148:151], v160
	ds_read_b128 v[152:155], v160 offset:1024
	ds_read_b128 v[156:159], v160 offset:2048
	ds_read_b128 v[160:163], v160 offset:3072
	s_add_u32 s46, s50, 0xb0000
	s_addc_u32 s47, s51, 0
	s_mov_b32 m0, s59
	v_lshl_add_u64 v[224:225], s[46:47], 0, v[192:193]
	ds_read_b128 v[164:167], v242 offset:32768
	ds_read_b128 v[168:171], v242 offset:33792
	ds_read_b128 v[172:175], v242 offset:34816
	ds_read_b128 v[176:179], v242 offset:35840
	ds_read_b128 v[180:183], v242 offset:36864
	ds_read_b128 v[184:187], v242 offset:37888
	ds_read_b128 v[196:199], v242 offset:38912
	ds_read_b128 v[212:215], v242 offset:39936
	global_load_lds_dwordx4 v[224:225], off
	v_lshl_add_u64 v[224:225], s[46:47], 0, v[188:189]
	s_mov_b32 m0, s60
	s_nop 0
	global_load_lds_dwordx4 v[224:225], off
	s_waitcnt vmcnt(8)
	s_waitcnt lgkmcnt(0)
	s_barrier
	s_setprio 1
	v_mfma_f32_16x16x32_bf16 v[128:131], v[132:135], v[164:167], v[128:131]
	v_mfma_f32_16x16x32_bf16 v[124:127], v[140:143], v[164:167], v[124:127]
	v_mfma_f32_16x16x32_bf16 v[112:115], v[132:135], v[172:175], v[112:115]
	v_mfma_f32_16x16x32_bf16 v[108:111], v[140:143], v[172:175], v[108:111]
	v_mfma_f32_16x16x32_bf16 v[96:99], v[132:135], v[180:183], v[96:99]
	v_mfma_f32_16x16x32_bf16 v[92:95], v[140:143], v[180:183], v[92:95]
	v_mfma_f32_16x16x32_bf16 v[80:83], v[132:135], v[196:199], v[80:83]
	v_mfma_f32_16x16x32_bf16 v[76:79], v[140:143], v[196:199], v[76:79]
	v_mfma_f32_16x16x32_bf16 v[128:131], v[136:139], v[168:171], v[128:131]
	v_mfma_f32_16x16x32_bf16 v[124:127], v[144:147], v[168:171], v[124:127]
	v_mfma_f32_16x16x32_bf16 v[112:115], v[136:139], v[176:179], v[112:115]
	v_mfma_f32_16x16x32_bf16 v[108:111], v[144:147], v[176:179], v[108:111]
	v_mfma_f32_16x16x32_bf16 v[96:99], v[136:139], v[184:187], v[96:99]
	v_mfma_f32_16x16x32_bf16 v[92:95], v[144:147], v[184:187], v[92:95]
	v_mfma_f32_16x16x32_bf16 v[80:83], v[136:139], v[212:215], v[80:83]
	v_mfma_f32_16x16x32_bf16 v[76:79], v[144:147], v[212:215], v[76:79]
	s_setprio 0
	s_setprio 1
	v_mfma_f32_16x16x32_bf16 v[120:123], v[148:151], v[164:167], v[120:123]
	v_mfma_f32_16x16x32_bf16 v[116:119], v[156:159], v[164:167], v[116:119]
	v_mfma_f32_16x16x32_bf16 v[104:107], v[148:151], v[172:175], v[104:107]
	v_mfma_f32_16x16x32_bf16 v[100:103], v[156:159], v[172:175], v[100:103]
	v_mfma_f32_16x16x32_bf16 v[88:91], v[148:151], v[180:183], v[88:91]
	v_mfma_f32_16x16x32_bf16 v[84:87], v[156:159], v[180:183], v[84:87]
	v_mfma_f32_16x16x32_bf16 v[72:75], v[148:151], v[196:199], v[72:75]
	v_mfma_f32_16x16x32_bf16 v[68:71], v[156:159], v[196:199], v[68:71]
	v_mfma_f32_16x16x32_bf16 v[120:123], v[152:155], v[168:171], v[120:123]
	v_mfma_f32_16x16x32_bf16 v[116:119], v[160:163], v[168:171], v[116:119]
	v_mfma_f32_16x16x32_bf16 v[104:107], v[152:155], v[176:179], v[104:107]
	v_mfma_f32_16x16x32_bf16 v[100:103], v[160:163], v[176:179], v[100:103]
	v_mfma_f32_16x16x32_bf16 v[88:91], v[152:155], v[184:187], v[88:91]
	v_mfma_f32_16x16x32_bf16 v[84:87], v[160:163], v[184:187], v[84:87]
	v_mfma_f32_16x16x32_bf16 v[72:75], v[152:155], v[212:215], v[72:75]
	v_mfma_f32_16x16x32_bf16 v[68:71], v[160:163], v[212:215], v[68:71]
	s_setprio 0
	s_barrier
; #define PG8_STAGE(bufoff, gbase, voff) do { _Pragma("unroll") for (int _i = 0; _i < 2; ++_i) \
;         __builtin_amdgcn_global_load_lds((const unsigned*)((const char*)(gbase) + (voff)[_i]), (LAS unsigned*)(lds + (bufoff) + ldsw + _i * 8192), 16, 0, 0); } while (0)
; #define PG8_LDA(dst, b, h) do { _Pragma("unroll") for (int m = 0; m < 4; ++m) _Pragma("unroll") for (int k = 0; k < 2; ++k) dst[m][k] = *(const LAS bf16x8*)(lds + PG8_SA(b, h) + aoff + m * 2048 + k * 1024); } while (0)
; #define PG8_MMA(ai, bj, At, Bt) do { __builtin_amdgcn_s_setprio(1); _Pragma("unroll") for (int m = 0; m < 4; ++m) _Pragma("unroll") for (int n = 0; n < 2; ++n) _Pragma("unroll") for (int k = 0; k < 2; ++k) \
;         acc[ai][bj][m][n] = __builtin_amdgcn_mfma_f32_16x16x32_bf16(Bt[n][k], At[m][k], acc[ai][bj][m][n], 0, 0, 0); __builtin_amdgcn_s_setprio(0); } while (0)
; #define PG8_WAIT_V(n) asm volatile("s_waitcnt vmcnt(" #n ")" ::: "memory")
; #define PG8_WAIT_L(n) asm volatile("s_waitcnt lgkmcnt(" #n ")" ::: "memory")
; #define PG8_BAR __builtin_amdgcn_s_barrier()
; #define PG8_SCHED __builtin_amdgcn_sched_barrier(0)
; template <class Epi>
; __device__ __forceinline__ void gemm_phase(LAS unsigned char* lds, const Gemm g, const StaticOrder& S, const Epi& E) {
;     ...
;             PG8_LDA(At, 1, 1); PG8_STAGE(PG8_SB(1, 0), b3, voffB); PG8_STAGE(PG8_SB(1, 1), b3 + hstepB, voffB); PG8_STAGE(PG8_SA(1, 0), a3, voffA);
;             PG8_WAIT_V(8); PG8_WAIT_L(0); PG8_BAR; PG8_MMA(1, 0, At, B0); PG8_MMA(1, 1, At, B1); PG8_BAR; PG8_SCHED;
;         }
;         if (wr == 0) PG8_BAR;
	s_add_i32 s46, s70, s56
	v_lshl_add_u64 v[216:217], v[216:217], 0, s[30:31]
	s_mov_b32 m0, s46
	ds_read_b128 v[164:167], v242 offset:49152
	ds_read_b128 v[168:171], v242 offset:50176
	ds_read_b128 v[172:175], v242 offset:51200
	ds_read_b128 v[176:179], v242 offset:52224
	ds_read_b128 v[180:183], v242 offset:53248
	ds_read_b128 v[184:187], v242 offset:54272
	ds_read_b128 v[196:199], v242 offset:55296
	ds_read_b128 v[212:215], v242 offset:56320
	global_load_lds_dwordx4 v[216:217], off
	s_add_i32 m0, s46, 0x2000
	s_add_u32 s22, s22, 0x2c080
	v_lshl_add_u64 v[216:217], v[218:219], 0, s[30:31]
	s_addc_u32 s23, s23, 0
	s_add_i32 s46, s71, s56
	global_load_lds_dwordx4 v[216:217], off
	v_lshl_add_u64 v[216:217], s[22:23], 0, v[190:191]
	s_mov_b32 m0, s46
	s_nop 0
	global_load_lds_dwordx4 v[216:217], off
	v_lshl_add_u64 v[216:217], s[22:23], 0, v[0:1]
	s_add_i32 m0, s46, 0x2000
	s_nop 0
	global_load_lds_dwordx4 v[216:217], off
	v_lshl_add_u64 v[216:217], v[220:221], 0, s[30:31]
	s_mov_b32 m0, s28
	s_nop 0
	global_load_lds_dwordx4 v[216:217], off
	v_lshl_add_u64 v[216:217], v[222:223], 0, s[30:31]
	s_mov_b32 m0, s61
	s_nop 0
	global_load_lds_dwordx4 v[216:217], off
	s_waitcnt vmcnt(8)
	s_waitcnt lgkmcnt(0)
	s_barrier
	s_setprio 1
	v_mfma_f32_16x16x32_bf16 v[64:67], v[132:135], v[164:167], v[64:67]
	v_mfma_f32_16x16x32_bf16 v[60:63], v[140:143], v[164:167], v[60:63]
	v_mfma_f32_16x16x32_bf16 v[48:51], v[132:135], v[172:175], v[48:51]
	v_mfma_f32_16x16x32_bf16 v[44:47], v[140:143], v[172:175], v[44:47]
	v_mfma_f32_16x16x32_bf16 v[32:35], v[132:135], v[180:183], v[32:35]
	v_mfma_f32_16x16x32_bf16 v[28:31], v[140:143], v[180:183], v[28:31]
	v_mfma_f32_16x16x32_bf16 v[16:19], v[132:135], v[196:199], v[16:19]
	v_mfma_f32_16x16x32_bf16 v[12:15], v[140:143], v[196:199], v[12:15]
	v_mfma_f32_16x16x32_bf16 v[64:67], v[136:139], v[168:171], v[64:67]
	v_mfma_f32_16x16x32_bf16 v[60:63], v[144:147], v[168:171], v[60:63]
	v_mfma_f32_16x16x32_bf16 v[48:51], v[136:139], v[176:179], v[48:51]
	v_mfma_f32_16x16x32_bf16 v[44:47], v[144:147], v[176:179], v[44:47]
	v_mfma_f32_16x16x32_bf16 v[32:35], v[136:139], v[184:187], v[32:35]
	v_mfma_f32_16x16x32_bf16 v[28:31], v[144:147], v[184:187], v[28:31]
	v_mfma_f32_16x16x32_bf16 v[16:19], v[136:139], v[212:215], v[16:19]
	v_mfma_f32_16x16x32_bf16 v[12:15], v[144:147], v[212:215], v[12:15]
	s_setprio 0
	s_setprio 1
	v_mfma_f32_16x16x32_bf16 v[56:59], v[148:151], v[164:167], v[56:59]
	v_mfma_f32_16x16x32_bf16 v[52:55], v[156:159], v[164:167], v[52:55]
	v_mfma_f32_16x16x32_bf16 v[40:43], v[148:151], v[172:175], v[40:43]
	v_mfma_f32_16x16x32_bf16 v[36:39], v[156:159], v[172:175], v[36:39]
	v_mfma_f32_16x16x32_bf16 v[24:27], v[148:151], v[180:183], v[24:27]
	v_mfma_f32_16x16x32_bf16 v[20:23], v[156:159], v[180:183], v[20:23]
	v_mfma_f32_16x16x32_bf16 v[8:11], v[148:151], v[196:199], v[8:11]
	v_mfma_f32_16x16x32_bf16 v[4:7], v[156:159], v[196:199], v[4:7]
	v_mfma_f32_16x16x32_bf16 v[56:59], v[152:155], v[168:171], v[56:59]
	v_mfma_f32_16x16x32_bf16 v[52:55], v[160:163], v[168:171], v[52:55]
	v_mfma_f32_16x16x32_bf16 v[40:43], v[152:155], v[176:179], v[40:43]
	v_mfma_f32_16x16x32_bf16 v[36:39], v[160:163], v[176:179], v[36:39]
	v_mfma_f32_16x16x32_bf16 v[24:27], v[152:155], v[184:187], v[24:27]
	v_mfma_f32_16x16x32_bf16 v[20:23], v[160:163], v[184:187], v[20:23]
	v_mfma_f32_16x16x32_bf16 v[8:11], v[152:155], v[212:215], v[8:11]
	v_mfma_f32_16x16x32_bf16 v[4:7], v[160:163], v[212:215], v[4:7]
	s_setprio 0
	s_barrier
	s_add_i32 s69, s69, 2
	s_add_u32 s67, s67, 0x100
	s_addc_u32 s68, s68, 0
	s_cmp_gt_u32 s69, 41
	s_mov_b64 s[46:47], s[48:49]
	s_cbranch_scc0 .LBB0_1163
	s_and_b64 vcc, exec, s[34:35]
	s_cbranch_vccz .LBB0_1166
	s_barrier

; #define PG8_STAGE(bufoff, gbase, voff) do { _Pragma("unroll") for (int _i = 0; _i < 2; ++_i) \
;         __builtin_amdgcn_global_load_lds((const unsigned*)((const char*)(gbase) + (voff)[_i]), (LAS unsigned*)(lds + (bufoff) + ldsw + _i * 8192), 16, 0, 0); } while (0)
; #define PG8_LDA(dst, b, h) do { _Pragma("unroll") for (int m = 0; m < 4; ++m) _Pragma("unroll") for (int k = 0; k < 2; ++k) dst[m][k] = *(const LAS bf16x8*)(lds + PG8_SA(b, h) + aoff + m * 2048 + k * 1024); } while (0)
; #define PG8_LDB(dst, b, h) do { _Pragma("unroll") for (int n = 0; n < 2; ++n) _Pragma("unroll") for (int k = 0; k < 2; ++k) dst[n][k] = *(const LAS bf16x8*)(lds + PG8_SB(b, h) + boff + n * 2048 + k * 1024); } while (0)
; #define PG8_MMA(ai, bj, At, Bt) do { __builtin_amdgcn_s_setprio(1); _Pragma("unroll") for (int m = 0; m < 4; ++m) _Pragma("unroll") for (int n = 0; n < 2; ++n) _Pragma("unroll") for (int k = 0; k < 2; ++k) \
;         acc[ai][bj][m][n] = __builtin_amdgcn_mfma_f32_16x16x32_bf16(Bt[n][k], At[m][k], acc[ai][bj][m][n], 0, 0, 0); __builtin_amdgcn_s_setprio(0); } while (0)
; #define PG8_WAIT_V(n) asm volatile("s_waitcnt vmcnt(" #n ")" ::: "memory")
; #define PG8_WAIT_L(n) asm volatile("s_waitcnt lgkmcnt(" #n ")" ::: "memory")
; #define PG8_BAR __builtin_amdgcn_s_barrier()
; #define PG8_SCHED __builtin_amdgcn_sched_barrier(0)
; template <class Epi>
; __device__ __forceinline__ void gemm_phase(LAS unsigned char* lds, const Gemm g, const StaticOrder& S, const Epi& E) {
;     ...
;         for (int t = 0; t < nt; t += 2) {
;             const bool last = (t == nt - 2);
;             const char* a1 = cA + (size_t)(t + 1) * kstep;
;             const char* a2 = last ? nA : cA + (size_t)(t + 2) * kstep; const char* b2 = last ? nB : cB + (size_t)(t + 2) * kstep;
;             const char* a3 = a2 + kstep; const char* b3 = b2 + kstep;
;             PG8_LDB(B0, 0, 0); PG8_LDB(B1, 0, 1); PG8_SCHED; PG8_LDA(At, 0, 0); PG8_STAGE(PG8_SA(1, 1), a1 + hstepA, voffA);
;             PG8_WAIT_V(8); PG8_WAIT_L(0); PG8_BAR; PG8_MMA(0, 0, At, B0); PG8_MMA(0, 1, At, B1); PG8_BAR; PG8_SCHED;
;             PG8_LDA(At, 0, 1); PG8_STAGE(PG8_SB(0, 0), b2, voffB); PG8_STAGE(PG8_SB(0, 1), b2 + hstepB, voffB); PG8_STAGE(PG8_SA(0, 0), a2, voffA);
.LBB0_1250:
	s_add_u32 s56, s38, s22
	s_addc_u32 s57, s39, 0
	s_add_u32 s23, s56, 0x100
	s_addc_u32 s54, s57, 0
	s_and_b64 s[52:53], s[50:51], exec
	s_cselect_b32 s53, s35, s54
	s_cselect_b32 s52, s74, s23
	s_add_u32 s22, s12, s22
	s_addc_u32 s23, s13, 0
	s_add_u32 s54, s22, 0x100
	s_addc_u32 s55, s23, 0
	s_add_i32 s84, 0, 0x10000
	s_and_b64 s[22:23], s[50:51], exec
	s_cselect_b32 s55, s15, s55
	s_cselect_b32 s54, s75, s54
	s_add_i32 s51, 0, 0x14000
	s_add_u32 s58, s56, 0x10080
	s_addc_u32 s59, s57, 0
	s_add_i32 s83, s84, s64
	s_add_i32 m0, s65, 0xc000
	s_add_i32 s86, s65, 0xe000
	s_add_i32 s80, s83, 0x2000
	v_add_u32_e32 v141, s84, v138
	s_add_u32 s56, s54, 0x4000
	ds_read_b128 v[142:145], v141
	ds_read_b128 v[146:149], v141 offset:1024
	ds_read_b128 v[150:153], v141 offset:2048
	ds_read_b128 v[154:157], v141 offset:3072
	v_add_u32_e32 v141, s51, v138
	s_addc_u32 s57, s55, 0
	s_add_i32 s82, s51, s64
	ds_read_b128 v[158:161], v141
	ds_read_b128 v[162:165], v141 offset:1024
	ds_read_b128 v[166:169], v141 offset:2048
	ds_read_b128 v[170:173], v141 offset:3072
	s_add_i32 s81, s82, 0x2000
	s_add_i32 s79, 0, 0x18000
	s_add_i32 s78, 0, 0x1c000
	s_add_u32 s22, s52, 0x10000
	s_addc_u32 s23, s53, 0
	s_add_i32 s77, s79, s64
	s_add_i32 s76, s77, 0x2000
	s_add_u32 s50, s54, 0x4080
	s_addc_u32 s51, s55, 0
	s_add_i32 s85, s78, s64
	s_add_i32 s84, s85, 0x2000
	v_lshl_add_u64 v[198:199], s[58:59], 0, v[136:137]
	ds_read_b128 v[174:177], v140
	ds_read_b128 v[178:181], v140 offset:1024
	ds_read_b128 v[182:185], v140 offset:2048
	ds_read_b128 v[186:189], v140 offset:3072
	ds_read_b128 v[190:193], v140 offset:4096
	ds_read_b128 v[194:197], v140 offset:5120
	ds_read_b128 v[210:213], v140 offset:6144
	ds_read_b128 v[214:217], v140 offset:7168
	global_load_lds_dwordx4 v[198:199], off
	v_lshl_add_u64 v[198:199], s[58:59], 0, v[132:133]
	s_mov_b32 m0, s86
	s_nop 0
	global_load_lds_dwordx4 v[198:199], off
	s_waitcnt vmcnt(8)
	s_waitcnt lgkmcnt(0)
	s_barrier
	s_setprio 1
	v_mfma_f32_16x16x32_bf16 v[128:131], v[142:145], v[174:177], v[128:131]
	v_mfma_f32_16x16x32_bf16 v[124:127], v[150:153], v[174:177], v[124:127]
	v_mfma_f32_16x16x32_bf16 v[120:123], v[142:145], v[182:185], v[120:123]
	v_mfma_f32_16x16x32_bf16 v[116:119], v[150:153], v[182:185], v[116:119]
	v_mfma_f32_16x16x32_bf16 v[104:107], v[142:145], v[190:193], v[104:107]
	v_mfma_f32_16x16x32_bf16 v[100:103], v[150:153], v[190:193], v[100:103]
	v_mfma_f32_16x16x32_bf16 v[88:91], v[142:145], v[210:213], v[88:91]
	v_mfma_f32_16x16x32_bf16 v[84:87], v[150:153], v[210:213], v[84:87]
	v_mfma_f32_16x16x32_bf16 v[128:131], v[146:149], v[178:181], v[128:131]
	v_mfma_f32_16x16x32_bf16 v[124:127], v[154:157], v[178:181], v[124:127]
	v_mfma_f32_16x16x32_bf16 v[120:123], v[146:149], v[186:189], v[120:123]
	v_mfma_f32_16x16x32_bf16 v[116:119], v[154:157], v[186:189], v[116:119]
	v_mfma_f32_16x16x32_bf16 v[104:107], v[146:149], v[194:197], v[104:107]
	v_mfma_f32_16x16x32_bf16 v[100:103], v[154:157], v[194:197], v[100:103]
	v_mfma_f32_16x16x32_bf16 v[88:91], v[146:149], v[214:217], v[88:91]
	v_mfma_f32_16x16x32_bf16 v[84:87], v[154:157], v[214:217], v[84:87]
	s_setprio 0
	s_setprio 1
	v_mfma_f32_16x16x32_bf16 v[112:115], v[158:161], v[174:177], v[112:115]
	v_mfma_f32_16x16x32_bf16 v[108:111], v[166:169], v[174:177], v[108:111]
	v_mfma_f32_16x16x32_bf16 v[96:99], v[158:161], v[182:185], v[96:99]
	v_mfma_f32_16x16x32_bf16 v[92:95], v[166:169], v[182:185], v[92:95]
	v_mfma_f32_16x16x32_bf16 v[80:83], v[158:161], v[190:193], v[80:83]
	v_mfma_f32_16x16x32_bf16 v[76:79], v[166:169], v[190:193], v[76:79]
	v_mfma_f32_16x16x32_bf16 v[72:75], v[158:161], v[210:213], v[72:75]
	v_mfma_f32_16x16x32_bf16 v[68:71], v[166:169], v[210:213], v[68:71]
	v_mfma_f32_16x16x32_bf16 v[112:115], v[162:165], v[178:181], v[112:115]
	v_mfma_f32_16x16x32_bf16 v[108:111], v[170:173], v[178:181], v[108:111]
	v_mfma_f32_16x16x32_bf16 v[96:99], v[162:165], v[186:189], v[96:99]
	v_mfma_f32_16x16x32_bf16 v[92:95], v[170:173], v[186:189], v[92:95]
	v_mfma_f32_16x16x32_bf16 v[80:83], v[162:165], v[194:197], v[80:83]
	v_mfma_f32_16x16x32_bf16 v[76:79], v[170:173], v[194:197], v[76:79]
	v_mfma_f32_16x16x32_bf16 v[72:75], v[162:165], v[214:217], v[72:75]
	v_mfma_f32_16x16x32_bf16 v[68:71], v[170:173], v[214:217], v[68:71]
	s_setprio 0
	s_barrier
	s_mov_b32 m0, s83
	v_lshl_add_u64 v[198:199], s[54:55], 0, v[134:135]
	ds_read_b128 v[174:177], v140 offset:16384
	ds_read_b128 v[178:181], v140 offset:17408
	ds_read_b128 v[182:185], v140 offset:18432
	ds_read_b128 v[186:189], v140 offset:19456
	ds_read_b128 v[190:193], v140 offset:20480
	ds_read_b128 v[194:197], v140 offset:21504
	ds_read_b128 v[210:213], v140 offset:22528
	ds_read_b128 v[214:217], v140 offset:23552
	global_load_lds_dwordx4 v[198:199], off
	v_lshl_add_u64 v[218:219], s[54:55], 0, v[0:1]
	s_mov_b32 m0, s80
	v_lshl_add_u64 v[220:221], s[56:57], 0, v[134:135]
	global_load_lds_dwordx4 v[218:219], off
	s_mov_b32 m0, s82
	v_lshl_add_u64 v[222:223], s[52:53], 0, v[132:133]
	global_load_lds_dwordx4 v[220:221], off
	v_lshl_add_u64 v[220:221], s[56:57], 0, v[0:1]
	s_mov_b32 m0, s81
	s_nop 0
	global_load_lds_dwordx4 v[220:221], off
	v_lshl_add_u64 v[220:221], s[52:53], 0, v[136:137]
	s_mov_b32 m0, s65
	s_nop 0
	global_load_lds_dwordx4 v[220:221], off
	s_mov_b32 m0, s66
	s_nop 0
	global_load_lds_dwordx4 v[222:223], off
	s_waitcnt vmcnt(8)
	s_waitcnt lgkmcnt(0)
	s_barrier
; #define PG8_STAGE(bufoff, gbase, voff) do { _Pragma("unroll") for (int _i = 0; _i < 2; ++_i) \
;         __builtin_amdgcn_global_load_lds((const unsigned*)((const char*)(gbase) + (voff)[_i]), (LAS unsigned*)(lds + (bufoff) + ldsw + _i * 8192), 16, 0, 0); } while (0)
; #define PG8_LDA(dst, b, h) do { _Pragma("unroll") for (int m = 0; m < 4; ++m) _Pragma("unroll") for (int k = 0; k < 2; ++k) dst[m][k] = *(const LAS bf16x8*)(lds + PG8_SA(b, h) + aoff + m * 2048 + k * 1024); } while (0)
; #define PG8_LDB(dst, b, h) do { _Pragma("unroll") for (int n = 0; n < 2; ++n) _Pragma("unroll") for (int k = 0; k < 2; ++k) dst[n][k] = *(const LAS bf16x8*)(lds + PG8_SB(b, h) + boff + n * 2048 + k * 1024); } while (0)
; #define PG8_MMA(ai, bj, At, Bt) do { __builtin_amdgcn_s_setprio(1); _Pragma("unroll") for (int m = 0; m < 4; ++m) _Pragma("unroll") for (int n = 0; n < 2; ++n) _Pragma("unroll") for (int k = 0; k < 2; ++k) \
;         acc[ai][bj][m][n] = __builtin_amdgcn_mfma_f32_16x16x32_bf16(Bt[n][k], At[m][k], acc[ai][bj][m][n], 0, 0, 0); __builtin_amdgcn_s_setprio(0); } while (0)
; #define PG8_WAIT_V(n) asm volatile("s_waitcnt vmcnt(" #n ")" ::: "memory")
; #define PG8_WAIT_L(n) asm volatile("s_waitcnt lgkmcnt(" #n ")" ::: "memory")
; #define PG8_BAR __builtin_amdgcn_s_barrier()
; #define PG8_SCHED __builtin_amdgcn_sched_barrier(0)
; template <class Epi>
; __device__ __forceinline__ void gemm_phase(LAS unsigned char* lds, const Gemm g, const StaticOrder& S, const Epi& E) {
;     ...
;             PG8_WAIT_V(8); PG8_WAIT_L(0); PG8_BAR; PG8_MMA(1, 0, At, B0); PG8_MMA(1, 1, At, B1); PG8_BAR; PG8_SCHED;
;             PG8_LDB(B0, 1, 0); PG8_LDB(B1, 1, 1); PG8_SCHED; PG8_LDA(At, 1, 0); PG8_STAGE(PG8_SA(0, 1), a2 + hstepA, voffA);
;             PG8_WAIT_V(8); PG8_WAIT_L(0); PG8_BAR; PG8_MMA(0, 0, At, B0); PG8_MMA(0, 1, At, B1); PG8_BAR; PG8_SCHED;
	s_setprio 1
	v_mfma_f32_16x16x32_bf16 v[64:67], v[142:145], v[174:177], v[64:67]
	v_mfma_f32_16x16x32_bf16 v[60:63], v[150:153], v[174:177], v[60:63]
	v_mfma_f32_16x16x32_bf16 v[56:59], v[142:145], v[182:185], v[56:59]
	v_mfma_f32_16x16x32_bf16 v[52:55], v[150:153], v[182:185], v[52:55]
	v_mfma_f32_16x16x32_bf16 v[40:43], v[142:145], v[190:193], v[40:43]
	v_mfma_f32_16x16x32_bf16 v[36:39], v[150:153], v[190:193], v[36:39]
	v_mfma_f32_16x16x32_bf16 v[24:27], v[142:145], v[210:213], v[24:27]
	v_mfma_f32_16x16x32_bf16 v[20:23], v[150:153], v[210:213], v[20:23]
	v_mfma_f32_16x16x32_bf16 v[64:67], v[146:149], v[178:181], v[64:67]
	v_mfma_f32_16x16x32_bf16 v[60:63], v[154:157], v[178:181], v[60:63]
	v_mfma_f32_16x16x32_bf16 v[56:59], v[146:149], v[186:189], v[56:59]
	v_mfma_f32_16x16x32_bf16 v[52:55], v[154:157], v[186:189], v[52:55]
	v_mfma_f32_16x16x32_bf16 v[40:43], v[146:149], v[194:197], v[40:43]
	v_mfma_f32_16x16x32_bf16 v[36:39], v[154:157], v[194:197], v[36:39]
	v_mfma_f32_16x16x32_bf16 v[24:27], v[146:149], v[214:217], v[24:27]
	v_mfma_f32_16x16x32_bf16 v[20:23], v[154:157], v[214:217], v[20:23]
	s_setprio 0
	s_setprio 1
	v_mfma_f32_16x16x32_bf16 v[48:51], v[158:161], v[174:177], v[48:51]
	v_mfma_f32_16x16x32_bf16 v[44:47], v[166:169], v[174:177], v[44:47]
	v_mfma_f32_16x16x32_bf16 v[32:35], v[158:161], v[182:185], v[32:35]
	v_mfma_f32_16x16x32_bf16 v[28:31], v[166:169], v[182:185], v[28:31]
	v_mfma_f32_16x16x32_bf16 v[16:19], v[158:161], v[190:193], v[16:19]
	v_mfma_f32_16x16x32_bf16 v[12:15], v[166:169], v[190:193], v[12:15]
	v_mfma_f32_16x16x32_bf16 v[8:11], v[158:161], v[210:213], v[8:11]
	v_mfma_f32_16x16x32_bf16 v[4:7], v[166:169], v[210:213], v[4:7]
	v_mfma_f32_16x16x32_bf16 v[48:51], v[162:165], v[178:181], v[48:51]
	v_mfma_f32_16x16x32_bf16 v[44:47], v[170:173], v[178:181], v[44:47]
	v_mfma_f32_16x16x32_bf16 v[32:35], v[162:165], v[186:189], v[32:35]
	v_mfma_f32_16x16x32_bf16 v[28:31], v[170:173], v[186:189], v[28:31]
	v_mfma_f32_16x16x32_bf16 v[16:19], v[162:165], v[194:197], v[16:19]
	v_mfma_f32_16x16x32_bf16 v[12:15], v[170:173], v[194:197], v[12:15]
	v_mfma_f32_16x16x32_bf16 v[8:11], v[162:165], v[214:217], v[8:11]
	v_mfma_f32_16x16x32_bf16 v[4:7], v[170:173], v[214:217], v[4:7]
	s_setprio 0
	s_barrier
	v_add_u32_e32 v141, s79, v138
	ds_read_b128 v[142:145], v141
	ds_read_b128 v[146:149], v141 offset:1024
	ds_read_b128 v[150:153], v141 offset:2048
	ds_read_b128 v[154:157], v141 offset:3072
	v_add_u32_e32 v141, s78, v138
	ds_read_b128 v[158:161], v141
	ds_read_b128 v[162:165], v141 offset:1024
	ds_read_b128 v[166:169], v141 offset:2048
	ds_read_b128 v[170:173], v141 offset:3072
	s_mov_b32 m0, s67
	v_lshl_add_u64 v[224:225], s[22:23], 0, v[136:137]
	ds_read_b128 v[174:177], v140 offset:32768
	ds_read_b128 v[178:181], v140 offset:33792
	ds_read_b128 v[182:185], v140 offset:34816
	ds_read_b128 v[186:189], v140 offset:35840
	ds_read_b128 v[190:193], v140 offset:36864
	ds_read_b128 v[194:197], v140 offset:37888
	ds_read_b128 v[210:213], v140 offset:38912
	ds_read_b128 v[214:217], v140 offset:39936
	global_load_lds_dwordx4 v[224:225], off
	v_lshl_add_u64 v[224:225], s[22:23], 0, v[132:133]
	s_mov_b32 m0, s68
	s_nop 0
	global_load_lds_dwordx4 v[224:225], off
	s_waitcnt vmcnt(8)
	s_waitcnt lgkmcnt(0)
	s_barrier
	s_setprio 1
	v_mfma_f32_16x16x32_bf16 v[128:131], v[142:145], v[174:177], v[128:131]
	v_mfma_f32_16x16x32_bf16 v[124:127], v[150:153], v[174:177], v[124:127]
	v_mfma_f32_16x16x32_bf16 v[120:123], v[142:145], v[182:185], v[120:123]
	v_mfma_f32_16x16x32_bf16 v[116:119], v[150:153], v[182:185], v[116:119]
	v_mfma_f32_16x16x32_bf16 v[104:107], v[142:145], v[190:193], v[104:107]
	v_mfma_f32_16x16x32_bf16 v[100:103], v[150:153], v[190:193], v[100:103]
	v_mfma_f32_16x16x32_bf16 v[88:91], v[142:145], v[210:213], v[88:91]
	v_mfma_f32_16x16x32_bf16 v[84:87], v[150:153], v[210:213], v[84:87]
	v_mfma_f32_16x16x32_bf16 v[128:131], v[146:149], v[178:181], v[128:131]
	v_mfma_f32_16x16x32_bf16 v[124:127], v[154:157], v[178:181], v[124:127]
	v_mfma_f32_16x16x32_bf16 v[120:123], v[146:149], v[186:189], v[120:123]
	v_mfma_f32_16x16x32_bf16 v[116:119], v[154:157], v[186:189], v[116:119]
	v_mfma_f32_16x16x32_bf16 v[104:107], v[146:149], v[194:197], v[104:107]
	v_mfma_f32_16x16x32_bf16 v[100:103], v[154:157], v[194:197], v[100:103]
	v_mfma_f32_16x16x32_bf16 v[88:91], v[146:149], v[214:217], v[88:91]
	v_mfma_f32_16x16x32_bf16 v[84:87], v[154:157], v[214:217], v[84:87]
	s_setprio 0
	s_setprio 1
	v_mfma_f32_16x16x32_bf16 v[112:115], v[158:161], v[174:177], v[112:115]
	v_mfma_f32_16x16x32_bf16 v[108:111], v[166:169], v[174:177], v[108:111]
	v_mfma_f32_16x16x32_bf16 v[96:99], v[158:161], v[182:185], v[96:99]
	v_mfma_f32_16x16x32_bf16 v[92:95], v[166:169], v[182:185], v[92:95]
	v_mfma_f32_16x16x32_bf16 v[80:83], v[158:161], v[190:193], v[80:83]
	v_mfma_f32_16x16x32_bf16 v[76:79], v[166:169], v[190:193], v[76:79]
	v_mfma_f32_16x16x32_bf16 v[72:75], v[158:161], v[210:213], v[72:75]
	v_mfma_f32_16x16x32_bf16 v[68:71], v[166:169], v[210:213], v[68:71]
	v_mfma_f32_16x16x32_bf16 v[112:115], v[162:165], v[178:181], v[112:115]
	v_mfma_f32_16x16x32_bf16 v[108:111], v[170:173], v[178:181], v[108:111]
	v_mfma_f32_16x16x32_bf16 v[96:99], v[162:165], v[186:189], v[96:99]
	v_mfma_f32_16x16x32_bf16 v[92:95], v[170:173], v[186:189], v[92:95]
	v_mfma_f32_16x16x32_bf16 v[80:83], v[162:165], v[194:197], v[80:83]
	v_mfma_f32_16x16x32_bf16 v[76:79], v[170:173], v[194:197], v[76:79]
	v_mfma_f32_16x16x32_bf16 v[72:75], v[162:165], v[214:217], v[72:75]
	v_mfma_f32_16x16x32_bf16 v[68:71], v[170:173], v[214:217], v[68:71]
	s_setprio 0
	s_barrier
; #define PG8_STAGE(bufoff, gbase, voff) do { _Pragma("unroll") for (int _i = 0; _i < 2; ++_i) \
;         __builtin_amdgcn_global_load_lds((const unsigned*)((const char*)(gbase) + (voff)[_i]), (LAS unsigned*)(lds + (bufoff) + ldsw + _i * 8192), 16, 0, 0); } while (0)
; #define PG8_LDA(dst, b, h) do { _Pragma("unroll") for (int m = 0; m < 4; ++m) _Pragma("unroll") for (int k = 0; k < 2; ++k) dst[m][k] = *(const LAS bf16x8*)(lds + PG8_SA(b, h) + aoff + m * 2048 + k * 1024); } while (0)
; #define PG8_MMA(ai, bj, At, Bt) do { __builtin_amdgcn_s_setprio(1); _Pragma("unroll") for (int m = 0; m < 4; ++m) _Pragma("unroll") for (int n = 0; n < 2; ++n) _Pragma("unroll") for (int k = 0; k < 2; ++k) \
;         acc[ai][bj][m][n] = __builtin_amdgcn_mfma_f32_16x16x32_bf16(Bt[n][k], At[m][k], acc[ai][bj][m][n], 0, 0, 0); __builtin_amdgcn_s_setprio(0); } while (0)
; #define PG8_WAIT_V(n) asm volatile("s_waitcnt vmcnt(" #n ")" ::: "memory")
; #define PG8_WAIT_L(n) asm volatile("s_waitcnt lgkmcnt(" #n ")" ::: "memory")
; #define PG8_BAR __builtin_amdgcn_s_barrier()
; #define PG8_SCHED __builtin_amdgcn_sched_barrier(0)
; template <class Epi>
; __device__ __forceinline__ void gemm_phase(LAS unsigned char* lds, const Gemm g, const StaticOrder& S, const Epi& E) {
;     ...
;             PG8_LDA(At, 1, 1); PG8_STAGE(PG8_SB(1, 0), b3, voffB); PG8_STAGE(PG8_SB(1, 1), b3 + hstepB, voffB); PG8_STAGE(PG8_SA(1, 0), a3, voffA);
;             PG8_WAIT_V(8); PG8_WAIT_L(0); PG8_BAR; PG8_MMA(1, 0, At, B0); PG8_MMA(1, 1, At, B1); PG8_BAR; PG8_SCHED;
;         }
;         if (wr == 0) PG8_BAR;
	s_mov_b32 m0, s77
	v_lshl_add_u64 v[198:199], v[198:199], 0, s[30:31]
	ds_read_b128 v[174:177], v140 offset:49152
	ds_read_b128 v[178:181], v140 offset:50176
	ds_read_b128 v[182:185], v140 offset:51200
	ds_read_b128 v[186:189], v140 offset:52224
	ds_read_b128 v[190:193], v140 offset:53248
	ds_read_b128 v[194:197], v140 offset:54272
	ds_read_b128 v[210:213], v140 offset:55296
	ds_read_b128 v[214:217], v140 offset:56320
	global_load_lds_dwordx4 v[198:199], off
	v_lshl_add_u64 v[198:199], v[218:219], 0, s[30:31]
	s_mov_b32 m0, s76
	s_nop 0
	global_load_lds_dwordx4 v[198:199], off
	v_lshl_add_u64 v[198:199], s[50:51], 0, v[134:135]
	s_mov_b32 m0, s85
	s_nop 0
	global_load_lds_dwordx4 v[198:199], off
	v_lshl_add_u64 v[198:199], s[50:51], 0, v[0:1]
	s_mov_b32 m0, s84
	s_nop 0
	global_load_lds_dwordx4 v[198:199], off
	v_lshl_add_u64 v[198:199], v[220:221], 0, s[30:31]
	s_mov_b32 m0, s69
	s_nop 0
	global_load_lds_dwordx4 v[198:199], off
	v_lshl_add_u64 v[198:199], v[222:223], 0, s[30:31]
	s_mov_b32 m0, s70
	s_nop 0
	global_load_lds_dwordx4 v[198:199], off
	s_waitcnt vmcnt(8)
	s_waitcnt lgkmcnt(0)
	s_barrier
	s_setprio 1
	v_mfma_f32_16x16x32_bf16 v[64:67], v[142:145], v[174:177], v[64:67]
	v_mfma_f32_16x16x32_bf16 v[60:63], v[150:153], v[174:177], v[60:63]
	v_mfma_f32_16x16x32_bf16 v[56:59], v[142:145], v[182:185], v[56:59]
	v_mfma_f32_16x16x32_bf16 v[52:55], v[150:153], v[182:185], v[52:55]
	v_mfma_f32_16x16x32_bf16 v[40:43], v[142:145], v[190:193], v[40:43]
	v_mfma_f32_16x16x32_bf16 v[36:39], v[150:153], v[190:193], v[36:39]
	v_mfma_f32_16x16x32_bf16 v[24:27], v[142:145], v[210:213], v[24:27]
	v_mfma_f32_16x16x32_bf16 v[20:23], v[150:153], v[210:213], v[20:23]
	v_mfma_f32_16x16x32_bf16 v[64:67], v[146:149], v[178:181], v[64:67]
	v_mfma_f32_16x16x32_bf16 v[60:63], v[154:157], v[178:181], v[60:63]
	v_mfma_f32_16x16x32_bf16 v[56:59], v[146:149], v[186:189], v[56:59]
	v_mfma_f32_16x16x32_bf16 v[52:55], v[154:157], v[186:189], v[52:55]
	v_mfma_f32_16x16x32_bf16 v[40:43], v[146:149], v[194:197], v[40:43]
	v_mfma_f32_16x16x32_bf16 v[36:39], v[154:157], v[194:197], v[36:39]
	v_mfma_f32_16x16x32_bf16 v[24:27], v[146:149], v[214:217], v[24:27]
	v_mfma_f32_16x16x32_bf16 v[20:23], v[154:157], v[214:217], v[20:23]
	s_setprio 0
	s_setprio 1
	v_mfma_f32_16x16x32_bf16 v[48:51], v[158:161], v[174:177], v[48:51]
	v_mfma_f32_16x16x32_bf16 v[44:47], v[166:169], v[174:177], v[44:47]
	v_mfma_f32_16x16x32_bf16 v[32:35], v[158:161], v[182:185], v[32:35]
	v_mfma_f32_16x16x32_bf16 v[28:31], v[166:169], v[182:185], v[28:31]
	v_mfma_f32_16x16x32_bf16 v[16:19], v[158:161], v[190:193], v[16:19]
	v_mfma_f32_16x16x32_bf16 v[12:15], v[166:169], v[190:193], v[12:15]
	v_mfma_f32_16x16x32_bf16 v[8:11], v[158:161], v[210:213], v[8:11]
	v_mfma_f32_16x16x32_bf16 v[4:7], v[166:169], v[210:213], v[4:7]
	v_mfma_f32_16x16x32_bf16 v[48:51], v[162:165], v[178:181], v[48:51]
	v_mfma_f32_16x16x32_bf16 v[44:47], v[170:173], v[178:181], v[44:47]
	v_mfma_f32_16x16x32_bf16 v[32:35], v[162:165], v[186:189], v[32:35]
	v_mfma_f32_16x16x32_bf16 v[28:31], v[170:173], v[186:189], v[28:31]
	v_mfma_f32_16x16x32_bf16 v[16:19], v[162:165], v[194:197], v[16:19]
	v_mfma_f32_16x16x32_bf16 v[12:15], v[170:173], v[194:197], v[12:15]
	v_mfma_f32_16x16x32_bf16 v[8:11], v[162:165], v[214:217], v[8:11]
	v_mfma_f32_16x16x32_bf16 v[4:7], v[170:173], v[214:217], v[4:7]
	s_setprio 0
	s_barrier
	s_movk_i32 s22, 0x100
	s_andn2_b64 vcc, exec, s[48:49]
	s_mov_b64 s[50:51], -1
	s_mov_b64 s[48:49], 0
	s_cbranch_vccz .LBB0_1250
	s_and_b64 vcc, exec, s[10:11]
	s_cbranch_vccz .LBB0_1253
	s_barrier

; #define PG8_STAGE(bufoff, gbase, voff) do { _Pragma("unroll") for (int _i = 0; _i < 2; ++_i) \
;         __builtin_amdgcn_global_load_lds((const unsigned*)((const char*)(gbase) + (voff)[_i]), (LAS unsigned*)(lds + (bufoff) + ldsw + _i * 8192), 16, 0, 0); } while (0)
; #define PG8_LDA(dst, b, h) do { _Pragma("unroll") for (int m = 0; m < 4; ++m) _Pragma("unroll") for (int k = 0; k < 2; ++k) dst[m][k] = *(const LAS bf16x8*)(lds + PG8_SA(b, h) + aoff + m * 2048 + k * 1024); } while (0)
; #define PG8_LDB(dst, b, h) do { _Pragma("unroll") for (int n = 0; n < 2; ++n) _Pragma("unroll") for (int k = 0; k < 2; ++k) dst[n][k] = *(const LAS bf16x8*)(lds + PG8_SB(b, h) + boff + n * 2048 + k * 1024); } while (0)
; #define PG8_MMA(ai, bj, At, Bt) do { __builtin_amdgcn_s_setprio(1); _Pragma("unroll") for (int m = 0; m < 4; ++m) _Pragma("unroll") for (int n = 0; n < 2; ++n) _Pragma("unroll") for (int k = 0; k < 2; ++k) \
;         acc[ai][bj][m][n] = __builtin_amdgcn_mfma_f32_16x16x32_bf16(Bt[n][k], At[m][k], acc[ai][bj][m][n], 0, 0, 0); __builtin_amdgcn_s_setprio(0); } while (0)
; #define PG8_WAIT_V(n) asm volatile("s_waitcnt vmcnt(" #n ")" ::: "memory")
; #define PG8_WAIT_L(n) asm volatile("s_waitcnt lgkmcnt(" #n ")" ::: "memory")
; #define PG8_BAR __builtin_amdgcn_s_barrier()
; #define PG8_SCHED __builtin_amdgcn_sched_barrier(0)
; template <class Epi>
; __device__ __forceinline__ void gemm_phase(LAS unsigned char* lds, const Gemm g, const StaticOrder& S, const Epi& E) {
;     ...
;         for (int t = 0; t < nt; t += 2) {
;             const bool last = (t == nt - 2);
;             const char* a1 = cA + (size_t)(t + 1) * kstep;
;             const char* a2 = last ? nA : cA + (size_t)(t + 2) * kstep; const char* b2 = last ? nB : cB + (size_t)(t + 2) * kstep;
;             const char* a3 = a2 + kstep; const char* b3 = b2 + kstep;
;             PG8_LDB(B0, 0, 0); PG8_LDB(B1, 0, 1); PG8_SCHED; PG8_LDA(At, 0, 0); PG8_STAGE(PG8_SA(1, 1), a1 + hstepA, voffA);
;             PG8_WAIT_V(8); PG8_WAIT_L(0); PG8_BAR; PG8_MMA(0, 0, At, B0); PG8_MMA(0, 1, At, B1); PG8_BAR; PG8_SCHED;
;             PG8_LDA(At, 0, 1); PG8_STAGE(PG8_SB(0, 0), b2, voffB); PG8_STAGE(PG8_SB(0, 1), b2 + hstepB, voffB); PG8_STAGE(PG8_SA(0, 0), a2, voffA);
.LBB0_1270:
	s_add_u32 s22, s56, 0xfffc0080
	s_addc_u32 s23, s57, -1
	s_add_i32 s74, 0, 0x10000
	s_cmp_eq_u32 s73, 12
	s_cselect_b32 s59, s47, s23
	s_cselect_b32 s58, s69, s22
	s_cselect_b32 s23, s45, s72
	s_cselect_b32 s22, s70, s71
	s_add_i32 s76, 0, 0x14000
	v_add_u32_e32 v144, s74, v180
	v_add_u32_e32 v170, s76, v180
	ds_read_b128 v[132:135], v144
	ds_read_b128 v[136:139], v144 offset:1024
	ds_read_b128 v[140:143], v144 offset:2048
	ds_read_b128 v[144:147], v144 offset:3072
	ds_read_b128 v[148:151], v170
	ds_read_b128 v[152:155], v170 offset:1024
	ds_read_b128 v[166:169], v170 offset:2048
	ds_read_b128 v[170:173], v170 offset:3072
	v_lshl_add_u64 v[178:179], s[56:57], 0, v[162:163]
	s_add_i32 m0, s53, 0xc000
	ds_read_b128 v[174:177], v182
	ds_read_b128 v[184:187], v182 offset:1024
	ds_read_b128 v[188:191], v182 offset:2048
	ds_read_b128 v[192:195], v182 offset:3072
	ds_read_b128 v[196:199], v182 offset:4096
	ds_read_b128 v[210:213], v182 offset:5120
	ds_read_b128 v[214:217], v182 offset:6144
	ds_read_b128 v[218:221], v182 offset:7168
	global_load_lds_dwordx4 v[178:179], off
	v_lshl_add_u64 v[178:179], s[56:57], 0, v[164:165]
	s_add_i32 m0, s53, 0xe000
	s_nop 0
	global_load_lds_dwordx4 v[178:179], off
	s_waitcnt vmcnt(8)
	s_waitcnt lgkmcnt(0)
	s_barrier
	s_setprio 1
	v_mfma_f32_16x16x32_bf16 v[128:131], v[132:135], v[174:177], v[128:131]
	v_mfma_f32_16x16x32_bf16 v[124:127], v[140:143], v[174:177], v[124:127]
	v_mfma_f32_16x16x32_bf16 v[112:115], v[132:135], v[188:191], v[112:115]
	v_mfma_f32_16x16x32_bf16 v[108:111], v[140:143], v[188:191], v[108:111]
	v_mfma_f32_16x16x32_bf16 v[96:99], v[132:135], v[196:199], v[96:99]
	v_mfma_f32_16x16x32_bf16 v[92:95], v[140:143], v[196:199], v[92:95]
	v_mfma_f32_16x16x32_bf16 v[80:83], v[132:135], v[214:217], v[80:83]
	v_mfma_f32_16x16x32_bf16 v[76:79], v[140:143], v[214:217], v[76:79]
	v_mfma_f32_16x16x32_bf16 v[128:131], v[136:139], v[184:187], v[128:131]
	v_mfma_f32_16x16x32_bf16 v[124:127], v[144:147], v[184:187], v[124:127]
	v_mfma_f32_16x16x32_bf16 v[112:115], v[136:139], v[192:195], v[112:115]
	v_mfma_f32_16x16x32_bf16 v[108:111], v[144:147], v[192:195], v[108:111]
	v_mfma_f32_16x16x32_bf16 v[96:99], v[136:139], v[210:213], v[96:99]
	v_mfma_f32_16x16x32_bf16 v[92:95], v[144:147], v[210:213], v[92:95]
	v_mfma_f32_16x16x32_bf16 v[80:83], v[136:139], v[218:221], v[80:83]
	v_mfma_f32_16x16x32_bf16 v[76:79], v[144:147], v[218:221], v[76:79]
	s_setprio 0
	s_setprio 1
	v_mfma_f32_16x16x32_bf16 v[120:123], v[148:151], v[174:177], v[120:123]
	v_mfma_f32_16x16x32_bf16 v[116:119], v[166:169], v[174:177], v[116:119]
	v_mfma_f32_16x16x32_bf16 v[104:107], v[148:151], v[188:191], v[104:107]
	v_mfma_f32_16x16x32_bf16 v[100:103], v[166:169], v[188:191], v[100:103]
	v_mfma_f32_16x16x32_bf16 v[88:91], v[148:151], v[196:199], v[88:91]
	v_mfma_f32_16x16x32_bf16 v[84:87], v[166:169], v[196:199], v[84:87]
	v_mfma_f32_16x16x32_bf16 v[72:75], v[148:151], v[214:217], v[72:75]
	v_mfma_f32_16x16x32_bf16 v[68:71], v[166:169], v[214:217], v[68:71]
	v_mfma_f32_16x16x32_bf16 v[120:123], v[152:155], v[184:187], v[120:123]
	v_mfma_f32_16x16x32_bf16 v[116:119], v[170:173], v[184:187], v[116:119]
	v_mfma_f32_16x16x32_bf16 v[104:107], v[152:155], v[192:195], v[104:107]
	v_mfma_f32_16x16x32_bf16 v[100:103], v[170:173], v[192:195], v[100:103]
	v_mfma_f32_16x16x32_bf16 v[88:91], v[152:155], v[210:213], v[88:91]
	v_mfma_f32_16x16x32_bf16 v[84:87], v[170:173], v[210:213], v[84:87]
	v_mfma_f32_16x16x32_bf16 v[72:75], v[152:155], v[218:221], v[72:75]
	v_mfma_f32_16x16x32_bf16 v[68:71], v[170:173], v[218:221], v[68:71]
	s_setprio 0
	s_barrier
	s_add_i32 s74, s74, s64
	v_lshl_add_u64 v[178:179], s[22:23], 0, v[158:159]
	s_mov_b32 m0, s74
	ds_read_b128 v[174:177], v182 offset:16384
	ds_read_b128 v[184:187], v182 offset:17408
	ds_read_b128 v[188:191], v182 offset:18432
	ds_read_b128 v[192:195], v182 offset:19456
	ds_read_b128 v[196:199], v182 offset:20480
	ds_read_b128 v[210:213], v182 offset:21504
	ds_read_b128 v[214:217], v182 offset:22528
	ds_read_b128 v[218:221], v182 offset:23552
	global_load_lds_dwordx4 v[178:179], off
	s_add_i32 m0, s74, 0x2000
	s_add_u32 s74, s22, 0x10000
	v_lshl_add_u64 v[222:223], s[22:23], 0, v[0:1]
	s_addc_u32 s75, s23, 0
	s_add_i32 s76, s76, s64
	global_load_lds_dwordx4 v[222:223], off
	v_lshl_add_u64 v[224:225], s[74:75], 0, v[158:159]
	s_mov_b32 m0, s76
	v_lshl_add_u64 v[226:227], s[58:59], 0, v[156:157]
	global_load_lds_dwordx4 v[224:225], off
	v_lshl_add_u64 v[224:225], s[74:75], 0, v[0:1]
	s_add_i32 m0, s76, 0x2000
	s_nop 0
	global_load_lds_dwordx4 v[224:225], off
	v_lshl_add_u64 v[224:225], s[58:59], 0, v[160:161]
	s_mov_b32 m0, s53
	s_nop 0
	global_load_lds_dwordx4 v[224:225], off
	s_mov_b32 m0, s55
	s_nop 0
	global_load_lds_dwordx4 v[226:227], off
	s_waitcnt vmcnt(8)
	s_waitcnt lgkmcnt(0)
	s_barrier
; #define PG8_STAGE(bufoff, gbase, voff) do { _Pragma("unroll") for (int _i = 0; _i < 2; ++_i) \
;         __builtin_amdgcn_global_load_lds((const unsigned*)((const char*)(gbase) + (voff)[_i]), (LAS unsigned*)(lds + (bufoff) + ldsw + _i * 8192), 16, 0, 0); } while (0)
; #define PG8_LDA(dst, b, h) do { _Pragma("unroll") for (int m = 0; m < 4; ++m) _Pragma("unroll") for (int k = 0; k < 2; ++k) dst[m][k] = *(const LAS bf16x8*)(lds + PG8_SA(b, h) + aoff + m * 2048 + k * 1024); } while (0)
; #define PG8_LDB(dst, b, h) do { _Pragma("unroll") for (int n = 0; n < 2; ++n) _Pragma("unroll") for (int k = 0; k < 2; ++k) dst[n][k] = *(const LAS bf16x8*)(lds + PG8_SB(b, h) + boff + n * 2048 + k * 1024); } while (0)
; #define PG8_MMA(ai, bj, At, Bt) do { __builtin_amdgcn_s_setprio(1); _Pragma("unroll") for (int m = 0; m < 4; ++m) _Pragma("unroll") for (int n = 0; n < 2; ++n) _Pragma("unroll") for (int k = 0; k < 2; ++k) \
;         acc[ai][bj][m][n] = __builtin_amdgcn_mfma_f32_16x16x32_bf16(Bt[n][k], At[m][k], acc[ai][bj][m][n], 0, 0, 0); __builtin_amdgcn_s_setprio(0); } while (0)
; #define PG8_WAIT_V(n) asm volatile("s_waitcnt vmcnt(" #n ")" ::: "memory")
; #define PG8_WAIT_L(n) asm volatile("s_waitcnt lgkmcnt(" #n ")" ::: "memory")
; #define PG8_BAR __builtin_amdgcn_s_barrier()
; #define PG8_SCHED __builtin_amdgcn_sched_barrier(0)
; template <class Epi>
; __device__ __forceinline__ void gemm_phase(LAS unsigned char* lds, const Gemm g, const StaticOrder& S, const Epi& E) {
;     ...
;             PG8_WAIT_V(8); PG8_WAIT_L(0); PG8_BAR; PG8_MMA(1, 0, At, B0); PG8_MMA(1, 1, At, B1); PG8_BAR; PG8_SCHED;
;             PG8_LDB(B0, 1, 0); PG8_LDB(B1, 1, 1); PG8_SCHED; PG8_LDA(At, 1, 0); PG8_STAGE(PG8_SA(0, 1), a2 + hstepA, voffA);
;             PG8_WAIT_V(8); PG8_WAIT_L(0); PG8_BAR; PG8_MMA(0, 0, At, B0); PG8_MMA(0, 1, At, B1); PG8_BAR; PG8_SCHED;
	s_setprio 1
	v_mfma_f32_16x16x32_bf16 v[64:67], v[132:135], v[174:177], v[64:67]
	v_mfma_f32_16x16x32_bf16 v[60:63], v[140:143], v[174:177], v[60:63]
	v_mfma_f32_16x16x32_bf16 v[48:51], v[132:135], v[188:191], v[48:51]
	v_mfma_f32_16x16x32_bf16 v[44:47], v[140:143], v[188:191], v[44:47]
	v_mfma_f32_16x16x32_bf16 v[32:35], v[132:135], v[196:199], v[32:35]
	v_mfma_f32_16x16x32_bf16 v[28:31], v[140:143], v[196:199], v[28:31]
	v_mfma_f32_16x16x32_bf16 v[16:19], v[132:135], v[214:217], v[16:19]
	v_mfma_f32_16x16x32_bf16 v[12:15], v[140:143], v[214:217], v[12:15]
	v_mfma_f32_16x16x32_bf16 v[64:67], v[136:139], v[184:187], v[64:67]
	v_mfma_f32_16x16x32_bf16 v[60:63], v[144:147], v[184:187], v[60:63]
	v_mfma_f32_16x16x32_bf16 v[48:51], v[136:139], v[192:195], v[48:51]
	v_mfma_f32_16x16x32_bf16 v[44:47], v[144:147], v[192:195], v[44:47]
	v_mfma_f32_16x16x32_bf16 v[32:35], v[136:139], v[210:213], v[32:35]
	v_mfma_f32_16x16x32_bf16 v[28:31], v[144:147], v[210:213], v[28:31]
	v_mfma_f32_16x16x32_bf16 v[16:19], v[136:139], v[218:221], v[16:19]
	v_mfma_f32_16x16x32_bf16 v[12:15], v[144:147], v[218:221], v[12:15]
	s_setprio 0
	s_setprio 1
	v_mfma_f32_16x16x32_bf16 v[56:59], v[148:151], v[174:177], v[56:59]
	v_mfma_f32_16x16x32_bf16 v[52:55], v[166:169], v[174:177], v[52:55]
	v_mfma_f32_16x16x32_bf16 v[40:43], v[148:151], v[188:191], v[40:43]
	v_mfma_f32_16x16x32_bf16 v[36:39], v[166:169], v[188:191], v[36:39]
	v_mfma_f32_16x16x32_bf16 v[24:27], v[148:151], v[196:199], v[24:27]
	v_mfma_f32_16x16x32_bf16 v[20:23], v[166:169], v[196:199], v[20:23]
	v_mfma_f32_16x16x32_bf16 v[8:11], v[148:151], v[214:217], v[8:11]
	v_mfma_f32_16x16x32_bf16 v[4:7], v[166:169], v[214:217], v[4:7]
	v_mfma_f32_16x16x32_bf16 v[56:59], v[152:155], v[184:187], v[56:59]
	v_mfma_f32_16x16x32_bf16 v[52:55], v[170:173], v[184:187], v[52:55]
	v_mfma_f32_16x16x32_bf16 v[40:43], v[152:155], v[192:195], v[40:43]
	v_mfma_f32_16x16x32_bf16 v[36:39], v[170:173], v[192:195], v[36:39]
	v_mfma_f32_16x16x32_bf16 v[24:27], v[152:155], v[210:213], v[24:27]
	v_mfma_f32_16x16x32_bf16 v[20:23], v[170:173], v[210:213], v[20:23]
	v_mfma_f32_16x16x32_bf16 v[8:11], v[152:155], v[218:221], v[8:11]
	v_mfma_f32_16x16x32_bf16 v[4:7], v[170:173], v[218:221], v[4:7]
	s_setprio 0
	s_barrier
	s_add_i32 s74, 0, 0x18000
	s_add_i32 s75, 0, 0x1c000
	v_add_u32_e32 v144, s74, v180
	v_add_u32_e32 v170, s75, v180
	ds_read_b128 v[132:135], v144
	ds_read_b128 v[136:139], v144 offset:1024
	ds_read_b128 v[140:143], v144 offset:2048
	ds_read_b128 v[144:147], v144 offset:3072
	ds_read_b128 v[148:151], v170
	ds_read_b128 v[152:155], v170 offset:1024
	ds_read_b128 v[166:169], v170 offset:2048
	ds_read_b128 v[170:173], v170 offset:3072
	s_add_u32 s58, s58, 0x40000
	s_addc_u32 s59, s59, 0
	s_mov_b32 m0, s65
	v_lshl_add_u64 v[228:229], s[58:59], 0, v[160:161]
	ds_read_b128 v[174:177], v182 offset:32768
	ds_read_b128 v[184:187], v182 offset:33792
	ds_read_b128 v[188:191], v182 offset:34816
	ds_read_b128 v[192:195], v182 offset:35840
	ds_read_b128 v[196:199], v182 offset:36864
	ds_read_b128 v[210:213], v182 offset:37888
	ds_read_b128 v[214:217], v182 offset:38912
	ds_read_b128 v[218:221], v182 offset:39936
	global_load_lds_dwordx4 v[228:229], off
	v_lshl_add_u64 v[228:229], s[58:59], 0, v[156:157]
	s_mov_b32 m0, s66
	s_nop 0
	global_load_lds_dwordx4 v[228:229], off
	s_waitcnt vmcnt(8)
	s_waitcnt lgkmcnt(0)
	s_barrier
	s_setprio 1
	v_mfma_f32_16x16x32_bf16 v[128:131], v[132:135], v[174:177], v[128:131]
	v_mfma_f32_16x16x32_bf16 v[124:127], v[140:143], v[174:177], v[124:127]
	v_mfma_f32_16x16x32_bf16 v[112:115], v[132:135], v[188:191], v[112:115]
	v_mfma_f32_16x16x32_bf16 v[108:111], v[140:143], v[188:191], v[108:111]
	v_mfma_f32_16x16x32_bf16 v[96:99], v[132:135], v[196:199], v[96:99]
	v_mfma_f32_16x16x32_bf16 v[92:95], v[140:143], v[196:199], v[92:95]
	v_mfma_f32_16x16x32_bf16 v[80:83], v[132:135], v[214:217], v[80:83]
	v_mfma_f32_16x16x32_bf16 v[76:79], v[140:143], v[214:217], v[76:79]
	v_mfma_f32_16x16x32_bf16 v[128:131], v[136:139], v[184:187], v[128:131]
	v_mfma_f32_16x16x32_bf16 v[124:127], v[144:147], v[184:187], v[124:127]
	v_mfma_f32_16x16x32_bf16 v[112:115], v[136:139], v[192:195], v[112:115]
	v_mfma_f32_16x16x32_bf16 v[108:111], v[144:147], v[192:195], v[108:111]
	v_mfma_f32_16x16x32_bf16 v[96:99], v[136:139], v[210:213], v[96:99]
	v_mfma_f32_16x16x32_bf16 v[92:95], v[144:147], v[210:213], v[92:95]
	v_mfma_f32_16x16x32_bf16 v[80:83], v[136:139], v[218:221], v[80:83]
	v_mfma_f32_16x16x32_bf16 v[76:79], v[144:147], v[218:221], v[76:79]
	s_setprio 0
	s_setprio 1
	v_mfma_f32_16x16x32_bf16 v[120:123], v[148:151], v[174:177], v[120:123]
	v_mfma_f32_16x16x32_bf16 v[116:119], v[166:169], v[174:177], v[116:119]
	v_mfma_f32_16x16x32_bf16 v[104:107], v[148:151], v[188:191], v[104:107]
	v_mfma_f32_16x16x32_bf16 v[100:103], v[166:169], v[188:191], v[100:103]
	v_mfma_f32_16x16x32_bf16 v[88:91], v[148:151], v[196:199], v[88:91]
	v_mfma_f32_16x16x32_bf16 v[84:87], v[166:169], v[196:199], v[84:87]
	v_mfma_f32_16x16x32_bf16 v[72:75], v[148:151], v[214:217], v[72:75]
	v_mfma_f32_16x16x32_bf16 v[68:71], v[166:169], v[214:217], v[68:71]
	v_mfma_f32_16x16x32_bf16 v[120:123], v[152:155], v[184:187], v[120:123]
	v_mfma_f32_16x16x32_bf16 v[116:119], v[170:173], v[184:187], v[116:119]
	v_mfma_f32_16x16x32_bf16 v[104:107], v[152:155], v[192:195], v[104:107]
	v_mfma_f32_16x16x32_bf16 v[100:103], v[170:173], v[192:195], v[100:103]
	v_mfma_f32_16x16x32_bf16 v[88:91], v[152:155], v[210:213], v[88:91]
	v_mfma_f32_16x16x32_bf16 v[84:87], v[170:173], v[210:213], v[84:87]
	v_mfma_f32_16x16x32_bf16 v[72:75], v[152:155], v[218:221], v[72:75]
	v_mfma_f32_16x16x32_bf16 v[68:71], v[170:173], v[218:221], v[68:71]
	s_setprio 0
	s_barrier
; #define PG8_STAGE(bufoff, gbase, voff) do { _Pragma("unroll") for (int _i = 0; _i < 2; ++_i) \
;         __builtin_amdgcn_global_load_lds((const unsigned*)((const char*)(gbase) + (voff)[_i]), (LAS unsigned*)(lds + (bufoff) + ldsw + _i * 8192), 16, 0, 0); } while (0)
; #define PG8_LDA(dst, b, h) do { _Pragma("unroll") for (int m = 0; m < 4; ++m) _Pragma("unroll") for (int k = 0; k < 2; ++k) dst[m][k] = *(const LAS bf16x8*)(lds + PG8_SA(b, h) + aoff + m * 2048 + k * 1024); } while (0)
; #define PG8_MMA(ai, bj, At, Bt) do { __builtin_amdgcn_s_setprio(1); _Pragma("unroll") for (int m = 0; m < 4; ++m) _Pragma("unroll") for (int n = 0; n < 2; ++n) _Pragma("unroll") for (int k = 0; k < 2; ++k) \
;         acc[ai][bj][m][n] = __builtin_amdgcn_mfma_f32_16x16x32_bf16(Bt[n][k], At[m][k], acc[ai][bj][m][n], 0, 0, 0); __builtin_amdgcn_s_setprio(0); } while (0)
; #define PG8_WAIT_V(n) asm volatile("s_waitcnt vmcnt(" #n ")" ::: "memory")
; #define PG8_WAIT_L(n) asm volatile("s_waitcnt lgkmcnt(" #n ")" ::: "memory")
; #define PG8_BAR __builtin_amdgcn_s_barrier()
; #define PG8_SCHED __builtin_amdgcn_sched_barrier(0)
; template <class Epi>
; __device__ __forceinline__ void gemm_phase(LAS unsigned char* lds, const Gemm g, const StaticOrder& S, const Epi& E) {
;     ...
;             PG8_LDA(At, 1, 1); PG8_STAGE(PG8_SB(1, 0), b3, voffB); PG8_STAGE(PG8_SB(1, 1), b3 + hstepB, voffB); PG8_STAGE(PG8_SA(1, 0), a3, voffA);
;             PG8_WAIT_V(8); PG8_WAIT_L(0); PG8_BAR; PG8_MMA(1, 0, At, B0); PG8_MMA(1, 1, At, B1); PG8_BAR; PG8_SCHED;
;         }
;         if (wr == 0) PG8_BAR;
	s_add_i32 s58, s74, s64
	v_lshl_add_u64 v[178:179], v[178:179], 0, s[30:31]
	s_mov_b32 m0, s58
	ds_read_b128 v[174:177], v182 offset:49152
	ds_read_b128 v[184:187], v182 offset:50176
	ds_read_b128 v[188:191], v182 offset:51200
	ds_read_b128 v[192:195], v182 offset:52224
	ds_read_b128 v[196:199], v182 offset:53248
	ds_read_b128 v[210:213], v182 offset:54272
	ds_read_b128 v[214:217], v182 offset:55296
	ds_read_b128 v[218:221], v182 offset:56320
	global_load_lds_dwordx4 v[178:179], off
	s_add_i32 m0, s58, 0x2000
	s_add_u32 s22, s22, 0x10080
	v_lshl_add_u64 v[178:179], v[222:223], 0, s[30:31]
	s_addc_u32 s23, s23, 0
	s_add_i32 s58, s75, s64
	global_load_lds_dwordx4 v[178:179], off
	v_lshl_add_u64 v[178:179], s[22:23], 0, v[158:159]
	s_mov_b32 m0, s58
	s_nop 0
	global_load_lds_dwordx4 v[178:179], off
	v_lshl_add_u64 v[178:179], s[22:23], 0, v[0:1]
	s_add_i32 m0, s58, 0x2000
	s_nop 0
	global_load_lds_dwordx4 v[178:179], off
	v_lshl_add_u64 v[178:179], v[224:225], 0, s[30:31]
	s_mov_b32 m0, s28
	s_nop 0
	global_load_lds_dwordx4 v[178:179], off
	v_lshl_add_u64 v[178:179], v[226:227], 0, s[30:31]
	s_mov_b32 m0, s67
	s_nop 0
	global_load_lds_dwordx4 v[178:179], off
	s_waitcnt vmcnt(8)
	s_waitcnt lgkmcnt(0)
	s_barrier
	s_setprio 1
	v_mfma_f32_16x16x32_bf16 v[64:67], v[132:135], v[174:177], v[64:67]
	v_mfma_f32_16x16x32_bf16 v[60:63], v[140:143], v[174:177], v[60:63]
	v_mfma_f32_16x16x32_bf16 v[48:51], v[132:135], v[188:191], v[48:51]
	v_mfma_f32_16x16x32_bf16 v[44:47], v[140:143], v[188:191], v[44:47]
	v_mfma_f32_16x16x32_bf16 v[32:35], v[132:135], v[196:199], v[32:35]
	v_mfma_f32_16x16x32_bf16 v[28:31], v[140:143], v[196:199], v[28:31]
	v_mfma_f32_16x16x32_bf16 v[16:19], v[132:135], v[214:217], v[16:19]
	v_mfma_f32_16x16x32_bf16 v[12:15], v[140:143], v[214:217], v[12:15]
	v_mfma_f32_16x16x32_bf16 v[64:67], v[136:139], v[184:187], v[64:67]
	v_mfma_f32_16x16x32_bf16 v[60:63], v[144:147], v[184:187], v[60:63]
	v_mfma_f32_16x16x32_bf16 v[48:51], v[136:139], v[192:195], v[48:51]
	v_mfma_f32_16x16x32_bf16 v[44:47], v[144:147], v[192:195], v[44:47]
	v_mfma_f32_16x16x32_bf16 v[32:35], v[136:139], v[210:213], v[32:35]
	v_mfma_f32_16x16x32_bf16 v[28:31], v[144:147], v[210:213], v[28:31]
	v_mfma_f32_16x16x32_bf16 v[16:19], v[136:139], v[218:221], v[16:19]
	v_mfma_f32_16x16x32_bf16 v[12:15], v[144:147], v[218:221], v[12:15]
	s_setprio 0
	s_setprio 1
	v_mfma_f32_16x16x32_bf16 v[56:59], v[148:151], v[174:177], v[56:59]
	v_mfma_f32_16x16x32_bf16 v[52:55], v[166:169], v[174:177], v[52:55]
	v_mfma_f32_16x16x32_bf16 v[40:43], v[148:151], v[188:191], v[40:43]
	v_mfma_f32_16x16x32_bf16 v[36:39], v[166:169], v[188:191], v[36:39]
	v_mfma_f32_16x16x32_bf16 v[24:27], v[148:151], v[196:199], v[24:27]
	v_mfma_f32_16x16x32_bf16 v[20:23], v[166:169], v[196:199], v[20:23]
	v_mfma_f32_16x16x32_bf16 v[8:11], v[148:151], v[214:217], v[8:11]
	v_mfma_f32_16x16x32_bf16 v[4:7], v[166:169], v[214:217], v[4:7]
	v_mfma_f32_16x16x32_bf16 v[56:59], v[152:155], v[184:187], v[56:59]
	v_mfma_f32_16x16x32_bf16 v[52:55], v[170:173], v[184:187], v[52:55]
	v_mfma_f32_16x16x32_bf16 v[40:43], v[152:155], v[192:195], v[40:43]
	v_mfma_f32_16x16x32_bf16 v[36:39], v[170:173], v[192:195], v[36:39]
	v_mfma_f32_16x16x32_bf16 v[24:27], v[152:155], v[210:213], v[24:27]
	v_mfma_f32_16x16x32_bf16 v[20:23], v[170:173], v[210:213], v[20:23]
	v_mfma_f32_16x16x32_bf16 v[8:11], v[152:155], v[218:221], v[8:11]
	v_mfma_f32_16x16x32_bf16 v[4:7], v[170:173], v[218:221], v[4:7]
	s_setprio 0
	s_barrier
	s_add_i32 s73, s73, 2
	s_add_u32 s56, s56, 0x100
	s_addc_u32 s57, s57, 0
	s_add_u32 s71, s71, 0x100
	s_addc_u32 s72, s72, 0
	s_cmp_gt_u32 s73, 13
	s_cbranch_scc0 .LBB0_1270
	s_and_b64 vcc, exec, s[38:39]
	s_cbranch_vccz .LBB0_1273
	s_barrier
